# v13 + every 16-byte global store made write-through (sc1) so the grid barrier release fence has less dirty L2 to flush
# baseline (speedup 1.0000x reference)
; DI void stb8(bf16_t* p, const F8& f) { *(uint4*)p = pack8(f); }
; DI void prep_phase(const Params& p) {
;     ...
;     for (size_t i = gt; i < (size_t)MT * 128; i += gn) {
;         const size_t e = i * 8;
;         const float* s = e < (size_t)MP * 1024 ? p.in[0] + e : p.in[1] + (e - (size_t)MP * 1024);
;         stb8(XB + e, ldf8(s));
;     }
.LBB0_8:
	v_lshl_add_u64 v[12:13], s[36:37], 0, v[6:7]
	v_lshl_add_u64 v[14:15], s[12:13], 0, v[6:7]
	v_cmp_gt_u64_e32 vcc, s[20:21], v[10:11]
	v_lshl_add_u64 v[10:11], v[10:11], 0, s[4:5]
	v_lshl_add_u64 v[6:7], v[6:7], 0, s[14:15]
	v_cndmask_b32_e32 v17, v15, v13, vcc
	v_cndmask_b32_e32 v16, v14, v12, vcc
	global_load_dwordx4 v[12:15], v[16:17], off
	s_nop 0
	global_load_dwordx4 v[16:19], v[16:17], off offset:16
	v_cmp_lt_u64_e32 vcc, s[22:23], v[10:11]
	s_or_b64 s[18:19], vcc, s[18:19]
	s_waitcnt vmcnt(1)
	v_cvt_pk_bf16_f32 v12, v12, v13
	v_cvt_pk_bf16_f32 v13, v14, v15
	s_waitcnt vmcnt(0)
	v_cvt_pk_bf16_f32 v14, v16, v17
	v_cvt_pk_bf16_f32 v15, v18, v19
	global_store_dwordx4 v[8:9], v[12:15], off sc1
	v_lshl_add_u64 v[8:9], v[8:9], 0, s[16:17]
	s_andn2_b64 exec, exec, s[18:19]
	s_cbranch_execnz .LBB0_8

; DI void stb8(bf16_t* p, const F8& f) { *(uint4*)p = pack8(f); }
; DI void wconv(const float* __restrict__ src, bf16_t* __restrict__ dst, int K, int N, int Npad, int perm, unsigned char* smem) {
;     ...
;             float* tp = tile + k * 65 + nl4; tp[0] = v.x; tp[1] = v.y; tp[2] = v.z; tp[3] = v.w;
;         }
;         __syncthreads();
;         const int nl = tid >> 3, kc = (tid & 7) * 8, n = n0 + nl;
;         if (n < Npad) {
;             int nd = n;
;             if (perm) nd = n < 2816 ? (n >> 6) * 128 + (n & 63) : ((n - 2816) >> 6) * 128 + 64 + ((n - 2816) & 63);
;             F8 a;
; #pragma unroll
;             for (int e = 0; e < 8; ++e) a.v[e] = tile[(kc + e) * 65 + nl];
;             stb8(dst + (size_t)nd * K + k0 + kc, a);
.LBB0_23:
	s_or_b64 exec, exec, s[4:5]
	s_waitcnt vmcnt(1)
	ds_write2_b32 v16, v2, v3 offset1:1
	ds_write2_b32 v16, v4, v5 offset0:2 offset1:3
	s_waitcnt vmcnt(0)
	ds_write2_b32 v17, v6, v7 offset1:1
	ds_write2_b32 v18, v8, v9 offset1:1
	v_add_u32_e32 v2, s1, v15
	v_cmp_gt_i32_e32 vcc, s9, v2
	s_waitcnt lgkmcnt(0)
	s_barrier
	s_and_saveexec_b64 s[4:5], vcc
	s_cbranch_execz .LBB0_20
	ds_read2_b32 v[4:5], v19 offset1:65
	ds_read2_b32 v[6:7], v19 offset0:130 offset1:195
	ds_read2_b32 v[8:9], v20 offset0:4 offset1:69
	ds_read2_b32 v[12:13], v20 offset0:134 offset1:199
	v_ashrrev_i32_e32 v3, 31, v2
	v_lshlrev_b64 v[2:3], 11, v[2:3]
	v_lshl_add_u64 v[2:3], s[62:63], 0, v[2:3]
	s_ashr_i32 s1, s0, 31
	v_lshl_add_u64 v[2:3], s[0:1], 1, v[2:3]
	v_lshl_add_u64 v[22:23], v[2:3], 0, v[10:11]
	s_waitcnt lgkmcnt(3)
	v_cvt_pk_bf16_f32 v2, v4, v5
	s_waitcnt lgkmcnt(2)
	v_cvt_pk_bf16_f32 v3, v6, v7
	s_waitcnt lgkmcnt(1)
	v_cvt_pk_bf16_f32 v4, v8, v9
	s_waitcnt lgkmcnt(0)
	v_cvt_pk_bf16_f32 v5, v12, v13
	global_store_dwordx4 v[22:23], v[2:5], off sc1
	s_branch .LBB0_20

; DI void stb8(bf16_t* p, const F8& f) { *(uint4*)p = pack8(f); }
; DI void wconv(const float* __restrict__ src, bf16_t* __restrict__ dst, int K, int N, int Npad, int perm, unsigned char* smem) {
;     ...
;             float* tp = tile + k * 65 + nl4; tp[0] = v.x; tp[1] = v.y; tp[2] = v.z; tp[3] = v.w;
;         }
;         __syncthreads();
;         const int nl = tid >> 3, kc = (tid & 7) * 8, n = n0 + nl;
;         if (n < Npad) {
;             int nd = n;
;             if (perm) nd = n < 2816 ? (n >> 6) * 128 + (n & 63) : ((n - 2816) >> 6) * 128 + 64 + ((n - 2816) & 63);
;             F8 a;
; #pragma unroll
;             for (int e = 0; e < 8; ++e) a.v[e] = tile[(kc + e) * 65 + nl];
;             stb8(dst + (size_t)nd * K + k0 + kc, a);
.LBB0_30:
	s_or_b64 exec, exec, s[4:5]
	s_waitcnt vmcnt(1)
	ds_write2_b32 v16, v2, v3 offset1:1
	ds_write2_b32 v16, v4, v5 offset0:2 offset1:3
	s_waitcnt vmcnt(0)
	ds_write2_b32 v17, v6, v7 offset1:1
	ds_write2_b32 v18, v8, v9 offset1:1
	v_add_u32_e32 v2, s1, v15
	v_cmp_gt_i32_e32 vcc, s7, v2
	s_waitcnt lgkmcnt(0)
	s_barrier
	s_and_saveexec_b64 s[4:5], vcc
	s_cbranch_execz .LBB0_27
	ds_read2_b32 v[4:5], v19 offset1:65
	ds_read2_b32 v[6:7], v19 offset0:130 offset1:195
	ds_read2_b32 v[8:9], v20 offset0:4 offset1:69
	ds_read2_b32 v[12:13], v20 offset0:134 offset1:199
	v_readlane_b32 s2, v252, 43
	v_readlane_b32 s3, v252, 44
	s_ashr_i32 s1, s0, 31
	s_nop 0
	v_mov_b64_e32 v[22:23], s[2:3]
	v_mad_i64_i32 v[2:3], s[10:11], v2, s7, v[22:23]
	v_lshl_add_u64 v[2:3], s[0:1], 1, v[2:3]
	v_lshl_add_u64 v[22:23], v[2:3], 0, v[10:11]
	s_waitcnt lgkmcnt(3)
	v_cvt_pk_bf16_f32 v2, v4, v5
	s_waitcnt lgkmcnt(2)
	v_cvt_pk_bf16_f32 v3, v6, v7
	s_waitcnt lgkmcnt(1)
	v_cvt_pk_bf16_f32 v4, v8, v9
	s_waitcnt lgkmcnt(0)
	v_cvt_pk_bf16_f32 v5, v12, v13
	global_store_dwordx4 v[22:23], v[2:5], off sc1
	s_branch .LBB0_27

; DI void stb8(bf16_t* p, const F8& f) { *(uint4*)p = pack8(f); }
; DI void wconv(const float* __restrict__ src, bf16_t* __restrict__ dst, int K, int N, int Npad, int perm, unsigned char* smem) {
;     ...
;             float* tp = tile + k * 65 + nl4; tp[0] = v.x; tp[1] = v.y; tp[2] = v.z; tp[3] = v.w;
;         }
;         __syncthreads();
;         const int nl = tid >> 3, kc = (tid & 7) * 8, n = n0 + nl;
;         if (n < Npad) {
;             int nd = n;
;             if (perm) nd = n < 2816 ? (n >> 6) * 128 + (n & 63) : ((n - 2816) >> 6) * 128 + 64 + ((n - 2816) & 63);
;             F8 a;
; #pragma unroll
;             for (int e = 0; e < 8; ++e) a.v[e] = tile[(kc + e) * 65 + nl];
;             stb8(dst + (size_t)nd * K + k0 + kc, a);
.LBB0_37:
	s_or_b64 exec, exec, s[4:5]
	s_waitcnt vmcnt(1)
	ds_write2_b32 v16, v2, v3 offset1:1
	ds_write2_b32 v16, v4, v5 offset0:2 offset1:3
	s_waitcnt vmcnt(0)
	ds_write2_b32 v17, v6, v7 offset1:1
	ds_write2_b32 v18, v8, v9 offset1:1
	v_add_u32_e32 v2, s1, v15
	v_cmp_gt_i32_e32 vcc, s7, v2
	s_waitcnt lgkmcnt(0)
	s_barrier
	s_and_saveexec_b64 s[4:5], vcc
	s_cbranch_execz .LBB0_34
	ds_read2_b32 v[4:5], v19 offset1:65
	ds_read2_b32 v[6:7], v19 offset0:130 offset1:195
	ds_read2_b32 v[8:9], v20 offset0:4 offset1:69
	ds_read2_b32 v[12:13], v20 offset0:134 offset1:199
	v_ashrrev_i32_e32 v3, 31, v2
	v_readlane_b32 s2, v252, 45
	v_lshlrev_b64 v[2:3], 9, v[2:3]
	v_readlane_b32 s3, v252, 46
	s_ashr_i32 s1, s0, 31
	s_nop 0
	v_lshl_add_u64 v[2:3], s[2:3], 0, v[2:3]
	v_lshl_add_u64 v[2:3], s[0:1], 1, v[2:3]
	v_lshl_add_u64 v[22:23], v[2:3], 0, v[10:11]
	s_waitcnt lgkmcnt(3)
	v_cvt_pk_bf16_f32 v2, v4, v5
	s_waitcnt lgkmcnt(2)
	v_cvt_pk_bf16_f32 v3, v6, v7
	s_waitcnt lgkmcnt(1)
	v_cvt_pk_bf16_f32 v4, v8, v9
	s_waitcnt lgkmcnt(0)
	v_cvt_pk_bf16_f32 v5, v12, v13
	global_store_dwordx4 v[22:23], v[2:5], off sc1
	s_branch .LBB0_34

; DI void stb8(bf16_t* p, const F8& f) { *(uint4*)p = pack8(f); }
; DI void wconv(const float* __restrict__ src, bf16_t* __restrict__ dst, int K, int N, int Npad, int perm, unsigned char* smem) {
;     ...
;             float* tp = tile + k * 65 + nl4; tp[0] = v.x; tp[1] = v.y; tp[2] = v.z; tp[3] = v.w;
;         }
;         __syncthreads();
;         const int nl = tid >> 3, kc = (tid & 7) * 8, n = n0 + nl;
;         if (n < Npad) {
;             int nd = n;
;             if (perm) nd = n < 2816 ? (n >> 6) * 128 + (n & 63) : ((n - 2816) >> 6) * 128 + 64 + ((n - 2816) & 63);
;             F8 a;
; #pragma unroll
;             for (int e = 0; e < 8; ++e) a.v[e] = tile[(kc + e) * 65 + nl];
;             stb8(dst + (size_t)nd * K + k0 + kc, a);
.LBB0_44:
	s_or_b64 exec, exec, s[4:5]
	s_waitcnt vmcnt(1)
	ds_write2_b32 v16, v2, v3 offset1:1
	ds_write2_b32 v16, v4, v5 offset0:2 offset1:3
	s_waitcnt vmcnt(0)
	ds_write2_b32 v17, v6, v7 offset1:1
	ds_write2_b32 v18, v8, v9 offset1:1
	v_add_u32_e32 v2, s1, v15
	v_cmp_gt_i32_e32 vcc, s7, v2
	s_waitcnt lgkmcnt(0)
	s_barrier
	s_and_saveexec_b64 s[4:5], vcc
	s_cbranch_execz .LBB0_41
	ds_read2_b32 v[4:5], v19 offset1:65
	ds_read2_b32 v[6:7], v19 offset0:130 offset1:195
	ds_read2_b32 v[8:9], v20 offset0:4 offset1:69
	ds_read2_b32 v[12:13], v20 offset0:134 offset1:199
	v_ashrrev_i32_e32 v3, 31, v2
	v_readlane_b32 s2, v252, 47
	v_lshlrev_b64 v[2:3], 11, v[2:3]
	v_readlane_b32 s3, v252, 48
	s_ashr_i32 s1, s0, 31
	s_nop 0
	v_lshl_add_u64 v[2:3], s[2:3], 0, v[2:3]
	v_lshl_add_u64 v[2:3], s[0:1], 1, v[2:3]
	v_lshl_add_u64 v[22:23], v[2:3], 0, v[10:11]
	s_waitcnt lgkmcnt(3)
	v_cvt_pk_bf16_f32 v2, v4, v5
	s_waitcnt lgkmcnt(2)
	v_cvt_pk_bf16_f32 v3, v6, v7
	s_waitcnt lgkmcnt(1)
	v_cvt_pk_bf16_f32 v4, v8, v9
	s_waitcnt lgkmcnt(0)
	v_cvt_pk_bf16_f32 v5, v12, v13
	global_store_dwordx4 v[22:23], v[2:5], off sc1
	s_branch .LBB0_41

; DI void stb8(bf16_t* p, const F8& f) { *(uint4*)p = pack8(f); }
; DI void wconv(const float* __restrict__ src, bf16_t* __restrict__ dst, int K, int N, int Npad, int perm, unsigned char* smem) {
;     ...
;         const int nl = tid >> 3, kc = (tid & 7) * 8, n = n0 + nl;
;         if (n < Npad) {
;             int nd = n;
;             if (perm) nd = n < 2816 ? (n >> 6) * 128 + (n & 63) : ((n - 2816) >> 6) * 128 + 64 + ((n - 2816) & 63);
;             F8 a;
; #pragma unroll
;             for (int e = 0; e < 8; ++e) a.v[e] = tile[(kc + e) * 65 + nl];
;             stb8(dst + (size_t)nd * K + k0 + kc, a);
.LBB0_48:
	s_or_b64 exec, exec, s[6:7]
	ds_read2_b32 v[4:5], v21 offset1:65
	ds_read2_b32 v[6:7], v21 offset0:130 offset1:195
	ds_read2_b32 v[8:9], v22 offset0:4 offset1:69
	ds_read2_b32 v[12:13], v22 offset0:134 offset1:199
	v_ashrrev_i32_e32 v3, 31, v2
	v_readlane_b32 s2, v252, 49
	v_lshlrev_b64 v[2:3], 11, v[2:3]
	v_readlane_b32 s3, v252, 50
	s_ashr_i32 s1, s0, 31
	s_nop 0
	v_lshl_add_u64 v[2:3], s[2:3], 0, v[2:3]
	v_lshl_add_u64 v[2:3], s[0:1], 1, v[2:3]
	v_lshl_add_u64 v[24:25], v[2:3], 0, v[10:11]
	s_waitcnt lgkmcnt(3)
	v_cvt_pk_bf16_f32 v2, v4, v5
	s_waitcnt lgkmcnt(2)
	v_cvt_pk_bf16_f32 v3, v6, v7
	s_waitcnt lgkmcnt(1)
	v_cvt_pk_bf16_f32 v4, v8, v9
	s_waitcnt lgkmcnt(0)
	v_cvt_pk_bf16_f32 v5, v12, v13
	global_store_dwordx4 v[24:25], v[2:5], off sc1

; DI void stb8(bf16_t* p, const F8& f) { *(uint4*)p = pack8(f); }
; DI void wconv(const float* __restrict__ src, bf16_t* __restrict__ dst, int K, int N, int Npad, int perm, unsigned char* smem) {
;     ...
;             float* tp = tile + k * 65 + nl4; tp[0] = v.x; tp[1] = v.y; tp[2] = v.z; tp[3] = v.w;
;         }
;         __syncthreads();
;         const int nl = tid >> 3, kc = (tid & 7) * 8, n = n0 + nl;
;         if (n < Npad) {
;             int nd = n;
;             if (perm) nd = n < 2816 ? (n >> 6) * 128 + (n & 63) : ((n - 2816) >> 6) * 128 + 64 + ((n - 2816) & 63);
;             F8 a;
; #pragma unroll
;             for (int e = 0; e < 8; ++e) a.v[e] = tile[(kc + e) * 65 + nl];
;             stb8(dst + (size_t)nd * K + k0 + kc, a);
.LBB0_62:
	s_or_b64 exec, exec, s[4:5]
	s_waitcnt vmcnt(1)
	ds_write2_b32 v16, v2, v3 offset1:1
	ds_write2_b32 v16, v4, v5 offset0:2 offset1:3
	s_waitcnt vmcnt(0)
	ds_write2_b32 v17, v6, v7 offset1:1
	ds_write2_b32 v18, v8, v9 offset1:1
	v_add_u32_e32 v2, s1, v15
	v_cmp_gt_i32_e32 vcc, s7, v2
	s_waitcnt lgkmcnt(0)
	s_barrier
	s_and_saveexec_b64 s[4:5], vcc
	s_cbranch_execz .LBB0_59
	ds_read2_b32 v[4:5], v19 offset1:65
	ds_read2_b32 v[6:7], v19 offset0:130 offset1:195
	ds_read2_b32 v[8:9], v20 offset0:4 offset1:69
	ds_read2_b32 v[12:13], v20 offset0:134 offset1:199
	v_readlane_b32 s2, v252, 51
	v_readlane_b32 s3, v252, 52
	s_ashr_i32 s1, s0, 31
	s_nop 0
	v_mov_b64_e32 v[22:23], s[2:3]
	v_mad_i64_i32 v[2:3], s[10:11], v2, s8, v[22:23]
	v_lshl_add_u64 v[2:3], s[0:1], 1, v[2:3]
	v_lshl_add_u64 v[22:23], v[2:3], 0, v[10:11]
	s_waitcnt lgkmcnt(3)
	v_cvt_pk_bf16_f32 v2, v4, v5
	s_waitcnt lgkmcnt(2)
	v_cvt_pk_bf16_f32 v3, v6, v7
	s_waitcnt lgkmcnt(1)
	v_cvt_pk_bf16_f32 v4, v8, v9
	s_waitcnt lgkmcnt(0)
	v_cvt_pk_bf16_f32 v5, v12, v13
	global_store_dwordx4 v[22:23], v[2:5], off sc1
	s_branch .LBB0_59

; DI void stb8(bf16_t* p, const F8& f) { *(uint4*)p = pack8(f); }
; template <int MODE>
; DI void gemm_epilogue(const float* Cs, int m0, int n0, const Epi& ep) {
;     ...
;     } else if (MODE == 3) {
;         if (n0 < 4224) {
;         bf16_t* dst = n0 < 3072 ? ep.b0 : ep.b1;
;         const int ld = n0 < 3072 ? 3072 : 1152, c0 = n0 < 3072 ? n0 : n0 - 3072;
; #pragma unroll
;         for (int it = 0; it < 4; ++it) {
;             const int row = (tid >> 4) + 32 * it, cc = (tid & 15) * 8;
;             stb8(dst + (size_t)(m0 + row) * ld + c0 + cc, ldf8(Cs + row * LDC + cc));
;         }
;         if (n0 == 4096) {
;             const int row = tid >> 2, c4 = (tid & 3) * 4;
;             *(float4*)(ep.f0 + (size_t)(m0 + row) * 16 + c4) = *(const float4*)(Cs + row * LDC + c4);
;         }
;         }
; template <int MODE>
; DI void gemm_phase(const bf16_t* __restrict__ A, const bf16_t* __restrict__ Bt, int M, int N, int K, const Epi& ep) {
;     ...
;         __syncthreads();
; #pragma unroll
;         for (int ai = 0; ai < 2; ++ai)
; #pragma unroll
;             for (int bj = 0; bj < 2; ++bj) {
; #pragma unroll
;                 for (int m = 0; m < 4; ++m)
; #pragma unroll
;                     for (int n = 0; n < 2; ++n)
;                         *(f32x4*)(Cs + (wr * 64 + m * 16 + fr) * LDC + wc * 32 + n * 16 + fq * 4) = acc[ai][bj][m][n];
;                 __syncthreads();
;                 gemm_epilogue<MODE>(Cs, brow + ai * 128, bcol + bj * 128, ep);
;                 __syncthreads();
.LBB0_94:
	s_or_b64 exec, exec, s[0:1]
	s_lshl_b32 s27, s27, 8
	s_cmp_lt_i32 s26, 17
	s_waitcnt vmcnt(0)
	s_barrier
	ds_write_b128 v154, v[96:99]
	ds_write_b128 v154, v[100:103] offset:64
	ds_write_b128 v154, v[104:107] offset:8448
	ds_write_b128 v154, v[108:111] offset:8512
	ds_write_b128 v154, v[112:115] offset:16896
	ds_write_b128 v154, v[116:119] offset:16960
	ds_write_b128 v154, v[120:123] offset:25344
	ds_write_b128 v154, v[124:127] offset:25408
	v_mov_b32_e32 v96, v250
	s_cselect_b64 s[0:1], -1, 0
	s_cmp_gt_i32 s26, 16
	s_waitcnt lgkmcnt(0)
	s_barrier
	s_cbranch_scc1 .LBB0_97
	s_add_i32 s6, s19, 0xfffff400
	s_cmp_lt_i32 s26, 12
	s_movk_i32 s7, 0xc00
	s_cselect_b32 s6, s19, s6
	s_cselect_b32 s30, s7, 0x480
	s_cselect_b32 s31, s85, s61
	s_cselect_b32 s40, s84, s60
	s_ashr_i32 s7, s6, 31
	v_lshlrev_b32_e32 v64, 3, v96
	s_lshl_b64 s[6:7], s[6:7], 1
	v_ashrrev_i32_e32 v66, 4, v96
	v_and_b32_e32 v64, 0x78, v64
	s_add_u32 s6, s40, s6
	s_addc_u32 s7, s31, s7
	v_lshlrev_b32_e32 v212, 1, v64
	v_add_u32_e32 v97, s27, v66
	v_lshl_add_u64 v[102:103], s[6:7], 0, v[212:213]
	v_lshlrev_b32_e32 v67, 2, v64
	v_mad_i64_i32 v[64:65], s[6:7], s30, v97, 0
	v_lshl_add_u64 v[104:105], v[64:65], 1, v[102:103]
	v_mul_lo_u32 v64, v66, s35
	v_add3_u32 v106, 16, v67, v64
	ds_read_b128 v[64:67], v106
	ds_read_b128 v[98:101], v106 offset:16
	s_waitcnt lgkmcnt(1)
	v_cvt_pk_bf16_f32 v64, v64, v65
	v_cvt_pk_bf16_f32 v65, v66, v67
	s_waitcnt lgkmcnt(0)
	v_cvt_pk_bf16_f32 v66, v98, v99
	v_cvt_pk_bf16_f32 v67, v100, v101
	global_store_dwordx4 v[104:105], v[64:67], off sc1
	s_nop 1
	v_add_u32_e32 v64, 32, v97
	v_mad_i64_i32 v[64:65], s[6:7], s30, v64, 0
	v_lshl_add_u64 v[104:105], v[64:65], 1, v[102:103]
	ds_read_b128 v[64:67], v106 offset:16896
	ds_read_b128 v[98:101], v106 offset:16912
	s_waitcnt lgkmcnt(1)
	v_cvt_pk_bf16_f32 v64, v64, v65
	v_cvt_pk_bf16_f32 v65, v66, v67
	s_waitcnt lgkmcnt(0)
	v_cvt_pk_bf16_f32 v66, v98, v99
	v_cvt_pk_bf16_f32 v67, v100, v101
	global_store_dwordx4 v[104:105], v[64:67], off sc1
	s_nop 1
	v_add_u32_e32 v64, 64, v97
	v_mad_i64_i32 v[64:65], s[6:7], s30, v64, 0
	v_lshl_add_u64 v[104:105], v[64:65], 1, v[102:103]
	ds_read_b128 v[64:67], v106 offset:33792
	ds_read_b128 v[98:101], v106 offset:33808
	s_waitcnt lgkmcnt(1)
	v_cvt_pk_bf16_f32 v64, v64, v65
	v_cvt_pk_bf16_f32 v65, v66, v67
	s_waitcnt lgkmcnt(0)
	v_cvt_pk_bf16_f32 v66, v98, v99
	v_cvt_pk_bf16_f32 v67, v100, v101
	global_store_dwordx4 v[104:105], v[64:67], off sc1
	s_nop 1
	v_add_u32_e32 v64, 0x60, v97
	v_mad_i64_i32 v[64:65], s[6:7], s30, v64, 0
	v_lshl_add_u64 v[102:103], v[64:65], 1, v[102:103]
	ds_read_b128 v[64:67], v106 offset:50688
	ds_read_b128 v[98:101], v106 offset:50704
	s_and_b32 s6, 0xffff, s23
	s_cmp_lg_u32 s6, 16
	s_waitcnt lgkmcnt(1)
	v_cvt_pk_bf16_f32 v64, v64, v65
	v_cvt_pk_bf16_f32 v65, v66, v67
	s_waitcnt lgkmcnt(0)
	v_cvt_pk_bf16_f32 v66, v98, v99
	v_cvt_pk_bf16_f32 v67, v100, v101
	global_store_dwordx4 v[102:103], v[64:67], off sc1
	s_cbranch_scc1 .LBB0_97
	s_nop 0
	v_ashrrev_i32_e32 v64, 2, v96
	v_lshlrev_b32_e32 v66, 4, v96
	v_mul_lo_u32 v65, v64, s35
	v_and_b32_e32 v212, 48, v66
	v_add_u32_e32 v64, s27, v64
	v_add3_u32 v66, 16, v65, v212
	v_ashrrev_i32_e32 v65, 31, v64
	v_readlane_b32 s6, v253, 5
	v_lshlrev_b64 v[64:65], 6, v[64:65]
	v_readlane_b32 s7, v253, 6
	s_nop 1
	v_lshl_add_u64 v[64:65], s[6:7], 0, v[64:65]
	v_lshl_add_u64 v[96:97], v[64:65], 0, v[212:213]
	ds_read_b128 v[64:67], v66
	s_waitcnt lgkmcnt(0)
	global_store_dwordx4 v[96:97], v[64:67], off sc1
.LBB0_97:
	s_cmpk_lt_i32 s22, 0x1080
	s_nop 0
	v_mov_b32_e32 v64, v250
	s_cselect_b64 s[6:7], -1, 0
	s_cmpk_gt_i32 s22, 0x107f
	s_barrier
	ds_write_b128 v154, v[222:225]
	ds_write_b128 v154, v[68:71] offset:64
	ds_write_b128 v154, v[72:75] offset:8448
	ds_write_b128 v154, v[76:79] offset:8512
	ds_write_b128 v154, v[80:83] offset:16896
	ds_write_b128 v154, v[84:87] offset:16960
	ds_write_b128 v154, v[88:91] offset:25344
	ds_write_b128 v154, v[92:95] offset:25408
	s_waitcnt lgkmcnt(0)
	s_barrier
	s_cbranch_scc1 .LBB0_99
	s_cmpk_lt_i32 s22, 0xc00
	s_cselect_b64 s[30:31], -1, 0
	s_and_b64 s[40:41], s[30:31], exec
	s_movk_i32 s40, 0xc00
	s_cselect_b32 s40, s40, 0x480
	s_cselect_b32 s41, s85, s61
	s_cselect_b32 s42, s84, s60
	s_add_i32 s43, s19, 0xfffff480
	s_and_b64 s[30:31], s[30:31], exec
	s_cselect_b32 s30, s22, s43
	s_ashr_i32 s31, s30, 31
	v_ashrrev_i32_e32 v66, 4, v64
	v_lshlrev_b32_e32 v64, 3, v64
	s_lshl_b64 s[30:31], s[30:31], 1
	v_and_b32_e32 v64, 0x78, v64
	s_add_u32 s30, s42, s30
	s_addc_u32 s31, s41, s31
	v_lshlrev_b32_e32 v212, 1, v64
	v_add_u32_e32 v76, s27, v66
	v_lshl_add_u64 v[72:73], s[30:31], 0, v[212:213]
	v_lshlrev_b32_e32 v67, 2, v64
	v_mad_i64_i32 v[64:65], s[30:31], s40, v76, 0
	v_lshl_add_u64 v[74:75], v[64:65], 1, v[72:73]
	v_mul_lo_u32 v64, v66, s35
	v_add3_u32 v77, 16, v67, v64
	ds_read_b128 v[64:67], v77
	ds_read_b128 v[68:71], v77 offset:16
	s_waitcnt lgkmcnt(1)
	v_cvt_pk_bf16_f32 v64, v64, v65
	v_cvt_pk_bf16_f32 v65, v66, v67
	s_waitcnt lgkmcnt(0)
	v_cvt_pk_bf16_f32 v66, v68, v69
	v_cvt_pk_bf16_f32 v67, v70, v71
	global_store_dwordx4 v[74:75], v[64:67], off sc1
	s_nop 1
	v_add_u32_e32 v64, 32, v76
	v_mad_i64_i32 v[64:65], s[30:31], s40, v64, 0
	v_lshl_add_u64 v[74:75], v[64:65], 1, v[72:73]
	ds_read_b128 v[64:67], v77 offset:16896
	ds_read_b128 v[68:71], v77 offset:16912
	s_waitcnt lgkmcnt(1)
	v_cvt_pk_bf16_f32 v64, v64, v65
	v_cvt_pk_bf16_f32 v65, v66, v67
	s_waitcnt lgkmcnt(0)
	v_cvt_pk_bf16_f32 v66, v68, v69
	v_cvt_pk_bf16_f32 v67, v70, v71
	global_store_dwordx4 v[74:75], v[64:67], off sc1
	s_nop 1
	v_add_u32_e32 v64, 64, v76
	v_mad_i64_i32 v[64:65], s[30:31], s40, v64, 0
	v_lshl_add_u64 v[74:75], v[64:65], 1, v[72:73]
	ds_read_b128 v[64:67], v77 offset:33792
	ds_read_b128 v[68:71], v77 offset:33808
	s_waitcnt lgkmcnt(1)
	v_cvt_pk_bf16_f32 v64, v64, v65
	v_cvt_pk_bf16_f32 v65, v66, v67
	s_waitcnt lgkmcnt(0)
	v_cvt_pk_bf16_f32 v66, v68, v69
	v_cvt_pk_bf16_f32 v67, v70, v71
	global_store_dwordx4 v[74:75], v[64:67], off sc1
	s_nop 1
	v_add_u32_e32 v64, 0x60, v76
	v_mad_i64_i32 v[64:65], s[30:31], s40, v64, 0
	v_lshl_add_u64 v[72:73], v[64:65], 1, v[72:73]
	ds_read_b128 v[64:67], v77 offset:50688
	ds_read_b128 v[68:71], v77 offset:50704
	s_waitcnt lgkmcnt(1)
	v_cvt_pk_bf16_f32 v64, v64, v65
	v_cvt_pk_bf16_f32 v65, v66, v67
	s_waitcnt lgkmcnt(0)
	v_cvt_pk_bf16_f32 v66, v68, v69
	v_cvt_pk_bf16_f32 v67, v70, v71
	global_store_dwordx4 v[72:73], v[64:67], off sc1
; DI void stb8(bf16_t* p, const F8& f) { *(uint4*)p = pack8(f); }
; template <int MODE>
; DI void gemm_epilogue(const float* Cs, int m0, int n0, const Epi& ep) {
;     ...
;     } else if (MODE == 3) {
;         if (n0 < 4224) {
;         bf16_t* dst = n0 < 3072 ? ep.b0 : ep.b1;
;         const int ld = n0 < 3072 ? 3072 : 1152, c0 = n0 < 3072 ? n0 : n0 - 3072;
; #pragma unroll
;         for (int it = 0; it < 4; ++it) {
;             const int row = (tid >> 4) + 32 * it, cc = (tid & 15) * 8;
;             stb8(dst + (size_t)(m0 + row) * ld + c0 + cc, ldf8(Cs + row * LDC + cc));
;         }
;         if (n0 == 4096) {
;             const int row = tid >> 2, c4 = (tid & 3) * 4;
;             *(float4*)(ep.f0 + (size_t)(m0 + row) * 16 + c4) = *(const float4*)(Cs + row * LDC + c4);
;         }
;         }
; template <int MODE>
; DI void gemm_phase(const bf16_t* __restrict__ A, const bf16_t* __restrict__ Bt, int M, int N, int K, const Epi& ep) {
;     ...
;         __syncthreads();
; #pragma unroll
;         for (int ai = 0; ai < 2; ++ai)
; #pragma unroll
;             for (int bj = 0; bj < 2; ++bj) {
; #pragma unroll
;                 for (int m = 0; m < 4; ++m)
; #pragma unroll
;                     for (int n = 0; n < 2; ++n)
;                         *(f32x4*)(Cs + (wr * 64 + m * 16 + fr) * LDC + wc * 32 + n * 16 + fq * 4) = acc[ai][bj][m][n];
;                 __syncthreads();
;                 gemm_epilogue<MODE>(Cs, brow + ai * 128, bcol + bj * 128, ep);
;                 __syncthreads();
.LBB0_99:
	s_barrier
	s_bitset1_b32 s27, 7
	ds_write_b128 v154, v[32:35]
	ds_write_b128 v154, v[36:39] offset:64
	ds_write_b128 v154, v[40:43] offset:8448
	ds_write_b128 v154, v[44:47] offset:8512
	ds_write_b128 v154, v[48:51] offset:16896
	ds_write_b128 v154, v[52:55] offset:16960
	ds_write_b128 v154, v[56:59] offset:25344
	ds_write_b128 v154, v[60:63] offset:25408
	v_mov_b32_e32 v32, v250
	s_andn2_b64 vcc, exec, s[0:1]
	s_waitcnt lgkmcnt(0)
	s_barrier
	s_cbranch_vccnz .LBB0_102
	s_add_i32 s0, s19, 0xfffff400
	s_cmp_lt_i32 s26, 12
	s_movk_i32 s1, 0xc00
	s_cselect_b32 s0, s19, s0
	s_cselect_b32 s26, s1, 0x480
	s_cselect_b32 s30, s85, s61
	s_cselect_b32 s31, s84, s60
	s_ashr_i32 s1, s0, 31
	v_lshlrev_b32_e32 v34, 3, v32
	s_lshl_b64 s[0:1], s[0:1], 1
	v_ashrrev_i32_e32 v33, 4, v32
	v_and_b32_e32 v34, 0x78, v34
	s_add_u32 s0, s31, s0
	s_addc_u32 s1, s30, s1
	v_lshlrev_b32_e32 v212, 1, v34
	v_lshlrev_b32_e32 v36, 2, v34
	v_add_u32_e32 v46, s27, v33
	v_mul_lo_u32 v33, v33, s35
	v_lshl_add_u64 v[42:43], s[0:1], 0, v[212:213]
	v_mad_i64_i32 v[34:35], s[0:1], s26, v46, 0
	v_add3_u32 v33, 16, v36, v33
	v_lshl_add_u64 v[44:45], v[34:35], 1, v[42:43]
	ds_read_b128 v[34:37], v33
	ds_read_b128 v[38:41], v33 offset:16
	s_waitcnt lgkmcnt(1)
	v_cvt_pk_bf16_f32 v34, v34, v35
	v_cvt_pk_bf16_f32 v35, v36, v37
	s_waitcnt lgkmcnt(0)
	v_cvt_pk_bf16_f32 v36, v38, v39
	v_cvt_pk_bf16_f32 v37, v40, v41
	global_store_dwordx4 v[44:45], v[34:37], off sc1
	s_nop 1
	v_add_u32_e32 v34, 32, v46
	v_mad_i64_i32 v[34:35], s[0:1], s26, v34, 0
	v_lshl_add_u64 v[44:45], v[34:35], 1, v[42:43]
	ds_read_b128 v[34:37], v33 offset:16896
	ds_read_b128 v[38:41], v33 offset:16912
	s_waitcnt lgkmcnt(1)
	v_cvt_pk_bf16_f32 v34, v34, v35
	v_cvt_pk_bf16_f32 v35, v36, v37
	s_waitcnt lgkmcnt(0)
	v_cvt_pk_bf16_f32 v36, v38, v39
	v_cvt_pk_bf16_f32 v37, v40, v41
	global_store_dwordx4 v[44:45], v[34:37], off sc1
	s_nop 1
	v_add_u32_e32 v34, 64, v46
	v_mad_i64_i32 v[34:35], s[0:1], s26, v34, 0
	v_lshl_add_u64 v[44:45], v[34:35], 1, v[42:43]
	ds_read_b128 v[34:37], v33 offset:33792
	ds_read_b128 v[38:41], v33 offset:33808
	s_waitcnt lgkmcnt(1)
	v_cvt_pk_bf16_f32 v34, v34, v35
	v_cvt_pk_bf16_f32 v35, v36, v37
	s_waitcnt lgkmcnt(0)
	v_cvt_pk_bf16_f32 v36, v38, v39
	v_cvt_pk_bf16_f32 v37, v40, v41
	global_store_dwordx4 v[44:45], v[34:37], off sc1
	s_nop 1
	v_add_u32_e32 v34, 0x60, v46
	v_mad_i64_i32 v[34:35], s[0:1], s26, v34, 0
	v_lshl_add_u64 v[42:43], v[34:35], 1, v[42:43]
	ds_read_b128 v[34:37], v33 offset:50688
	ds_read_b128 v[38:41], v33 offset:50704
	s_and_b32 s0, 0xffff, s23
	s_cmp_lg_u32 s0, 16
	s_waitcnt lgkmcnt(1)
	v_cvt_pk_bf16_f32 v34, v34, v35
	v_cvt_pk_bf16_f32 v35, v36, v37
	s_waitcnt lgkmcnt(0)
	v_cvt_pk_bf16_f32 v36, v38, v39
	v_cvt_pk_bf16_f32 v37, v40, v41
	global_store_dwordx4 v[42:43], v[34:37], off sc1
	s_cbranch_scc1 .LBB0_102
	v_ashrrev_i32_e32 v33, 2, v32
	v_lshlrev_b32_e32 v32, 4, v32
	v_and_b32_e32 v212, 48, v32
	v_add_u32_e32 v32, s27, v33
	v_mul_lo_u32 v34, v33, s35
	v_ashrrev_i32_e32 v33, 31, v32
	v_readlane_b32 s0, v253, 5
	v_lshlrev_b64 v[32:33], 6, v[32:33]
	v_readlane_b32 s1, v253, 6
	v_add3_u32 v34, 16, v34, v212
	s_nop 0
	v_lshl_add_u64 v[32:33], s[0:1], 0, v[32:33]
	v_lshl_add_u64 v[36:37], v[32:33], 0, v[212:213]
	ds_read_b128 v[32:35], v34
	s_waitcnt lgkmcnt(0)
	global_store_dwordx4 v[36:37], v[32:35], off sc1
.LBB0_102:
	s_barrier
	ds_write_b128 v154, v[0:3]
	ds_write_b128 v154, v[4:7] offset:64
	ds_write_b128 v154, v[8:11] offset:8448
	ds_write_b128 v154, v[12:15] offset:8512
	ds_write_b128 v154, v[16:19] offset:16896
	ds_write_b128 v154, v[20:23] offset:16960
	ds_write_b128 v154, v[24:27] offset:25344
	ds_write_b128 v154, v[28:31] offset:25408
	v_mov_b32_e32 v0, v250
	s_andn2_b64 vcc, exec, s[6:7]
	s_waitcnt lgkmcnt(0)
	s_barrier
	s_cbranch_vccnz .LBB0_83
	s_cmpk_lt_i32 s22, 0xc00
	s_cselect_b64 s[0:1], -1, 0
	s_and_b64 s[6:7], s[0:1], exec
	s_movk_i32 s6, 0xc00
	s_cselect_b32 s6, s6, 0x480
	s_cselect_b32 s7, s85, s61
	s_cselect_b32 s23, s84, s60
	s_addk_i32 s19, 0xf480
	s_and_b64 s[0:1], s[0:1], exec
	s_cselect_b32 s0, s22, s19
	s_ashr_i32 s1, s0, 31
	v_ashrrev_i32_e32 v2, 4, v0
	v_lshlrev_b32_e32 v0, 3, v0
	s_lshl_b64 s[0:1], s[0:1], 1
	v_and_b32_e32 v0, 0x78, v0
	s_add_u32 s0, s23, s0
	s_addc_u32 s1, s7, s1
	v_lshlrev_b32_e32 v212, 1, v0
	v_add_u32_e32 v12, s27, v2
	v_lshl_add_u64 v[8:9], s[0:1], 0, v[212:213]
	v_lshlrev_b32_e32 v3, 2, v0
	v_mad_i64_i32 v[0:1], s[0:1], s6, v12, 0
	v_lshl_add_u64 v[10:11], v[0:1], 1, v[8:9]
	v_mul_lo_u32 v0, v2, s35
	v_add3_u32 v13, 16, v3, v0
	ds_read_b128 v[0:3], v13
	ds_read_b128 v[4:7], v13 offset:16
	s_waitcnt lgkmcnt(1)
	v_cvt_pk_bf16_f32 v0, v0, v1
	v_cvt_pk_bf16_f32 v1, v2, v3
	s_waitcnt lgkmcnt(0)
	v_cvt_pk_bf16_f32 v2, v4, v5
	v_cvt_pk_bf16_f32 v3, v6, v7
	global_store_dwordx4 v[10:11], v[0:3], off sc1
	s_nop 1
	v_add_u32_e32 v0, 32, v12
	v_mad_i64_i32 v[0:1], s[0:1], s6, v0, 0
	v_lshl_add_u64 v[10:11], v[0:1], 1, v[8:9]
	ds_read_b128 v[0:3], v13 offset:16896
	ds_read_b128 v[4:7], v13 offset:16912
	s_waitcnt lgkmcnt(1)
	v_cvt_pk_bf16_f32 v0, v0, v1
	v_cvt_pk_bf16_f32 v1, v2, v3
	s_waitcnt lgkmcnt(0)
	v_cvt_pk_bf16_f32 v2, v4, v5
	v_cvt_pk_bf16_f32 v3, v6, v7
	global_store_dwordx4 v[10:11], v[0:3], off sc1
	s_nop 1
	v_add_u32_e32 v0, 64, v12
	v_mad_i64_i32 v[0:1], s[0:1], s6, v0, 0
	v_lshl_add_u64 v[10:11], v[0:1], 1, v[8:9]
	ds_read_b128 v[0:3], v13 offset:33792
	ds_read_b128 v[4:7], v13 offset:33808
	s_waitcnt lgkmcnt(1)
	v_cvt_pk_bf16_f32 v0, v0, v1
	v_cvt_pk_bf16_f32 v1, v2, v3
	s_waitcnt lgkmcnt(0)
	v_cvt_pk_bf16_f32 v2, v4, v5
	v_cvt_pk_bf16_f32 v3, v6, v7
	global_store_dwordx4 v[10:11], v[0:3], off sc1
	s_nop 1
	v_add_u32_e32 v0, 0x60, v12
	v_mad_i64_i32 v[0:1], s[0:1], s6, v0, 0
	v_lshl_add_u64 v[8:9], v[0:1], 1, v[8:9]
	ds_read_b128 v[0:3], v13 offset:50688
	ds_read_b128 v[4:7], v13 offset:50704
	s_waitcnt lgkmcnt(1)
	v_cvt_pk_bf16_f32 v0, v0, v1
	v_cvt_pk_bf16_f32 v1, v2, v3
	s_waitcnt lgkmcnt(0)
	v_cvt_pk_bf16_f32 v2, v4, v5
	v_cvt_pk_bf16_f32 v3, v6, v7
	global_store_dwordx4 v[8:9], v[0:3], off sc1
	s_branch .LBB0_83

; DI F8 unpack8(uint4 u) { F8 r; r.v[0] = lo16(u.x); r.v[1] = hi16(u.x); r.v[2] = lo16(u.y); r.v[3] = hi16(u.y); r.v[4] = lo16(u.z); r.v[5] = hi16(u.z); r.v[6] = lo16(u.w); r.v[7] = hi16(u.w); return r; }
; DI void stf8(float* p, const F8& f) { *(float4*)p = make_float4(f.v[0], f.v[1], f.v[2], f.v[3]); *(float4*)(p + 4) = make_float4(f.v[4], f.v[5], f.v[6], f.v[7]); }
; DI void stb8(bf16_t* p, const F8& f) { *(uint4*)p = pack8(f); }
; DI float gsum16(float v) { v += __shfl_xor(v, 8); v += __shfl_xor(v, 4); v += __shfl_xor(v, 2); v += __shfl_xor(v, 1); return v; }
; DI float siluf(float x) { return x / (1.f + __expf(-x)); }
; DI void odd_elem(const Params& p, int o) {
;     ...
;         for (int t = 0; t < 16; ++t) {
;             const F8 x0 = unpack8(xr[t]);
;             F8 acc; float ss = 0.f;
; #pragma unroll
;             for (int k = 0; k < 8; ++k) { const float a = w3.v[k] * x0.v[k] + w2.v[k] * h1.v[k] + w1.v[k] * h2.v[k] + w0.v[k] * h3.v[k]; acc.v[k] = siluf(a); ss += acc.v[k] * acc.v[k]; }
;             if (gi < 4) {
;                 const float rs = rsqrtf(gsum16(ss) + EPS) * nsc;
; #pragma unroll
;                 for (int k = 0; k < 8; ++k) acc.v[k] *= rs;
;             }
;             stb8(Q2 + (size_t)(r0 + t) * 3072 + c, acc);
;             if (last && t >= 13) {
;                 float* so = sq < 4 ? p.out + O_PDC + (((size_t)o * 4 + sq) * 3 + (t - 13)) * 3072 : p.out + O_SDC + (((size_t)o * 8 + (sq - 4)) * 3 + (t - 13)) * 3072;
;                 stf8(so + c, x0);
;             }
;             h3 = h2; h2 = h1; h1 = x0;
.LBB0_169:
	s_or_b64 exec, exec, s[40:41]
	v_mad_i64_i32 v[158:159], s[40:41], v123, s33, 0
	v_lshl_add_u64 v[110:111], v[130:131], 1, s[76:77]
	v_lshl_add_u64 v[158:159], v[110:111], 0, v[158:159]
	v_cvt_pk_bf16_f32 v152, v152, v153
	v_cvt_pk_bf16_f32 v153, v154, v155
	v_cvt_pk_bf16_f32 v154, v164, v165
	v_cvt_pk_bf16_f32 v155, v166, v167
	global_store_dwordx4 v[158:159], v[152:155], off sc1
	v_lshlrev_b32_e32 v29, 16, v100
	v_lshlrev_b32_e32 v21, 16, v101
	v_and_b32_e32 v153, 0xffff0000, v100
	v_mov_b32_e32 v152, v151
	v_pk_mul_f32 v[162:163], v[112:113], v[152:153]
	v_and_b32_e32 v105, 0xffff0000, v101
	v_lshlrev_b32_e32 v5, 16, v102
	v_and_b32_e32 v97, 0xffff0000, v102
	v_lshlrev_b32_e32 v100, 16, v103
	v_and_b32_e32 v101, 0xffff0000, v103
	v_mul_f32_e32 v102, v32, v29
	v_mul_f32_e32 v154, v28, v168
	v_pk_mul_f32 v[148:149], v[148:149], v[114:115]
	v_mov_b32_e32 v155, v162
	v_mov_b32_e32 v103, v163
	v_mul_f32_e32 v158, v92, v24
	v_pk_add_f32 v[102:103], v[154:155], v[102:103]
	v_mov_b32_e32 v159, v149
	v_mul_f32_e32 v160, v104, v20
	v_pk_add_f32 v[102:103], v[158:159], v[102:103]
	v_mov_b32_e32 v161, v148
	v_pk_add_f32 v[102:103], v[160:161], v[102:103]
	v_mov_b32_e32 v104, v145
	v_mul_f32_e32 v9, 0xbfb8aa3b, v102
	v_exp_f32_e32 v148, v9
	v_mul_f32_e32 v9, 0xbfb8aa3b, v103
	v_exp_f32_e32 v149, v9
	v_pk_mul_f32 v[160:161], v[116:117], v[104:105]
	v_mul_f32_e32 v154, v30, v156
	v_pk_mul_f32 v[146:147], v[146:147], v[118:119]
	v_pk_add_f32 v[148:149], v[148:149], 1.0 op_sel_hi:[1,0]
	v_mov_b32_e32 v155, v160
	v_mul_f32_e32 v158, v94, v26
	v_mov_b32_e32 v159, v147
	v_mul_f32_e32 v106, v106, v22
	v_rcp_f32_e32 v9, v149
	s_nop 0
	v_mul_f32_e32 v103, v103, v9
	v_mov_b32_e32 v149, v161
	v_mov_b32_e32 v107, v146
	v_pk_mul_f32 v[142:143], v[142:143], v[108:109]
	v_rcp_f32_e32 v9, v148
	s_nop 0
	v_mul_f32_e32 v102, v102, v9
	v_mul_f32_e32 v148, v34, v21
	v_pk_add_f32 v[148:149], v[154:155], v[148:149]
	v_mul_f32_e32 v154, v84, v8
	v_pk_add_f32 v[148:149], v[158:159], v[148:149]
	v_mul_f32_e32 v158, v96, v4
	v_pk_add_f32 v[106:107], v[106:107], v[148:149]
	v_mov_b32_e32 v96, v141
	v_mul_f32_e32 v9, 0xbfb8aa3b, v106
	v_exp_f32_e32 v146, v9
	v_mul_f32_e32 v9, 0xbfb8aa3b, v107
	v_exp_f32_e32 v147, v9
	v_pk_mul_f32 v[160:161], v[136:137], v[96:97]
	v_mul_f32_e32 v148, v12, v133
	v_mov_b32_e32 v149, v160
	v_pk_add_f32 v[146:147], v[146:147], 1.0 op_sel_hi:[1,0]
	v_mov_b32_e32 v155, v143
	v_mov_b32_e32 v159, v142
	v_rcp_f32_e32 v9, v147
	s_nop 0
	v_mul_f32_e32 v107, v107, v9
	v_mov_b32_e32 v147, v161
	v_rcp_f32_e32 v9, v146
	s_nop 0
	v_mul_f32_e32 v106, v106, v9
	v_mul_f32_e32 v146, v16, v5
	v_pk_add_f32 v[146:147], v[148:149], v[146:147]
	s_nop 0
	v_pk_add_f32 v[146:147], v[154:155], v[146:147]
	s_nop 0
	v_pk_add_f32 v[142:143], v[158:159], v[146:147]
	s_nop 0
	v_mul_f32_e32 v9, 0xbfb8aa3b, v142
	v_exp_f32_e32 v146, v9
	v_mul_f32_e32 v9, 0xbfb8aa3b, v143
	v_exp_f32_e32 v147, v9
	s_nop 0
	v_pk_add_f32 v[146:147], v[146:147], 1.0 op_sel_hi:[1,0]
	s_nop 0
	v_rcp_f32_e32 v9, v147
	s_nop 0
	v_mul_f32_e32 v143, v143, v9
	v_rcp_f32_e32 v9, v146
	s_nop 0
	v_mul_f32_e32 v142, v142, v9
	v_pk_mul_f32 v[146:147], v[18:19], v[100:101]
	s_nop 0
	v_pk_fma_f32 v[146:147], v[14:15], v[138:139], v[146:147]
	s_nop 0
	v_pk_fma_f32 v[146:147], v[86:87], v[10:11], v[146:147]
	s_nop 0
	v_pk_fma_f32 v[98:99], v[98:99], v[6:7], v[146:147]
	s_nop 0
	v_mul_f32_e32 v9, 0xbfb8aa3b, v98
	v_exp_f32_e32 v146, v9
	v_mul_f32_e32 v9, 0xbfb8aa3b, v99
	v_exp_f32_e32 v147, v9
	s_nop 0
	v_pk_add_f32 v[146:147], v[146:147], 1.0 op_sel_hi:[1,0]
	s_nop 0
	v_rcp_f32_e32 v9, v147
	s_nop 0
	v_mul_f32_e32 v99, v99, v9
	v_rcp_f32_e32 v9, v146
	s_nop 0
	v_mul_f32_e32 v98, v98, v9
	s_and_saveexec_b64 s[40:41], s[36:37]
	s_cbranch_execz .LBB0_171
	v_pk_mul_f32 v[146:147], v[102:103], v[102:103]
	v_pk_mul_f32 v[148:149], v[106:107], v[106:107]
	v_add_f32_e32 v9, v146, v147
	v_add_f32_e32 v9, v9, v148
	v_pk_mul_f32 v[154:155], v[142:143], v[142:143]
	v_add_f32_e32 v9, v9, v149
	v_and_b32_e32 v17, 64, v251
	v_add_f32_e32 v9, v9, v154
	v_add_u32_e32 v17, 64, v17
	v_pk_mul_f32 v[158:159], v[98:99], v[98:99]
	v_add_f32_e32 v9, v9, v155
	v_add_f32_e32 v9, v9, v158
	v_add_f32_e32 v9, v9, v159
	s_waitcnt lgkmcnt(0)
	s_nop 1
	v_add_f32_dpp v9, v9, v9 row_ror:8 row_mask:0xf bank_mask:0xf
	s_waitcnt lgkmcnt(0)
	s_nop 1
	v_add_f32_dpp v9, v9, v9 row_ror:4 row_mask:0xf bank_mask:0xf
	s_waitcnt lgkmcnt(0)
	s_nop 1
	v_add_f32_dpp v9, v9, v9 row_ror:2 row_mask:0xf bank_mask:0xf
	s_waitcnt lgkmcnt(0)
	s_nop 1
	v_add_f32_dpp v9, v9, v9 row_ror:1 row_mask:0xf bank_mask:0xf
	v_add_f32_e32 v9, 0x358637bd, v9
	v_mul_f32_e32 v13, 0x4b800000, v9
	v_cmp_gt_f32_e32 vcc, s2, v9
	s_nop 1
	v_cndmask_b32_e32 v9, v9, v13, vcc
	v_rsq_f32_e32 v9, v9
	s_nop 0
	v_mul_f32_e32 v13, 0x45800000, v9
	v_cndmask_b32_e32 v9, v9, v13, vcc
	v_mul_f32_e32 v146, v129, v9
	v_pk_mul_f32 v[102:103], v[102:103], v[146:147] op_sel_hi:[1,0]
	v_pk_mul_f32 v[106:107], v[106:107], v[146:147] op_sel_hi:[1,0]
	v_pk_mul_f32 v[142:143], v[142:143], v[146:147] op_sel_hi:[1,0]
	v_pk_mul_f32 v[98:99], v[98:99], v[146:147] op_sel_hi:[1,0]
; DI F8 unpack8(uint4 u) { F8 r; r.v[0] = lo16(u.x); r.v[1] = hi16(u.x); r.v[2] = lo16(u.y); r.v[3] = hi16(u.y); r.v[4] = lo16(u.z); r.v[5] = hi16(u.z); r.v[6] = lo16(u.w); r.v[7] = hi16(u.w); return r; }
; DI void stf8(float* p, const F8& f) { *(float4*)p = make_float4(f.v[0], f.v[1], f.v[2], f.v[3]); *(float4*)(p + 4) = make_float4(f.v[4], f.v[5], f.v[6], f.v[7]); }
; DI void stb8(bf16_t* p, const F8& f) { *(uint4*)p = pack8(f); }
; DI float gsum16(float v) { v += __shfl_xor(v, 8); v += __shfl_xor(v, 4); v += __shfl_xor(v, 2); v += __shfl_xor(v, 1); return v; }
; DI float siluf(float x) { return x / (1.f + __expf(-x)); }
; DI void odd_elem(const Params& p, int o) {
;     ...
;         for (int t = 0; t < 16; ++t) {
;             const F8 x0 = unpack8(xr[t]);
;             F8 acc; float ss = 0.f;
; #pragma unroll
;             for (int k = 0; k < 8; ++k) { const float a = w3.v[k] * x0.v[k] + w2.v[k] * h1.v[k] + w1.v[k] * h2.v[k] + w0.v[k] * h3.v[k]; acc.v[k] = siluf(a); ss += acc.v[k] * acc.v[k]; }
;             if (gi < 4) {
;                 const float rs = rsqrtf(gsum16(ss) + EPS) * nsc;
; #pragma unroll
;                 for (int k = 0; k < 8; ++k) acc.v[k] *= rs;
;             }
;             stb8(Q2 + (size_t)(r0 + t) * 3072 + c, acc);
;             if (last && t >= 13) {
;                 float* so = sq < 4 ? p.out + O_PDC + (((size_t)o * 4 + sq) * 3 + (t - 13)) * 3072 : p.out + O_SDC + (((size_t)o * 8 + (sq - 4)) * 3 + (t - 13)) * 3072;
;                 stf8(so + c, x0);
;             }
;             h3 = h2; h2 = h1; h1 = x0;
.LBB0_171:
	s_or_b64 exec, exec, s[40:41]
	v_or_b32_e32 v9, 1, v123
	v_mad_i64_i32 v[154:155], s[40:41], v9, s33, v[110:111]
	v_cvt_pk_bf16_f32 v146, v102, v103
	v_cvt_pk_bf16_f32 v147, v106, v107
	v_cvt_pk_bf16_f32 v148, v142, v143
	v_cvt_pk_bf16_f32 v149, v98, v99
	v_and_b32_e32 v143, 0xffff0000, v88
	v_mov_b32_e32 v142, v153
	global_store_dwordx4 v[154:155], v[146:149], off sc1
	v_lshlrev_b32_e32 v31, 16, v88
	v_lshlrev_b32_e32 v23, 16, v89
	v_pk_mul_f32 v[148:149], v[112:113], v[142:143]
	v_and_b32_e32 v103, 0xffff0000, v89
	v_lshlrev_b32_e32 v9, 16, v90
	v_and_b32_e32 v93, 0xffff0000, v90
	v_lshlrev_b32_e32 v88, 16, v91
	v_and_b32_e32 v89, 0xffff0000, v91
	v_mul_f32_e32 v90, v32, v31
	v_mul_f32_e32 v98, v28, v29
	v_pk_mul_f32 v[150:151], v[150:151], v[114:115]
	v_mov_b32_e32 v99, v148
	v_mov_b32_e32 v91, v149
	v_mul_f32_e32 v106, v24, v168
	v_pk_add_f32 v[90:91], v[98:99], v[90:91]
	v_mov_b32_e32 v107, v151
	v_mul_f32_e32 v146, v92, v20
	v_pk_add_f32 v[90:91], v[106:107], v[90:91]
	v_mov_b32_e32 v147, v150
	v_pk_add_f32 v[90:91], v[146:147], v[90:91]
	v_mov_b32_e32 v102, v105
	v_mul_f32_e32 v13, 0xbfb8aa3b, v90
	v_exp_f32_e32 v98, v13
	v_mul_f32_e32 v13, 0xbfb8aa3b, v91
	v_exp_f32_e32 v99, v13
	v_pk_mul_f32 v[148:149], v[116:117], v[102:103]
	v_mul_f32_e32 v106, v30, v21
	v_pk_mul_f32 v[144:145], v[144:145], v[118:119]
	v_pk_add_f32 v[98:99], v[98:99], 1.0 op_sel_hi:[1,0]
	v_mov_b32_e32 v107, v148
	v_mul_f32_e32 v146, v26, v156
	v_mov_b32_e32 v147, v145
	v_mul_f32_e32 v94, v94, v22
	v_rcp_f32_e32 v13, v99
	s_nop 0
	v_mul_f32_e32 v91, v91, v13
	v_mov_b32_e32 v99, v149
	v_mov_b32_e32 v95, v144
	v_mov_b32_e32 v92, v97
	v_rcp_f32_e32 v13, v98
	s_nop 0
	v_mul_f32_e32 v90, v90, v13
	v_mul_f32_e32 v98, v34, v23
	v_pk_add_f32 v[98:99], v[106:107], v[98:99]
	v_mul_f32_e32 v106, v12, v5
	v_pk_add_f32 v[98:99], v[146:147], v[98:99]
	v_pk_mul_f32 v[146:147], v[136:137], v[92:93]
	v_pk_add_f32 v[94:95], v[94:95], v[98:99]
	v_pk_mul_f32 v[140:141], v[140:141], v[108:109]
	v_mul_f32_e32 v13, 0xbfb8aa3b, v94
	v_exp_f32_e32 v98, v13
	v_mul_f32_e32 v13, 0xbfb8aa3b, v95
	v_exp_f32_e32 v99, v13
	v_mov_b32_e32 v107, v146
	v_mul_f32_e32 v144, v8, v133
	v_mov_b32_e32 v145, v141
	v_pk_add_f32 v[98:99], v[98:99], 1.0 op_sel_hi:[1,0]
	v_mul_f32_e32 v84, v84, v4
	v_mov_b32_e32 v85, v140
	v_rcp_f32_e32 v13, v99
	s_nop 0
	v_mul_f32_e32 v95, v95, v13
	v_mov_b32_e32 v99, v147
	v_rcp_f32_e32 v13, v98
	s_nop 0
	v_mul_f32_e32 v94, v94, v13
	v_mul_f32_e32 v98, v16, v9
	v_pk_add_f32 v[98:99], v[106:107], v[98:99]
	s_nop 0
	v_pk_add_f32 v[98:99], v[144:145], v[98:99]
	s_nop 0
	v_pk_add_f32 v[84:85], v[84:85], v[98:99]
	s_nop 0
	v_mul_f32_e32 v13, 0xbfb8aa3b, v84
	v_exp_f32_e32 v98, v13
	v_mul_f32_e32 v13, 0xbfb8aa3b, v85
	v_exp_f32_e32 v99, v13
	s_nop 0
	v_pk_add_f32 v[98:99], v[98:99], 1.0 op_sel_hi:[1,0]
	s_nop 0
	v_rcp_f32_e32 v13, v99
	s_nop 0
	v_mul_f32_e32 v85, v85, v13
	v_rcp_f32_e32 v13, v98
	s_nop 0
	v_mul_f32_e32 v84, v84, v13
	v_pk_mul_f32 v[98:99], v[18:19], v[88:89]
	s_nop 0
	v_pk_fma_f32 v[98:99], v[14:15], v[100:101], v[98:99]
	s_nop 0
	v_pk_fma_f32 v[98:99], v[10:11], v[138:139], v[98:99]
	s_nop 0
	v_pk_fma_f32 v[86:87], v[86:87], v[6:7], v[98:99]
	s_nop 0
	v_mul_f32_e32 v13, 0xbfb8aa3b, v86
	v_exp_f32_e32 v98, v13
	v_mul_f32_e32 v13, 0xbfb8aa3b, v87
	v_exp_f32_e32 v99, v13
	s_nop 0
	v_pk_add_f32 v[98:99], v[98:99], 1.0 op_sel_hi:[1,0]
	s_nop 0
	v_rcp_f32_e32 v13, v99
	s_nop 0
	v_mul_f32_e32 v87, v87, v13
	v_rcp_f32_e32 v13, v98
	s_nop 0
	v_mul_f32_e32 v86, v86, v13
	s_and_saveexec_b64 s[40:41], s[36:37]
	s_cbranch_execz .LBB0_173
	v_pk_mul_f32 v[98:99], v[90:91], v[90:91]
	v_pk_mul_f32 v[106:107], v[94:95], v[94:95]
	v_add_f32_e32 v13, v98, v99
	v_add_f32_e32 v13, v13, v106
	v_pk_mul_f32 v[140:141], v[84:85], v[84:85]
	v_add_f32_e32 v13, v13, v107
	v_and_b32_e32 v25, 64, v251
	v_add_f32_e32 v13, v13, v140
	v_add_u32_e32 v25, 64, v25
	v_pk_mul_f32 v[144:145], v[86:87], v[86:87]
	v_add_f32_e32 v13, v13, v141
	v_add_f32_e32 v13, v13, v144
	v_add_f32_e32 v13, v13, v145
	s_waitcnt lgkmcnt(0)
	s_nop 1
	v_add_f32_dpp v13, v13, v13 row_ror:8 row_mask:0xf bank_mask:0xf
	s_waitcnt lgkmcnt(0)
	s_nop 1
	v_add_f32_dpp v13, v13, v13 row_ror:4 row_mask:0xf bank_mask:0xf
	s_waitcnt lgkmcnt(0)
	s_nop 1
	v_add_f32_dpp v13, v13, v13 row_ror:2 row_mask:0xf bank_mask:0xf
	s_waitcnt lgkmcnt(0)
	s_nop 1
	v_add_f32_dpp v13, v13, v13 row_ror:1 row_mask:0xf bank_mask:0xf
	v_add_f32_e32 v13, 0x358637bd, v13
	v_mul_f32_e32 v17, 0x4b800000, v13
	v_cmp_gt_f32_e32 vcc, s2, v13
	s_nop 1
	v_cndmask_b32_e32 v13, v13, v17, vcc
	v_rsq_f32_e32 v13, v13
	s_nop 0
	v_mul_f32_e32 v17, 0x45800000, v13
	v_cndmask_b32_e32 v13, v13, v17, vcc
	v_mul_f32_e32 v98, v129, v13
	v_pk_mul_f32 v[90:91], v[90:91], v[98:99] op_sel_hi:[1,0]
	v_pk_mul_f32 v[94:95], v[94:95], v[98:99] op_sel_hi:[1,0]
	v_pk_mul_f32 v[84:85], v[84:85], v[98:99] op_sel_hi:[1,0]
	v_pk_mul_f32 v[86:87], v[86:87], v[98:99] op_sel_hi:[1,0]
; DI F8 unpack8(uint4 u) { F8 r; r.v[0] = lo16(u.x); r.v[1] = hi16(u.x); r.v[2] = lo16(u.y); r.v[3] = hi16(u.y); r.v[4] = lo16(u.z); r.v[5] = hi16(u.z); r.v[6] = lo16(u.w); r.v[7] = hi16(u.w); return r; }
; DI void stf8(float* p, const F8& f) { *(float4*)p = make_float4(f.v[0], f.v[1], f.v[2], f.v[3]); *(float4*)(p + 4) = make_float4(f.v[4], f.v[5], f.v[6], f.v[7]); }
; DI void stb8(bf16_t* p, const F8& f) { *(uint4*)p = pack8(f); }
; DI float gsum16(float v) { v += __shfl_xor(v, 8); v += __shfl_xor(v, 4); v += __shfl_xor(v, 2); v += __shfl_xor(v, 1); return v; }
; DI float siluf(float x) { return x / (1.f + __expf(-x)); }
; DI void odd_elem(const Params& p, int o) {
;     ...
;         for (int t = 0; t < 16; ++t) {
;             const F8 x0 = unpack8(xr[t]);
;             F8 acc; float ss = 0.f;
; #pragma unroll
;             for (int k = 0; k < 8; ++k) { const float a = w3.v[k] * x0.v[k] + w2.v[k] * h1.v[k] + w1.v[k] * h2.v[k] + w0.v[k] * h3.v[k]; acc.v[k] = siluf(a); ss += acc.v[k] * acc.v[k]; }
;             if (gi < 4) {
;                 const float rs = rsqrtf(gsum16(ss) + EPS) * nsc;
; #pragma unroll
;                 for (int k = 0; k < 8; ++k) acc.v[k] *= rs;
;             }
;             stb8(Q2 + (size_t)(r0 + t) * 3072 + c, acc);
;             if (last && t >= 13) {
;                 float* so = sq < 4 ? p.out + O_PDC + (((size_t)o * 4 + sq) * 3 + (t - 13)) * 3072 : p.out + O_SDC + (((size_t)o * 8 + (sq - 4)) * 3 + (t - 13)) * 3072;
;                 stf8(so + c, x0);
;             }
;             h3 = h2; h2 = h1; h1 = x0;
.LBB0_173:
	s_or_b64 exec, exec, s[40:41]
	v_or_b32_e32 v13, 2, v123
	v_and_b32_e32 v107, 0xffff0000, v80
	v_mov_b32_e32 v106, v143
	v_mad_i64_i32 v[98:99], s[40:41], v13, s33, v[110:111]
	v_cvt_pk_bf16_f32 v144, v90, v91
	v_cvt_pk_bf16_f32 v145, v94, v95
	v_cvt_pk_bf16_f32 v146, v84, v85
	v_cvt_pk_bf16_f32 v147, v86, v87
	v_lshlrev_b32_e32 v33, 16, v80
	v_pk_mul_f32 v[140:141], v[112:113], v[106:107]
	global_store_dwordx4 v[98:99], v[144:147], off sc1
	v_lshlrev_b32_e32 v25, 16, v81
	v_and_b32_e32 v99, 0xffff0000, v81
	v_lshlrev_b32_e32 v13, 16, v82
	v_and_b32_e32 v87, 0xffff0000, v82
	v_lshlrev_b32_e32 v80, 16, v83
	v_and_b32_e32 v81, 0xffff0000, v83
	v_mul_f32_e32 v82, v32, v33
	v_mul_f32_e32 v84, v28, v31
	v_pk_mul_f32 v[144:145], v[114:115], v[152:153]
	v_mov_b32_e32 v85, v140
	v_mov_b32_e32 v83, v141
	v_mul_f32_e32 v90, v24, v29
	v_pk_add_f32 v[82:83], v[84:85], v[82:83]
	v_mov_b32_e32 v91, v145
	v_mul_f32_e32 v94, v20, v168
	v_pk_add_f32 v[82:83], v[90:91], v[82:83]
	v_mov_b32_e32 v95, v144
	v_pk_add_f32 v[82:83], v[94:95], v[82:83]
	v_mov_b32_e32 v98, v103
	v_mul_f32_e32 v17, 0xbfb8aa3b, v82
	v_exp_f32_e32 v84, v17
	v_mul_f32_e32 v17, 0xbfb8aa3b, v83
	v_exp_f32_e32 v85, v17
	v_pk_mul_f32 v[144:145], v[116:117], v[98:99]
	v_pk_mul_f32 v[104:105], v[118:119], v[104:105]
	v_mov_b32_e32 v91, v144
	v_pk_add_f32 v[84:85], v[84:85], 1.0 op_sel_hi:[1,0]
	v_mul_f32_e32 v94, v26, v21
	v_mov_b32_e32 v95, v105
	v_mul_f32_e32 v140, v22, v156
	v_mov_b32_e32 v141, v104
	v_rcp_f32_e32 v17, v85
	s_nop 0
	v_mul_f32_e32 v83, v83, v17
	v_mul_f32_e32 v90, v30, v23
	v_pk_mul_f32 v[96:97], v[108:109], v[96:97]
	v_mul_f32_e32 v104, v8, v5
	v_rcp_f32_e32 v17, v84
	s_nop 0
	v_mul_f32_e32 v82, v82, v17
	v_mul_f32_e32 v84, v34, v25
	v_mov_b32_e32 v85, v145
	v_pk_add_f32 v[84:85], v[90:91], v[84:85]
	v_mov_b32_e32 v105, v97
	v_pk_add_f32 v[84:85], v[94:95], v[84:85]
	s_nop 0
	v_pk_add_f32 v[84:85], v[140:141], v[84:85]
	v_mul_f32_e32 v140, v4, v133
	v_mul_f32_e32 v17, 0xbfb8aa3b, v84
	v_exp_f32_e32 v90, v17
	v_mul_f32_e32 v17, 0xbfb8aa3b, v85
	v_exp_f32_e32 v91, v17
	v_mov_b32_e32 v141, v96
	v_pk_add_f32 v[90:91], v[90:91], 1.0 op_sel_hi:[1,0]
	s_nop 0
	v_rcp_f32_e32 v17, v91
	s_nop 0
	v_mul_f32_e32 v85, v85, v17
	v_mul_f32_e32 v94, v12, v9
	v_mov_b32_e32 v86, v93
	v_pk_mul_f32 v[144:145], v[136:137], v[86:87]
	v_rcp_f32_e32 v17, v90
	s_nop 0
	v_mul_f32_e32 v84, v84, v17
	v_mul_f32_e32 v90, v16, v13
	v_mov_b32_e32 v95, v144
	v_mov_b32_e32 v91, v145
	v_pk_add_f32 v[90:91], v[94:95], v[90:91]
	s_nop 0
	v_pk_add_f32 v[90:91], v[104:105], v[90:91]
	s_nop 0
	v_pk_add_f32 v[90:91], v[140:141], v[90:91]
	s_nop 0
	v_mul_f32_e32 v17, 0xbfb8aa3b, v90
	v_exp_f32_e32 v94, v17
	v_mul_f32_e32 v17, 0xbfb8aa3b, v91
	v_exp_f32_e32 v95, v17
	s_nop 0
	v_pk_add_f32 v[94:95], v[94:95], 1.0 op_sel_hi:[1,0]
	s_nop 0
	v_rcp_f32_e32 v17, v95
	s_nop 0
	v_mul_f32_e32 v91, v91, v17
	v_rcp_f32_e32 v17, v94
	s_nop 0
	v_mul_f32_e32 v90, v90, v17
	v_pk_mul_f32 v[94:95], v[18:19], v[80:81]
	s_nop 0
	v_pk_fma_f32 v[94:95], v[14:15], v[88:89], v[94:95]
	s_nop 0
	v_pk_fma_f32 v[94:95], v[10:11], v[100:101], v[94:95]
	s_nop 0
	v_pk_fma_f32 v[94:95], v[6:7], v[138:139], v[94:95]
	s_nop 0
	v_mul_f32_e32 v17, 0xbfb8aa3b, v94
	v_exp_f32_e32 v96, v17
	v_mul_f32_e32 v17, 0xbfb8aa3b, v95
	v_exp_f32_e32 v97, v17
	s_nop 0
	v_pk_add_f32 v[96:97], v[96:97], 1.0 op_sel_hi:[1,0]
	s_nop 0
	v_rcp_f32_e32 v17, v97
	s_nop 0
	v_mul_f32_e32 v95, v95, v17
	v_rcp_f32_e32 v17, v96
	s_nop 0
	v_mul_f32_e32 v94, v94, v17
	s_and_saveexec_b64 s[40:41], s[36:37]
	s_cbranch_execz .LBB0_175
	v_pk_mul_f32 v[96:97], v[82:83], v[82:83]
	v_pk_mul_f32 v[104:105], v[84:85], v[84:85]
	v_add_f32_e32 v17, v96, v97
	v_add_f32_e32 v17, v17, v104
	v_pk_mul_f32 v[138:139], v[90:91], v[90:91]
	v_add_f32_e32 v17, v17, v105
	v_and_b32_e32 v35, 64, v251
	v_add_f32_e32 v17, v17, v138
	v_add_u32_e32 v35, 64, v35
	v_pk_mul_f32 v[140:141], v[94:95], v[94:95]
	v_add_f32_e32 v17, v17, v139
	v_add_f32_e32 v17, v17, v140
	v_add_f32_e32 v17, v17, v141
	s_waitcnt lgkmcnt(0)
	s_nop 1
	v_add_f32_dpp v17, v17, v17 row_ror:8 row_mask:0xf bank_mask:0xf
	s_waitcnt lgkmcnt(0)
	s_nop 1
	v_add_f32_dpp v17, v17, v17 row_ror:4 row_mask:0xf bank_mask:0xf
	s_waitcnt lgkmcnt(0)
	s_nop 1
	v_add_f32_dpp v17, v17, v17 row_ror:2 row_mask:0xf bank_mask:0xf
	s_waitcnt lgkmcnt(0)
	s_nop 1
	v_add_f32_dpp v17, v17, v17 row_ror:1 row_mask:0xf bank_mask:0xf
	v_add_f32_e32 v17, 0x358637bd, v17
	v_mul_f32_e32 v27, 0x4b800000, v17
	v_cmp_gt_f32_e32 vcc, s2, v17
	s_nop 1
	v_cndmask_b32_e32 v17, v17, v27, vcc
	v_rsq_f32_e32 v17, v17
	s_nop 0
	v_mul_f32_e32 v27, 0x45800000, v17
	v_cndmask_b32_e32 v17, v17, v27, vcc
	v_mul_f32_e32 v96, v129, v17
	v_pk_mul_f32 v[82:83], v[82:83], v[96:97] op_sel_hi:[1,0]
	v_pk_mul_f32 v[84:85], v[84:85], v[96:97] op_sel_hi:[1,0]
	v_pk_mul_f32 v[90:91], v[90:91], v[96:97] op_sel_hi:[1,0]
	v_pk_mul_f32 v[94:95], v[94:95], v[96:97] op_sel_hi:[1,0]
; DI F8 unpack8(uint4 u) { F8 r; r.v[0] = lo16(u.x); r.v[1] = hi16(u.x); r.v[2] = lo16(u.y); r.v[3] = hi16(u.y); r.v[4] = lo16(u.z); r.v[5] = hi16(u.z); r.v[6] = lo16(u.w); r.v[7] = hi16(u.w); return r; }
; DI void stf8(float* p, const F8& f) { *(float4*)p = make_float4(f.v[0], f.v[1], f.v[2], f.v[3]); *(float4*)(p + 4) = make_float4(f.v[4], f.v[5], f.v[6], f.v[7]); }
; DI void stb8(bf16_t* p, const F8& f) { *(uint4*)p = pack8(f); }
; DI float gsum16(float v) { v += __shfl_xor(v, 8); v += __shfl_xor(v, 4); v += __shfl_xor(v, 2); v += __shfl_xor(v, 1); return v; }
; DI float siluf(float x) { return x / (1.f + __expf(-x)); }
; DI void odd_elem(const Params& p, int o) {
;     ...
;         for (int t = 0; t < 16; ++t) {
;             const F8 x0 = unpack8(xr[t]);
;             F8 acc; float ss = 0.f;
; #pragma unroll
;             for (int k = 0; k < 8; ++k) { const float a = w3.v[k] * x0.v[k] + w2.v[k] * h1.v[k] + w1.v[k] * h2.v[k] + w0.v[k] * h3.v[k]; acc.v[k] = siluf(a); ss += acc.v[k] * acc.v[k]; }
;             if (gi < 4) {
;                 const float rs = rsqrtf(gsum16(ss) + EPS) * nsc;
; #pragma unroll
;                 for (int k = 0; k < 8; ++k) acc.v[k] *= rs;
;             }
;             stb8(Q2 + (size_t)(r0 + t) * 3072 + c, acc);
;             if (last && t >= 13) {
;                 float* so = sq < 4 ? p.out + O_PDC + (((size_t)o * 4 + sq) * 3 + (t - 13)) * 3072 : p.out + O_SDC + (((size_t)o * 8 + (sq - 4)) * 3 + (t - 13)) * 3072;
;                 stf8(so + c, x0);
;             }
;             h3 = h2; h2 = h1; h1 = x0;
.LBB0_175:
	s_or_b64 exec, exec, s[40:41]
	v_or_b32_e32 v17, 3, v123
	v_and_b32_e32 v105, 0xffff0000, v76
	v_mov_b32_e32 v104, v107
	v_mad_i64_i32 v[96:97], s[40:41], v17, s33, v[110:111]
	v_cvt_pk_bf16_f32 v82, v82, v83
	v_cvt_pk_bf16_f32 v83, v84, v85
	v_cvt_pk_bf16_f32 v84, v90, v91
	v_cvt_pk_bf16_f32 v85, v94, v95
	v_lshlrev_b32_e32 v35, 16, v76
	v_pk_mul_f32 v[138:139], v[112:113], v[104:105]
	global_store_dwordx4 v[96:97], v[82:85], off sc1
	v_lshlrev_b32_e32 v27, 16, v77
	v_and_b32_e32 v95, 0xffff0000, v77
	v_lshlrev_b32_e32 v17, 16, v78
	v_and_b32_e32 v85, 0xffff0000, v78
	v_lshlrev_b32_e32 v76, 16, v79
	v_and_b32_e32 v77, 0xffff0000, v79
	v_mul_f32_e32 v78, v32, v35
	v_mul_f32_e32 v82, v28, v33
	v_pk_mul_f32 v[140:141], v[114:115], v[142:143]
	v_mov_b32_e32 v83, v138
	v_mov_b32_e32 v79, v139
	v_mul_f32_e32 v90, v24, v31
	v_pk_add_f32 v[78:79], v[82:83], v[78:79]
	v_mov_b32_e32 v91, v141
	v_mul_f32_e32 v96, v20, v29
	v_pk_add_f32 v[78:79], v[90:91], v[78:79]
	v_mov_b32_e32 v97, v140
	v_pk_add_f32 v[78:79], v[96:97], v[78:79]
	v_pk_mul_f32 v[102:103], v[118:119], v[102:103]
	v_mul_f32_e32 v29, 0xbfb8aa3b, v78
	v_exp_f32_e32 v82, v29
	v_mul_f32_e32 v29, 0xbfb8aa3b, v79
	v_exp_f32_e32 v83, v29
	v_mul_f32_e32 v96, v26, v23
	v_mov_b32_e32 v97, v103
	v_mul_f32_e32 v138, v22, v21
	v_pk_add_f32 v[82:83], v[82:83], 1.0 op_sel_hi:[1,0]
	v_mov_b32_e32 v139, v102
	v_pk_mul_f32 v[92:93], v[108:109], v[92:93]
	v_mul_f32_e32 v102, v8, v9
	v_mov_b32_e32 v103, v93
	v_rcp_f32_e32 v29, v83
	s_nop 0
	v_mul_f32_e32 v79, v79, v29
	v_mov_b32_e32 v94, v99
	v_pk_mul_f32 v[140:141], v[116:117], v[94:95]
	v_rcp_f32_e32 v29, v82
	s_nop 0
	v_mul_f32_e32 v78, v78, v29
	v_mul_f32_e32 v82, v34, v27
	v_mul_f32_e32 v90, v30, v25
	v_mov_b32_e32 v91, v140
	v_mov_b32_e32 v83, v141
	v_pk_add_f32 v[82:83], v[90:91], v[82:83]
	s_nop 0
	v_pk_add_f32 v[82:83], v[96:97], v[82:83]
	s_nop 0
	v_pk_add_f32 v[82:83], v[138:139], v[82:83]
	v_mul_f32_e32 v138, v4, v5
	v_mul_f32_e32 v21, 0xbfb8aa3b, v82
	v_exp_f32_e32 v90, v21
	v_mul_f32_e32 v21, 0xbfb8aa3b, v83
	v_exp_f32_e32 v91, v21
	v_mov_b32_e32 v139, v92
	v_pk_add_f32 v[90:91], v[90:91], 1.0 op_sel_hi:[1,0]
	s_nop 0
	v_rcp_f32_e32 v21, v91
	s_nop 0
	v_mul_f32_e32 v83, v83, v21
	v_mov_b32_e32 v84, v87
	v_pk_mul_f32 v[140:141], v[136:137], v[84:85]
	v_rcp_f32_e32 v21, v90
	s_nop 0
	v_mul_f32_e32 v82, v82, v21
	v_mul_f32_e32 v90, v16, v17
	v_mul_f32_e32 v96, v12, v13
	v_mov_b32_e32 v97, v140
	v_mov_b32_e32 v91, v141
	v_pk_add_f32 v[90:91], v[96:97], v[90:91]
	s_nop 0
	v_pk_add_f32 v[90:91], v[102:103], v[90:91]
	s_nop 0
	v_pk_add_f32 v[90:91], v[138:139], v[90:91]
	s_nop 0
	v_mul_f32_e32 v5, 0xbfb8aa3b, v90
	v_exp_f32_e32 v92, v5
	v_mul_f32_e32 v5, 0xbfb8aa3b, v91
	v_exp_f32_e32 v93, v5
	s_nop 0
	v_pk_add_f32 v[92:93], v[92:93], 1.0 op_sel_hi:[1,0]
	s_nop 0
	v_rcp_f32_e32 v5, v93
	s_nop 0
	v_mul_f32_e32 v91, v91, v5
	v_rcp_f32_e32 v5, v92
	s_nop 0
	v_mul_f32_e32 v90, v90, v5
	v_pk_mul_f32 v[92:93], v[18:19], v[76:77]
	s_nop 0
	v_pk_fma_f32 v[92:93], v[14:15], v[80:81], v[92:93]
	s_nop 0
	v_pk_fma_f32 v[92:93], v[10:11], v[88:89], v[92:93]
	s_nop 0
	v_pk_fma_f32 v[92:93], v[6:7], v[100:101], v[92:93]
	s_nop 0
	v_mul_f32_e32 v5, 0xbfb8aa3b, v92
	v_exp_f32_e32 v96, v5
	v_mul_f32_e32 v5, 0xbfb8aa3b, v93
	v_exp_f32_e32 v97, v5
	s_nop 0
	v_pk_add_f32 v[96:97], v[96:97], 1.0 op_sel_hi:[1,0]
	s_nop 0
	v_rcp_f32_e32 v5, v97
	s_nop 0
	v_mul_f32_e32 v93, v93, v5
	v_rcp_f32_e32 v5, v96
	s_nop 0
	v_mul_f32_e32 v92, v92, v5
	s_and_saveexec_b64 s[40:41], s[36:37]
	s_cbranch_execz .LBB0_177
	v_pk_mul_f32 v[96:97], v[78:79], v[78:79]
	v_pk_mul_f32 v[100:101], v[82:83], v[82:83]
	v_add_f32_e32 v5, v96, v97
	v_add_f32_e32 v5, v5, v100
	v_pk_mul_f32 v[102:103], v[90:91], v[90:91]
	v_add_f32_e32 v5, v5, v101
	v_and_b32_e32 v29, 64, v251
	v_add_f32_e32 v5, v5, v102
	v_add_u32_e32 v29, 64, v29
	v_pk_mul_f32 v[138:139], v[92:93], v[92:93]
	v_add_f32_e32 v5, v5, v103
	v_add_f32_e32 v5, v5, v138
	v_add_f32_e32 v5, v5, v139
	s_waitcnt lgkmcnt(0)
	s_nop 1
	v_add_f32_dpp v5, v5, v5 row_ror:8 row_mask:0xf bank_mask:0xf
	s_waitcnt lgkmcnt(0)
	s_nop 1
	v_add_f32_dpp v5, v5, v5 row_ror:4 row_mask:0xf bank_mask:0xf
	s_waitcnt lgkmcnt(0)
	s_nop 1
	v_add_f32_dpp v5, v5, v5 row_ror:2 row_mask:0xf bank_mask:0xf
	s_waitcnt lgkmcnt(0)
	s_nop 1
	v_add_f32_dpp v5, v5, v5 row_ror:1 row_mask:0xf bank_mask:0xf
	v_add_f32_e32 v5, 0x358637bd, v5
	v_mul_f32_e32 v21, 0x4b800000, v5
	v_cmp_gt_f32_e32 vcc, s2, v5
	s_nop 1
	v_cndmask_b32_e32 v5, v5, v21, vcc
	v_rsq_f32_e32 v5, v5
	s_nop 0
	v_mul_f32_e32 v21, 0x45800000, v5
	v_cndmask_b32_e32 v5, v5, v21, vcc
	v_mul_f32_e32 v96, v129, v5
	v_pk_mul_f32 v[78:79], v[78:79], v[96:97] op_sel_hi:[1,0]
	v_pk_mul_f32 v[82:83], v[82:83], v[96:97] op_sel_hi:[1,0]
	v_pk_mul_f32 v[90:91], v[90:91], v[96:97] op_sel_hi:[1,0]
	v_pk_mul_f32 v[92:93], v[92:93], v[96:97] op_sel_hi:[1,0]
; DI F8 unpack8(uint4 u) { F8 r; r.v[0] = lo16(u.x); r.v[1] = hi16(u.x); r.v[2] = lo16(u.y); r.v[3] = hi16(u.y); r.v[4] = lo16(u.z); r.v[5] = hi16(u.z); r.v[6] = lo16(u.w); r.v[7] = hi16(u.w); return r; }
; DI void stf8(float* p, const F8& f) { *(float4*)p = make_float4(f.v[0], f.v[1], f.v[2], f.v[3]); *(float4*)(p + 4) = make_float4(f.v[4], f.v[5], f.v[6], f.v[7]); }
; DI void stb8(bf16_t* p, const F8& f) { *(uint4*)p = pack8(f); }
; DI float gsum16(float v) { v += __shfl_xor(v, 8); v += __shfl_xor(v, 4); v += __shfl_xor(v, 2); v += __shfl_xor(v, 1); return v; }
; DI float siluf(float x) { return x / (1.f + __expf(-x)); }
; DI void odd_elem(const Params& p, int o) {
;     ...
;         for (int t = 0; t < 16; ++t) {
;             const F8 x0 = unpack8(xr[t]);
;             F8 acc; float ss = 0.f;
; #pragma unroll
;             for (int k = 0; k < 8; ++k) { const float a = w3.v[k] * x0.v[k] + w2.v[k] * h1.v[k] + w1.v[k] * h2.v[k] + w0.v[k] * h3.v[k]; acc.v[k] = siluf(a); ss += acc.v[k] * acc.v[k]; }
;             if (gi < 4) {
;                 const float rs = rsqrtf(gsum16(ss) + EPS) * nsc;
; #pragma unroll
;                 for (int k = 0; k < 8; ++k) acc.v[k] *= rs;
;             }
;             stb8(Q2 + (size_t)(r0 + t) * 3072 + c, acc);
;             if (last && t >= 13) {
;                 float* so = sq < 4 ? p.out + O_PDC + (((size_t)o * 4 + sq) * 3 + (t - 13)) * 3072 : p.out + O_SDC + (((size_t)o * 8 + (sq - 4)) * 3 + (t - 13)) * 3072;
;                 stf8(so + c, x0);
;             }
;             h3 = h2; h2 = h1; h1 = x0;
.LBB0_177:
	s_or_b64 exec, exec, s[40:41]
	v_or_b32_e32 v5, 4, v123
	v_mad_i64_i32 v[96:97], s[40:41], v5, s33, v[110:111]
	v_cvt_pk_bf16_f32 v100, v78, v79
	v_cvt_pk_bf16_f32 v101, v82, v83
	v_cvt_pk_bf16_f32 v102, v90, v91
	v_cvt_pk_bf16_f32 v103, v92, v93
	global_store_dwordx4 v[96:97], v[100:103], off sc1
	v_lshlrev_b32_e32 v29, 16, v72
	v_lshlrev_b32_e32 v21, 16, v73
	v_and_b32_e32 v101, 0xffff0000, v72
	v_mov_b32_e32 v100, v105
	v_pk_mul_f32 v[102:103], v[112:113], v[100:101]
	v_and_b32_e32 v91, 0xffff0000, v73
	v_lshlrev_b32_e32 v5, 16, v74
	v_and_b32_e32 v83, 0xffff0000, v74
	v_lshlrev_b32_e32 v72, 16, v75
	v_and_b32_e32 v73, 0xffff0000, v75
	v_mul_f32_e32 v74, v32, v29
	v_mul_f32_e32 v78, v28, v35
	v_pk_mul_f32 v[106:107], v[114:115], v[106:107]
	v_mov_b32_e32 v79, v102
	v_mov_b32_e32 v75, v103
	v_mul_f32_e32 v92, v24, v33
	v_pk_add_f32 v[74:75], v[78:79], v[74:75]
	v_mov_b32_e32 v93, v107
	v_mul_f32_e32 v96, v20, v31
	v_pk_add_f32 v[74:75], v[92:93], v[74:75]
	v_mov_b32_e32 v97, v106
	v_pk_add_f32 v[74:75], v[96:97], v[74:75]
	v_pk_mul_f32 v[98:99], v[118:119], v[98:99]
	v_mul_f32_e32 v31, 0xbfb8aa3b, v74
	v_exp_f32_e32 v78, v31
	v_mul_f32_e32 v31, 0xbfb8aa3b, v75
	v_exp_f32_e32 v79, v31
	v_mul_f32_e32 v96, v26, v25
	v_mov_b32_e32 v97, v99
	v_mul_f32_e32 v102, v22, v23
	v_pk_add_f32 v[78:79], v[78:79], 1.0 op_sel_hi:[1,0]
	v_mov_b32_e32 v103, v98
	v_pk_mul_f32 v[86:87], v[108:109], v[86:87]
	v_mul_f32_e32 v98, v8, v13
	v_mov_b32_e32 v99, v87
	v_rcp_f32_e32 v31, v79
	s_nop 0
	v_mul_f32_e32 v75, v75, v31
	v_mov_b32_e32 v90, v95
	v_pk_mul_f32 v[106:107], v[116:117], v[90:91]
	v_rcp_f32_e32 v31, v78
	s_nop 0
	v_mul_f32_e32 v74, v74, v31
	v_mul_f32_e32 v78, v34, v21
	v_mul_f32_e32 v92, v30, v27
	v_mov_b32_e32 v93, v106
	v_mov_b32_e32 v79, v107
	v_pk_add_f32 v[78:79], v[92:93], v[78:79]
	s_nop 0
	v_pk_add_f32 v[78:79], v[96:97], v[78:79]
	s_nop 0
	v_pk_add_f32 v[78:79], v[102:103], v[78:79]
	v_mul_f32_e32 v102, v4, v9
	v_mul_f32_e32 v23, 0xbfb8aa3b, v78
	v_exp_f32_e32 v92, v23
	v_mul_f32_e32 v23, 0xbfb8aa3b, v79
	v_exp_f32_e32 v93, v23
	v_mov_b32_e32 v103, v86
	v_pk_add_f32 v[92:93], v[92:93], 1.0 op_sel_hi:[1,0]
	s_nop 0
	v_rcp_f32_e32 v23, v93
	s_nop 0
	v_mul_f32_e32 v79, v79, v23
	v_mov_b32_e32 v82, v85
	v_pk_mul_f32 v[106:107], v[136:137], v[82:83]
	v_rcp_f32_e32 v23, v92
	s_nop 0
	v_mul_f32_e32 v78, v78, v23
	v_mul_f32_e32 v92, v16, v5
	v_mul_f32_e32 v96, v12, v17
	v_mov_b32_e32 v97, v106
	v_mov_b32_e32 v93, v107
	v_pk_add_f32 v[92:93], v[96:97], v[92:93]
	s_nop 0
	v_pk_add_f32 v[92:93], v[98:99], v[92:93]
	s_nop 0
	v_pk_add_f32 v[86:87], v[102:103], v[92:93]
	s_nop 0
	v_mul_f32_e32 v9, 0xbfb8aa3b, v86
	v_exp_f32_e32 v92, v9
	v_mul_f32_e32 v9, 0xbfb8aa3b, v87
	v_exp_f32_e32 v93, v9
	s_nop 0
	v_pk_add_f32 v[92:93], v[92:93], 1.0 op_sel_hi:[1,0]
	s_nop 0
	v_rcp_f32_e32 v9, v93
	s_nop 0
	v_mul_f32_e32 v87, v87, v9
	v_rcp_f32_e32 v9, v92
	s_nop 0
	v_mul_f32_e32 v86, v86, v9
	v_pk_mul_f32 v[92:93], v[18:19], v[72:73]
	s_nop 0
	v_pk_fma_f32 v[92:93], v[14:15], v[76:77], v[92:93]
	s_nop 0
	v_pk_fma_f32 v[92:93], v[10:11], v[80:81], v[92:93]
	s_nop 0
	v_pk_fma_f32 v[88:89], v[6:7], v[88:89], v[92:93]
	s_nop 0
	v_mul_f32_e32 v9, 0xbfb8aa3b, v88
	v_exp_f32_e32 v92, v9
	v_mul_f32_e32 v9, 0xbfb8aa3b, v89
	v_exp_f32_e32 v93, v9
	s_nop 0
	v_pk_add_f32 v[92:93], v[92:93], 1.0 op_sel_hi:[1,0]
	s_nop 0
	v_rcp_f32_e32 v9, v93
	s_nop 0
	v_mul_f32_e32 v89, v89, v9
	v_rcp_f32_e32 v9, v92
	s_nop 0
	v_mul_f32_e32 v88, v88, v9
	s_and_saveexec_b64 s[40:41], s[36:37]
	s_cbranch_execz .LBB0_179
	v_pk_mul_f32 v[92:93], v[74:75], v[74:75]
	v_pk_mul_f32 v[96:97], v[78:79], v[78:79]
	v_add_f32_e32 v9, v92, v93
	v_add_f32_e32 v9, v9, v96
	v_pk_mul_f32 v[98:99], v[86:87], v[86:87]
	v_add_f32_e32 v9, v9, v97
	v_and_b32_e32 v31, 64, v251
	v_add_f32_e32 v9, v9, v98
	v_add_u32_e32 v31, 64, v31
	v_pk_mul_f32 v[102:103], v[88:89], v[88:89]
	v_add_f32_e32 v9, v9, v99
	v_add_f32_e32 v9, v9, v102
	v_add_f32_e32 v9, v9, v103
	s_waitcnt lgkmcnt(0)
	s_nop 1
	v_add_f32_dpp v9, v9, v9 row_ror:8 row_mask:0xf bank_mask:0xf
	s_waitcnt lgkmcnt(0)
	s_nop 1
	v_add_f32_dpp v9, v9, v9 row_ror:4 row_mask:0xf bank_mask:0xf
	s_waitcnt lgkmcnt(0)
	s_nop 1
	v_add_f32_dpp v9, v9, v9 row_ror:2 row_mask:0xf bank_mask:0xf
	s_waitcnt lgkmcnt(0)
	s_nop 1
	v_add_f32_dpp v9, v9, v9 row_ror:1 row_mask:0xf bank_mask:0xf
	v_add_f32_e32 v9, 0x358637bd, v9
	v_mul_f32_e32 v23, 0x4b800000, v9
	v_cmp_gt_f32_e32 vcc, s2, v9
	s_nop 1
	v_cndmask_b32_e32 v9, v9, v23, vcc
	v_rsq_f32_e32 v9, v9
	s_nop 0
	v_mul_f32_e32 v23, 0x45800000, v9
	v_cndmask_b32_e32 v9, v9, v23, vcc
	v_mul_f32_e32 v92, v129, v9
	v_pk_mul_f32 v[74:75], v[74:75], v[92:93] op_sel_hi:[1,0]
	v_pk_mul_f32 v[78:79], v[78:79], v[92:93] op_sel_hi:[1,0]
	v_pk_mul_f32 v[86:87], v[86:87], v[92:93] op_sel_hi:[1,0]
	v_pk_mul_f32 v[88:89], v[88:89], v[92:93] op_sel_hi:[1,0]
; DI F8 unpack8(uint4 u) { F8 r; r.v[0] = lo16(u.x); r.v[1] = hi16(u.x); r.v[2] = lo16(u.y); r.v[3] = hi16(u.y); r.v[4] = lo16(u.z); r.v[5] = hi16(u.z); r.v[6] = lo16(u.w); r.v[7] = hi16(u.w); return r; }
; DI void stf8(float* p, const F8& f) { *(float4*)p = make_float4(f.v[0], f.v[1], f.v[2], f.v[3]); *(float4*)(p + 4) = make_float4(f.v[4], f.v[5], f.v[6], f.v[7]); }
; DI void stb8(bf16_t* p, const F8& f) { *(uint4*)p = pack8(f); }
; DI float gsum16(float v) { v += __shfl_xor(v, 8); v += __shfl_xor(v, 4); v += __shfl_xor(v, 2); v += __shfl_xor(v, 1); return v; }
; DI float siluf(float x) { return x / (1.f + __expf(-x)); }
; DI void odd_elem(const Params& p, int o) {
;     ...
;         for (int t = 0; t < 16; ++t) {
;             const F8 x0 = unpack8(xr[t]);
;             F8 acc; float ss = 0.f;
; #pragma unroll
;             for (int k = 0; k < 8; ++k) { const float a = w3.v[k] * x0.v[k] + w2.v[k] * h1.v[k] + w1.v[k] * h2.v[k] + w0.v[k] * h3.v[k]; acc.v[k] = siluf(a); ss += acc.v[k] * acc.v[k]; }
;             if (gi < 4) {
;                 const float rs = rsqrtf(gsum16(ss) + EPS) * nsc;
; #pragma unroll
;                 for (int k = 0; k < 8; ++k) acc.v[k] *= rs;
;             }
;             stb8(Q2 + (size_t)(r0 + t) * 3072 + c, acc);
;             if (last && t >= 13) {
;                 float* so = sq < 4 ? p.out + O_PDC + (((size_t)o * 4 + sq) * 3 + (t - 13)) * 3072 : p.out + O_SDC + (((size_t)o * 8 + (sq - 4)) * 3 + (t - 13)) * 3072;
;                 stf8(so + c, x0);
;             }
;             h3 = h2; h2 = h1; h1 = x0;
.LBB0_179:
	s_or_b64 exec, exec, s[40:41]
	v_or_b32_e32 v9, 5, v123
	v_mad_i64_i32 v[92:93], s[40:41], v9, s33, v[110:111]
	v_cvt_pk_bf16_f32 v96, v74, v75
	v_cvt_pk_bf16_f32 v97, v78, v79
	v_cvt_pk_bf16_f32 v98, v86, v87
	v_cvt_pk_bf16_f32 v99, v88, v89
	global_store_dwordx4 v[92:93], v[96:99], off sc1
	v_lshlrev_b32_e32 v31, 16, v68
	v_lshlrev_b32_e32 v23, 16, v69
	v_and_b32_e32 v97, 0xffff0000, v68
	v_mov_b32_e32 v96, v101
	v_pk_mul_f32 v[98:99], v[112:113], v[96:97]
	v_and_b32_e32 v87, 0xffff0000, v69
	v_lshlrev_b32_e32 v9, 16, v70
	v_and_b32_e32 v79, 0xffff0000, v70
	v_lshlrev_b32_e32 v68, 16, v71
	v_and_b32_e32 v69, 0xffff0000, v71
	v_mul_f32_e32 v70, v32, v31
	v_mul_f32_e32 v74, v28, v29
	v_pk_mul_f32 v[102:103], v[114:115], v[104:105]
	v_mov_b32_e32 v75, v98
	v_mov_b32_e32 v71, v99
	v_mul_f32_e32 v88, v24, v35
	v_pk_add_f32 v[70:71], v[74:75], v[70:71]
	v_mov_b32_e32 v89, v103
	v_mul_f32_e32 v92, v20, v33
	v_pk_add_f32 v[70:71], v[88:89], v[70:71]
	v_mov_b32_e32 v93, v102
	v_pk_add_f32 v[70:71], v[92:93], v[70:71]
	v_pk_mul_f32 v[94:95], v[118:119], v[94:95]
	v_mul_f32_e32 v33, 0xbfb8aa3b, v70
	v_exp_f32_e32 v74, v33
	v_mul_f32_e32 v33, 0xbfb8aa3b, v71
	v_exp_f32_e32 v75, v33
	v_mul_f32_e32 v92, v26, v27
	v_mov_b32_e32 v93, v95
	v_mul_f32_e32 v98, v22, v25
	v_pk_add_f32 v[74:75], v[74:75], 1.0 op_sel_hi:[1,0]
	v_mov_b32_e32 v99, v94
	v_pk_mul_f32 v[84:85], v[108:109], v[84:85]
	v_mul_f32_e32 v94, v8, v17
	v_mov_b32_e32 v95, v85
	v_rcp_f32_e32 v33, v75
	s_nop 0
	v_mul_f32_e32 v71, v71, v33
	v_mov_b32_e32 v86, v91
	v_pk_mul_f32 v[102:103], v[116:117], v[86:87]
	v_rcp_f32_e32 v33, v74
	s_nop 0
	v_mul_f32_e32 v70, v70, v33
	v_mul_f32_e32 v74, v34, v23
	v_mul_f32_e32 v88, v30, v21
	v_mov_b32_e32 v89, v102
	v_mov_b32_e32 v75, v103
	v_pk_add_f32 v[74:75], v[88:89], v[74:75]
	s_nop 0
	v_pk_add_f32 v[74:75], v[92:93], v[74:75]
	s_nop 0
	v_pk_add_f32 v[74:75], v[98:99], v[74:75]
	v_mul_f32_e32 v98, v4, v13
	v_mul_f32_e32 v25, 0xbfb8aa3b, v74
	v_exp_f32_e32 v88, v25
	v_mul_f32_e32 v25, 0xbfb8aa3b, v75
	v_exp_f32_e32 v89, v25
	v_mov_b32_e32 v99, v84
	v_pk_add_f32 v[88:89], v[88:89], 1.0 op_sel_hi:[1,0]
	s_nop 0
	v_rcp_f32_e32 v25, v89
	s_nop 0
	v_mul_f32_e32 v75, v75, v25
	v_mov_b32_e32 v78, v83
	v_pk_mul_f32 v[102:103], v[136:137], v[78:79]
	v_rcp_f32_e32 v25, v88
	s_nop 0
	v_mul_f32_e32 v74, v74, v25
	v_mul_f32_e32 v88, v16, v9
	v_mul_f32_e32 v92, v12, v5
	v_mov_b32_e32 v93, v102
	v_mov_b32_e32 v89, v103
	v_pk_add_f32 v[88:89], v[92:93], v[88:89]
	s_nop 0
	v_pk_add_f32 v[88:89], v[94:95], v[88:89]
	s_nop 0
	v_pk_add_f32 v[84:85], v[98:99], v[88:89]
	s_nop 0
	v_mul_f32_e32 v13, 0xbfb8aa3b, v84
	v_exp_f32_e32 v88, v13
	v_mul_f32_e32 v13, 0xbfb8aa3b, v85
	v_exp_f32_e32 v89, v13
	s_nop 0
	v_pk_add_f32 v[88:89], v[88:89], 1.0 op_sel_hi:[1,0]
	s_nop 0
	v_rcp_f32_e32 v13, v89
	s_nop 0
	v_mul_f32_e32 v85, v85, v13
	v_rcp_f32_e32 v13, v88
	s_nop 0
	v_mul_f32_e32 v84, v84, v13
	v_pk_mul_f32 v[88:89], v[18:19], v[68:69]
	s_nop 0
	v_pk_fma_f32 v[88:89], v[14:15], v[72:73], v[88:89]
	s_nop 0
	v_pk_fma_f32 v[88:89], v[10:11], v[76:77], v[88:89]
	s_nop 0
	v_pk_fma_f32 v[80:81], v[6:7], v[80:81], v[88:89]
	s_nop 0
	v_mul_f32_e32 v13, 0xbfb8aa3b, v80
	v_exp_f32_e32 v88, v13
	v_mul_f32_e32 v13, 0xbfb8aa3b, v81
	v_exp_f32_e32 v89, v13
	s_nop 0
	v_pk_add_f32 v[88:89], v[88:89], 1.0 op_sel_hi:[1,0]
	s_nop 0
	v_rcp_f32_e32 v13, v89
	s_nop 0
	v_mul_f32_e32 v81, v81, v13
	v_rcp_f32_e32 v13, v88
	s_nop 0
	v_mul_f32_e32 v80, v80, v13
	s_and_saveexec_b64 s[40:41], s[36:37]
	s_cbranch_execz .LBB0_181
	v_pk_mul_f32 v[88:89], v[70:71], v[70:71]
	v_pk_mul_f32 v[92:93], v[74:75], v[74:75]
	v_add_f32_e32 v13, v88, v89
	v_add_f32_e32 v13, v13, v92
	v_pk_mul_f32 v[94:95], v[84:85], v[84:85]
	v_add_f32_e32 v13, v13, v93
	v_and_b32_e32 v33, 64, v251
	v_add_f32_e32 v13, v13, v94
	v_add_u32_e32 v33, 64, v33
	v_pk_mul_f32 v[98:99], v[80:81], v[80:81]
	v_add_f32_e32 v13, v13, v95
	v_add_f32_e32 v13, v13, v98
	v_add_f32_e32 v13, v13, v99
	s_waitcnt lgkmcnt(0)
	s_nop 1
	v_add_f32_dpp v13, v13, v13 row_ror:8 row_mask:0xf bank_mask:0xf
	s_waitcnt lgkmcnt(0)
	s_nop 1
	v_add_f32_dpp v13, v13, v13 row_ror:4 row_mask:0xf bank_mask:0xf
	s_waitcnt lgkmcnt(0)
	s_nop 1
	v_add_f32_dpp v13, v13, v13 row_ror:2 row_mask:0xf bank_mask:0xf
	s_waitcnt lgkmcnt(0)
	s_nop 1
	v_add_f32_dpp v13, v13, v13 row_ror:1 row_mask:0xf bank_mask:0xf
	v_add_f32_e32 v13, 0x358637bd, v13
	v_mul_f32_e32 v25, 0x4b800000, v13
	v_cmp_gt_f32_e32 vcc, s2, v13
	s_nop 1
	v_cndmask_b32_e32 v13, v13, v25, vcc
	v_rsq_f32_e32 v13, v13
	s_nop 0
	v_mul_f32_e32 v25, 0x45800000, v13
	v_cndmask_b32_e32 v13, v13, v25, vcc
	v_mul_f32_e32 v88, v129, v13
	v_pk_mul_f32 v[70:71], v[70:71], v[88:89] op_sel_hi:[1,0]
	v_pk_mul_f32 v[74:75], v[74:75], v[88:89] op_sel_hi:[1,0]
	v_pk_mul_f32 v[84:85], v[84:85], v[88:89] op_sel_hi:[1,0]
	v_pk_mul_f32 v[80:81], v[80:81], v[88:89] op_sel_hi:[1,0]
; DI F8 unpack8(uint4 u) { F8 r; r.v[0] = lo16(u.x); r.v[1] = hi16(u.x); r.v[2] = lo16(u.y); r.v[3] = hi16(u.y); r.v[4] = lo16(u.z); r.v[5] = hi16(u.z); r.v[6] = lo16(u.w); r.v[7] = hi16(u.w); return r; }
; DI void stf8(float* p, const F8& f) { *(float4*)p = make_float4(f.v[0], f.v[1], f.v[2], f.v[3]); *(float4*)(p + 4) = make_float4(f.v[4], f.v[5], f.v[6], f.v[7]); }
; DI void stb8(bf16_t* p, const F8& f) { *(uint4*)p = pack8(f); }
; DI float gsum16(float v) { v += __shfl_xor(v, 8); v += __shfl_xor(v, 4); v += __shfl_xor(v, 2); v += __shfl_xor(v, 1); return v; }
; DI float siluf(float x) { return x / (1.f + __expf(-x)); }
; DI void odd_elem(const Params& p, int o) {
;     ...
;         for (int t = 0; t < 16; ++t) {
;             const F8 x0 = unpack8(xr[t]);
;             F8 acc; float ss = 0.f;
; #pragma unroll
;             for (int k = 0; k < 8; ++k) { const float a = w3.v[k] * x0.v[k] + w2.v[k] * h1.v[k] + w1.v[k] * h2.v[k] + w0.v[k] * h3.v[k]; acc.v[k] = siluf(a); ss += acc.v[k] * acc.v[k]; }
;             if (gi < 4) {
;                 const float rs = rsqrtf(gsum16(ss) + EPS) * nsc;
; #pragma unroll
;                 for (int k = 0; k < 8; ++k) acc.v[k] *= rs;
;             }
;             stb8(Q2 + (size_t)(r0 + t) * 3072 + c, acc);
;             if (last && t >= 13) {
;                 float* so = sq < 4 ? p.out + O_PDC + (((size_t)o * 4 + sq) * 3 + (t - 13)) * 3072 : p.out + O_SDC + (((size_t)o * 8 + (sq - 4)) * 3 + (t - 13)) * 3072;
;                 stf8(so + c, x0);
;             }
;             h3 = h2; h2 = h1; h1 = x0;
;         }
.LBB0_181:
	s_or_b64 exec, exec, s[40:41]
	v_or_b32_e32 v13, 6, v123
	v_mad_i64_i32 v[88:89], s[40:41], v13, s33, v[110:111]
	v_cvt_pk_bf16_f32 v92, v70, v71
	v_cvt_pk_bf16_f32 v93, v74, v75
	v_cvt_pk_bf16_f32 v94, v84, v85
	v_cvt_pk_bf16_f32 v95, v80, v81
	global_store_dwordx4 v[88:89], v[92:95], off sc1
	v_lshlrev_b32_e32 v33, 16, v64
	v_lshlrev_b32_e32 v25, 16, v65
	v_and_b32_e32 v93, 0xffff0000, v64
	v_mov_b32_e32 v92, v97
	v_pk_mul_f32 v[94:95], v[112:113], v[92:93]
	v_and_b32_e32 v85, 0xffff0000, v65
	v_lshlrev_b32_e32 v13, 16, v66
	v_and_b32_e32 v75, 0xffff0000, v66
	v_lshlrev_b32_e32 v64, 16, v67
	v_and_b32_e32 v65, 0xffff0000, v67
	v_mul_f32_e32 v66, v32, v33
	v_mul_f32_e32 v70, v28, v31
	v_pk_mul_f32 v[98:99], v[114:115], v[100:101]
	v_mov_b32_e32 v71, v94
	v_mov_b32_e32 v67, v95
	v_mul_f32_e32 v80, v24, v29
	v_pk_add_f32 v[66:67], v[70:71], v[66:67]
	v_mov_b32_e32 v81, v99
	v_mul_f32_e32 v88, v20, v35
	v_pk_add_f32 v[66:67], v[80:81], v[66:67]
	v_mov_b32_e32 v89, v98
	v_pk_add_f32 v[66:67], v[88:89], v[66:67]
	v_pk_mul_f32 v[90:91], v[118:119], v[90:91]
	v_mul_f32_e32 v35, 0xbfb8aa3b, v66
	v_exp_f32_e32 v70, v35
	v_mul_f32_e32 v35, 0xbfb8aa3b, v67
	v_exp_f32_e32 v71, v35
	v_mul_f32_e32 v88, v26, v21
	v_mov_b32_e32 v89, v91
	v_mul_f32_e32 v94, v22, v27
	v_pk_add_f32 v[70:71], v[70:71], 1.0 op_sel_hi:[1,0]
	v_mov_b32_e32 v95, v90
	v_pk_mul_f32 v[82:83], v[108:109], v[82:83]
	v_mul_f32_e32 v90, v8, v5
	v_mov_b32_e32 v91, v83
	v_rcp_f32_e32 v35, v71
	s_nop 0
	v_mul_f32_e32 v67, v67, v35
	v_mov_b32_e32 v84, v87
	v_pk_mul_f32 v[98:99], v[116:117], v[84:85]
	v_rcp_f32_e32 v35, v70
	s_nop 0
	v_mul_f32_e32 v66, v66, v35
	v_mul_f32_e32 v70, v34, v25
	v_mul_f32_e32 v80, v30, v23
	v_mov_b32_e32 v81, v98
	v_mov_b32_e32 v71, v99
	v_pk_add_f32 v[70:71], v[80:81], v[70:71]
	s_nop 0
	v_pk_add_f32 v[70:71], v[88:89], v[70:71]
	s_nop 0
	v_pk_add_f32 v[70:71], v[94:95], v[70:71]
	v_mul_f32_e32 v94, v4, v17
	v_mul_f32_e32 v27, 0xbfb8aa3b, v70
	v_exp_f32_e32 v80, v27
	v_mul_f32_e32 v27, 0xbfb8aa3b, v71
	v_exp_f32_e32 v81, v27
	v_mov_b32_e32 v95, v82
	v_pk_add_f32 v[80:81], v[80:81], 1.0 op_sel_hi:[1,0]
	s_nop 0
	v_rcp_f32_e32 v27, v81
	s_nop 0
	v_mul_f32_e32 v71, v71, v27
	v_mov_b32_e32 v74, v79
	v_pk_mul_f32 v[98:99], v[136:137], v[74:75]
	v_rcp_f32_e32 v27, v80
	s_nop 0
	v_mul_f32_e32 v70, v70, v27
	v_mul_f32_e32 v80, v16, v13
	v_mul_f32_e32 v88, v12, v9
	v_mov_b32_e32 v89, v98
	v_mov_b32_e32 v81, v99
	v_pk_add_f32 v[80:81], v[88:89], v[80:81]
	s_nop 0
	v_pk_add_f32 v[80:81], v[90:91], v[80:81]
	s_nop 0
	v_pk_add_f32 v[80:81], v[94:95], v[80:81]
	s_nop 0
	v_mul_f32_e32 v17, 0xbfb8aa3b, v80
	v_exp_f32_e32 v82, v17
	v_mul_f32_e32 v17, 0xbfb8aa3b, v81
	v_exp_f32_e32 v83, v17
	s_nop 0
	v_pk_add_f32 v[82:83], v[82:83], 1.0 op_sel_hi:[1,0]
	s_nop 0
	v_rcp_f32_e32 v17, v83
	s_nop 0
	v_mul_f32_e32 v81, v81, v17
	v_rcp_f32_e32 v17, v82
	s_nop 0
	v_mul_f32_e32 v80, v80, v17
	v_pk_mul_f32 v[82:83], v[18:19], v[64:65]
	s_nop 0
	v_pk_fma_f32 v[82:83], v[14:15], v[68:69], v[82:83]
	s_nop 0
	v_pk_fma_f32 v[82:83], v[10:11], v[72:73], v[82:83]
	s_nop 0
	v_pk_fma_f32 v[76:77], v[6:7], v[76:77], v[82:83]
	s_nop 0
	v_mul_f32_e32 v17, 0xbfb8aa3b, v76
	v_exp_f32_e32 v82, v17
	v_mul_f32_e32 v17, 0xbfb8aa3b, v77
	v_exp_f32_e32 v83, v17
	s_nop 0
	v_pk_add_f32 v[82:83], v[82:83], 1.0 op_sel_hi:[1,0]
	s_nop 0
	v_rcp_f32_e32 v17, v83
	s_nop 0
	v_mul_f32_e32 v77, v77, v17
	v_rcp_f32_e32 v17, v82
	s_nop 0
	v_mul_f32_e32 v76, v76, v17
	s_and_saveexec_b64 s[40:41], s[36:37]
	s_cbranch_execz .LBB0_183
	v_pk_mul_f32 v[82:83], v[66:67], v[66:67]
	v_pk_mul_f32 v[88:89], v[70:71], v[70:71]
	v_add_f32_e32 v17, v82, v83
	v_add_f32_e32 v17, v17, v88
	v_pk_mul_f32 v[90:91], v[80:81], v[80:81]
	v_add_f32_e32 v17, v17, v89
	v_and_b32_e32 v35, 64, v251
	v_add_f32_e32 v17, v17, v90
	v_add_u32_e32 v35, 64, v35
	v_pk_mul_f32 v[94:95], v[76:77], v[76:77]
	v_add_f32_e32 v17, v17, v91
	v_add_f32_e32 v17, v17, v94
	v_add_f32_e32 v17, v17, v95
	s_waitcnt lgkmcnt(0)
	s_nop 1
	v_add_f32_dpp v17, v17, v17 row_ror:8 row_mask:0xf bank_mask:0xf
	s_waitcnt lgkmcnt(0)
	s_nop 1
	v_add_f32_dpp v17, v17, v17 row_ror:4 row_mask:0xf bank_mask:0xf
	s_waitcnt lgkmcnt(0)
	s_nop 1
	v_add_f32_dpp v17, v17, v17 row_ror:2 row_mask:0xf bank_mask:0xf
	s_waitcnt lgkmcnt(0)
	s_nop 1
	v_add_f32_dpp v17, v17, v17 row_ror:1 row_mask:0xf bank_mask:0xf
	v_add_f32_e32 v17, 0x358637bd, v17
	v_mul_f32_e32 v27, 0x4b800000, v17
	v_cmp_gt_f32_e32 vcc, s2, v17
	s_nop 1
	v_cndmask_b32_e32 v17, v17, v27, vcc
	v_rsq_f32_e32 v17, v17
	s_nop 0
	v_mul_f32_e32 v27, 0x45800000, v17
	v_cndmask_b32_e32 v17, v17, v27, vcc
	v_mul_f32_e32 v82, v129, v17
	v_pk_mul_f32 v[66:67], v[66:67], v[82:83] op_sel_hi:[1,0]
	v_pk_mul_f32 v[70:71], v[70:71], v[82:83] op_sel_hi:[1,0]
	v_pk_mul_f32 v[80:81], v[80:81], v[82:83] op_sel_hi:[1,0]
	v_pk_mul_f32 v[76:77], v[76:77], v[82:83] op_sel_hi:[1,0]
; DI F8 unpack8(uint4 u) { F8 r; r.v[0] = lo16(u.x); r.v[1] = hi16(u.x); r.v[2] = lo16(u.y); r.v[3] = hi16(u.y); r.v[4] = lo16(u.z); r.v[5] = hi16(u.z); r.v[6] = lo16(u.w); r.v[7] = hi16(u.w); return r; }
; DI void stf8(float* p, const F8& f) { *(float4*)p = make_float4(f.v[0], f.v[1], f.v[2], f.v[3]); *(float4*)(p + 4) = make_float4(f.v[4], f.v[5], f.v[6], f.v[7]); }
; DI void stb8(bf16_t* p, const F8& f) { *(uint4*)p = pack8(f); }
; DI float gsum16(float v) { v += __shfl_xor(v, 8); v += __shfl_xor(v, 4); v += __shfl_xor(v, 2); v += __shfl_xor(v, 1); return v; }
; DI float siluf(float x) { return x / (1.f + __expf(-x)); }
; DI void odd_elem(const Params& p, int o) {
;     ...
;         for (int t = 0; t < 16; ++t) {
;             const F8 x0 = unpack8(xr[t]);
;             F8 acc; float ss = 0.f;
; #pragma unroll
;             for (int k = 0; k < 8; ++k) { const float a = w3.v[k] * x0.v[k] + w2.v[k] * h1.v[k] + w1.v[k] * h2.v[k] + w0.v[k] * h3.v[k]; acc.v[k] = siluf(a); ss += acc.v[k] * acc.v[k]; }
;             if (gi < 4) {
;                 const float rs = rsqrtf(gsum16(ss) + EPS) * nsc;
; #pragma unroll
;                 for (int k = 0; k < 8; ++k) acc.v[k] *= rs;
;             }
;             stb8(Q2 + (size_t)(r0 + t) * 3072 + c, acc);
;             if (last && t >= 13) {
;                 float* so = sq < 4 ? p.out + O_PDC + (((size_t)o * 4 + sq) * 3 + (t - 13)) * 3072 : p.out + O_SDC + (((size_t)o * 8 + (sq - 4)) * 3 + (t - 13)) * 3072;
;                 stf8(so + c, x0);
;             }
;             h3 = h2; h2 = h1; h1 = x0;
;         }
.LBB0_183:
	s_or_b64 exec, exec, s[40:41]
	v_or_b32_e32 v17, 7, v123
	v_mad_i64_i32 v[82:83], s[40:41], v17, s33, v[110:111]
	v_cvt_pk_bf16_f32 v88, v66, v67
	v_cvt_pk_bf16_f32 v89, v70, v71
	v_cvt_pk_bf16_f32 v90, v80, v81
	v_cvt_pk_bf16_f32 v91, v76, v77
	global_store_dwordx4 v[82:83], v[88:91], off sc1
	v_lshlrev_b32_e32 v35, 16, v60
	v_lshlrev_b32_e32 v27, 16, v61
	v_and_b32_e32 v89, 0xffff0000, v60
	v_mov_b32_e32 v88, v93
	v_pk_mul_f32 v[90:91], v[112:113], v[88:89]
	v_and_b32_e32 v81, 0xffff0000, v61
	v_lshlrev_b32_e32 v17, 16, v62
	v_and_b32_e32 v71, 0xffff0000, v62
	v_lshlrev_b32_e32 v60, 16, v63
	v_and_b32_e32 v61, 0xffff0000, v63
	v_mul_f32_e32 v62, v32, v35
	v_mul_f32_e32 v66, v28, v33
	v_pk_mul_f32 v[94:95], v[114:115], v[96:97]
	v_mov_b32_e32 v67, v90
	v_mov_b32_e32 v63, v91
	v_mul_f32_e32 v76, v24, v31
	v_pk_add_f32 v[62:63], v[66:67], v[62:63]
	v_mov_b32_e32 v77, v95
	v_mul_f32_e32 v82, v20, v29
	v_pk_add_f32 v[62:63], v[76:77], v[62:63]
	v_mov_b32_e32 v83, v94
	v_pk_add_f32 v[62:63], v[82:83], v[62:63]
	v_pk_mul_f32 v[86:87], v[118:119], v[86:87]
	v_mul_f32_e32 v29, 0xbfb8aa3b, v62
	v_exp_f32_e32 v66, v29
	v_mul_f32_e32 v29, 0xbfb8aa3b, v63
	v_exp_f32_e32 v67, v29
	v_mul_f32_e32 v82, v26, v23
	v_mov_b32_e32 v83, v87
	v_mul_f32_e32 v90, v22, v21
	v_pk_add_f32 v[66:67], v[66:67], 1.0 op_sel_hi:[1,0]
	v_mov_b32_e32 v91, v86
	v_pk_mul_f32 v[78:79], v[108:109], v[78:79]
	v_mul_f32_e32 v86, v8, v9
	v_mov_b32_e32 v87, v79
	v_rcp_f32_e32 v29, v67
	s_nop 0
	v_mul_f32_e32 v63, v63, v29
	v_mov_b32_e32 v80, v85
	v_pk_mul_f32 v[94:95], v[116:117], v[80:81]
	v_rcp_f32_e32 v29, v66
	s_nop 0
	v_mul_f32_e32 v62, v62, v29
	v_mul_f32_e32 v66, v34, v27
	v_mul_f32_e32 v76, v30, v25
	v_mov_b32_e32 v77, v94
	v_mov_b32_e32 v67, v95
	v_pk_add_f32 v[66:67], v[76:77], v[66:67]
	s_nop 0
	v_pk_add_f32 v[66:67], v[82:83], v[66:67]
	s_nop 0
	v_pk_add_f32 v[66:67], v[90:91], v[66:67]
	v_mul_f32_e32 v90, v4, v5
	v_mul_f32_e32 v21, 0xbfb8aa3b, v66
	v_exp_f32_e32 v76, v21
	v_mul_f32_e32 v21, 0xbfb8aa3b, v67
	v_exp_f32_e32 v77, v21
	v_mov_b32_e32 v91, v78
	v_pk_add_f32 v[76:77], v[76:77], 1.0 op_sel_hi:[1,0]
	s_nop 0
	v_rcp_f32_e32 v21, v77
	s_nop 0
	v_mul_f32_e32 v67, v67, v21
	v_mov_b32_e32 v70, v75
	v_pk_mul_f32 v[94:95], v[136:137], v[70:71]
	v_rcp_f32_e32 v21, v76
	s_nop 0
	v_mul_f32_e32 v66, v66, v21
	v_mul_f32_e32 v76, v16, v17
	v_mul_f32_e32 v82, v12, v13
	v_mov_b32_e32 v83, v94
	v_mov_b32_e32 v77, v95
	v_pk_add_f32 v[76:77], v[82:83], v[76:77]
	s_nop 0
	v_pk_add_f32 v[76:77], v[86:87], v[76:77]
	s_nop 0
	v_pk_add_f32 v[76:77], v[90:91], v[76:77]
	s_nop 0
	v_mul_f32_e32 v5, 0xbfb8aa3b, v76
	v_exp_f32_e32 v78, v5
	v_mul_f32_e32 v5, 0xbfb8aa3b, v77
	v_exp_f32_e32 v79, v5
	s_nop 0
	v_pk_add_f32 v[78:79], v[78:79], 1.0 op_sel_hi:[1,0]
	s_nop 0
	v_rcp_f32_e32 v5, v79
	s_nop 0
	v_mul_f32_e32 v77, v77, v5
	v_rcp_f32_e32 v5, v78
	s_nop 0
	v_mul_f32_e32 v76, v76, v5
	v_pk_mul_f32 v[78:79], v[18:19], v[60:61]
	s_nop 0
	v_pk_fma_f32 v[78:79], v[14:15], v[64:65], v[78:79]
	s_nop 0
	v_pk_fma_f32 v[78:79], v[10:11], v[68:69], v[78:79]
	s_nop 0
	v_pk_fma_f32 v[72:73], v[6:7], v[72:73], v[78:79]
	s_nop 0
	v_mul_f32_e32 v5, 0xbfb8aa3b, v72
	v_exp_f32_e32 v78, v5
	v_mul_f32_e32 v5, 0xbfb8aa3b, v73
	v_exp_f32_e32 v79, v5
	s_nop 0
	v_pk_add_f32 v[78:79], v[78:79], 1.0 op_sel_hi:[1,0]
	s_nop 0
	v_rcp_f32_e32 v5, v79
	s_nop 0
	v_mul_f32_e32 v73, v73, v5
	v_rcp_f32_e32 v5, v78
	s_nop 0
	v_mul_f32_e32 v72, v72, v5
	s_and_saveexec_b64 s[40:41], s[36:37]
	s_cbranch_execz .LBB0_185
	v_pk_mul_f32 v[78:79], v[62:63], v[62:63]
	v_pk_mul_f32 v[82:83], v[66:67], v[66:67]
	v_add_f32_e32 v5, v78, v79
	v_add_f32_e32 v5, v5, v82
	v_pk_mul_f32 v[86:87], v[76:77], v[76:77]
	v_add_f32_e32 v5, v5, v83
	v_and_b32_e32 v29, 64, v251
	v_add_f32_e32 v5, v5, v86
	v_add_u32_e32 v29, 64, v29
	v_pk_mul_f32 v[90:91], v[72:73], v[72:73]
	v_add_f32_e32 v5, v5, v87
	v_add_f32_e32 v5, v5, v90
	v_add_f32_e32 v5, v5, v91
	s_waitcnt lgkmcnt(0)
	s_nop 1
	v_add_f32_dpp v5, v5, v5 row_ror:8 row_mask:0xf bank_mask:0xf
	s_waitcnt lgkmcnt(0)
	s_nop 1
	v_add_f32_dpp v5, v5, v5 row_ror:4 row_mask:0xf bank_mask:0xf
	s_waitcnt lgkmcnt(0)
	s_nop 1
	v_add_f32_dpp v5, v5, v5 row_ror:2 row_mask:0xf bank_mask:0xf
	s_waitcnt lgkmcnt(0)
	s_nop 1
	v_add_f32_dpp v5, v5, v5 row_ror:1 row_mask:0xf bank_mask:0xf
	v_add_f32_e32 v5, 0x358637bd, v5
	v_mul_f32_e32 v21, 0x4b800000, v5
	v_cmp_gt_f32_e32 vcc, s2, v5
	s_nop 1
	v_cndmask_b32_e32 v5, v5, v21, vcc
	v_rsq_f32_e32 v5, v5
	s_nop 0
	v_mul_f32_e32 v21, 0x45800000, v5
	v_cndmask_b32_e32 v5, v5, v21, vcc
	v_mul_f32_e32 v78, v129, v5
	v_pk_mul_f32 v[62:63], v[62:63], v[78:79] op_sel_hi:[1,0]
	v_pk_mul_f32 v[66:67], v[66:67], v[78:79] op_sel_hi:[1,0]
	v_pk_mul_f32 v[76:77], v[76:77], v[78:79] op_sel_hi:[1,0]
	v_pk_mul_f32 v[72:73], v[72:73], v[78:79] op_sel_hi:[1,0]
; DI F8 unpack8(uint4 u) { F8 r; r.v[0] = lo16(u.x); r.v[1] = hi16(u.x); r.v[2] = lo16(u.y); r.v[3] = hi16(u.y); r.v[4] = lo16(u.z); r.v[5] = hi16(u.z); r.v[6] = lo16(u.w); r.v[7] = hi16(u.w); return r; }
; DI void stf8(float* p, const F8& f) { *(float4*)p = make_float4(f.v[0], f.v[1], f.v[2], f.v[3]); *(float4*)(p + 4) = make_float4(f.v[4], f.v[5], f.v[6], f.v[7]); }
; DI void stb8(bf16_t* p, const F8& f) { *(uint4*)p = pack8(f); }
; DI float gsum16(float v) { v += __shfl_xor(v, 8); v += __shfl_xor(v, 4); v += __shfl_xor(v, 2); v += __shfl_xor(v, 1); return v; }
; DI float siluf(float x) { return x / (1.f + __expf(-x)); }
; DI void odd_elem(const Params& p, int o) {
;     ...
;         for (int t = 0; t < 16; ++t) {
;             const F8 x0 = unpack8(xr[t]);
;             F8 acc; float ss = 0.f;
; #pragma unroll
;             for (int k = 0; k < 8; ++k) { const float a = w3.v[k] * x0.v[k] + w2.v[k] * h1.v[k] + w1.v[k] * h2.v[k] + w0.v[k] * h3.v[k]; acc.v[k] = siluf(a); ss += acc.v[k] * acc.v[k]; }
;             if (gi < 4) {
;                 const float rs = rsqrtf(gsum16(ss) + EPS) * nsc;
; #pragma unroll
;                 for (int k = 0; k < 8; ++k) acc.v[k] *= rs;
;             }
;             stb8(Q2 + (size_t)(r0 + t) * 3072 + c, acc);
;             if (last && t >= 13) {
;                 float* so = sq < 4 ? p.out + O_PDC + (((size_t)o * 4 + sq) * 3 + (t - 13)) * 3072 : p.out + O_SDC + (((size_t)o * 8 + (sq - 4)) * 3 + (t - 13)) * 3072;
;                 stf8(so + c, x0);
;             }
;             h3 = h2; h2 = h1; h1 = x0;
;         }
.LBB0_185:
	s_or_b64 exec, exec, s[40:41]
	v_and_b32_e32 v83, 0xffff0000, v56
	v_mov_b32_e32 v82, v89
	v_lshlrev_b32_e32 v86, 16, v56
	v_pk_mul_f32 v[90:91], v[112:113], v[82:83]
	v_or_b32_e32 v5, 8, v123
	v_cvt_pk_bf16_f32 v94, v62, v63
	v_cvt_pk_bf16_f32 v95, v66, v67
	v_cvt_pk_bf16_f32 v96, v76, v77
	v_lshlrev_b32_e32 v29, 16, v57
	v_and_b32_e32 v77, 0xffff0000, v57
	v_lshlrev_b32_e32 v21, 16, v58
	v_and_b32_e32 v67, 0xffff0000, v58
	v_lshlrev_b32_e32 v56, 16, v59
	v_and_b32_e32 v57, 0xffff0000, v59
	v_mul_f32_e32 v58, v32, v86
	v_mul_f32_e32 v62, v28, v35
	v_pk_mul_f32 v[92:93], v[114:115], v[92:93]
	v_mov_b32_e32 v63, v90
	v_mov_b32_e32 v59, v91
	v_mad_i64_i32 v[78:79], s[40:41], v5, s33, v[110:111]
	v_cvt_pk_bf16_f32 v97, v72, v73
	v_mul_f32_e32 v72, v24, v33
	v_pk_add_f32 v[58:59], v[62:63], v[58:59]
	v_mov_b32_e32 v73, v93
	global_store_dwordx4 v[78:79], v[94:97], off sc1
	v_mul_f32_e32 v78, v20, v31
	v_pk_add_f32 v[58:59], v[72:73], v[58:59]
	v_mov_b32_e32 v79, v92
	v_pk_add_f32 v[58:59], v[78:79], v[58:59]
	v_mov_b32_e32 v76, v81
	v_mul_f32_e32 v5, 0xbfb8aa3b, v58
	v_exp_f32_e32 v62, v5
	v_mul_f32_e32 v5, 0xbfb8aa3b, v59
	v_exp_f32_e32 v63, v5
	v_pk_mul_f32 v[92:93], v[116:117], v[76:77]
	v_pk_mul_f32 v[84:85], v[118:119], v[84:85]
	v_mul_f32_e32 v78, v26, v25
	v_pk_add_f32 v[62:63], v[62:63], 1.0 op_sel_hi:[1,0]
	v_mov_b32_e32 v79, v85
	v_mul_f32_e32 v90, v22, v23
	v_mov_b32_e32 v91, v84
	v_pk_mul_f32 v[74:75], v[108:109], v[74:75]
	v_rcp_f32_e32 v5, v63
	s_nop 0
	v_mul_f32_e32 v59, v59, v5
	v_mov_b32_e32 v73, v92
	v_mul_f32_e32 v84, v8, v13
	v_mov_b32_e32 v85, v75
	v_rcp_f32_e32 v5, v62
	s_nop 0
	v_mul_f32_e32 v58, v58, v5
	v_mul_f32_e32 v62, v34, v29
	v_mul_f32_e32 v72, v30, v27
	v_mov_b32_e32 v63, v93
	v_pk_add_f32 v[62:63], v[72:73], v[62:63]
	s_nop 0
	v_pk_add_f32 v[62:63], v[78:79], v[62:63]
	s_nop 0
	v_pk_add_f32 v[62:63], v[90:91], v[62:63]
	v_mul_f32_e32 v90, v4, v9
	v_mul_f32_e32 v5, 0xbfb8aa3b, v62
	v_exp_f32_e32 v72, v5
	v_mul_f32_e32 v5, 0xbfb8aa3b, v63
	v_exp_f32_e32 v73, v5
	v_mov_b32_e32 v91, v74
	v_pk_add_f32 v[72:73], v[72:73], 1.0 op_sel_hi:[1,0]
	s_nop 0
	v_rcp_f32_e32 v5, v73
	s_nop 0
	v_mul_f32_e32 v63, v63, v5
	v_mul_f32_e32 v78, v12, v17
	v_mov_b32_e32 v66, v71
	v_pk_mul_f32 v[92:93], v[136:137], v[66:67]
	v_rcp_f32_e32 v5, v72
	s_nop 0
	v_mul_f32_e32 v62, v62, v5
	v_mul_f32_e32 v72, v16, v21
	v_mov_b32_e32 v79, v92
	v_mov_b32_e32 v73, v93
	v_pk_add_f32 v[72:73], v[78:79], v[72:73]
	s_nop 0
	v_pk_add_f32 v[72:73], v[84:85], v[72:73]
	s_nop 0
	v_pk_add_f32 v[72:73], v[90:91], v[72:73]
	s_nop 0
	v_mul_f32_e32 v5, 0xbfb8aa3b, v72
	v_exp_f32_e32 v74, v5
	v_mul_f32_e32 v5, 0xbfb8aa3b, v73
	v_exp_f32_e32 v75, v5
	s_nop 0
	v_pk_add_f32 v[74:75], v[74:75], 1.0 op_sel_hi:[1,0]
	s_nop 0
	v_rcp_f32_e32 v5, v75
	s_nop 0
	v_mul_f32_e32 v73, v73, v5
	v_rcp_f32_e32 v5, v74
	s_nop 0
	v_mul_f32_e32 v72, v72, v5
	v_pk_mul_f32 v[74:75], v[18:19], v[56:57]
	s_nop 0
	v_pk_fma_f32 v[74:75], v[14:15], v[60:61], v[74:75]
	s_nop 0
	v_pk_fma_f32 v[74:75], v[10:11], v[64:65], v[74:75]
	s_nop 0
	v_pk_fma_f32 v[68:69], v[6:7], v[68:69], v[74:75]
	s_nop 0
	v_mul_f32_e32 v5, 0xbfb8aa3b, v68
	v_exp_f32_e32 v74, v5
	v_mul_f32_e32 v5, 0xbfb8aa3b, v69
	v_exp_f32_e32 v75, v5
	s_nop 0
	v_pk_add_f32 v[74:75], v[74:75], 1.0 op_sel_hi:[1,0]
	s_nop 0
	v_rcp_f32_e32 v5, v75
	s_nop 0
	v_mul_f32_e32 v69, v69, v5
	v_rcp_f32_e32 v5, v74
	s_nop 0
	v_mul_f32_e32 v68, v68, v5
	s_and_saveexec_b64 s[40:41], s[36:37]
	s_cbranch_execz .LBB0_187
	v_pk_mul_f32 v[74:75], v[58:59], v[58:59]
	v_pk_mul_f32 v[78:79], v[62:63], v[62:63]
	v_add_f32_e32 v5, v74, v75
	v_add_f32_e32 v5, v5, v78
	v_pk_mul_f32 v[84:85], v[72:73], v[72:73]
	v_add_f32_e32 v5, v5, v79
	v_and_b32_e32 v23, 64, v251
	v_add_f32_e32 v5, v5, v84
	v_add_u32_e32 v23, 64, v23
	v_pk_mul_f32 v[90:91], v[68:69], v[68:69]
	v_add_f32_e32 v5, v5, v85
	v_add_f32_e32 v5, v5, v90
	v_add_f32_e32 v5, v5, v91
	s_waitcnt lgkmcnt(0)
	s_nop 1
	v_add_f32_dpp v5, v5, v5 row_ror:8 row_mask:0xf bank_mask:0xf
	s_waitcnt lgkmcnt(0)
	s_nop 1
	v_add_f32_dpp v5, v5, v5 row_ror:4 row_mask:0xf bank_mask:0xf
	s_waitcnt lgkmcnt(0)
	s_nop 1
	v_add_f32_dpp v5, v5, v5 row_ror:2 row_mask:0xf bank_mask:0xf
	s_waitcnt lgkmcnt(0)
	s_nop 1
	v_add_f32_dpp v5, v5, v5 row_ror:1 row_mask:0xf bank_mask:0xf
	v_add_f32_e32 v5, 0x358637bd, v5
	v_mul_f32_e32 v9, 0x4b800000, v5
	v_cmp_gt_f32_e32 vcc, s2, v5
	s_nop 1
	v_cndmask_b32_e32 v5, v5, v9, vcc
	v_rsq_f32_e32 v5, v5
	s_nop 0
	v_mul_f32_e32 v9, 0x45800000, v5
	v_cndmask_b32_e32 v5, v5, v9, vcc
	v_mul_f32_e32 v74, v129, v5
	v_pk_mul_f32 v[58:59], v[58:59], v[74:75] op_sel_hi:[1,0]
	v_pk_mul_f32 v[62:63], v[62:63], v[74:75] op_sel_hi:[1,0]
	v_pk_mul_f32 v[72:73], v[72:73], v[74:75] op_sel_hi:[1,0]
	v_pk_mul_f32 v[68:69], v[68:69], v[74:75] op_sel_hi:[1,0]
; DI F8 unpack8(uint4 u) { F8 r; r.v[0] = lo16(u.x); r.v[1] = hi16(u.x); r.v[2] = lo16(u.y); r.v[3] = hi16(u.y); r.v[4] = lo16(u.z); r.v[5] = hi16(u.z); r.v[6] = lo16(u.w); r.v[7] = hi16(u.w); return r; }
; DI void stf8(float* p, const F8& f) { *(float4*)p = make_float4(f.v[0], f.v[1], f.v[2], f.v[3]); *(float4*)(p + 4) = make_float4(f.v[4], f.v[5], f.v[6], f.v[7]); }
; DI void stb8(bf16_t* p, const F8& f) { *(uint4*)p = pack8(f); }
; DI float gsum16(float v) { v += __shfl_xor(v, 8); v += __shfl_xor(v, 4); v += __shfl_xor(v, 2); v += __shfl_xor(v, 1); return v; }
; DI float siluf(float x) { return x / (1.f + __expf(-x)); }
; DI void odd_elem(const Params& p, int o) {
;     ...
;         for (int t = 0; t < 16; ++t) {
;             const F8 x0 = unpack8(xr[t]);
;             F8 acc; float ss = 0.f;
; #pragma unroll
;             for (int k = 0; k < 8; ++k) { const float a = w3.v[k] * x0.v[k] + w2.v[k] * h1.v[k] + w1.v[k] * h2.v[k] + w0.v[k] * h3.v[k]; acc.v[k] = siluf(a); ss += acc.v[k] * acc.v[k]; }
;             if (gi < 4) {
;                 const float rs = rsqrtf(gsum16(ss) + EPS) * nsc;
; #pragma unroll
;                 for (int k = 0; k < 8; ++k) acc.v[k] *= rs;
;             }
;             stb8(Q2 + (size_t)(r0 + t) * 3072 + c, acc);
;             if (last && t >= 13) {
;                 float* so = sq < 4 ? p.out + O_PDC + (((size_t)o * 4 + sq) * 3 + (t - 13)) * 3072 : p.out + O_SDC + (((size_t)o * 8 + (sq - 4)) * 3 + (t - 13)) * 3072;
;                 stf8(so + c, x0);
;             }
;             h3 = h2; h2 = h1; h1 = x0;
;         }
.LBB0_187:
	s_or_b64 exec, exec, s[40:41]
	v_or_b32_e32 v5, 9, v123
	v_mad_i64_i32 v[74:75], s[40:41], v5, s33, v[110:111]
	v_cvt_pk_bf16_f32 v90, v58, v59
	v_cvt_pk_bf16_f32 v91, v62, v63
	v_cvt_pk_bf16_f32 v92, v72, v73
	v_cvt_pk_bf16_f32 v93, v68, v69
	v_and_b32_e32 v79, 0xffff0000, v52
	v_mov_b32_e32 v78, v83
	global_store_dwordx4 v[74:75], v[90:93], off sc1
	v_lshlrev_b32_e32 v84, 16, v52
	v_lshlrev_b32_e32 v31, 16, v53
	v_pk_mul_f32 v[90:91], v[112:113], v[78:79]
	v_and_b32_e32 v73, 0xffff0000, v53
	v_mul_f32_e32 v52, v32, v84
	v_mul_f32_e32 v58, v28, v86
	v_pk_mul_f32 v[88:89], v[114:115], v[88:89]
	v_mov_b32_e32 v59, v90
	v_mov_b32_e32 v53, v91
	v_mul_f32_e32 v68, v24, v35
	v_pk_add_f32 v[52:53], v[58:59], v[52:53]
	v_mov_b32_e32 v69, v89
	v_mul_f32_e32 v74, v20, v33
	v_pk_add_f32 v[52:53], v[68:69], v[52:53]
	v_mov_b32_e32 v75, v88
	v_pk_add_f32 v[52:53], v[74:75], v[52:53]
	v_mov_b32_e32 v72, v77
	v_mul_f32_e32 v5, 0xbfb8aa3b, v52
	v_exp_f32_e32 v58, v5
	v_mul_f32_e32 v5, 0xbfb8aa3b, v53
	v_exp_f32_e32 v59, v5
	v_pk_mul_f32 v[90:91], v[116:117], v[72:73]
	v_pk_mul_f32 v[80:81], v[118:119], v[80:81]
	v_mov_b32_e32 v69, v90
	v_pk_add_f32 v[58:59], v[58:59], 1.0 op_sel_hi:[1,0]
	v_mul_f32_e32 v74, v26, v27
	v_mov_b32_e32 v75, v81
	v_mul_f32_e32 v88, v22, v25
	v_mov_b32_e32 v89, v80
	v_rcp_f32_e32 v5, v59
	s_nop 0
	v_mul_f32_e32 v53, v53, v5
	v_mul_f32_e32 v68, v30, v29
	v_and_b32_e32 v63, 0xffff0000, v54
	v_lshlrev_b32_e32 v23, 16, v54
	v_rcp_f32_e32 v5, v58
	s_nop 0
	v_mul_f32_e32 v52, v52, v5
	v_mul_f32_e32 v58, v34, v31
	v_mov_b32_e32 v59, v91
	v_pk_add_f32 v[58:59], v[68:69], v[58:59]
	v_pk_mul_f32 v[70:71], v[108:109], v[70:71]
	v_pk_add_f32 v[58:59], v[74:75], v[58:59]
	v_mul_f32_e32 v74, v12, v21
	v_pk_add_f32 v[58:59], v[88:89], v[58:59]
	v_mul_f32_e32 v80, v8, v17
	v_mul_f32_e32 v5, 0xbfb8aa3b, v58
	v_exp_f32_e32 v68, v5
	v_mul_f32_e32 v5, 0xbfb8aa3b, v59
	v_exp_f32_e32 v69, v5
	v_mov_b32_e32 v81, v71
	v_mul_f32_e32 v88, v4, v13
	v_mov_b32_e32 v89, v70
	v_pk_add_f32 v[68:69], v[68:69], 1.0 op_sel_hi:[1,0]
	v_lshlrev_b32_e32 v54, 16, v55
	v_and_b32_e32 v55, 0xffff0000, v55
	v_rcp_f32_e32 v5, v69
	s_nop 0
	v_mul_f32_e32 v59, v59, v5
	v_mov_b32_e32 v62, v67
	v_pk_mul_f32 v[90:91], v[136:137], v[62:63]
	v_rcp_f32_e32 v5, v68
	s_nop 0
	v_mul_f32_e32 v58, v58, v5
	v_mul_f32_e32 v68, v16, v23
	v_mov_b32_e32 v75, v90
	v_mov_b32_e32 v69, v91
	v_pk_add_f32 v[68:69], v[74:75], v[68:69]
	s_nop 0
	v_pk_add_f32 v[68:69], v[80:81], v[68:69]
	s_nop 0
	v_pk_add_f32 v[68:69], v[88:89], v[68:69]
	s_nop 0
	v_mul_f32_e32 v5, 0xbfb8aa3b, v68
	v_exp_f32_e32 v70, v5
	v_mul_f32_e32 v5, 0xbfb8aa3b, v69
	v_exp_f32_e32 v71, v5
	s_nop 0
	v_pk_add_f32 v[70:71], v[70:71], 1.0 op_sel_hi:[1,0]
	s_nop 0
	v_rcp_f32_e32 v5, v71
	s_nop 0
	v_mul_f32_e32 v69, v69, v5
	v_rcp_f32_e32 v5, v70
	s_nop 0
	v_mul_f32_e32 v68, v68, v5
	v_pk_mul_f32 v[70:71], v[18:19], v[54:55]
	s_nop 0
	v_pk_fma_f32 v[70:71], v[14:15], v[56:57], v[70:71]
	s_nop 0
	v_pk_fma_f32 v[70:71], v[10:11], v[60:61], v[70:71]
	s_nop 0
	v_pk_fma_f32 v[64:65], v[6:7], v[64:65], v[70:71]
	s_nop 0
	v_mul_f32_e32 v5, 0xbfb8aa3b, v64
	v_exp_f32_e32 v70, v5
	v_mul_f32_e32 v5, 0xbfb8aa3b, v65
	v_exp_f32_e32 v71, v5
	s_nop 0
	v_pk_add_f32 v[70:71], v[70:71], 1.0 op_sel_hi:[1,0]
	s_nop 0
	v_rcp_f32_e32 v5, v71
	s_nop 0
	v_mul_f32_e32 v65, v65, v5
	v_rcp_f32_e32 v5, v70
	s_nop 0
	v_mul_f32_e32 v64, v64, v5
	s_and_saveexec_b64 s[40:41], s[36:37]
	s_cbranch_execz .LBB0_189
	v_pk_mul_f32 v[70:71], v[52:53], v[52:53]
	v_pk_mul_f32 v[74:75], v[58:59], v[58:59]
	v_add_f32_e32 v5, v70, v71
	v_add_f32_e32 v5, v5, v74
	v_pk_mul_f32 v[80:81], v[68:69], v[68:69]
	v_add_f32_e32 v5, v5, v75
	v_and_b32_e32 v13, 64, v251
	v_add_f32_e32 v5, v5, v80
	v_add_u32_e32 v13, 64, v13
	v_pk_mul_f32 v[88:89], v[64:65], v[64:65]
	v_add_f32_e32 v5, v5, v81
	v_add_f32_e32 v5, v5, v88
	v_add_f32_e32 v5, v5, v89
	s_waitcnt lgkmcnt(0)
	s_nop 1
	v_add_f32_dpp v5, v5, v5 row_ror:8 row_mask:0xf bank_mask:0xf
	s_waitcnt lgkmcnt(0)
	s_nop 1
	v_add_f32_dpp v5, v5, v5 row_ror:4 row_mask:0xf bank_mask:0xf
	s_waitcnt lgkmcnt(0)
	s_nop 1
	v_add_f32_dpp v5, v5, v5 row_ror:2 row_mask:0xf bank_mask:0xf
	s_waitcnt lgkmcnt(0)
	s_nop 1
	v_add_f32_dpp v5, v5, v5 row_ror:1 row_mask:0xf bank_mask:0xf
	v_add_f32_e32 v5, 0x358637bd, v5
	v_mul_f32_e32 v9, 0x4b800000, v5
	v_cmp_gt_f32_e32 vcc, s2, v5
	s_nop 1
	v_cndmask_b32_e32 v5, v5, v9, vcc
	v_rsq_f32_e32 v5, v5
	s_nop 0
	v_mul_f32_e32 v9, 0x45800000, v5
	v_cndmask_b32_e32 v5, v5, v9, vcc
	v_mul_f32_e32 v70, v129, v5
	v_pk_mul_f32 v[52:53], v[52:53], v[70:71] op_sel_hi:[1,0]
	v_pk_mul_f32 v[58:59], v[58:59], v[70:71] op_sel_hi:[1,0]
	v_pk_mul_f32 v[68:69], v[68:69], v[70:71] op_sel_hi:[1,0]
	v_pk_mul_f32 v[64:65], v[64:65], v[70:71] op_sel_hi:[1,0]
; DI F8 unpack8(uint4 u) { F8 r; r.v[0] = lo16(u.x); r.v[1] = hi16(u.x); r.v[2] = lo16(u.y); r.v[3] = hi16(u.y); r.v[4] = lo16(u.z); r.v[5] = hi16(u.z); r.v[6] = lo16(u.w); r.v[7] = hi16(u.w); return r; }
; DI void stf8(float* p, const F8& f) { *(float4*)p = make_float4(f.v[0], f.v[1], f.v[2], f.v[3]); *(float4*)(p + 4) = make_float4(f.v[4], f.v[5], f.v[6], f.v[7]); }
; DI void stb8(bf16_t* p, const F8& f) { *(uint4*)p = pack8(f); }
; DI float gsum16(float v) { v += __shfl_xor(v, 8); v += __shfl_xor(v, 4); v += __shfl_xor(v, 2); v += __shfl_xor(v, 1); return v; }
; DI float siluf(float x) { return x / (1.f + __expf(-x)); }
; DI void odd_elem(const Params& p, int o) {
;     ...
;         for (int t = 0; t < 16; ++t) {
;             const F8 x0 = unpack8(xr[t]);
;             F8 acc; float ss = 0.f;
; #pragma unroll
;             for (int k = 0; k < 8; ++k) { const float a = w3.v[k] * x0.v[k] + w2.v[k] * h1.v[k] + w1.v[k] * h2.v[k] + w0.v[k] * h3.v[k]; acc.v[k] = siluf(a); ss += acc.v[k] * acc.v[k]; }
;             if (gi < 4) {
;                 const float rs = rsqrtf(gsum16(ss) + EPS) * nsc;
; #pragma unroll
;                 for (int k = 0; k < 8; ++k) acc.v[k] *= rs;
;             }
;             stb8(Q2 + (size_t)(r0 + t) * 3072 + c, acc);
;             if (last && t >= 13) {
;                 float* so = sq < 4 ? p.out + O_PDC + (((size_t)o * 4 + sq) * 3 + (t - 13)) * 3072 : p.out + O_SDC + (((size_t)o * 8 + (sq - 4)) * 3 + (t - 13)) * 3072;
;                 stf8(so + c, x0);
;             }
;             h3 = h2; h2 = h1; h1 = x0;
;         }
.LBB0_189:
	s_or_b64 exec, exec, s[40:41]
	v_and_b32_e32 v75, 0xffff0000, v48
	v_mov_b32_e32 v74, v79
	v_or_b32_e32 v5, 10, v123
	v_lshlrev_b32_e32 v33, 16, v48
	v_pk_mul_f32 v[80:81], v[112:113], v[74:75]
	v_mad_i64_i32 v[70:71], s[40:41], v5, s33, v[110:111]
	v_cvt_pk_bf16_f32 v88, v52, v53
	v_cvt_pk_bf16_f32 v89, v58, v59
	v_cvt_pk_bf16_f32 v90, v68, v69
	v_lshlrev_b32_e32 v25, 16, v49
	v_and_b32_e32 v69, 0xffff0000, v49
	v_lshlrev_b32_e32 v5, 16, v50
	v_and_b32_e32 v49, 0xffff0000, v50
	v_lshlrev_b32_e32 v52, 16, v51
	v_and_b32_e32 v53, 0xffff0000, v51
	v_mul_f32_e32 v50, v32, v33
	v_mul_f32_e32 v58, v28, v84
	v_pk_mul_f32 v[82:83], v[114:115], v[82:83]
	v_mov_b32_e32 v59, v80
	v_mov_b32_e32 v51, v81
	v_cvt_pk_bf16_f32 v91, v64, v65
	v_mul_f32_e32 v64, v24, v86
	v_pk_add_f32 v[50:51], v[58:59], v[50:51]
	v_mov_b32_e32 v65, v83
	global_store_dwordx4 v[70:71], v[88:91], off sc1
	v_mul_f32_e32 v70, v20, v35
	v_pk_add_f32 v[50:51], v[64:65], v[50:51]
	v_mov_b32_e32 v71, v82
	v_pk_add_f32 v[50:51], v[70:71], v[50:51]
	v_mov_b32_e32 v68, v73
	v_mul_f32_e32 v9, 0xbfb8aa3b, v50
	v_exp_f32_e32 v58, v9
	v_mul_f32_e32 v9, 0xbfb8aa3b, v51
	v_exp_f32_e32 v59, v9
	v_pk_mul_f32 v[82:83], v[116:117], v[68:69]
	v_pk_mul_f32 v[76:77], v[118:119], v[76:77]
	v_mov_b32_e32 v65, v82
	v_pk_add_f32 v[58:59], v[58:59], 1.0 op_sel_hi:[1,0]
	v_mul_f32_e32 v70, v26, v29
	v_mov_b32_e32 v71, v77
	v_mul_f32_e32 v80, v22, v27
	v_mov_b32_e32 v81, v76
	v_rcp_f32_e32 v9, v59
	s_nop 0
	v_mul_f32_e32 v51, v51, v9
	v_mul_f32_e32 v64, v30, v31
	v_pk_mul_f32 v[66:67], v[108:109], v[66:67]
	v_mul_f32_e32 v76, v8, v21
	v_rcp_f32_e32 v9, v58
	s_nop 0
	v_mul_f32_e32 v50, v50, v9
	v_mul_f32_e32 v58, v34, v25
	v_mov_b32_e32 v59, v83
	v_pk_add_f32 v[58:59], v[64:65], v[58:59]
	v_mov_b32_e32 v77, v67
	v_pk_add_f32 v[58:59], v[70:71], v[58:59]
	v_mul_f32_e32 v70, v12, v23
	v_pk_add_f32 v[58:59], v[80:81], v[58:59]
	v_mul_f32_e32 v80, v4, v17
	v_mul_f32_e32 v9, 0xbfb8aa3b, v58
	v_exp_f32_e32 v64, v9
	v_mul_f32_e32 v9, 0xbfb8aa3b, v59
	v_exp_f32_e32 v65, v9
	v_mov_b32_e32 v81, v66
	v_pk_add_f32 v[64:65], v[64:65], 1.0 op_sel_hi:[1,0]
	s_nop 0
	v_rcp_f32_e32 v9, v65
	s_nop 0
	v_mul_f32_e32 v59, v59, v9
	v_mov_b32_e32 v48, v63
	v_pk_mul_f32 v[82:83], v[136:137], v[48:49]
	v_rcp_f32_e32 v9, v64
	s_nop 0
	v_mul_f32_e32 v58, v58, v9
	v_mul_f32_e32 v64, v16, v5
	v_mov_b32_e32 v71, v82
	v_mov_b32_e32 v65, v83
	v_pk_add_f32 v[64:65], v[70:71], v[64:65]
	s_nop 0
	v_pk_add_f32 v[64:65], v[76:77], v[64:65]
	s_nop 0
	v_pk_add_f32 v[64:65], v[80:81], v[64:65]
	s_nop 0
	v_mul_f32_e32 v9, 0xbfb8aa3b, v64
	v_exp_f32_e32 v66, v9
	v_mul_f32_e32 v9, 0xbfb8aa3b, v65
	v_exp_f32_e32 v67, v9
	s_nop 0
	v_pk_add_f32 v[66:67], v[66:67], 1.0 op_sel_hi:[1,0]
	s_nop 0
	v_rcp_f32_e32 v9, v67
	s_nop 0
	v_mul_f32_e32 v65, v65, v9
	v_rcp_f32_e32 v9, v66
	s_nop 0
	v_mul_f32_e32 v64, v64, v9
	v_pk_mul_f32 v[66:67], v[18:19], v[52:53]
	s_nop 0
	v_pk_fma_f32 v[66:67], v[14:15], v[54:55], v[66:67]
	s_nop 0
	v_pk_fma_f32 v[66:67], v[10:11], v[56:57], v[66:67]
	s_nop 0
	v_pk_fma_f32 v[60:61], v[6:7], v[60:61], v[66:67]
	s_nop 0
	v_mul_f32_e32 v9, 0xbfb8aa3b, v60
	v_exp_f32_e32 v66, v9
	v_mul_f32_e32 v9, 0xbfb8aa3b, v61
	v_exp_f32_e32 v67, v9
	s_nop 0
	v_pk_add_f32 v[66:67], v[66:67], 1.0 op_sel_hi:[1,0]
	s_nop 0
	v_rcp_f32_e32 v9, v67
	s_nop 0
	v_mul_f32_e32 v61, v61, v9
	v_rcp_f32_e32 v9, v66
	s_nop 0
	v_mul_f32_e32 v60, v60, v9
	s_and_saveexec_b64 s[40:41], s[36:37]
	s_cbranch_execz .LBB0_191
	v_pk_mul_f32 v[66:67], v[50:51], v[50:51]
	v_pk_mul_f32 v[70:71], v[58:59], v[58:59]
	v_add_f32_e32 v9, v66, v67
	v_add_f32_e32 v9, v9, v70
	v_pk_mul_f32 v[76:77], v[64:65], v[64:65]
	v_add_f32_e32 v9, v9, v71
	v_and_b32_e32 v17, 64, v251
	v_add_f32_e32 v9, v9, v76
	v_add_u32_e32 v17, 64, v17
	v_pk_mul_f32 v[80:81], v[60:61], v[60:61]
	v_add_f32_e32 v9, v9, v77
	v_add_f32_e32 v9, v9, v80
	v_add_f32_e32 v9, v9, v81
	s_waitcnt lgkmcnt(0)
	s_nop 1
	v_add_f32_dpp v9, v9, v9 row_ror:8 row_mask:0xf bank_mask:0xf
	s_waitcnt lgkmcnt(0)
	s_nop 1
	v_add_f32_dpp v9, v9, v9 row_ror:4 row_mask:0xf bank_mask:0xf
	s_waitcnt lgkmcnt(0)
	s_nop 1
	v_add_f32_dpp v9, v9, v9 row_ror:2 row_mask:0xf bank_mask:0xf
	s_waitcnt lgkmcnt(0)
	s_nop 1
	v_add_f32_dpp v9, v9, v9 row_ror:1 row_mask:0xf bank_mask:0xf
	v_add_f32_e32 v9, 0x358637bd, v9
	v_mul_f32_e32 v13, 0x4b800000, v9
	v_cmp_gt_f32_e32 vcc, s2, v9
	s_nop 1
	v_cndmask_b32_e32 v9, v9, v13, vcc
	v_rsq_f32_e32 v9, v9
	s_nop 0
	v_mul_f32_e32 v13, 0x45800000, v9
	v_cndmask_b32_e32 v9, v9, v13, vcc
	v_mul_f32_e32 v66, v129, v9
	v_pk_mul_f32 v[50:51], v[50:51], v[66:67] op_sel_hi:[1,0]
	v_pk_mul_f32 v[58:59], v[58:59], v[66:67] op_sel_hi:[1,0]
	v_pk_mul_f32 v[64:65], v[64:65], v[66:67] op_sel_hi:[1,0]
	v_pk_mul_f32 v[60:61], v[60:61], v[66:67] op_sel_hi:[1,0]
; DI F8 unpack8(uint4 u) { F8 r; r.v[0] = lo16(u.x); r.v[1] = hi16(u.x); r.v[2] = lo16(u.y); r.v[3] = hi16(u.y); r.v[4] = lo16(u.z); r.v[5] = hi16(u.z); r.v[6] = lo16(u.w); r.v[7] = hi16(u.w); return r; }
; DI void stf8(float* p, const F8& f) { *(float4*)p = make_float4(f.v[0], f.v[1], f.v[2], f.v[3]); *(float4*)(p + 4) = make_float4(f.v[4], f.v[5], f.v[6], f.v[7]); }
; DI void stb8(bf16_t* p, const F8& f) { *(uint4*)p = pack8(f); }
; DI float gsum16(float v) { v += __shfl_xor(v, 8); v += __shfl_xor(v, 4); v += __shfl_xor(v, 2); v += __shfl_xor(v, 1); return v; }
; DI float siluf(float x) { return x / (1.f + __expf(-x)); }
; DI void odd_elem(const Params& p, int o) {
;     ...
;         for (int t = 0; t < 16; ++t) {
;             const F8 x0 = unpack8(xr[t]);
;             F8 acc; float ss = 0.f;
; #pragma unroll
;             for (int k = 0; k < 8; ++k) { const float a = w3.v[k] * x0.v[k] + w2.v[k] * h1.v[k] + w1.v[k] * h2.v[k] + w0.v[k] * h3.v[k]; acc.v[k] = siluf(a); ss += acc.v[k] * acc.v[k]; }
;             if (gi < 4) {
;                 const float rs = rsqrtf(gsum16(ss) + EPS) * nsc;
; #pragma unroll
;                 for (int k = 0; k < 8; ++k) acc.v[k] *= rs;
;             }
;             stb8(Q2 + (size_t)(r0 + t) * 3072 + c, acc);
;             if (last && t >= 13) {
;                 float* so = sq < 4 ? p.out + O_PDC + (((size_t)o * 4 + sq) * 3 + (t - 13)) * 3072 : p.out + O_SDC + (((size_t)o * 8 + (sq - 4)) * 3 + (t - 13)) * 3072;
;                 stf8(so + c, x0);
;             }
;             h3 = h2; h2 = h1; h1 = x0;
;         }
.LBB0_191:
	s_or_b64 exec, exec, s[40:41]
	v_or_b32_e32 v9, 11, v123
	v_and_b32_e32 v71, 0xffff0000, v44
	v_mov_b32_e32 v70, v75
	v_mad_i64_i32 v[66:67], s[40:41], v9, s33, v[110:111]
	v_cvt_pk_bf16_f32 v80, v50, v51
	v_cvt_pk_bf16_f32 v81, v58, v59
	v_cvt_pk_bf16_f32 v82, v64, v65
	v_cvt_pk_bf16_f32 v83, v60, v61
	v_lshlrev_b32_e32 v17, 16, v44
	v_pk_mul_f32 v[76:77], v[112:113], v[70:71]
	global_store_dwordx4 v[66:67], v[80:83], off sc1
	v_lshlrev_b32_e32 v13, 16, v45
	v_and_b32_e32 v67, 0xffff0000, v45
	v_lshlrev_b32_e32 v9, 16, v46
	v_and_b32_e32 v59, 0xffff0000, v46
	v_lshlrev_b32_e32 v60, 16, v47
	v_and_b32_e32 v61, 0xffff0000, v47
	v_mul_f32_e32 v44, v32, v17
	v_mul_f32_e32 v46, v28, v33
	v_pk_mul_f32 v[78:79], v[114:115], v[78:79]
	v_mov_b32_e32 v47, v76
	v_mov_b32_e32 v45, v77
	v_mul_f32_e32 v50, v24, v84
	v_pk_add_f32 v[44:45], v[46:47], v[44:45]
	v_mov_b32_e32 v51, v79
	v_mul_f32_e32 v64, v20, v86
	v_pk_add_f32 v[44:45], v[50:51], v[44:45]
	v_mov_b32_e32 v65, v78
	v_pk_add_f32 v[44:45], v[64:65], v[44:45]
	v_mov_b32_e32 v66, v69
	v_mul_f32_e32 v27, 0xbfb8aa3b, v44
	v_exp_f32_e32 v46, v27
	v_mul_f32_e32 v27, 0xbfb8aa3b, v45
	v_exp_f32_e32 v47, v27
	v_pk_mul_f32 v[78:79], v[116:117], v[66:67]
	v_pk_mul_f32 v[72:73], v[118:119], v[72:73]
	v_mul_f32_e32 v64, v26, v31
	v_pk_add_f32 v[46:47], v[46:47], 1.0 op_sel_hi:[1,0]
	v_mov_b32_e32 v65, v73
	v_mul_f32_e32 v76, v22, v29
	v_mov_b32_e32 v77, v72
	v_pk_mul_f32 v[62:63], v[108:109], v[62:63]
	v_rcp_f32_e32 v27, v47
	s_nop 0
	v_mul_f32_e32 v45, v45, v27
	v_mul_f32_e32 v72, v8, v23
	v_mov_b32_e32 v73, v63
	v_rcp_f32_e32 v27, v46
	s_nop 0
	v_mul_f32_e32 v44, v44, v27
	v_mul_f32_e32 v46, v34, v13
	v_mul_f32_e32 v50, v30, v25
	v_mov_b32_e32 v51, v78
	v_mov_b32_e32 v47, v79
	v_pk_add_f32 v[46:47], v[50:51], v[46:47]
	s_nop 0
	v_pk_add_f32 v[46:47], v[64:65], v[46:47]
	s_nop 0
	v_pk_add_f32 v[46:47], v[76:77], v[46:47]
	v_mul_f32_e32 v76, v4, v21
	v_mul_f32_e32 v27, 0xbfb8aa3b, v46
	v_exp_f32_e32 v50, v27
	v_mul_f32_e32 v27, 0xbfb8aa3b, v47
	v_exp_f32_e32 v51, v27
	v_mov_b32_e32 v77, v62
	v_pk_add_f32 v[50:51], v[50:51], 1.0 op_sel_hi:[1,0]
	s_nop 0
	v_rcp_f32_e32 v27, v51
	s_nop 0
	v_mul_f32_e32 v47, v47, v27
	v_mul_f32_e32 v64, v12, v5
	v_mov_b32_e32 v58, v49
	v_pk_mul_f32 v[78:79], v[136:137], v[58:59]
	v_rcp_f32_e32 v27, v50
	s_nop 0
	v_mul_f32_e32 v46, v46, v27
	v_mul_f32_e32 v50, v16, v9
	v_mov_b32_e32 v65, v78
	v_mov_b32_e32 v51, v79
	v_pk_add_f32 v[50:51], v[64:65], v[50:51]
	s_nop 0
	v_pk_add_f32 v[50:51], v[72:73], v[50:51]
	s_nop 0
	v_pk_add_f32 v[50:51], v[76:77], v[50:51]
	s_nop 0
	v_mul_f32_e32 v21, 0xbfb8aa3b, v50
	v_exp_f32_e32 v62, v21
	v_mul_f32_e32 v21, 0xbfb8aa3b, v51
	v_exp_f32_e32 v63, v21
	s_nop 0
	v_pk_add_f32 v[62:63], v[62:63], 1.0 op_sel_hi:[1,0]
	s_nop 0
	v_rcp_f32_e32 v21, v63
	s_nop 0
	v_mul_f32_e32 v51, v51, v21
	v_rcp_f32_e32 v21, v62
	s_nop 0
	v_mul_f32_e32 v50, v50, v21
	v_pk_mul_f32 v[62:63], v[18:19], v[60:61]
	s_nop 0
	v_pk_fma_f32 v[62:63], v[14:15], v[52:53], v[62:63]
	s_nop 0
	v_pk_fma_f32 v[62:63], v[10:11], v[54:55], v[62:63]
	s_nop 0
	v_pk_fma_f32 v[56:57], v[6:7], v[56:57], v[62:63]
	s_nop 0
	v_mul_f32_e32 v21, 0xbfb8aa3b, v56
	v_exp_f32_e32 v62, v21
	v_mul_f32_e32 v21, 0xbfb8aa3b, v57
	v_exp_f32_e32 v63, v21
	s_nop 0
	v_pk_add_f32 v[62:63], v[62:63], 1.0 op_sel_hi:[1,0]
	s_nop 0
	v_rcp_f32_e32 v21, v63
	s_nop 0
	v_mul_f32_e32 v57, v57, v21
	v_rcp_f32_e32 v21, v62
	s_nop 0
	v_mul_f32_e32 v56, v56, v21
	s_and_saveexec_b64 s[40:41], s[36:37]
	s_cbranch_execz .LBB0_193
	v_pk_mul_f32 v[62:63], v[44:45], v[44:45]
	v_pk_mul_f32 v[64:65], v[46:47], v[46:47]
	v_add_f32_e32 v21, v62, v63
	v_add_f32_e32 v21, v21, v64
	v_pk_mul_f32 v[72:73], v[50:51], v[50:51]
	v_add_f32_e32 v21, v21, v65
	v_and_b32_e32 v29, 64, v251
	v_add_f32_e32 v21, v21, v72
	v_add_u32_e32 v29, 64, v29
	v_pk_mul_f32 v[76:77], v[56:57], v[56:57]
	v_add_f32_e32 v21, v21, v73
	v_add_f32_e32 v21, v21, v76
	v_add_f32_e32 v21, v21, v77
	s_waitcnt lgkmcnt(0)
	s_nop 1
	v_add_f32_dpp v21, v21, v21 row_ror:8 row_mask:0xf bank_mask:0xf
	s_waitcnt lgkmcnt(0)
	s_nop 1
	v_add_f32_dpp v21, v21, v21 row_ror:4 row_mask:0xf bank_mask:0xf
	s_waitcnt lgkmcnt(0)
	s_nop 1
	v_add_f32_dpp v21, v21, v21 row_ror:2 row_mask:0xf bank_mask:0xf
	s_waitcnt lgkmcnt(0)
	s_nop 1
	v_add_f32_dpp v21, v21, v21 row_ror:1 row_mask:0xf bank_mask:0xf
	v_add_f32_e32 v21, 0x358637bd, v21
	v_mul_f32_e32 v27, 0x4b800000, v21
	v_cmp_gt_f32_e32 vcc, s2, v21
	s_nop 1
	v_cndmask_b32_e32 v21, v21, v27, vcc
	v_rsq_f32_e32 v21, v21
	s_nop 0
	v_mul_f32_e32 v27, 0x45800000, v21
	v_cndmask_b32_e32 v21, v21, v27, vcc
	v_mul_f32_e32 v62, v129, v21
	v_pk_mul_f32 v[44:45], v[44:45], v[62:63] op_sel_hi:[1,0]
	v_pk_mul_f32 v[46:47], v[46:47], v[62:63] op_sel_hi:[1,0]
	v_pk_mul_f32 v[50:51], v[50:51], v[62:63] op_sel_hi:[1,0]
	v_pk_mul_f32 v[56:57], v[56:57], v[62:63] op_sel_hi:[1,0]
; DI F8 unpack8(uint4 u) { F8 r; r.v[0] = lo16(u.x); r.v[1] = hi16(u.x); r.v[2] = lo16(u.y); r.v[3] = hi16(u.y); r.v[4] = lo16(u.z); r.v[5] = hi16(u.z); r.v[6] = lo16(u.w); r.v[7] = hi16(u.w); return r; }
; DI void stf8(float* p, const F8& f) { *(float4*)p = make_float4(f.v[0], f.v[1], f.v[2], f.v[3]); *(float4*)(p + 4) = make_float4(f.v[4], f.v[5], f.v[6], f.v[7]); }
; DI void stb8(bf16_t* p, const F8& f) { *(uint4*)p = pack8(f); }
; DI float gsum16(float v) { v += __shfl_xor(v, 8); v += __shfl_xor(v, 4); v += __shfl_xor(v, 2); v += __shfl_xor(v, 1); return v; }
; DI float siluf(float x) { return x / (1.f + __expf(-x)); }
; DI void odd_elem(const Params& p, int o) {
;     ...
;         for (int t = 0; t < 16; ++t) {
;             const F8 x0 = unpack8(xr[t]);
;             F8 acc; float ss = 0.f;
; #pragma unroll
;             for (int k = 0; k < 8; ++k) { const float a = w3.v[k] * x0.v[k] + w2.v[k] * h1.v[k] + w1.v[k] * h2.v[k] + w0.v[k] * h3.v[k]; acc.v[k] = siluf(a); ss += acc.v[k] * acc.v[k]; }
;             if (gi < 4) {
;                 const float rs = rsqrtf(gsum16(ss) + EPS) * nsc;
; #pragma unroll
;                 for (int k = 0; k < 8; ++k) acc.v[k] *= rs;
;             }
;             stb8(Q2 + (size_t)(r0 + t) * 3072 + c, acc);
;             if (last && t >= 13) {
;                 float* so = sq < 4 ? p.out + O_PDC + (((size_t)o * 4 + sq) * 3 + (t - 13)) * 3072 : p.out + O_SDC + (((size_t)o * 8 + (sq - 4)) * 3 + (t - 13)) * 3072;
;                 stf8(so + c, x0);
;             }
.LBB0_193:
	s_or_b64 exec, exec, s[40:41]
	v_or_b32_e32 v21, 12, v123
	v_mad_i64_i32 v[62:63], s[40:41], v21, s33, v[110:111]
	v_cvt_pk_bf16_f32 v44, v44, v45
	v_cvt_pk_bf16_f32 v45, v46, v47
	v_cvt_pk_bf16_f32 v46, v50, v51
	v_cvt_pk_bf16_f32 v47, v56, v57
	v_and_b32_e32 v57, 0xffff0000, v40
	v_mov_b32_e32 v56, v71
	global_store_dwordx4 v[62:63], v[44:47], off sc1
	v_pk_mul_f32 v[80:81], v[112:113], v[56:57]
	v_mul_f32_e32 v72, v28, v17
	v_lshlrev_b32_e32 v44, 16, v40
	v_mul_f32_e32 v50, v32, v44
	v_pk_mul_f32 v[74:75], v[114:115], v[74:75]
	v_mov_b32_e32 v73, v80
	v_mov_b32_e32 v51, v81
	v_mul_f32_e32 v76, v24, v33
	v_pk_add_f32 v[50:51], v[72:73], v[50:51]
	v_mov_b32_e32 v77, v75
	v_mul_f32_e32 v78, v20, v84
	v_pk_add_f32 v[50:51], v[76:77], v[50:51]
	v_mov_b32_e32 v79, v74
	v_pk_add_f32 v[50:51], v[78:79], v[50:51]
	v_lshlrev_b32_e32 v46, 16, v41
	v_mul_f32_e32 v21, 0xbfb8aa3b, v50
	v_exp_f32_e32 v72, v21
	v_mul_f32_e32 v21, 0xbfb8aa3b, v51
	v_exp_f32_e32 v73, v21
	v_and_b32_e32 v65, 0xffff0000, v41
	v_mov_b32_e32 v64, v67
	v_pk_mul_f32 v[80:81], v[116:117], v[64:65]
	v_pk_add_f32 v[72:73], v[72:73], 1.0 op_sel_hi:[1,0]
	v_mul_f32_e32 v74, v30, v13
	v_pk_mul_f32 v[68:69], v[118:119], v[68:69]
	v_mov_b32_e32 v75, v80
	v_mul_f32_e32 v76, v26, v25
	v_rcp_f32_e32 v21, v73
	s_nop 0
	v_mul_f32_e32 v51, v51, v21
	v_mov_b32_e32 v73, v81
	v_mov_b32_e32 v77, v69
	v_mul_f32_e32 v78, v22, v31
	v_rcp_f32_e32 v21, v72
	s_nop 0
	v_mul_f32_e32 v50, v50, v21
	v_mul_f32_e32 v72, v34, v46
	v_pk_add_f32 v[72:73], v[74:75], v[72:73]
	v_mov_b32_e32 v79, v68
	v_pk_add_f32 v[72:73], v[76:77], v[72:73]
	v_and_b32_e32 v63, 0xffff0000, v42
	v_pk_add_f32 v[68:69], v[78:79], v[72:73]
	v_mov_b32_e32 v62, v59
	v_mul_f32_e32 v21, 0xbfb8aa3b, v68
	v_exp_f32_e32 v72, v21
	v_mul_f32_e32 v21, 0xbfb8aa3b, v69
	v_exp_f32_e32 v73, v21
	v_lshlrev_b32_e32 v40, 16, v42
	v_pk_mul_f32 v[80:81], v[136:137], v[62:63]
	v_mul_f32_e32 v74, v12, v9
	v_pk_add_f32 v[72:73], v[72:73], 1.0 op_sel_hi:[1,0]
	v_pk_mul_f32 v[48:49], v[108:109], v[48:49]
	v_mov_b32_e32 v75, v80
	v_mul_f32_e32 v76, v8, v5
	v_mov_b32_e32 v77, v49
	v_rcp_f32_e32 v21, v73
	s_nop 0
	v_mul_f32_e32 v69, v69, v21
	v_mov_b32_e32 v73, v81
	v_mul_f32_e32 v78, v4, v23
	v_mov_b32_e32 v79, v48
	v_rcp_f32_e32 v21, v72
	s_nop 0
	v_mul_f32_e32 v68, v68, v21
	v_mul_f32_e32 v72, v16, v40
	v_pk_add_f32 v[72:73], v[74:75], v[72:73]
	v_lshlrev_b32_e32 v42, 16, v43
	v_pk_add_f32 v[72:73], v[76:77], v[72:73]
	v_and_b32_e32 v43, 0xffff0000, v43
	v_pk_add_f32 v[48:49], v[78:79], v[72:73]
	s_nop 0
	v_mul_f32_e32 v21, 0xbfb8aa3b, v48
	v_exp_f32_e32 v72, v21
	v_mul_f32_e32 v21, 0xbfb8aa3b, v49
	v_exp_f32_e32 v73, v21
	s_nop 0
	v_pk_add_f32 v[72:73], v[72:73], 1.0 op_sel_hi:[1,0]
	s_nop 0
	v_rcp_f32_e32 v21, v73
	s_nop 0
	v_mul_f32_e32 v49, v49, v21
	v_rcp_f32_e32 v21, v72
	s_nop 0
	v_mul_f32_e32 v48, v48, v21
	v_pk_mul_f32 v[72:73], v[18:19], v[42:43]
	s_nop 0
	v_pk_fma_f32 v[72:73], v[14:15], v[60:61], v[72:73]
	s_nop 0
	v_pk_fma_f32 v[72:73], v[10:11], v[52:53], v[72:73]
	s_nop 0
	v_pk_fma_f32 v[54:55], v[6:7], v[54:55], v[72:73]
	s_nop 0
	v_mul_f32_e32 v21, 0xbfb8aa3b, v54
	v_exp_f32_e32 v72, v21
	v_mul_f32_e32 v21, 0xbfb8aa3b, v55
	v_exp_f32_e32 v73, v21
	s_nop 0
	v_pk_add_f32 v[72:73], v[72:73], 1.0 op_sel_hi:[1,0]
	s_nop 0
	v_rcp_f32_e32 v21, v73
	s_nop 0
	v_mul_f32_e32 v55, v55, v21
	v_rcp_f32_e32 v21, v72
	s_nop 0
	v_mul_f32_e32 v54, v54, v21
	s_and_saveexec_b64 s[40:41], s[36:37]
	s_cbranch_execz .LBB0_195
	v_pk_mul_f32 v[72:73], v[50:51], v[50:51]
	v_pk_mul_f32 v[74:75], v[68:69], v[68:69]
	v_add_f32_e32 v21, v72, v73
	v_add_f32_e32 v21, v21, v74
	v_pk_mul_f32 v[76:77], v[48:49], v[48:49]
	v_add_f32_e32 v21, v21, v75
	v_and_b32_e32 v27, 64, v251
	v_add_f32_e32 v21, v21, v76
	v_add_u32_e32 v27, 64, v27
	v_pk_mul_f32 v[78:79], v[54:55], v[54:55]
	v_add_f32_e32 v21, v21, v77
	v_add_f32_e32 v21, v21, v78
	v_add_f32_e32 v21, v21, v79
	s_waitcnt lgkmcnt(0)
	s_nop 1
	v_add_f32_dpp v21, v21, v21 row_ror:8 row_mask:0xf bank_mask:0xf
	s_waitcnt lgkmcnt(0)
	s_nop 1
	v_add_f32_dpp v21, v21, v21 row_ror:4 row_mask:0xf bank_mask:0xf
	s_waitcnt lgkmcnt(0)
	s_nop 1
	v_add_f32_dpp v21, v21, v21 row_ror:2 row_mask:0xf bank_mask:0xf
	s_waitcnt lgkmcnt(0)
	s_nop 1
	v_add_f32_dpp v21, v21, v21 row_ror:1 row_mask:0xf bank_mask:0xf
	v_add_f32_e32 v21, 0x358637bd, v21
	v_mul_f32_e32 v23, 0x4b800000, v21
	v_cmp_gt_f32_e32 vcc, s2, v21
	s_nop 1
	v_cndmask_b32_e32 v21, v21, v23, vcc
	v_rsq_f32_e32 v21, v21
	s_nop 0
	v_mul_f32_e32 v23, 0x45800000, v21
	v_cndmask_b32_e32 v21, v21, v23, vcc
	v_mul_f32_e32 v72, v129, v21
	v_pk_mul_f32 v[50:51], v[50:51], v[72:73] op_sel_hi:[1,0]
	v_pk_mul_f32 v[68:69], v[68:69], v[72:73] op_sel_hi:[1,0]
	v_pk_mul_f32 v[48:49], v[48:49], v[72:73] op_sel_hi:[1,0]
	v_pk_mul_f32 v[54:55], v[54:55], v[72:73] op_sel_hi:[1,0]
.LBB0_195:
	s_or_b64 exec, exec, s[40:41]
	v_mov_b32_e32 v21, 0x1ff0
	v_cndmask_b32_e64 v21, 48, v21, s[38:39]
	v_cmp_eq_u32_e64 s[38:39], v135, v21
	v_or_b32_e32 v21, 13, v123
	v_add_u32_e32 v212, -4, v134
	v_ashrrev_i32_e32 v135, 31, v134
	v_mad_i64_i32 v[80:81], s[40:41], v21, s33, v[110:111]
	v_lshl_add_u64 v[76:77], s[18:19], 0, v[212:213]
	v_lshl_add_u64 v[78:79], s[6:7], 0, v[134:135]
	v_cmp_gt_i32_e64 s[40:41], 4, v134
	v_cvt_pk_bf16_f32 v72, v50, v51
	v_cvt_pk_bf16_f32 v73, v68, v69
	v_cvt_pk_bf16_f32 v74, v48, v49
	v_cvt_pk_bf16_f32 v75, v54, v55
	v_cndmask_b32_e64 v27, v77, v79, s[40:41]
	v_cndmask_b32_e64 v29, v76, v78, s[40:41]
	global_store_dwordx4 v[80:81], v[72:75], off sc1
	s_and_saveexec_b64 s[44:45], s[38:39]
	s_cbranch_execz .LBB0_197
	v_mov_b32_e32 v21, 0xcfd8000
	v_mov_b32_e32 v23, 0xca08000
	v_cndmask_b32_e64 v212, v21, v23, s[40:41]
	v_lshl_add_u64 v[48:49], s[60:61], 0, v[212:213]
	s_mov_b32 s50, 0x9000
	v_mad_u64_u32 v[48:49], s[48:49], v29, s50, v[48:49]
	v_mad_i32_i24 v49, v27, s50, v49
	v_lshl_add_u64 v[48:49], v[130:131], 2, v[48:49]
	v_mov_b32_e32 v45, v57
	v_mov_b32_e32 v47, v65
	v_mov_b32_e32 v41, v63
	global_store_dwordx4 v[48:49], v[44:47], off sc1
	global_store_dwordx4 v[48:49], v[40:43], off offset:16 sc1

; DI F8 unpack8(uint4 u) { F8 r; r.v[0] = lo16(u.x); r.v[1] = hi16(u.x); r.v[2] = lo16(u.y); r.v[3] = hi16(u.y); r.v[4] = lo16(u.z); r.v[5] = hi16(u.z); r.v[6] = lo16(u.w); r.v[7] = hi16(u.w); return r; }
; DI void stf8(float* p, const F8& f) { *(float4*)p = make_float4(f.v[0], f.v[1], f.v[2], f.v[3]); *(float4*)(p + 4) = make_float4(f.v[4], f.v[5], f.v[6], f.v[7]); }
; DI void stb8(bf16_t* p, const F8& f) { *(uint4*)p = pack8(f); }
; DI float gsum16(float v) { v += __shfl_xor(v, 8); v += __shfl_xor(v, 4); v += __shfl_xor(v, 2); v += __shfl_xor(v, 1); return v; }
; DI float siluf(float x) { return x / (1.f + __expf(-x)); }
; DI void odd_elem(const Params& p, int o) {
;     ...
;         for (int t = 0; t < 16; ++t) {
;             const F8 x0 = unpack8(xr[t]);
;             F8 acc; float ss = 0.f;
; #pragma unroll
;             for (int k = 0; k < 8; ++k) { const float a = w3.v[k] * x0.v[k] + w2.v[k] * h1.v[k] + w1.v[k] * h2.v[k] + w0.v[k] * h3.v[k]; acc.v[k] = siluf(a); ss += acc.v[k] * acc.v[k]; }
;             if (gi < 4) {
;                 const float rs = rsqrtf(gsum16(ss) + EPS) * nsc;
; #pragma unroll
;                 for (int k = 0; k < 8; ++k) acc.v[k] *= rs;
;             }
;             stb8(Q2 + (size_t)(r0 + t) * 3072 + c, acc);
;             if (last && t >= 13) {
;                 float* so = sq < 4 ? p.out + O_PDC + (((size_t)o * 4 + sq) * 3 + (t - 13)) * 3072 : p.out + O_SDC + (((size_t)o * 8 + (sq - 4)) * 3 + (t - 13)) * 3072;
;                 stf8(so + c, x0);
;             }
.LBB0_199:
	s_or_b64 exec, exec, s[44:45]
	v_or_b32_e32 v5, 14, v123
	v_mad_i64_i32 v[78:79], s[44:45], v5, s33, v[110:111]
	v_cvt_pk_bf16_f32 v74, v70, v71
	v_cvt_pk_bf16_f32 v75, v66, v67
	v_cvt_pk_bf16_f32 v76, v58, v59
	v_cvt_pk_bf16_f32 v77, v52, v53
	global_store_dwordx4 v[78:79], v[74:77], off sc1
	s_and_saveexec_b64 s[44:45], s[38:39]
	s_cbranch_execz .LBB0_201
	v_mov_b32_e32 v5, 0xcfdb000
	v_mov_b32_e32 v21, 0xca0b000
	v_cndmask_b32_e64 v212, v5, v21, s[40:41]
	v_lshl_add_u64 v[52:53], s[60:61], 0, v[212:213]
	s_mov_b32 s50, 0x9000
	v_mad_u64_u32 v[52:53], s[48:49], v29, s50, v[52:53]
	v_mad_i32_i24 v53, v27, s50, v53
	v_lshl_add_u64 v[52:53], v[130:131], 2, v[52:53]
	v_mov_b32_e32 v49, v73
	v_mov_b32_e32 v51, v69
	v_mov_b32_e32 v37, v55
	global_store_dwordx4 v[52:53], v[48:51], off sc1
	global_store_dwordx4 v[52:53], v[36:39], off offset:16 sc1

; DI F8 unpack8(uint4 u) { F8 r; r.v[0] = lo16(u.x); r.v[1] = hi16(u.x); r.v[2] = lo16(u.y); r.v[3] = hi16(u.y); r.v[4] = lo16(u.z); r.v[5] = hi16(u.z); r.v[6] = lo16(u.w); r.v[7] = hi16(u.w); return r; }
; DI void stf8(float* p, const F8& f) { *(float4*)p = make_float4(f.v[0], f.v[1], f.v[2], f.v[3]); *(float4*)(p + 4) = make_float4(f.v[4], f.v[5], f.v[6], f.v[7]); }
; DI void stb8(bf16_t* p, const F8& f) { *(uint4*)p = pack8(f); }
; DI float gsum16(float v) { v += __shfl_xor(v, 8); v += __shfl_xor(v, 4); v += __shfl_xor(v, 2); v += __shfl_xor(v, 1); return v; }
; DI float siluf(float x) { return x / (1.f + __expf(-x)); }
; DI void odd_elem(const Params& p, int o) {
;     ...
;         for (int t = 0; t < 16; ++t) {
;             const F8 x0 = unpack8(xr[t]);
;             F8 acc; float ss = 0.f;
; #pragma unroll
;             for (int k = 0; k < 8; ++k) { const float a = w3.v[k] * x0.v[k] + w2.v[k] * h1.v[k] + w1.v[k] * h2.v[k] + w0.v[k] * h3.v[k]; acc.v[k] = siluf(a); ss += acc.v[k] * acc.v[k]; }
;             if (gi < 4) {
;                 const float rs = rsqrtf(gsum16(ss) + EPS) * nsc;
; #pragma unroll
;                 for (int k = 0; k < 8; ++k) acc.v[k] *= rs;
;             }
;             stb8(Q2 + (size_t)(r0 + t) * 3072 + c, acc);
;             if (last && t >= 13) {
;                 float* so = sq < 4 ? p.out + O_PDC + (((size_t)o * 4 + sq) * 3 + (t - 13)) * 3072 : p.out + O_SDC + (((size_t)o * 8 + (sq - 4)) * 3 + (t - 13)) * 3072;
;                 stf8(so + c, x0);
;             }
.LBB0_203:
	s_or_b64 exec, exec, s[44:45]
	v_or_b32_e32 v0, 15, v123
	v_mad_i64_i32 v[14:15], s[36:37], v0, s33, v[110:111]
	v_cvt_pk_bf16_f32 v10, v22, v23
	v_cvt_pk_bf16_f32 v11, v4, v5
	v_cvt_pk_bf16_f32 v12, v8, v9
	v_cvt_pk_bf16_f32 v13, v6, v7
	global_store_dwordx4 v[14:15], v[10:13], off sc1
	s_and_saveexec_b64 s[36:37], s[38:39]
	s_cbranch_execz .LBB0_205
	v_mov_b32_e32 v0, 0xcfde000
	v_mov_b32_e32 v2, 0xca0e000
	v_cndmask_b32_e64 v212, v0, v2, s[40:41]
	v_lshl_add_u64 v[4:5], s[60:61], 0, v[212:213]
	s_mov_b32 s40, 0x9000
	v_mad_u64_u32 v[4:5], s[38:39], v29, s40, v[4:5]
	v_mad_i32_i24 v5, v27, s40, v5
	v_lshl_add_u64 v[4:5], v[130:131], 2, v[4:5]
	v_mov_b32_e32 v57, v3
	v_mov_b32_e32 v53, v21
	v_mov_b32_e32 v55, v1
	global_store_dwordx4 v[4:5], v[56:59], off offset:16 sc1
	global_store_dwordx4 v[4:5], v[52:55], off sc1

; DI F8 ldb8(const bf16_t* p) { return unpack8(*(const uint4*)p); }
; DI float gsum16(float v) { v += __shfl_xor(v, 8); v += __shfl_xor(v, 4); v += __shfl_xor(v, 2); v += __shfl_xor(v, 1); return v; }
; DI float siluf(float x) { return x / (1.f + __expf(-x)); }
; DI void odd_gate(const Params& p, int o) {
;     ...
;     for (int r = gw; r < MT; r += nw) {
; #pragma unroll
;         for (int it = 0; it < 2; ++it) {
;             const int c = it * 512 + lane * 8;
;             F8 x = ldb8(OB + (size_t)r * 1024 + c); const F8 z = ldb8(ZAB + (size_t)r * 1152 + c), gg = ldf8(go + (c & 127));
;             float ss = 0.f;
;             for (int k = 0; k < 8; ++k) ss += x.v[k] * x.v[k];
;             const float rs = rsqrtf(gsum16(ss) * (1.f / 128.f) + EPS);
;             for (int k = 0; k < 8; ++k) x.v[k] = x.v[k] * rs * gg.v[k] * siluf(z.v[k]);
.LBB0_425:
	v_lshl_add_u64 v[0:1], v[12:13], 0, v[212:213]
	v_add_co_u32_e32 v16, vcc, 0x7800000, v0
	v_lshl_add_u64 v[26:27], v[14:15], 0, v[212:213]
	s_nop 0
	v_addc_co_u32_e32 v17, vcc, 0, v1, vcc
	global_load_dwordx4 v[0:3], v[16:17], off
	v_add_u32_e32 v8, s6, v8
	v_lshl_add_u64 v[12:13], v[12:13], 0, s[14:15]
	v_lshl_add_u64 v[14:15], v[14:15], 0, s[18:19]
	s_waitcnt vmcnt(0)
	v_lshlrev_b32_e32 v24, 16, v0
	v_and_b32_e32 v25, 0xffff0000, v0
	v_lshlrev_b32_e32 v22, 16, v1
	v_and_b32_e32 v23, 0xffff0000, v1
	v_lshlrev_b32_e32 v20, 16, v2
	v_and_b32_e32 v21, 0xffff0000, v2
	v_lshlrev_b32_e32 v18, 16, v3
	v_and_b32_e32 v19, 0xffff0000, v3
	global_load_dwordx4 v[0:3], v[26:27], off
	v_mov_b32_e32 v63, v25
	v_pk_mul_f32 v[54:55], v[22:23], v[22:23]
	v_mov_b32_e32 v61, v24
	v_pk_mul_f32 v[52:53], v[20:21], v[20:21]
	v_pk_mul_f32 v[50:51], v[18:19], v[18:19]
	s_waitcnt vmcnt(0)
	v_lshlrev_b32_e32 v33, 16, v2
	v_and_b32_e32 v34, 0xffff0000, v2
	v_mul_f32_e32 v28, 0xbfb8aa3b, v33
	v_mul_f32_e32 v29, 0xbfb8aa3b, v34
	v_exp_f32_e32 v28, v28
	v_exp_f32_e32 v29, v29
	v_lshlrev_b32_e32 v31, 16, v1
	v_and_b32_e32 v32, 0xffff0000, v1
	v_lshlrev_b32_e32 v9, 16, v0
	v_pk_add_f32 v[28:29], v[28:29], 1.0 op_sel_hi:[1,0]
	v_and_b32_e32 v30, 0xffff0000, v0
	v_lshlrev_b32_e32 v35, 16, v3
	v_and_b32_e32 v46, 0xffff0000, v3
	global_load_dwordx4 v[0:3], v[10:11], off offset:16
	global_load_dwordx4 v[4:7], v[10:11], off
	v_rcp_f32_e32 v36, v29
	s_nop 0
	v_mul_f32_e32 v37, v34, v36
	v_rcp_f32_e32 v29, v28
	s_nop 0
	v_mul_f32_e32 v36, v33, v29
	v_mul_f32_e32 v28, 0xbfb8aa3b, v31
	v_mul_f32_e32 v29, 0xbfb8aa3b, v32
	v_exp_f32_e32 v28, v28
	v_exp_f32_e32 v29, v29
	s_nop 0
	v_pk_add_f32 v[28:29], v[28:29], 1.0 op_sel_hi:[1,0]
	s_nop 0
	v_rcp_f32_e32 v33, v29
	s_nop 0
	v_mul_f32_e32 v39, v32, v33
	v_rcp_f32_e32 v29, v28
	s_nop 0
	v_mul_f32_e32 v38, v31, v29
	v_mul_f32_e32 v28, 0xbfb8aa3b, v9
	v_mul_f32_e32 v29, 0xbfb8aa3b, v30
	v_exp_f32_e32 v28, v28
	v_exp_f32_e32 v29, v29
	s_nop 0
	v_pk_add_f32 v[28:29], v[28:29], 1.0 op_sel_hi:[1,0]
	s_nop 0
	v_rcp_f32_e32 v31, v29
	s_nop 0
	v_mul_f32_e32 v41, v30, v31
	v_rcp_f32_e32 v29, v28
	s_nop 0
	v_mul_f32_e32 v40, v9, v29
	v_mul_f32_e32 v9, 0xbfb8aa3b, v35
	v_exp_f32_e32 v28, v9
	v_mul_f32_e32 v9, 0xbfb8aa3b, v46
	v_exp_f32_e32 v29, v9
	s_nop 0
	v_pk_add_f32 v[28:29], v[28:29], 1.0 op_sel_hi:[1,0]
	s_nop 0
	v_rcp_f32_e32 v9, v29
	s_nop 0
	v_mul_f32_e32 v57, v46, v9
	global_load_dwordx4 v[46:49], v[16:17], off offset:1024
	s_brev_b32 s26, 60
	v_rcp_f32_e32 v9, v28
	s_nop 0
	v_mul_f32_e32 v56, v35, v9
	s_waitcnt vmcnt(0)
	v_and_b32_e32 v35, 0xffff0000, v46
	v_lshlrev_b32_e32 v34, 16, v46
	v_lshlrev_b32_e32 v32, 16, v47
	v_and_b32_e32 v33, 0xffff0000, v47
	v_mov_b32_e32 v62, v35
	v_pk_mul_f32 v[58:59], v[32:33], v[32:33]
	v_mov_b32_e32 v60, v34
	v_pk_mul_f32 v[62:63], v[62:63], v[62:63]
	v_lshlrev_b32_e32 v30, 16, v48
	v_and_b32_e32 v31, 0xffff0000, v48
	v_pk_fma_f32 v[60:61], v[60:61], v[60:61], v[62:63]
	v_mov_b32_e32 v62, v58
	v_mov_b32_e32 v63, v54
	v_lshlrev_b32_e32 v28, 16, v49
	v_and_b32_e32 v29, 0xffff0000, v49
	v_pk_mul_f32 v[48:49], v[30:31], v[30:31]
	v_pk_add_f32 v[60:61], v[60:61], v[62:63]
	v_mov_b32_e32 v54, v59
	v_pk_add_f32 v[54:55], v[54:55], v[60:61]
	v_mov_b32_e32 v58, v48
	v_mov_b32_e32 v59, v52
	v_pk_mul_f32 v[46:47], v[28:29], v[28:29]
	v_pk_add_f32 v[54:55], v[58:59], v[54:55]
	v_mov_b32_e32 v52, v49
	v_pk_add_f32 v[48:49], v[52:53], v[54:55]
	v_mov_b32_e32 v52, v46
	v_mov_b32_e32 v53, v50
	v_pk_add_f32 v[48:49], v[52:53], v[48:49]
	v_mov_b32_e32 v50, v47
	v_pk_add_f32 v[46:47], v[50:51], v[48:49]
	s_waitcnt lgkmcnt(0)
	s_nop 1
	v_add_f32_dpp v46, v46, v46 row_ror:8 row_mask:0xf bank_mask:0xf
	v_add_f32_dpp v47, v47, v47 row_ror:8 row_mask:0xf bank_mask:0xf
	s_waitcnt lgkmcnt(0)
	s_nop 1
	v_add_f32_dpp v46, v46, v46 row_ror:4 row_mask:0xf bank_mask:0xf
	v_add_f32_dpp v47, v47, v47 row_ror:4 row_mask:0xf bank_mask:0xf
	s_waitcnt lgkmcnt(0)
; DI F8 ldb8(const bf16_t* p) { return unpack8(*(const uint4*)p); }
; DI void stb8(bf16_t* p, const F8& f) { *(uint4*)p = pack8(f); }
; DI float gsum16(float v) { v += __shfl_xor(v, 8); v += __shfl_xor(v, 4); v += __shfl_xor(v, 2); v += __shfl_xor(v, 1); return v; }
; DI float siluf(float x) { return x / (1.f + __expf(-x)); }
; DI void odd_gate(const Params& p, int o) {
;     ...
;         for (int it = 0; it < 2; ++it) {
;             const int c = it * 512 + lane * 8;
;             F8 x = ldb8(OB + (size_t)r * 1024 + c); const F8 z = ldb8(ZAB + (size_t)r * 1152 + c), gg = ldf8(go + (c & 127));
;             float ss = 0.f;
;             for (int k = 0; k < 8; ++k) ss += x.v[k] * x.v[k];
;             const float rs = rsqrtf(gsum16(ss) * (1.f / 128.f) + EPS);
;             for (int k = 0; k < 8; ++k) x.v[k] = x.v[k] * rs * gg.v[k] * siluf(z.v[k]);
;             stb8(OB + (size_t)r * 1024 + c, x);
;         }
	s_nop 1
	v_add_f32_dpp v46, v46, v46 row_ror:2 row_mask:0xf bank_mask:0xf
	v_add_f32_dpp v47, v47, v47 row_ror:2 row_mask:0xf bank_mask:0xf
	ds_bpermute_b32 v49, v45, v47
	ds_bpermute_b32 v48, v45, v46
	s_waitcnt lgkmcnt(0)
	v_pk_add_f32 v[46:47], v[46:47], v[48:49]
	s_nop 0
	v_pk_fma_f32 v[46:47], v[46:47], s[26:27], v[64:65] op_sel_hi:[1,0,0]
	s_nop 0
	v_mul_f32_e32 v9, 0x4b800000, v47
	v_cmp_gt_f32_e32 vcc, s2, v47
	v_cmp_gt_f32_e64 s[36:37], s2, v46
	s_nop 0
	v_cndmask_b32_e32 v9, v47, v9, vcc
	v_rsq_f32_e32 v9, v9
	s_nop 0
	v_mul_f32_e32 v47, 0x45800000, v9
	v_cndmask_b32_e32 v48, v9, v47, vcc
	v_pk_mul_f32 v[20:21], v[48:49], v[20:21] op_sel_hi:[0,1]
	v_pk_mul_f32 v[0:1], v[0:1], v[20:21]
	v_pk_mul_f32 v[24:25], v[48:49], v[24:25] op_sel_hi:[0,1]
	v_pk_mul_f32 v[22:23], v[48:49], v[22:23] op_sel_hi:[0,1]
	v_pk_mul_f32 v[20:21], v[36:37], v[0:1]
	v_pk_mul_f32 v[0:1], v[48:49], v[18:19] op_sel_hi:[0,1]
	v_pk_mul_f32 v[4:5], v[4:5], v[24:25]
	v_pk_mul_f32 v[6:7], v[6:7], v[22:23]
	v_pk_mul_f32 v[0:1], v[2:3], v[0:1]
	v_pk_mul_f32 v[4:5], v[40:41], v[4:5]
	v_pk_mul_f32 v[6:7], v[38:39], v[6:7]
	v_pk_mul_f32 v[18:19], v[56:57], v[0:1]
	v_cvt_pk_bf16_f32 v0, v4, v5
	v_cvt_pk_bf16_f32 v1, v6, v7
	v_cvt_pk_bf16_f32 v2, v20, v21
	v_cvt_pk_bf16_f32 v3, v18, v19
	global_store_dwordx4 v[16:17], v[0:3], off sc1
	global_load_dwordx4 v[0:3], v[26:27], off offset:1024
	s_waitcnt vmcnt(0)
	v_lshlrev_b32_e32 v20, 16, v2
	v_and_b32_e32 v21, 0xffff0000, v2
	v_mul_f32_e32 v18, 0xbfb8aa3b, v20
	v_mul_f32_e32 v19, 0xbfb8aa3b, v21
	v_exp_f32_e32 v18, v18
	v_exp_f32_e32 v19, v19
	v_lshlrev_b32_e32 v9, 16, v0
	v_and_b32_e32 v24, 0xffff0000, v0
	v_lshlrev_b32_e32 v22, 16, v1
	v_pk_add_f32 v[18:19], v[18:19], 1.0 op_sel_hi:[1,0]
	v_and_b32_e32 v23, 0xffff0000, v1
	v_lshlrev_b32_e32 v25, 16, v3
	v_and_b32_e32 v36, 0xffff0000, v3
	global_load_dwordx4 v[0:3], v[10:11], off offset:16
	global_load_dwordx4 v[4:7], v[10:11], off
	v_rcp_f32_e32 v26, v19
	s_nop 0
	v_mul_f32_e32 v19, v21, v26
	v_rcp_f32_e32 v21, v18
	s_nop 0
	v_mul_f32_e32 v18, v20, v21
	v_mul_f32_e32 v20, 0xbfb8aa3b, v22
	v_mul_f32_e32 v21, 0xbfb8aa3b, v23
	v_exp_f32_e32 v20, v20
	v_exp_f32_e32 v21, v21
	s_nop 0
	v_pk_add_f32 v[20:21], v[20:21], 1.0 op_sel_hi:[1,0]
	s_nop 0
	v_rcp_f32_e32 v26, v21
	s_nop 0
	v_mul_f32_e32 v21, v23, v26
	v_rcp_f32_e32 v23, v20
	s_nop 0
	v_mul_f32_e32 v20, v22, v23
	v_mul_f32_e32 v22, 0xbfb8aa3b, v9
	v_mul_f32_e32 v23, 0xbfb8aa3b, v24
	v_exp_f32_e32 v22, v22
	v_exp_f32_e32 v23, v23
	s_nop 0
	v_pk_add_f32 v[22:23], v[22:23], 1.0 op_sel_hi:[1,0]
	s_nop 0
	v_rcp_f32_e32 v26, v23
	s_nop 0
	v_mul_f32_e32 v23, v24, v26
	v_rcp_f32_e32 v24, v22
	s_nop 0
	v_mul_f32_e32 v22, v9, v24
	v_mul_f32_e32 v9, 0x4b800000, v46
	v_cndmask_b32_e64 v9, v46, v9, s[36:37]
	v_rsq_f32_e32 v9, v9
	s_nop 0
	v_mul_f32_e32 v24, 0x45800000, v9
	v_cndmask_b32_e64 v24, v9, v24, s[36:37]
	v_pk_mul_f32 v[26:27], v[24:25], v[34:35] op_sel_hi:[0,1]
	s_waitcnt vmcnt(0)
	v_pk_mul_f32 v[4:5], v[4:5], v[26:27]
	s_nop 0
	v_pk_mul_f32 v[4:5], v[22:23], v[4:5]
	v_pk_mul_f32 v[22:23], v[24:25], v[32:33] op_sel_hi:[0,1]
	v_pk_mul_f32 v[6:7], v[6:7], v[22:23]
	s_nop 0
	v_pk_mul_f32 v[6:7], v[20:21], v[6:7]
	v_pk_mul_f32 v[20:21], v[24:25], v[30:31] op_sel_hi:[0,1]
	v_pk_mul_f32 v[0:1], v[0:1], v[20:21]
	v_pk_mul_f32 v[20:21], v[24:25], v[28:29] op_sel_hi:[0,1]
	v_pk_mul_f32 v[18:19], v[18:19], v[0:1]
	v_mul_f32_e32 v0, 0xbfb8aa3b, v25
	v_mul_f32_e32 v1, 0xbfb8aa3b, v36
	v_exp_f32_e32 v0, v0
	v_exp_f32_e32 v1, v1
	v_pk_mul_f32 v[2:3], v[2:3], v[20:21]
	v_pk_add_f32 v[0:1], v[0:1], 1.0 op_sel_hi:[1,0]
	s_nop 0
	v_rcp_f32_e32 v9, v1
	s_nop 0
	v_mul_f32_e32 v1, v36, v9
	v_rcp_f32_e32 v9, v0
	s_nop 0
	v_mul_f32_e32 v0, v25, v9
	v_pk_mul_f32 v[20:21], v[0:1], v[2:3]
	v_cmp_lt_i32_e32 vcc, s30, v8
	v_cvt_pk_bf16_f32 v0, v4, v5
	v_cvt_pk_bf16_f32 v1, v6, v7
	v_cvt_pk_bf16_f32 v2, v18, v19
	v_cvt_pk_bf16_f32 v3, v20, v21
	s_or_b64 s[22:23], vcc, s[22:23]
	global_store_dwordx4 v[16:17], v[0:3], off offset:1024 sc1
	s_andn2_b64 exec, exec, s[22:23]
	s_cbranch_execnz .LBB0_425

; DI void stb8(bf16_t* p, const F8& f) { *(uint4*)p = pack8(f); }
; template <int MODE>
; DI void gemm_epilogue(const float* Cs, int m0, int n0, const Epi& ep) {
;     ...
;     if (MODE == 0) {
; #pragma unroll
;         for (int it = 0; it < 4; ++it) {
;             const int row = (tid >> 4) + 32 * it, cc = (tid & 15) * 8;
;             stb8(ep.b0 + (size_t)(m0 + row) * ep.ld + n0 + cc, ldf8(Cs + row * LDC + cc));
;         }
; template <int MODE>
; DI void gemm_phase(const bf16_t* __restrict__ A, const bf16_t* __restrict__ Bt, int M, int N, int K, const Epi& ep) {
;     ...
; #pragma unroll
;         for (int ai = 0; ai < 2; ++ai)
; #pragma unroll
;             for (int bj = 0; bj < 2; ++bj) {
; #pragma unroll
;                 for (int m = 0; m < 4; ++m)
; #pragma unroll
;                     for (int n = 0; n < 2; ++n)
;                         *(f32x4*)(Cs + (wr * 64 + m * 16 + fr) * LDC + wc * 32 + n * 16 + fq * 4) = acc[ai][bj][m][n];
;                 __syncthreads();
;                 gemm_epilogue<MODE>(Cs, brow + ai * 128, bcol + bj * 128, ep);
;                 __syncthreads();
.LBB0_480:
	s_or_b64 exec, exec, s[6:7]
	v_mov_b32_e32 v64, v250
	s_waitcnt vmcnt(0)
	s_barrier
	ds_write_b128 v146, v[96:99]
	ds_write_b128 v146, v[100:103] offset:64
	ds_write_b128 v146, v[104:107] offset:8448
	ds_write_b128 v146, v[108:111] offset:8512
	ds_write_b128 v146, v[112:115] offset:16896
	ds_write_b128 v146, v[116:119] offset:16960
	ds_write_b128 v146, v[120:123] offset:25344
	ds_write_b128 v146, v[124:127] offset:25408
	s_waitcnt lgkmcnt(0)
	s_barrier
	s_lshl_b64 s[0:1], s[0:1], 1
	v_ashrrev_i32_e32 v66, 4, v64
	v_add_u32_e32 v100, s26, v66
	v_lshlrev_b32_e32 v64, 3, v64
	v_ashrrev_i32_e32 v101, 31, v100
	v_and_b32_e32 v104, 0x78, v64
	v_lshlrev_b64 v[64:65], 11, v[100:101]
	v_lshlrev_b32_e32 v67, 2, v104
	v_lshl_add_u64 v[96:97], s[76:77], 0, v[64:65]
	v_mul_lo_u32 v64, v66, s35
	v_add3_u32 v105, 16, v67, v64
	ds_read_b128 v[64:67], v105
	v_lshl_add_u64 v[102:103], v[96:97], 0, s[0:1]
	ds_read_b128 v[96:99], v105 offset:16
	v_lshlrev_b32_e32 v212, 1, v104
	v_lshl_add_u64 v[102:103], v[102:103], 0, v[212:213]
	s_waitcnt lgkmcnt(1)
	v_cvt_pk_bf16_f32 v64, v64, v65
	v_cvt_pk_bf16_f32 v65, v66, v67
	s_waitcnt lgkmcnt(0)
	v_cvt_pk_bf16_f32 v66, v96, v97
	v_cvt_pk_bf16_f32 v67, v98, v99
	global_store_dwordx4 v[102:103], v[64:67], off sc1
	s_add_i32 s22, s22, 1
	s_nop 0
	v_add_u32_e32 v64, 32, v100
	v_ashrrev_i32_e32 v65, 31, v64
	v_lshlrev_b64 v[96:97], 11, v[64:65]
	ds_read_b128 v[64:67], v105 offset:16896
	v_lshl_add_u64 v[102:103], s[76:77], 0, v[96:97]
	ds_read_b128 v[96:99], v105 offset:16912
	v_lshl_add_u64 v[102:103], v[102:103], 0, s[0:1]
	v_lshl_add_u64 v[102:103], v[102:103], 0, v[212:213]
	s_waitcnt lgkmcnt(1)
	v_cvt_pk_bf16_f32 v64, v64, v65
	v_cvt_pk_bf16_f32 v65, v66, v67
	s_waitcnt lgkmcnt(0)
	v_cvt_pk_bf16_f32 v66, v96, v97
	v_cvt_pk_bf16_f32 v67, v98, v99
	global_store_dwordx4 v[102:103], v[64:67], off sc1
	s_nop 1
	v_add_u32_e32 v64, 64, v100
	v_ashrrev_i32_e32 v65, 31, v64
	v_lshlrev_b64 v[96:97], 11, v[64:65]
	ds_read_b128 v[64:67], v105 offset:33792
	v_lshl_add_u64 v[102:103], s[76:77], 0, v[96:97]
	ds_read_b128 v[96:99], v105 offset:33808
	v_lshl_add_u64 v[102:103], v[102:103], 0, s[0:1]
	v_lshl_add_u64 v[102:103], v[102:103], 0, v[212:213]
	s_waitcnt lgkmcnt(1)
	v_cvt_pk_bf16_f32 v64, v64, v65
	v_cvt_pk_bf16_f32 v65, v66, v67
	s_waitcnt lgkmcnt(0)
	v_cvt_pk_bf16_f32 v66, v96, v97
	v_cvt_pk_bf16_f32 v67, v98, v99
	global_store_dwordx4 v[102:103], v[64:67], off sc1
	s_nop 1
	v_add_u32_e32 v64, 0x60, v100
	v_ashrrev_i32_e32 v65, 31, v64
	v_lshlrev_b64 v[96:97], 11, v[64:65]
	ds_read_b128 v[64:67], v105 offset:50688
	v_lshl_add_u64 v[100:101], s[76:77], 0, v[96:97]
	ds_read_b128 v[96:99], v105 offset:50704
	v_lshl_add_u64 v[100:101], v[100:101], 0, s[0:1]
	v_lshl_add_u64 v[100:101], v[100:101], 0, v[212:213]
	s_waitcnt lgkmcnt(1)
	v_cvt_pk_bf16_f32 v64, v64, v65
	v_cvt_pk_bf16_f32 v65, v66, v67
	s_waitcnt lgkmcnt(0)
	v_cvt_pk_bf16_f32 v66, v96, v97
	v_cvt_pk_bf16_f32 v67, v98, v99
	global_store_dwordx4 v[100:101], v[64:67], off sc1
	s_barrier
	s_nop 0
	v_mov_b32_e32 v64, v250
	ds_write_b128 v146, v[222:225]
	ds_write_b128 v146, v[68:71] offset:64
	ds_write_b128 v146, v[72:75] offset:8448
	ds_write_b128 v146, v[76:79] offset:8512
	ds_write_b128 v146, v[80:83] offset:16896
	ds_write_b128 v146, v[84:87] offset:16960
	ds_write_b128 v146, v[88:91] offset:25344
	ds_write_b128 v146, v[92:95] offset:25408
	s_waitcnt lgkmcnt(0)
	s_barrier
	s_nop 0
	v_ashrrev_i32_e32 v66, 4, v64
	v_add_u32_e32 v72, s26, v66
	v_lshlrev_b32_e32 v64, 3, v64
	v_ashrrev_i32_e32 v73, 31, v72
	v_and_b32_e32 v76, 0x78, v64
	v_lshlrev_b64 v[64:65], 11, v[72:73]
	v_lshlrev_b32_e32 v67, 2, v76
	v_lshl_add_u64 v[68:69], s[76:77], 0, v[64:65]
	v_mul_lo_u32 v64, v66, s35
	v_add3_u32 v77, 16, v67, v64
	ds_read_b128 v[64:67], v77
	v_lshl_add_u64 v[74:75], v[68:69], 0, s[0:1]
	ds_read_b128 v[68:71], v77 offset:16
	v_lshlrev_b32_e32 v212, 1, v76
	v_lshl_add_u64 v[74:75], v[74:75], 0, v[212:213]
	s_waitcnt lgkmcnt(1)
	v_cvt_pk_bf16_f32 v64, v64, v65
	v_cvt_pk_bf16_f32 v65, v66, v67
	s_waitcnt lgkmcnt(0)
	v_cvt_pk_bf16_f32 v66, v68, v69
	v_cvt_pk_bf16_f32 v67, v70, v71
	global_store_dwordx4 v[74:75], v[64:67], off offset:256 sc1
	s_nop 1
	v_add_u32_e32 v64, 32, v72
	v_ashrrev_i32_e32 v65, 31, v64
	v_lshlrev_b64 v[68:69], 11, v[64:65]
	ds_read_b128 v[64:67], v77 offset:16896
	v_lshl_add_u64 v[74:75], s[76:77], 0, v[68:69]
	ds_read_b128 v[68:71], v77 offset:16912
	v_lshl_add_u64 v[74:75], v[74:75], 0, s[0:1]
	v_lshl_add_u64 v[74:75], v[74:75], 0, v[212:213]
	s_waitcnt lgkmcnt(1)
	v_cvt_pk_bf16_f32 v64, v64, v65
	v_cvt_pk_bf16_f32 v65, v66, v67
	s_waitcnt lgkmcnt(0)
	v_cvt_pk_bf16_f32 v66, v68, v69
	v_cvt_pk_bf16_f32 v67, v70, v71
	global_store_dwordx4 v[74:75], v[64:67], off offset:256 sc1
	s_nop 1
	v_add_u32_e32 v64, 64, v72
	v_ashrrev_i32_e32 v65, 31, v64
	v_lshlrev_b64 v[68:69], 11, v[64:65]
	ds_read_b128 v[64:67], v77 offset:33792
	v_lshl_add_u64 v[74:75], s[76:77], 0, v[68:69]
	ds_read_b128 v[68:71], v77 offset:33808
	v_lshl_add_u64 v[74:75], v[74:75], 0, s[0:1]
	v_lshl_add_u64 v[74:75], v[74:75], 0, v[212:213]
	s_waitcnt lgkmcnt(1)
	v_cvt_pk_bf16_f32 v64, v64, v65
	v_cvt_pk_bf16_f32 v65, v66, v67
	s_waitcnt lgkmcnt(0)
	v_cvt_pk_bf16_f32 v66, v68, v69
	v_cvt_pk_bf16_f32 v67, v70, v71
	global_store_dwordx4 v[74:75], v[64:67], off offset:256 sc1
	s_nop 1
	v_add_u32_e32 v64, 0x60, v72
	v_ashrrev_i32_e32 v65, 31, v64
	v_lshlrev_b64 v[68:69], 11, v[64:65]
	ds_read_b128 v[64:67], v77 offset:50688
	v_lshl_add_u64 v[72:73], s[76:77], 0, v[68:69]
	ds_read_b128 v[68:71], v77 offset:50704
	v_lshl_add_u64 v[72:73], v[72:73], 0, s[0:1]
	v_lshl_add_u64 v[72:73], v[72:73], 0, v[212:213]
	s_waitcnt lgkmcnt(1)
	v_cvt_pk_bf16_f32 v64, v64, v65
	v_cvt_pk_bf16_f32 v65, v66, v67
	s_waitcnt lgkmcnt(0)
	v_cvt_pk_bf16_f32 v66, v68, v69
	v_cvt_pk_bf16_f32 v67, v70, v71
	global_store_dwordx4 v[72:73], v[64:67], off offset:256 sc1
	s_barrier
; DI void stb8(bf16_t* p, const F8& f) { *(uint4*)p = pack8(f); }
; template <int MODE>
; DI void gemm_epilogue(const float* Cs, int m0, int n0, const Epi& ep) {
;     ...
;     if (MODE == 0) {
; #pragma unroll
;         for (int it = 0; it < 4; ++it) {
;             const int row = (tid >> 4) + 32 * it, cc = (tid & 15) * 8;
;             stb8(ep.b0 + (size_t)(m0 + row) * ep.ld + n0 + cc, ldf8(Cs + row * LDC + cc));
;         }
; template <int MODE>
; DI void gemm_phase(const bf16_t* __restrict__ A, const bf16_t* __restrict__ Bt, int M, int N, int K, const Epi& ep) {
;     ...
; #pragma unroll
;         for (int ai = 0; ai < 2; ++ai)
; #pragma unroll
;             for (int bj = 0; bj < 2; ++bj) {
; #pragma unroll
;                 for (int m = 0; m < 4; ++m)
; #pragma unroll
;                     for (int n = 0; n < 2; ++n)
;                         *(f32x4*)(Cs + (wr * 64 + m * 16 + fr) * LDC + wc * 32 + n * 16 + fq * 4) = acc[ai][bj][m][n];
;                 __syncthreads();
;                 gemm_epilogue<MODE>(Cs, brow + ai * 128, bcol + bj * 128, ep);
;                 __syncthreads();
	ds_write_b128 v146, v[32:35]
	ds_write_b128 v146, v[36:39] offset:64
	ds_write_b128 v146, v[40:43] offset:8448
	ds_write_b128 v146, v[44:47] offset:8512
	ds_write_b128 v146, v[48:51] offset:16896
	ds_write_b128 v146, v[52:55] offset:16960
	ds_write_b128 v146, v[56:59] offset:25344
	ds_write_b128 v146, v[60:63] offset:25408
	v_mov_b32_e32 v32, v250
	s_waitcnt lgkmcnt(0)
	s_barrier
	s_nop 0
	v_ashrrev_i32_e32 v34, 4, v32
	v_add_u32_e32 v40, s23, v34
	v_lshlrev_b32_e32 v32, 3, v32
	v_ashrrev_i32_e32 v41, 31, v40
	v_and_b32_e32 v44, 0x78, v32
	v_lshlrev_b64 v[32:33], 11, v[40:41]
	v_lshlrev_b32_e32 v35, 2, v44
	v_lshl_add_u64 v[36:37], s[76:77], 0, v[32:33]
	v_mul_lo_u32 v32, v34, s35
	v_add3_u32 v45, 16, v35, v32
	ds_read_b128 v[32:35], v45
	v_lshl_add_u64 v[42:43], v[36:37], 0, s[0:1]
	ds_read_b128 v[36:39], v45 offset:16
	v_lshlrev_b32_e32 v212, 1, v44
	v_lshl_add_u64 v[42:43], v[42:43], 0, v[212:213]
	s_waitcnt lgkmcnt(1)
	v_cvt_pk_bf16_f32 v32, v32, v33
	v_cvt_pk_bf16_f32 v33, v34, v35
	s_waitcnt lgkmcnt(0)
	v_cvt_pk_bf16_f32 v34, v36, v37
	v_cvt_pk_bf16_f32 v35, v38, v39
	global_store_dwordx4 v[42:43], v[32:35], off sc1
	s_nop 1
	v_add_u32_e32 v32, 32, v40
	v_ashrrev_i32_e32 v33, 31, v32
	v_lshlrev_b64 v[36:37], 11, v[32:33]
	ds_read_b128 v[32:35], v45 offset:16896
	v_lshl_add_u64 v[42:43], s[76:77], 0, v[36:37]
	ds_read_b128 v[36:39], v45 offset:16912
	v_lshl_add_u64 v[42:43], v[42:43], 0, s[0:1]
	v_lshl_add_u64 v[42:43], v[42:43], 0, v[212:213]
	s_waitcnt lgkmcnt(1)
	v_cvt_pk_bf16_f32 v32, v32, v33
	v_cvt_pk_bf16_f32 v33, v34, v35
	s_waitcnt lgkmcnt(0)
	v_cvt_pk_bf16_f32 v34, v36, v37
	v_cvt_pk_bf16_f32 v35, v38, v39
	global_store_dwordx4 v[42:43], v[32:35], off sc1
	s_nop 1
	v_add_u32_e32 v32, 64, v40
	v_ashrrev_i32_e32 v33, 31, v32
	v_lshlrev_b64 v[36:37], 11, v[32:33]
	ds_read_b128 v[32:35], v45 offset:33792
	v_lshl_add_u64 v[42:43], s[76:77], 0, v[36:37]
	ds_read_b128 v[36:39], v45 offset:33808
	v_lshl_add_u64 v[42:43], v[42:43], 0, s[0:1]
	v_lshl_add_u64 v[42:43], v[42:43], 0, v[212:213]
	s_waitcnt lgkmcnt(1)
	v_cvt_pk_bf16_f32 v32, v32, v33
	v_cvt_pk_bf16_f32 v33, v34, v35
	s_waitcnt lgkmcnt(0)
	v_cvt_pk_bf16_f32 v34, v36, v37
	v_cvt_pk_bf16_f32 v35, v38, v39
	global_store_dwordx4 v[42:43], v[32:35], off sc1
	s_nop 1
	v_add_u32_e32 v32, 0x60, v40
	v_ashrrev_i32_e32 v33, 31, v32
	v_lshlrev_b64 v[36:37], 11, v[32:33]
	ds_read_b128 v[32:35], v45 offset:50688
	v_lshl_add_u64 v[40:41], s[76:77], 0, v[36:37]
	ds_read_b128 v[36:39], v45 offset:50704
	v_lshl_add_u64 v[40:41], v[40:41], 0, s[0:1]
	v_lshl_add_u64 v[40:41], v[40:41], 0, v[212:213]
	s_waitcnt lgkmcnt(1)
	v_cvt_pk_bf16_f32 v32, v32, v33
	v_cvt_pk_bf16_f32 v33, v34, v35
	s_waitcnt lgkmcnt(0)
	v_cvt_pk_bf16_f32 v34, v36, v37
	v_cvt_pk_bf16_f32 v35, v38, v39
	global_store_dwordx4 v[40:41], v[32:35], off sc1
	s_barrier
	ds_write_b128 v146, v[0:3]
	ds_write_b128 v146, v[4:7] offset:64
	ds_write_b128 v146, v[8:11] offset:8448
	ds_write_b128 v146, v[12:15] offset:8512
	ds_write_b128 v146, v[16:19] offset:16896
	ds_write_b128 v146, v[20:23] offset:16960
	ds_write_b128 v146, v[24:27] offset:25344
	ds_write_b128 v146, v[28:31] offset:25408
	v_mov_b32_e32 v0, v250
	s_waitcnt lgkmcnt(0)
	s_barrier
	s_nop 0
	v_ashrrev_i32_e32 v2, 4, v0
	v_add_u32_e32 v8, s23, v2
	v_lshlrev_b32_e32 v0, 3, v0
	v_ashrrev_i32_e32 v9, 31, v8
	v_and_b32_e32 v12, 0x78, v0
	v_lshlrev_b64 v[0:1], 11, v[8:9]
	v_lshlrev_b32_e32 v3, 2, v12
	v_lshl_add_u64 v[4:5], s[76:77], 0, v[0:1]
	v_mul_lo_u32 v0, v2, s35
	v_add3_u32 v13, 16, v3, v0
	ds_read_b128 v[0:3], v13
	v_lshl_add_u64 v[10:11], v[4:5], 0, s[0:1]
	ds_read_b128 v[4:7], v13 offset:16
	v_lshlrev_b32_e32 v212, 1, v12
	v_lshl_add_u64 v[10:11], v[10:11], 0, v[212:213]
	s_waitcnt lgkmcnt(1)
	v_cvt_pk_bf16_f32 v0, v0, v1
	v_cvt_pk_bf16_f32 v1, v2, v3
	s_waitcnt lgkmcnt(0)
	v_cvt_pk_bf16_f32 v2, v4, v5
	v_cvt_pk_bf16_f32 v3, v6, v7
	global_store_dwordx4 v[10:11], v[0:3], off offset:256 sc1
	s_nop 1
	v_add_u32_e32 v0, 32, v8
	v_ashrrev_i32_e32 v1, 31, v0
	v_lshlrev_b64 v[4:5], 11, v[0:1]
	ds_read_b128 v[0:3], v13 offset:16896
	v_lshl_add_u64 v[10:11], s[76:77], 0, v[4:5]
	ds_read_b128 v[4:7], v13 offset:16912
	v_lshl_add_u64 v[10:11], v[10:11], 0, s[0:1]
	v_lshl_add_u64 v[10:11], v[10:11], 0, v[212:213]
	s_waitcnt lgkmcnt(1)
	v_cvt_pk_bf16_f32 v0, v0, v1
	v_cvt_pk_bf16_f32 v1, v2, v3
	s_waitcnt lgkmcnt(0)
	v_cvt_pk_bf16_f32 v2, v4, v5
	v_cvt_pk_bf16_f32 v3, v6, v7
	global_store_dwordx4 v[10:11], v[0:3], off offset:256 sc1
	s_nop 1
	v_add_u32_e32 v0, 64, v8
	v_ashrrev_i32_e32 v1, 31, v0
	v_lshlrev_b64 v[4:5], 11, v[0:1]
	ds_read_b128 v[0:3], v13 offset:33792
	v_lshl_add_u64 v[10:11], s[76:77], 0, v[4:5]
	ds_read_b128 v[4:7], v13 offset:33808
	v_lshl_add_u64 v[10:11], v[10:11], 0, s[0:1]
	v_lshl_add_u64 v[10:11], v[10:11], 0, v[212:213]
	s_waitcnt lgkmcnt(1)
	v_cvt_pk_bf16_f32 v0, v0, v1
	v_cvt_pk_bf16_f32 v1, v2, v3
	s_waitcnt lgkmcnt(0)
	v_cvt_pk_bf16_f32 v2, v4, v5
	v_cvt_pk_bf16_f32 v3, v6, v7
	global_store_dwordx4 v[10:11], v[0:3], off offset:256 sc1
	s_nop 1
	v_add_u32_e32 v0, 0x60, v8
	v_ashrrev_i32_e32 v1, 31, v0
	v_lshlrev_b64 v[4:5], 11, v[0:1]
	ds_read_b128 v[0:3], v13 offset:50688
	v_lshl_add_u64 v[8:9], s[76:77], 0, v[4:5]
	ds_read_b128 v[4:7], v13 offset:50704
	v_lshl_add_u64 v[8:9], v[8:9], 0, s[0:1]
	s_mul_i32 s0, s22, s18
	s_add_i32 s0, s0, s19
	v_lshl_add_u64 v[8:9], v[8:9], 0, v[212:213]
	s_waitcnt lgkmcnt(1)
	v_cvt_pk_bf16_f32 v0, v0, v1
	v_cvt_pk_bf16_f32 v1, v2, v3
	s_waitcnt lgkmcnt(0)
	v_cvt_pk_bf16_f32 v2, v4, v5
	v_cvt_pk_bf16_f32 v3, v6, v7
	s_cmpk_lt_i32 s0, 0x200
	global_store_dwordx4 v[8:9], v[0:3], off offset:256 sc1
	s_barrier
	s_cbranch_scc0 .LBB0_491

; DI void stb8(bf16_t* p, const F8& f) { *(uint4*)p = pack8(f); }
; template <int MODE>
; DI void gemm_epilogue(const float* Cs, int m0, int n0, const Epi& ep) {
;     ...
;     if (MODE == 0) {
; #pragma unroll
;         for (int it = 0; it < 4; ++it) {
;             const int row = (tid >> 4) + 32 * it, cc = (tid & 15) * 8;
;             stb8(ep.b0 + (size_t)(m0 + row) * ep.ld + n0 + cc, ldf8(Cs + row * LDC + cc));
;         }
; template <int MODE>
; DI void gemm_phase(const bf16_t* __restrict__ A, const bf16_t* __restrict__ Bt, int M, int N, int K, const Epi& ep) {
;     ...
; #pragma unroll
;         for (int ai = 0; ai < 2; ++ai)
; #pragma unroll
;             for (int bj = 0; bj < 2; ++bj) {
; #pragma unroll
;                 for (int m = 0; m < 4; ++m)
; #pragma unroll
;                     for (int n = 0; n < 2; ++n)
;                         *(f32x4*)(Cs + (wr * 64 + m * 16 + fr) * LDC + wc * 32 + n * 16 + fq * 4) = acc[ai][bj][m][n];
;                 __syncthreads();
;                 gemm_epilogue<MODE>(Cs, brow + ai * 128, bcol + bj * 128, ep);
;                 __syncthreads();
.LBB0_550:
	s_or_b64 exec, exec, s[6:7]
	v_mov_b32_e32 v64, v250
	s_waitcnt vmcnt(0)
	s_barrier
	ds_write_b128 v146, v[96:99]
	ds_write_b128 v146, v[100:103] offset:64
	ds_write_b128 v146, v[104:107] offset:8448
	ds_write_b128 v146, v[108:111] offset:8512
	ds_write_b128 v146, v[112:115] offset:16896
	ds_write_b128 v146, v[116:119] offset:16960
	ds_write_b128 v146, v[120:123] offset:25344
	ds_write_b128 v146, v[124:127] offset:25408
	s_waitcnt lgkmcnt(0)
	s_barrier
	v_mov_b64_e32 v[96:97], s[84:85]
	v_ashrrev_i32_e32 v65, 4, v64
	v_lshlrev_b32_e32 v64, 3, v64
	v_and_b32_e32 v104, 0x78, v64
	v_lshlrev_b32_e32 v64, 2, v104
	v_add_u32_e32 v105, s22, v65
	s_movk_i32 s23, 0x1200
	v_mul_lo_u32 v65, v65, s35
	v_mad_i64_i32 v[98:99], s[6:7], v105, s23, v[96:97]
	s_lshl_b64 s[0:1], s[0:1], 1
	v_add3_u32 v106, 16, v64, v65
	ds_read_b128 v[64:67], v106
	v_lshl_add_u64 v[102:103], v[98:99], 0, s[0:1]
	ds_read_b128 v[98:101], v106 offset:16
	v_lshlrev_b32_e32 v212, 1, v104
	v_lshl_add_u64 v[102:103], v[102:103], 0, v[212:213]
	s_waitcnt lgkmcnt(1)
	v_cvt_pk_bf16_f32 v64, v64, v65
	v_cvt_pk_bf16_f32 v65, v66, v67
	s_waitcnt lgkmcnt(0)
	v_cvt_pk_bf16_f32 v66, v98, v99
	v_cvt_pk_bf16_f32 v67, v100, v101
	v_add_u32_e32 v98, 32, v105
	global_store_dwordx4 v[102:103], v[64:67], off sc1
	ds_read_b128 v[64:67], v106 offset:16896
	v_mad_i64_i32 v[102:103], s[6:7], v98, s23, v[96:97]
	ds_read_b128 v[98:101], v106 offset:16912
	v_lshl_add_u64 v[102:103], v[102:103], 0, s[0:1]
	v_lshl_add_u64 v[102:103], v[102:103], 0, v[212:213]
	s_waitcnt lgkmcnt(1)
	v_cvt_pk_bf16_f32 v64, v64, v65
	v_cvt_pk_bf16_f32 v65, v66, v67
	s_waitcnt lgkmcnt(0)
	v_cvt_pk_bf16_f32 v66, v98, v99
	v_cvt_pk_bf16_f32 v67, v100, v101
	v_add_u32_e32 v98, 64, v105
	global_store_dwordx4 v[102:103], v[64:67], off sc1
	ds_read_b128 v[64:67], v106 offset:33792
	v_mad_i64_i32 v[102:103], s[6:7], v98, s23, v[96:97]
	ds_read_b128 v[98:101], v106 offset:33808
	v_lshl_add_u64 v[102:103], v[102:103], 0, s[0:1]
	v_lshl_add_u64 v[102:103], v[102:103], 0, v[212:213]
	s_waitcnt lgkmcnt(1)
	v_cvt_pk_bf16_f32 v64, v64, v65
	v_cvt_pk_bf16_f32 v65, v66, v67
	s_waitcnt lgkmcnt(0)
	v_cvt_pk_bf16_f32 v66, v98, v99
	v_cvt_pk_bf16_f32 v67, v100, v101
	v_add_u32_e32 v98, 0x60, v105
	global_store_dwordx4 v[102:103], v[64:67], off sc1
	ds_read_b128 v[64:67], v106 offset:50688
	v_mad_i64_i32 v[102:103], s[6:7], v98, s23, v[96:97]
	ds_read_b128 v[98:101], v106 offset:50704
	v_lshl_add_u64 v[102:103], v[102:103], 0, s[0:1]
	v_lshl_add_u64 v[102:103], v[102:103], 0, v[212:213]
	s_waitcnt lgkmcnt(1)
	v_cvt_pk_bf16_f32 v64, v64, v65
	v_cvt_pk_bf16_f32 v65, v66, v67
	s_waitcnt lgkmcnt(0)
	v_cvt_pk_bf16_f32 v66, v98, v99
	v_cvt_pk_bf16_f32 v67, v100, v101
	global_store_dwordx4 v[102:103], v[64:67], off sc1
	s_barrier
	s_nop 0
	v_mov_b32_e32 v64, v250
	ds_write_b128 v146, v[160:163]
	ds_write_b128 v146, v[68:71] offset:64
	ds_write_b128 v146, v[72:75] offset:8448
	ds_write_b128 v146, v[76:79] offset:8512
	ds_write_b128 v146, v[80:83] offset:16896
	ds_write_b128 v146, v[84:87] offset:16960
	ds_write_b128 v146, v[88:91] offset:25344
	ds_write_b128 v146, v[92:95] offset:25408
	s_waitcnt lgkmcnt(0)
	s_barrier
	s_add_i32 s18, s18, 1
	v_ashrrev_i32_e32 v65, 4, v64
	v_lshlrev_b32_e32 v64, 3, v64
	v_and_b32_e32 v74, 0x78, v64
	v_lshlrev_b32_e32 v64, 2, v74
	v_add_u32_e32 v75, s22, v65
	v_mul_lo_u32 v65, v65, s35
	v_mad_i64_i32 v[68:69], s[6:7], v75, s23, v[96:97]
	v_add3_u32 v76, 16, v64, v65
	ds_read_b128 v[64:67], v76
	v_lshl_add_u64 v[72:73], v[68:69], 0, s[0:1]
	ds_read_b128 v[68:71], v76 offset:16
	v_lshlrev_b32_e32 v212, 1, v74
	v_lshl_add_u64 v[72:73], v[72:73], 0, v[212:213]
	s_waitcnt lgkmcnt(1)
	v_cvt_pk_bf16_f32 v64, v64, v65
	v_cvt_pk_bf16_f32 v65, v66, v67
	s_waitcnt lgkmcnt(0)
	v_cvt_pk_bf16_f32 v66, v68, v69
	v_cvt_pk_bf16_f32 v67, v70, v71
	v_add_u32_e32 v68, 32, v75
	global_store_dwordx4 v[72:73], v[64:67], off offset:256 sc1
	ds_read_b128 v[64:67], v76 offset:16896
	v_mad_i64_i32 v[72:73], s[6:7], v68, s23, v[96:97]
	ds_read_b128 v[68:71], v76 offset:16912
	v_lshl_add_u64 v[72:73], v[72:73], 0, s[0:1]
	v_lshl_add_u64 v[72:73], v[72:73], 0, v[212:213]
	s_waitcnt lgkmcnt(1)
	v_cvt_pk_bf16_f32 v64, v64, v65
	v_cvt_pk_bf16_f32 v65, v66, v67
	s_waitcnt lgkmcnt(0)
	v_cvt_pk_bf16_f32 v66, v68, v69
	v_cvt_pk_bf16_f32 v67, v70, v71
	v_add_u32_e32 v68, 64, v75
	global_store_dwordx4 v[72:73], v[64:67], off offset:256 sc1
	ds_read_b128 v[64:67], v76 offset:33792
	v_mad_i64_i32 v[72:73], s[6:7], v68, s23, v[96:97]
	ds_read_b128 v[68:71], v76 offset:33808
	v_lshl_add_u64 v[72:73], v[72:73], 0, s[0:1]
	v_lshl_add_u64 v[72:73], v[72:73], 0, v[212:213]
	s_waitcnt lgkmcnt(1)
	v_cvt_pk_bf16_f32 v64, v64, v65
	v_cvt_pk_bf16_f32 v65, v66, v67
	s_waitcnt lgkmcnt(0)
	v_cvt_pk_bf16_f32 v66, v68, v69
	v_cvt_pk_bf16_f32 v67, v70, v71
	v_add_u32_e32 v68, 0x60, v75
	global_store_dwordx4 v[72:73], v[64:67], off offset:256 sc1
	ds_read_b128 v[64:67], v76 offset:50688
	v_mad_i64_i32 v[72:73], s[6:7], v68, s23, v[96:97]
	ds_read_b128 v[68:71], v76 offset:50704
	v_lshl_add_u64 v[72:73], v[72:73], 0, s[0:1]
	v_lshl_add_u64 v[72:73], v[72:73], 0, v[212:213]
	s_waitcnt lgkmcnt(1)
	v_cvt_pk_bf16_f32 v64, v64, v65
	v_cvt_pk_bf16_f32 v65, v66, v67
	s_waitcnt lgkmcnt(0)
	v_cvt_pk_bf16_f32 v66, v68, v69
	v_cvt_pk_bf16_f32 v67, v70, v71
	global_store_dwordx4 v[72:73], v[64:67], off offset:256 sc1
	s_barrier
; DI void stb8(bf16_t* p, const F8& f) { *(uint4*)p = pack8(f); }
; template <int MODE>
; DI void gemm_epilogue(const float* Cs, int m0, int n0, const Epi& ep) {
;     ...
;     if (MODE == 0) {
; #pragma unroll
;         for (int it = 0; it < 4; ++it) {
;             const int row = (tid >> 4) + 32 * it, cc = (tid & 15) * 8;
;             stb8(ep.b0 + (size_t)(m0 + row) * ep.ld + n0 + cc, ldf8(Cs + row * LDC + cc));
;         }
; template <int MODE>
; DI void gemm_phase(const bf16_t* __restrict__ A, const bf16_t* __restrict__ Bt, int M, int N, int K, const Epi& ep) {
;     ...
; #pragma unroll
;         for (int ai = 0; ai < 2; ++ai)
; #pragma unroll
;             for (int bj = 0; bj < 2; ++bj) {
; #pragma unroll
;                 for (int m = 0; m < 4; ++m)
; #pragma unroll
;                     for (int n = 0; n < 2; ++n)
;                         *(f32x4*)(Cs + (wr * 64 + m * 16 + fr) * LDC + wc * 32 + n * 16 + fq * 4) = acc[ai][bj][m][n];
;                 __syncthreads();
;                 gemm_epilogue<MODE>(Cs, brow + ai * 128, bcol + bj * 128, ep);
;                 __syncthreads();
	ds_write_b128 v146, v[32:35]
	ds_write_b128 v146, v[36:39] offset:64
	ds_write_b128 v146, v[40:43] offset:8448
	ds_write_b128 v146, v[44:47] offset:8512
	ds_write_b128 v146, v[48:51] offset:16896
	ds_write_b128 v146, v[52:55] offset:16960
	ds_write_b128 v146, v[56:59] offset:25344
	ds_write_b128 v146, v[60:63] offset:25408
	v_mov_b32_e32 v32, v250
	s_waitcnt lgkmcnt(0)
	s_barrier
	s_nop 0
	v_ashrrev_i32_e32 v33, 4, v32
	v_lshlrev_b32_e32 v32, 3, v32
	v_and_b32_e32 v42, 0x78, v32
	v_lshlrev_b32_e32 v32, 2, v42
	v_add_u32_e32 v43, s19, v33
	v_mul_lo_u32 v33, v33, s35
	v_mad_i64_i32 v[36:37], s[6:7], v43, s23, v[96:97]
	v_add3_u32 v44, 16, v32, v33
	ds_read_b128 v[32:35], v44
	v_lshl_add_u64 v[40:41], v[36:37], 0, s[0:1]
	ds_read_b128 v[36:39], v44 offset:16
	v_lshlrev_b32_e32 v212, 1, v42
	v_lshl_add_u64 v[40:41], v[40:41], 0, v[212:213]
	s_waitcnt lgkmcnt(1)
	v_cvt_pk_bf16_f32 v32, v32, v33
	v_cvt_pk_bf16_f32 v33, v34, v35
	s_waitcnt lgkmcnt(0)
	v_cvt_pk_bf16_f32 v34, v36, v37
	v_cvt_pk_bf16_f32 v35, v38, v39
	v_add_u32_e32 v36, 32, v43
	global_store_dwordx4 v[40:41], v[32:35], off sc1
	ds_read_b128 v[32:35], v44 offset:16896
	v_mad_i64_i32 v[40:41], s[6:7], v36, s23, v[96:97]
	ds_read_b128 v[36:39], v44 offset:16912
	v_lshl_add_u64 v[40:41], v[40:41], 0, s[0:1]
	v_lshl_add_u64 v[40:41], v[40:41], 0, v[212:213]
	s_waitcnt lgkmcnt(1)
	v_cvt_pk_bf16_f32 v32, v32, v33
	v_cvt_pk_bf16_f32 v33, v34, v35
	s_waitcnt lgkmcnt(0)
	v_cvt_pk_bf16_f32 v34, v36, v37
	v_cvt_pk_bf16_f32 v35, v38, v39
	v_add_u32_e32 v36, 64, v43
	global_store_dwordx4 v[40:41], v[32:35], off sc1
	ds_read_b128 v[32:35], v44 offset:33792
	v_mad_i64_i32 v[40:41], s[6:7], v36, s23, v[96:97]
	ds_read_b128 v[36:39], v44 offset:33808
	v_lshl_add_u64 v[40:41], v[40:41], 0, s[0:1]
	v_lshl_add_u64 v[40:41], v[40:41], 0, v[212:213]
	s_waitcnt lgkmcnt(1)
	v_cvt_pk_bf16_f32 v32, v32, v33
	v_cvt_pk_bf16_f32 v33, v34, v35
	s_waitcnt lgkmcnt(0)
	v_cvt_pk_bf16_f32 v34, v36, v37
	v_cvt_pk_bf16_f32 v35, v38, v39
	v_add_u32_e32 v36, 0x60, v43
	global_store_dwordx4 v[40:41], v[32:35], off sc1
	ds_read_b128 v[32:35], v44 offset:50688
	v_mad_i64_i32 v[40:41], s[6:7], v36, s23, v[96:97]
	ds_read_b128 v[36:39], v44 offset:50704
	v_lshl_add_u64 v[40:41], v[40:41], 0, s[0:1]
	v_lshl_add_u64 v[40:41], v[40:41], 0, v[212:213]
	s_waitcnt lgkmcnt(1)
	v_cvt_pk_bf16_f32 v32, v32, v33
	v_cvt_pk_bf16_f32 v33, v34, v35
	s_waitcnt lgkmcnt(0)
	v_cvt_pk_bf16_f32 v34, v36, v37
	v_cvt_pk_bf16_f32 v35, v38, v39
	global_store_dwordx4 v[40:41], v[32:35], off sc1
	s_barrier
	ds_write_b128 v146, v[0:3]
	ds_write_b128 v146, v[4:7] offset:64
	ds_write_b128 v146, v[8:11] offset:8448
	ds_write_b128 v146, v[12:15] offset:8512
	ds_write_b128 v146, v[16:19] offset:16896
	ds_write_b128 v146, v[20:23] offset:16960
	ds_write_b128 v146, v[24:27] offset:25344
	ds_write_b128 v146, v[28:31] offset:25408
	v_mov_b32_e32 v0, v250
	s_waitcnt lgkmcnt(0)
	s_barrier
	s_nop 0
	v_ashrrev_i32_e32 v1, 4, v0
	v_lshlrev_b32_e32 v0, 3, v0
	v_and_b32_e32 v10, 0x78, v0
	v_lshlrev_b32_e32 v0, 2, v10
	v_add_u32_e32 v11, s19, v1
	v_mul_lo_u32 v1, v1, s35
	v_mad_i64_i32 v[4:5], s[6:7], v11, s23, v[96:97]
	v_add3_u32 v12, 16, v0, v1
	ds_read_b128 v[0:3], v12
	v_lshl_add_u64 v[8:9], v[4:5], 0, s[0:1]
	ds_read_b128 v[4:7], v12 offset:16
	v_lshlrev_b32_e32 v212, 1, v10
	v_lshl_add_u64 v[8:9], v[8:9], 0, v[212:213]
	s_waitcnt lgkmcnt(1)
	v_cvt_pk_bf16_f32 v0, v0, v1
	v_cvt_pk_bf16_f32 v1, v2, v3
	s_waitcnt lgkmcnt(0)
	v_cvt_pk_bf16_f32 v2, v4, v5
	v_cvt_pk_bf16_f32 v3, v6, v7
	v_add_u32_e32 v4, 32, v11
	global_store_dwordx4 v[8:9], v[0:3], off offset:256 sc1
	ds_read_b128 v[0:3], v12 offset:16896
	v_mad_i64_i32 v[8:9], s[6:7], v4, s23, v[96:97]
	ds_read_b128 v[4:7], v12 offset:16912
	v_lshl_add_u64 v[8:9], v[8:9], 0, s[0:1]
	v_lshl_add_u64 v[8:9], v[8:9], 0, v[212:213]
	s_waitcnt lgkmcnt(1)
	v_cvt_pk_bf16_f32 v0, v0, v1
	v_cvt_pk_bf16_f32 v1, v2, v3
	s_waitcnt lgkmcnt(0)
	v_cvt_pk_bf16_f32 v2, v4, v5
	v_cvt_pk_bf16_f32 v3, v6, v7
	v_add_u32_e32 v4, 64, v11
	global_store_dwordx4 v[8:9], v[0:3], off offset:256 sc1
	ds_read_b128 v[0:3], v12 offset:33792
	v_mad_i64_i32 v[8:9], s[6:7], v4, s23, v[96:97]
	ds_read_b128 v[4:7], v12 offset:33808
	v_lshl_add_u64 v[8:9], v[8:9], 0, s[0:1]
	v_lshl_add_u64 v[8:9], v[8:9], 0, v[212:213]
	s_waitcnt lgkmcnt(1)
	v_cvt_pk_bf16_f32 v0, v0, v1
	v_cvt_pk_bf16_f32 v1, v2, v3
	s_waitcnt lgkmcnt(0)
	v_cvt_pk_bf16_f32 v2, v4, v5
	v_cvt_pk_bf16_f32 v3, v6, v7
	v_add_u32_e32 v4, 0x60, v11
	global_store_dwordx4 v[8:9], v[0:3], off offset:256 sc1
	ds_read_b128 v[0:3], v12 offset:50688
	v_mad_i64_i32 v[8:9], s[6:7], v4, s23, v[96:97]
	ds_read_b128 v[4:7], v12 offset:50704
	v_lshl_add_u64 v[8:9], v[8:9], 0, s[0:1]
	s_mul_i32 s0, s18, s14
	s_add_i32 s0, s0, s15
	v_lshl_add_u64 v[8:9], v[8:9], 0, v[212:213]
	s_waitcnt lgkmcnt(1)
	v_cvt_pk_bf16_f32 v0, v0, v1
	v_cvt_pk_bf16_f32 v1, v2, v3
	s_waitcnt lgkmcnt(0)
	v_cvt_pk_bf16_f32 v2, v4, v5
	v_cvt_pk_bf16_f32 v3, v6, v7
	s_cmpk_lt_i32 s0, 0x492
	global_store_dwordx4 v[8:9], v[0:3], off offset:256 sc1
	s_barrier
	s_cbranch_scc0 .LBB0_561

; DI F8 unpack8(uint4 u) { F8 r; r.v[0] = lo16(u.x); r.v[1] = hi16(u.x); r.v[2] = lo16(u.y); r.v[3] = hi16(u.y); r.v[4] = lo16(u.z); r.v[5] = hi16(u.z); r.v[6] = lo16(u.w); r.v[7] = hi16(u.w); return r; }
; DI void stf8(float* p, const F8& f) { *(float4*)p = make_float4(f.v[0], f.v[1], f.v[2], f.v[3]); *(float4*)(p + 4) = make_float4(f.v[4], f.v[5], f.v[6], f.v[7]); }
; DI void stb8(bf16_t* p, const F8& f) { *(uint4*)p = pack8(f); }
; DI void even_elem(const Params& p, int e) {
;     ...
;                 if (lane < 2) {
;                     const F8 a1 = unpack8(x1[q]), a2 = unpack8(x2[q]);
;                     F8 o1, o2; const float2* rp = ROPE + apos * 16 + lane * 8;
; #pragma unroll
;                     for (int k = 0; k < 8; ++k) { const float2 cs = rp[k]; o1.v[k] = a1.v[k] * cs.x - a2.v[k] * cs.y; o2.v[k] = a2.v[k] * cs.x + a1.v[k] * cs.y; }
;                     float* ko = sq < 4 ? p.out + O_PKR + (((size_t)e * 4 + sq) * 8192 + pos) * 32 : p.out + O_SKR + (((size_t)e * 8 + (sq - 4)) * 64 + pos) * 32;
;                     stf8(ko + lane * 8, o1); stf8(ko + 16 + lane * 8, o2);
; #pragma unroll
;                     for (int h = 0; h < 8; ++h) { stb8(KB + (size_t)kvr * 768 + h * 96 + 64 + lane * 8, o1); stb8(KB + (size_t)kvr * 768 + h * 96 + 80 + lane * 8, o2); }
.LBB0_617:
	s_or_b64 exec, exec, s[44:45]
	v_lshlrev_b32_e32 v42, 16, v20
	v_and_b32_e32 v43, 0xffff0000, v20
	v_lshlrev_b32_e32 v54, 16, v19
	v_and_b32_e32 v55, 0xffff0000, v19
	s_waitcnt vmcnt(0)
	v_mov_b32_e32 v19, v38
	v_mov_b32_e32 v38, v37
	v_lshlrev_b32_e32 v46, 16, v21
	v_and_b32_e32 v47, 0xffff0000, v21
	v_lshlrev_b32_e32 v20, 16, v16
	v_and_b32_e32 v21, 0xffff0000, v16
	v_lshlrev_b32_e32 v52, 16, v18
	v_and_b32_e32 v53, 0xffff0000, v18
	v_mov_b32_e32 v18, v36
	v_pk_mul_f32 v[36:37], v[38:39], v[42:43]
	v_lshlrev_b32_e32 v48, 16, v22
	v_and_b32_e32 v49, 0xffff0000, v22
	v_lshlrev_b32_e32 v50, 16, v23
	v_and_b32_e32 v51, 0xffff0000, v23
	v_lshlrev_b32_e32 v22, 16, v17
	v_and_b32_e32 v23, 0xffff0000, v17
	v_pk_mul_f32 v[16:17], v[38:39], v[20:21]
	v_pk_fma_f32 v[20:21], v[18:19], v[20:21], v[36:37]
	v_mov_b32_e32 v37, v34
	v_mov_b32_e32 v34, v33
	v_mov_b32_e32 v36, v32
	v_pk_mul_f32 v[32:33], v[34:35], v[46:47]
	v_pk_fma_f32 v[16:17], v[18:19], v[42:43], v[16:17] neg_lo:[0,0,1] neg_hi:[0,0,1]
	v_pk_mul_f32 v[18:19], v[34:35], v[22:23]
	v_pk_fma_f32 v[22:23], v[36:37], v[22:23], v[32:33]
	v_mov_b32_e32 v33, v30
	v_mov_b32_e32 v30, v29
	v_mov_b32_e32 v35, v26
	v_mov_b32_e32 v26, v25
	v_mov_b32_e32 v32, v28
	v_pk_mul_f32 v[28:29], v[30:31], v[52:53]
	v_pk_mul_f32 v[30:31], v[30:31], v[48:49]
	v_mov_b32_e32 v34, v24
	v_pk_mul_f32 v[24:25], v[26:27], v[54:55]
	v_pk_fma_f32 v[28:29], v[32:33], v[48:49], v[28:29] neg_lo:[0,0,1] neg_hi:[0,0,1]
	v_pk_fma_f32 v[32:33], v[32:33], v[52:53], v[30:31]
	v_pk_fma_f32 v[30:31], v[34:35], v[50:51], v[24:25] neg_lo:[0,0,1] neg_hi:[0,0,1]
	v_pk_mul_f32 v[24:25], v[26:27], v[50:51]
	v_pk_fma_f32 v[18:19], v[36:37], v[46:47], v[18:19] neg_lo:[0,0,1] neg_hi:[0,0,1]
	v_pk_fma_f32 v[34:35], v[34:35], v[54:55], v[24:25]
	v_lshl_add_u64 v[24:25], v[136:137], 2, v[44:45]
	global_store_dwordx4 v[24:25], v[16:19], off sc1
	global_store_dwordx4 v[24:25], v[28:31], off offset:16 sc1
	global_store_dwordx4 v[24:25], v[20:23], off offset:64 sc1
	global_store_dwordx4 v[24:25], v[32:35], off offset:80 sc1
	v_cvt_pk_bf16_f32 v16, v16, v17
	v_cvt_pk_bf16_f32 v17, v18, v19
	v_cvt_pk_bf16_f32 v18, v28, v29
	v_cvt_pk_bf16_f32 v19, v30, v31
	v_mad_i64_i32 v[24:25], s[44:45], v40, s97, v[62:63]
	v_cvt_pk_bf16_f32 v20, v20, v21
	v_cvt_pk_bf16_f32 v21, v22, v23
	v_cvt_pk_bf16_f32 v22, v32, v33
	v_cvt_pk_bf16_f32 v23, v34, v35
	global_store_dwordx4 v[24:25], v[16:19], off offset:128 sc1
	global_store_dwordx4 v[24:25], v[20:23], off offset:160 sc1
	global_store_dwordx4 v[24:25], v[16:19], off offset:320 sc1
	global_store_dwordx4 v[24:25], v[20:23], off offset:352 sc1
	global_store_dwordx4 v[24:25], v[16:19], off offset:512 sc1
	global_store_dwordx4 v[24:25], v[20:23], off offset:544 sc1
	global_store_dwordx4 v[24:25], v[16:19], off offset:704 sc1
	global_store_dwordx4 v[24:25], v[20:23], off offset:736 sc1
	global_store_dwordx4 v[24:25], v[16:19], off offset:896 sc1
	global_store_dwordx4 v[24:25], v[20:23], off offset:928 sc1
	global_store_dwordx4 v[24:25], v[16:19], off offset:1088 sc1
	global_store_dwordx4 v[24:25], v[20:23], off offset:1120 sc1
	global_store_dwordx4 v[24:25], v[16:19], off offset:1280 sc1
	global_store_dwordx4 v[24:25], v[20:23], off offset:1312 sc1
	global_store_dwordx4 v[24:25], v[16:19], off offset:1472 sc1
	global_store_dwordx4 v[24:25], v[20:23], off offset:1504 sc1

; DI F8 unpack8(uint4 u) { F8 r; r.v[0] = lo16(u.x); r.v[1] = hi16(u.x); r.v[2] = lo16(u.y); r.v[3] = hi16(u.y); r.v[4] = lo16(u.z); r.v[5] = hi16(u.z); r.v[6] = lo16(u.w); r.v[7] = hi16(u.w); return r; }
; DI void stb8(bf16_t* p, const F8& f) { *(uint4*)p = pack8(f); }
; DI float wsum(float v) { v += __shfl_xor(v, 32); v += __shfl_xor(v, 16); v += __shfl_xor(v, 8); v += __shfl_xor(v, 4); v += __shfl_xor(v, 2); v += __shfl_xor(v, 1); return v; }
; DI void rowinfo(int r, int& sq, int& pos, int& len) { if (r < MP) { sq = r >> 13; pos = r & 8191; len = 8192; } else { sq = 4 + ((r - MP) >> 6); pos = r & 63; len = 64; } }
; DI void even_elem(const Params& p, int e) {
;     ...
;                 xq[q] = *(const uint4*)(hr + lq * 8); xkv[q] = *(const uint4*)(hr + 384 + lk * 8); x1[q] = *(const uint4*)(hr + 640 + lr * 8); x2[q] = *(const uint4*)(hr + 656 + lr * 8); }
; #pragma unroll
;             for (int q = 0; q < 2; ++q) {
;                 if (q == 1 && !two) break;
;                 const int r = rr[q]; int sq, pos, len; rowinfo(r, sq, pos, len);
;                 const int kvr = kvrow_of(r), apos = sq >= 4 ? pos + 2048 : pos;
;                 { F8 x = unpack8(xq[q]); float ss = 0.f;
;                   if (lane < 48) { for (int k = 0; k < 8; ++k) ss += x.v[k] * x.v[k]; }
;                   const float rs = rsqrtf(wsum(ss) * (1.f / 384.f) + EPS);
;                   if (lane < 48) { for (int k = 0; k < 8; ++k) x.v[k] *= rs * gqv.v[k]; stb8(QN + (size_t)r * 384 + lane * 8, x); } }
.LBB0_619:
	s_waitcnt vmcnt(2)
	v_lshl_add_u64 v[16:17], s[62:63], 0, v[70:71]
	v_add_co_u32_e32 v16, vcc, 0x7800000, v16
	v_add_u32_e32 v89, s54, v88
	s_nop 0
	v_addc_co_u32_e32 v17, vcc, 0, v17, vcc
	global_load_dwordx4 v[52:55], v[16:17], off
	v_lshl_add_u64 v[16:17], s[62:63], 0, v[66:67]
	s_mov_b32 s44, 0x8200
	v_cmp_gt_i32_e64 s[44:45], s44, v89
	v_add_co_u32_e32 v16, vcc, 0x7800000, v16
	v_lshl_add_u64 v[18:19], s[62:63], 0, v[68:69]
	v_mov_b64_e32 v[20:21], s[84:85]
	v_cndmask_b32_e64 v90, v88, v89, s[44:45]
	s_movk_i32 s46, 0x1200
	v_addc_co_u32_e32 v17, vcc, 0, v17, vcc
	v_mov_b32_e32 v73, v213
	v_mov_b32_e32 v75, v213
	v_mad_i64_i32 v[20:21], s[46:47], v90, s46, v[20:21]
	s_waitcnt vmcnt(1)
	v_add_co_u32_e32 v32, vcc, 0x7800000, v18
	v_lshl_add_u64 v[22:23], v[20:21], 0, v[212:213]
	v_lshl_add_u64 v[24:25], v[20:21], 0, v[72:73]
	s_waitcnt lgkmcnt(0)
	v_lshl_add_u64 v[34:35], v[20:21], 0, v[74:75]
	v_addc_co_u32_e32 v33, vcc, 0, v19, vcc
	global_load_dwordx4 v[40:43], v[16:17], off offset:768
	global_load_dwordx4 v[28:31], v[22:23], off
	s_nop 0
	global_load_dwordx4 v[24:27], v[24:25], off offset:768
	s_nop 0
	global_load_dwordx4 v[20:23], v[34:35], off offset:1280
	global_load_dwordx4 v[16:19], v[34:35], off offset:1312
	global_load_dwordx4 v[36:39], v[32:33], off offset:1280
	s_nop 0
	global_load_dwordx4 v[32:35], v[32:33], off offset:1312
	s_waitcnt vmcnt(7)
	v_lshlrev_b32_e32 v50, 16, v52
	v_and_b32_e32 v51, 0xffff0000, v52
	v_lshlrev_b32_e32 v48, 16, v53
	v_and_b32_e32 v49, 0xffff0000, v53
	v_pk_mul_f32 v[52:53], v[50:51], v[50:51]
	v_lshlrev_b32_e32 v46, 16, v54
	v_and_b32_e32 v47, 0xffff0000, v54
	v_lshlrev_b32_e32 v44, 16, v55
	v_and_b32_e32 v45, 0xffff0000, v55
	v_pk_mul_f32 v[54:55], v[48:49], v[48:49]
	v_add_f32_e32 v52, v52, v53
	v_add_f32_e32 v52, v52, v54
	v_pk_mul_f32 v[76:77], v[46:47], v[46:47]
	v_add_f32_e32 v52, v55, v52
	v_add_f32_e32 v52, v76, v52
	v_pk_mul_f32 v[78:79], v[44:45], v[44:45]
	v_add_f32_e32 v52, v77, v52
	v_add_f32_e32 v52, v78, v52
	v_add_f32_e32 v52, v79, v52
	v_cndmask_b32_e64 v52, 0, v52, s[40:41]
	v_mov_b32_e32 v53, v52
	s_waitcnt lgkmcnt(0)
	s_nop 1
	v_permlane32_swap_b32_e32 v52, v53
	v_add_f32_e32 v52, v52, v53
	v_mov_b32_e32 v53, v52
	s_waitcnt lgkmcnt(0)
	s_nop 1
	v_permlane16_swap_b32_e32 v52, v53
	v_add_f32_e32 v52, v52, v53
	s_waitcnt lgkmcnt(0)
	s_nop 1
	v_add_f32_dpp v52, v52, v52 row_ror:8 row_mask:0xf bank_mask:0xf
	s_waitcnt lgkmcnt(0)
	s_nop 1
	v_add_f32_dpp v52, v52, v52 row_ror:4 row_mask:0xf bank_mask:0xf
	s_waitcnt lgkmcnt(0)
	s_nop 1
	v_add_f32_dpp v52, v52, v52 row_ror:2 row_mask:0xf bank_mask:0xf
	ds_bpermute_b32 v53, v87, v52
	s_and_saveexec_b64 s[46:47], s[40:41]
	s_cbranch_execz .LBB0_621
	s_waitcnt lgkmcnt(0)
	v_add_f32_e32 v52, v52, v53
	v_mov_b32_e32 v54, 0x358637bd
	v_fmamk_f32 v52, v52, 0x3b2aaaab, v54
	v_cmp_gt_f32_e32 vcc, s2, v52
	v_mul_f32_e32 v53, 0x4b800000, v52
	s_nop 0
	v_cndmask_b32_e32 v52, v52, v53, vcc
	v_rsq_f32_e32 v52, v52
	s_nop 0
	v_mul_f32_e32 v53, 0x45800000, v52
	v_cndmask_b32_e32 v52, v52, v53, vcc
	v_pk_mul_f32 v[54:55], v[4:5], v[52:53] op_sel_hi:[1,0]
	s_nop 0
	v_pk_mul_f32 v[50:51], v[54:55], v[50:51]
	v_pk_mul_f32 v[54:55], v[6:7], v[52:53] op_sel_hi:[1,0]
	s_nop 0
	v_pk_mul_f32 v[48:49], v[54:55], v[48:49]
	v_pk_mul_f32 v[54:55], v[0:1], v[52:53] op_sel_hi:[1,0]
	v_pk_mul_f32 v[52:53], v[2:3], v[52:53] op_sel_hi:[1,0]
	v_pk_mul_f32 v[46:47], v[54:55], v[46:47]
	v_lshl_add_u64 v[54:55], s[62:63], 0, v[64:65]
	v_pk_mul_f32 v[52:53], v[52:53], v[44:45]
	v_cvt_pk_bf16_f32 v45, v48, v49
	v_add_co_u32_e32 v48, vcc, 0x10a40000, v54
	v_cvt_pk_bf16_f32 v44, v50, v51
	v_cvt_pk_bf16_f32 v46, v46, v47
	v_cvt_pk_bf16_f32 v47, v52, v53
	v_addc_co_u32_e32 v49, vcc, 0, v55, vcc
	global_store_dwordx4 v[48:49], v[44:47], off sc1

; DI F8 unpack8(uint4 u) { F8 r; r.v[0] = lo16(u.x); r.v[1] = hi16(u.x); r.v[2] = lo16(u.y); r.v[3] = hi16(u.y); r.v[4] = lo16(u.z); r.v[5] = hi16(u.z); r.v[6] = lo16(u.w); r.v[7] = hi16(u.w); return r; }
; DI void stf8(float* p, const F8& f) { *(float4*)p = make_float4(f.v[0], f.v[1], f.v[2], f.v[3]); *(float4*)(p + 4) = make_float4(f.v[4], f.v[5], f.v[6], f.v[7]); }
; DI void stb8(bf16_t* p, const F8& f) { *(uint4*)p = pack8(f); }
; DI float wsum(float v) { v += __shfl_xor(v, 32); v += __shfl_xor(v, 16); v += __shfl_xor(v, 8); v += __shfl_xor(v, 4); v += __shfl_xor(v, 2); v += __shfl_xor(v, 1); return v; }
; DI void even_elem(const Params& p, int e) {
;     ...
;                 { F8 x = unpack8(xkv[q]); float ss = 0.f;
;                   if (lane < 32) { for (int k = 0; k < 8; ++k) ss += x.v[k] * x.v[k]; }
;                   const float rs = rsqrtf(wsum(ss) * (1.f / 256.f) + EPS);
;                   if (lane < 32) { for (int k = 0; k < 8; ++k) x.v[k] *= rs * gkvv.v[k];
;                       float* lo = sq < 4 ? p.out + O_PLAT + (((size_t)e * 4 + sq) * 8192 + pos) * 256 : p.out + O_SLAT + (((size_t)e * 8 + (sq - 4)) * 64 + pos) * 256;
;                       stf8(lo + lane * 8, x); stb8(LAT + (size_t)kvr * 256 + lane * 8, x); } }
.LBB0_628:
	s_or_b64 exec, exec, s[48:49]
	s_waitcnt lgkmcnt(0)
	v_add_f32_e32 v50, v50, v51
	v_mov_b32_e32 v52, 0x358637bd
	v_fmamk_f32 v50, v50, 0x3b800000, v52
	v_cmp_gt_f32_e32 vcc, s2, v50
	v_mul_f32_e32 v51, 0x4b800000, v50
	v_ashrrev_i32_e32 v77, 31, v76
	v_cndmask_b32_e32 v50, v50, v51, vcc
	v_rsq_f32_e32 v50, v50
	s_nop 0
	v_mul_f32_e32 v51, 0x45800000, v50
	v_cndmask_b32_e32 v52, v50, v51, vcc
	v_pk_mul_f32 v[50:51], v[12:13], v[52:53] op_sel_hi:[1,0]
	s_nop 0
	v_pk_mul_f32 v[48:49], v[50:51], v[48:49]
	v_pk_mul_f32 v[50:51], v[14:15], v[52:53] op_sel_hi:[1,0]
	s_nop 0
	v_pk_mul_f32 v[50:51], v[50:51], v[46:47]
	v_pk_mul_f32 v[46:47], v[8:9], v[52:53] op_sel_hi:[1,0]
	s_nop 0
	v_pk_mul_f32 v[44:45], v[46:47], v[44:45]
	v_pk_mul_f32 v[46:47], v[10:11], v[52:53] op_sel_hi:[1,0]
	s_nop 0
	v_pk_mul_f32 v[46:47], v[46:47], v[40:41]
	v_lshl_add_u64 v[40:41], v[136:137], 2, v[42:43]
	global_store_dwordx4 v[40:41], v[48:51], off sc1
	global_store_dwordx4 v[40:41], v[44:47], off offset:16 sc1
	v_lshlrev_b64 v[40:41], 9, v[76:77]
	v_lshl_add_u64 v[52:53], v[58:59], 0, v[40:41]
	v_cvt_pk_bf16_f32 v40, v48, v49
	v_cvt_pk_bf16_f32 v41, v50, v51
	v_cvt_pk_bf16_f32 v42, v44, v45
	v_cvt_pk_bf16_f32 v43, v46, v47
	global_store_dwordx4 v[52:53], v[40:43], off sc1
	s_or_b64 exec, exec, s[46:47]
	s_and_saveexec_b64 s[46:47], s[42:43]
	s_cbranch_execz .LBB0_623

; DI F8 unpack8(uint4 u) { F8 r; r.v[0] = lo16(u.x); r.v[1] = hi16(u.x); r.v[2] = lo16(u.y); r.v[3] = hi16(u.y); r.v[4] = lo16(u.z); r.v[5] = hi16(u.z); r.v[6] = lo16(u.w); r.v[7] = hi16(u.w); return r; }
; DI void stf8(float* p, const F8& f) { *(float4*)p = make_float4(f.v[0], f.v[1], f.v[2], f.v[3]); *(float4*)(p + 4) = make_float4(f.v[4], f.v[5], f.v[6], f.v[7]); }
; DI void stb8(bf16_t* p, const F8& f) { *(uint4*)p = pack8(f); }
; DI float wsum(float v) { v += __shfl_xor(v, 32); v += __shfl_xor(v, 16); v += __shfl_xor(v, 8); v += __shfl_xor(v, 4); v += __shfl_xor(v, 2); v += __shfl_xor(v, 1); return v; }
; DI void even_elem(const Params& p, int e) {
;     ...
;                 { F8 x = unpack8(xq[q]); float ss = 0.f;
;                   if (lane < 48) { for (int k = 0; k < 8; ++k) ss += x.v[k] * x.v[k]; }
;                   const float rs = rsqrtf(wsum(ss) * (1.f / 384.f) + EPS);
;                   if (lane < 48) { for (int k = 0; k < 8; ++k) x.v[k] *= rs * gqv.v[k]; stb8(QN + (size_t)r * 384 + lane * 8, x); } }
;     ...
;                 if (lane < 2) {
;                     const F8 a1 = unpack8(x1[q]), a2 = unpack8(x2[q]);
;                     F8 o1, o2; const float2* rp = ROPE + apos * 16 + lane * 8;
; #pragma unroll
;                     for (int k = 0; k < 8; ++k) { const float2 cs = rp[k]; o1.v[k] = a1.v[k] * cs.x - a2.v[k] * cs.y; o2.v[k] = a2.v[k] * cs.x + a1.v[k] * cs.y; }
;                     float* ko = sq < 4 ? p.out + O_PKR + (((size_t)e * 4 + sq) * 8192 + pos) * 32 : p.out + O_SKR + (((size_t)e * 8 + (sq - 4)) * 64 + pos) * 32;
;                     stf8(ko + lane * 8, o1); stf8(ko + 16 + lane * 8, o2);
; #pragma unroll
;                     for (int h = 0; h < 8; ++h) { stb8(KB + (size_t)kvr * 768 + h * 96 + 64 + lane * 8, o1); stb8(KB + (size_t)kvr * 768 + h * 96 + 80 + lane * 8, o2); }
.LBB0_633:
	s_or_b64 exec, exec, s[48:49]
	s_waitcnt vmcnt(5)
	v_lshlrev_b32_e32 v78, 16, v36
	v_and_b32_e32 v79, 0xffff0000, v36
	s_waitcnt vmcnt(4)
	v_lshlrev_b32_e32 v100, 16, v35
	v_and_b32_e32 v101, 0xffff0000, v35
	s_waitcnt vmcnt(0)
	v_mov_b32_e32 v35, v54
	v_mov_b32_e32 v54, v53
	v_lshlrev_b32_e32 v92, 16, v37
	v_and_b32_e32 v93, 0xffff0000, v37
	v_lshlrev_b32_e32 v36, 16, v32
	v_and_b32_e32 v37, 0xffff0000, v32
	v_lshlrev_b32_e32 v98, 16, v34
	v_and_b32_e32 v99, 0xffff0000, v34
	v_mov_b32_e32 v34, v52
	v_pk_mul_f32 v[52:53], v[54:55], v[78:79]
	v_lshlrev_b32_e32 v94, 16, v38
	v_and_b32_e32 v95, 0xffff0000, v38
	v_lshlrev_b32_e32 v96, 16, v39
	v_and_b32_e32 v97, 0xffff0000, v39
	v_lshlrev_b32_e32 v38, 16, v33
	v_and_b32_e32 v39, 0xffff0000, v33
	v_pk_mul_f32 v[32:33], v[54:55], v[36:37]
	v_pk_fma_f32 v[36:37], v[34:35], v[36:37], v[52:53]
	v_mov_b32_e32 v53, v50
	v_mov_b32_e32 v50, v49
	v_mov_b32_e32 v52, v48
	v_pk_mul_f32 v[48:49], v[50:51], v[92:93]
	v_pk_fma_f32 v[32:33], v[34:35], v[78:79], v[32:33] neg_lo:[0,0,1] neg_hi:[0,0,1]
	v_pk_mul_f32 v[34:35], v[50:51], v[38:39]
	v_pk_fma_f32 v[38:39], v[52:53], v[38:39], v[48:49]
	v_mov_b32_e32 v49, v46
	v_mov_b32_e32 v46, v45
	v_mov_b32_e32 v51, v42
	v_mov_b32_e32 v42, v41
	v_mov_b32_e32 v48, v44
	v_pk_mul_f32 v[44:45], v[46:47], v[98:99]
	v_pk_mul_f32 v[46:47], v[46:47], v[94:95]
	v_mov_b32_e32 v50, v40
	v_pk_mul_f32 v[40:41], v[42:43], v[100:101]
	v_pk_fma_f32 v[44:45], v[48:49], v[94:95], v[44:45] neg_lo:[0,0,1] neg_hi:[0,0,1]
	v_pk_fma_f32 v[48:49], v[48:49], v[98:99], v[46:47]
	v_pk_fma_f32 v[46:47], v[50:51], v[96:97], v[40:41] neg_lo:[0,0,1] neg_hi:[0,0,1]
	v_pk_mul_f32 v[40:41], v[42:43], v[96:97]
	v_pk_fma_f32 v[34:35], v[52:53], v[92:93], v[34:35] neg_lo:[0,0,1] neg_hi:[0,0,1]
	v_pk_fma_f32 v[50:51], v[50:51], v[100:101], v[40:41]
	v_lshl_add_u64 v[40:41], v[136:137], 2, v[80:81]
	global_store_dwordx4 v[40:41], v[32:35], off sc1
	global_store_dwordx4 v[40:41], v[44:47], off offset:16 sc1
	global_store_dwordx4 v[40:41], v[36:39], off offset:64 sc1
	global_store_dwordx4 v[40:41], v[48:51], off offset:80 sc1
	v_cvt_pk_bf16_f32 v32, v32, v33
	v_cvt_pk_bf16_f32 v33, v34, v35
	v_cvt_pk_bf16_f32 v34, v44, v45
	v_cvt_pk_bf16_f32 v35, v46, v47
	v_mad_i64_i32 v[40:41], s[48:49], v76, s97, v[62:63]
	v_cvt_pk_bf16_f32 v36, v36, v37
	v_cvt_pk_bf16_f32 v37, v38, v39
	v_cvt_pk_bf16_f32 v38, v48, v49
	v_cvt_pk_bf16_f32 v39, v50, v51
	global_store_dwordx4 v[40:41], v[32:35], off offset:128 sc1
	global_store_dwordx4 v[40:41], v[36:39], off offset:160 sc1
	global_store_dwordx4 v[40:41], v[32:35], off offset:320 sc1
	global_store_dwordx4 v[40:41], v[36:39], off offset:352 sc1
	global_store_dwordx4 v[40:41], v[32:35], off offset:512 sc1
	global_store_dwordx4 v[40:41], v[36:39], off offset:544 sc1
	global_store_dwordx4 v[40:41], v[32:35], off offset:704 sc1
	global_store_dwordx4 v[40:41], v[36:39], off offset:736 sc1
	global_store_dwordx4 v[40:41], v[32:35], off offset:896 sc1
	global_store_dwordx4 v[40:41], v[36:39], off offset:928 sc1
	global_store_dwordx4 v[40:41], v[32:35], off offset:1088 sc1
	global_store_dwordx4 v[40:41], v[36:39], off offset:1120 sc1
	global_store_dwordx4 v[40:41], v[32:35], off offset:1280 sc1
	global_store_dwordx4 v[40:41], v[36:39], off offset:1312 sc1
	global_store_dwordx4 v[40:41], v[32:35], off offset:1472 sc1
	global_store_dwordx4 v[40:41], v[36:39], off offset:1504 sc1
	s_or_b64 exec, exec, s[46:47]
	s_and_saveexec_b64 s[46:47], s[44:45]
	s_cbranch_execz .LBB0_618
.LBB0_634:
	s_waitcnt vmcnt(1)
	v_lshlrev_b32_e32 v36, 16, v28
	v_and_b32_e32 v37, 0xffff0000, v28
	s_waitcnt vmcnt(0)
	v_lshlrev_b32_e32 v34, 16, v29
	v_and_b32_e32 v35, 0xffff0000, v29
	v_lshlrev_b32_e32 v32, 16, v30
	v_and_b32_e32 v33, 0xffff0000, v30
	v_lshlrev_b32_e32 v28, 16, v31
	v_and_b32_e32 v29, 0xffff0000, v31
	v_pk_mul_f32 v[30:31], v[36:37], v[36:37]
	v_pk_mul_f32 v[38:39], v[34:35], v[34:35]
	v_add_f32_e32 v30, v30, v31
	v_add_f32_e32 v30, v30, v38
	v_pk_mul_f32 v[40:41], v[32:33], v[32:33]
	v_add_f32_e32 v30, v39, v30
	v_add_f32_e32 v30, v40, v30
	v_pk_mul_f32 v[42:43], v[28:29], v[28:29]
	v_add_f32_e32 v30, v41, v30
	v_add_f32_e32 v30, v42, v30
	v_add_f32_e32 v30, v43, v30
	v_cndmask_b32_e64 v30, 0, v30, s[40:41]
	v_mov_b32_e32 v31, v30
	s_waitcnt lgkmcnt(0)
	s_nop 1
	v_permlane32_swap_b32_e32 v30, v31
	v_add_f32_e32 v30, v30, v31
	v_mov_b32_e32 v31, v30
	s_waitcnt lgkmcnt(0)
	s_nop 1
	v_permlane16_swap_b32_e32 v30, v31
	v_add_f32_e32 v30, v30, v31
	s_waitcnt lgkmcnt(0)
	s_nop 1
	v_add_f32_dpp v30, v30, v30 row_ror:8 row_mask:0xf bank_mask:0xf
	s_waitcnt lgkmcnt(0)
	s_nop 1
	v_add_f32_dpp v30, v30, v30 row_ror:4 row_mask:0xf bank_mask:0xf
	s_waitcnt lgkmcnt(0)
	s_nop 1
	v_add_f32_dpp v30, v30, v30 row_ror:2 row_mask:0xf bank_mask:0xf
	ds_bpermute_b32 v31, v87, v30
	s_and_saveexec_b64 s[44:45], s[40:41]
	s_cbranch_execz .LBB0_636
	s_waitcnt lgkmcnt(0)
	v_add_f32_e32 v30, v30, v31
	v_mov_b32_e32 v38, 0x358637bd
	v_fmamk_f32 v30, v30, 0x3b2aaaab, v38
	v_cmp_gt_f32_e32 vcc, s2, v30
	v_mul_f32_e32 v31, 0x4b800000, v30
	s_movk_i32 s48, 0x300
	v_cndmask_b32_e32 v30, v30, v31, vcc
	v_rsq_f32_e32 v30, v30
	v_mad_i64_i32 v[40:41], s[48:49], v90, s48, v[56:57]
	v_mul_f32_e32 v31, 0x45800000, v30
	v_cndmask_b32_e32 v30, v30, v31, vcc
	v_pk_mul_f32 v[38:39], v[4:5], v[30:31] op_sel_hi:[1,0]
	s_nop 0
	v_pk_mul_f32 v[36:37], v[38:39], v[36:37]
	v_pk_mul_f32 v[38:39], v[6:7], v[30:31] op_sel_hi:[1,0]
	s_nop 0
	v_pk_mul_f32 v[34:35], v[38:39], v[34:35]
	v_pk_mul_f32 v[38:39], v[0:1], v[30:31] op_sel_hi:[1,0]
	v_pk_mul_f32 v[30:31], v[2:3], v[30:31] op_sel_hi:[1,0]
	v_pk_mul_f32 v[32:33], v[38:39], v[32:33]
	v_pk_mul_f32 v[38:39], v[30:31], v[28:29]
	v_cvt_pk_bf16_f32 v28, v36, v37
	v_cvt_pk_bf16_f32 v29, v34, v35
	v_cvt_pk_bf16_f32 v30, v32, v33
	v_cvt_pk_bf16_f32 v31, v38, v39
	global_store_dwordx4 v[40:41], v[28:31], off sc1

; DI F8 unpack8(uint4 u) { F8 r; r.v[0] = lo16(u.x); r.v[1] = hi16(u.x); r.v[2] = lo16(u.y); r.v[3] = hi16(u.y); r.v[4] = lo16(u.z); r.v[5] = hi16(u.z); r.v[6] = lo16(u.w); r.v[7] = hi16(u.w); return r; }
; DI void stf8(float* p, const F8& f) { *(float4*)p = make_float4(f.v[0], f.v[1], f.v[2], f.v[3]); *(float4*)(p + 4) = make_float4(f.v[4], f.v[5], f.v[6], f.v[7]); }
; DI void stb8(bf16_t* p, const F8& f) { *(uint4*)p = pack8(f); }
; DI float wsum(float v) { v += __shfl_xor(v, 32); v += __shfl_xor(v, 16); v += __shfl_xor(v, 8); v += __shfl_xor(v, 4); v += __shfl_xor(v, 2); v += __shfl_xor(v, 1); return v; }
; DI void even_elem(const Params& p, int e) {
;     ...
;                 { F8 x = unpack8(xkv[q]); float ss = 0.f;
;                   if (lane < 32) { for (int k = 0; k < 8; ++k) ss += x.v[k] * x.v[k]; }
;                   const float rs = rsqrtf(wsum(ss) * (1.f / 256.f) + EPS);
;                   if (lane < 32) { for (int k = 0; k < 8; ++k) x.v[k] *= rs * gkvv.v[k];
;                       float* lo = sq < 4 ? p.out + O_PLAT + (((size_t)e * 4 + sq) * 8192 + pos) * 256 : p.out + O_SLAT + (((size_t)e * 8 + (sq - 4)) * 64 + pos) * 256;
;                       stf8(lo + lane * 8, x); stb8(LAT + (size_t)kvr * 256 + lane * 8, x); } }
.LBB0_641:
	s_or_b64 exec, exec, s[48:49]
	s_waitcnt lgkmcnt(0)
	v_add_f32_e32 v34, v34, v35
	v_mov_b32_e32 v36, 0x358637bd
	v_fmamk_f32 v34, v34, 0x3b800000, v36
	v_cmp_gt_f32_e32 vcc, s2, v34
	v_mul_f32_e32 v35, 0x4b800000, v34
	v_ashrrev_i32_e32 v41, 31, v40
	v_cndmask_b32_e32 v34, v34, v35, vcc
	v_rsq_f32_e32 v34, v34
	s_nop 0
	v_mul_f32_e32 v35, 0x45800000, v34
	v_cndmask_b32_e32 v36, v34, v35, vcc
	v_pk_mul_f32 v[34:35], v[12:13], v[36:37] op_sel_hi:[1,0]
	s_nop 0
	v_pk_mul_f32 v[32:33], v[34:35], v[32:33]
	v_pk_mul_f32 v[34:35], v[14:15], v[36:37] op_sel_hi:[1,0]
	s_nop 0
	v_pk_mul_f32 v[34:35], v[34:35], v[30:31]
	v_pk_mul_f32 v[30:31], v[8:9], v[36:37] op_sel_hi:[1,0]
	s_nop 0
	v_pk_mul_f32 v[28:29], v[30:31], v[28:29]
	v_pk_mul_f32 v[30:31], v[10:11], v[36:37] op_sel_hi:[1,0]
	s_nop 0
	v_pk_mul_f32 v[30:31], v[30:31], v[24:25]
	v_lshl_add_u64 v[24:25], v[136:137], 2, v[26:27]
	global_store_dwordx4 v[24:25], v[32:35], off sc1
	global_store_dwordx4 v[24:25], v[28:31], off offset:16 sc1
	v_lshlrev_b64 v[24:25], 9, v[40:41]
	v_lshl_add_u64 v[36:37], v[58:59], 0, v[24:25]
	v_cvt_pk_bf16_f32 v24, v32, v33
	v_cvt_pk_bf16_f32 v25, v34, v35
	v_cvt_pk_bf16_f32 v26, v28, v29
	v_cvt_pk_bf16_f32 v27, v30, v31
	global_store_dwordx4 v[36:37], v[24:27], off sc1

; DI F8 unpack8(uint4 u) { F8 r; r.v[0] = lo16(u.x); r.v[1] = hi16(u.x); r.v[2] = lo16(u.y); r.v[3] = hi16(u.y); r.v[4] = lo16(u.z); r.v[5] = hi16(u.z); r.v[6] = lo16(u.w); r.v[7] = hi16(u.w); return r; }
; DI void stf8(float* p, const F8& f) { *(float4*)p = make_float4(f.v[0], f.v[1], f.v[2], f.v[3]); *(float4*)(p + 4) = make_float4(f.v[4], f.v[5], f.v[6], f.v[7]); }
; DI void stb8(bf16_t* p, const F8& f) { *(uint4*)p = pack8(f); }
; DI void even_elem(const Params& p, int e) {
;     ...
;             for (int t = 0; t < 8; ++t) {
;                 const F8 gb = unpack8(gbr[t]), gc = unpack8(gcr[t]), sh = unpack8(shr[t]);
;                 F8 a0, o;
; #pragma unroll
;                 for (int k = 0; k < 8; ++k) { a0.v[k] = gc.v[k] * sh.v[k]; o.v[k] = gb.v[k] * (w0.v[k] * a2.v[k] + w1.v[k] * a1.v[k] + w2.v[k] * a0.v[k]); }
;                 stb8(CAT + (size_t)(r0 + t) * 1024 + 512 + c, o);
;                 if (last && t >= 6) {
;                     float* so = sq < 4 ? p.out + O_PSC + (((size_t)e * 4 + sq) * 2 + (t - 6)) * 512 : p.out + O_SSC + (((size_t)e * 8 + (sq - 4)) * 2 + (t - 6)) * 512;
;                     stf8(so + c, a0);
;                 }
;                 a2 = a1; a1 = a0;
;             }
.LBB0_657:
	s_or_b64 exec, exec, s[22:23]
	s_waitcnt vmcnt(22)
	v_lshlrev_b32_e32 v160, 16, v112
	v_and_b32_e32 v161, 0xffff0000, v112
	v_lshlrev_b32_e32 v112, 16, v113
	v_and_b32_e32 v113, 0xffff0000, v113
	s_waitcnt vmcnt(21)
	v_lshlrev_b32_e32 v164, 16, v108
	v_and_b32_e32 v165, 0xffff0000, v108
	v_lshlrev_b32_e32 v108, 16, v109
	v_and_b32_e32 v109, 0xffff0000, v109
	v_pk_mul_f32 v[112:113], v[112:113], v[108:109]
	s_waitcnt vmcnt(0)
	v_pk_mul_f32 v[108:109], v[6:7], v[134:135]
	v_lshlrev_b32_e32 v156, 16, v116
	v_pk_fma_f32 v[108:109], v[14:15], v[126:127], v[108:109]
	v_and_b32_e32 v157, 0xffff0000, v116
	v_lshlrev_b32_e32 v116, 16, v117
	v_and_b32_e32 v117, 0xffff0000, v117
	v_pk_fma_f32 v[108:109], v[18:19], v[112:113], v[108:109]
	v_lshlrev_b32_e32 v162, 16, v114
	v_and_b32_e32 v163, 0xffff0000, v114
	v_lshlrev_b32_e32 v166, 16, v110
	v_and_b32_e32 v167, 0xffff0000, v110
	v_pk_mul_f32 v[116:117], v[108:109], v[116:117]
	v_pk_mul_f32 v[108:109], v[0:1], v[128:129]
	v_pk_mul_f32 v[134:135], v[162:163], v[166:167]
	v_pk_fma_f32 v[108:109], v[8:9], v[120:121], v[108:109]
	v_lshlrev_b32_e32 v158, 16, v118
	v_and_b32_e32 v159, 0xffff0000, v118
	v_pk_fma_f32 v[108:109], v[20:21], v[134:135], v[108:109]
	v_lshlrev_b32_e32 v114, 16, v115
	v_and_b32_e32 v115, 0xffff0000, v115
	v_lshlrev_b32_e32 v110, 16, v111
	v_and_b32_e32 v111, 0xffff0000, v111
	v_pk_mul_f32 v[128:129], v[108:109], v[158:159]
	v_pk_mul_f32 v[108:109], v[2:3], v[130:131]
	v_pk_mul_f32 v[114:115], v[114:115], v[110:111]
	v_pk_fma_f32 v[108:109], v[10:11], v[122:123], v[108:109]
	v_ashrrev_i32_e32 v151, 31, v150
	v_lshlrev_b32_e32 v118, 16, v119
	v_and_b32_e32 v119, 0xffff0000, v119
	v_pk_mul_f32 v[132:133], v[4:5], v[132:133]
	v_pk_fma_f32 v[108:109], v[22:23], v[114:115], v[108:109]
	v_pk_mul_f32 v[160:161], v[160:161], v[164:165]
	v_pk_fma_f32 v[132:133], v[12:13], v[124:125], v[132:133]
	v_pk_mul_f32 v[118:119], v[108:109], v[118:119]
	v_lshlrev_b64 v[108:109], 11, v[150:151]
	v_pk_fma_f32 v[132:133], v[16:17], v[160:161], v[132:133]
	v_lshl_add_u64 v[130:131], v[142:143], 0, v[108:109]
	v_cvt_pk_bf16_f32 v109, v116, v117
	v_cvt_pk_bf16_f32 v110, v128, v129
	v_lshlrev_b32_e32 v116, 16, v100
	v_and_b32_e32 v117, 0xffff0000, v100
	v_lshlrev_b32_e32 v100, 16, v101
	v_and_b32_e32 v101, 0xffff0000, v101
	v_lshlrev_b32_e32 v128, 16, v96
	v_and_b32_e32 v129, 0xffff0000, v96
	v_lshlrev_b32_e32 v96, 16, v97
	v_and_b32_e32 v97, 0xffff0000, v97
	v_pk_mul_f32 v[132:133], v[132:133], v[156:157]
	v_pk_mul_f32 v[100:101], v[100:101], v[96:97]
	v_pk_mul_f32 v[96:97], v[6:7], v[126:127]
	v_cvt_pk_bf16_f32 v108, v132, v133
	v_cvt_pk_bf16_f32 v111, v118, v119
	v_pk_fma_f32 v[96:97], v[14:15], v[112:113], v[96:97]
	global_store_dwordx4 v[130:131], v[108:111], off offset:1024 sc1
	v_pk_fma_f32 v[96:97], v[18:19], v[100:101], v[96:97]
	v_lshlrev_b32_e32 v118, 16, v102
	v_lshlrev_b32_e32 v108, 16, v104
	v_and_b32_e32 v109, 0xffff0000, v104
	v_lshlrev_b32_e32 v104, 16, v105
	v_and_b32_e32 v105, 0xffff0000, v105
	v_and_b32_e32 v119, 0xffff0000, v102
	v_lshlrev_b32_e32 v130, 16, v98
	v_and_b32_e32 v131, 0xffff0000, v98
	v_pk_mul_f32 v[104:105], v[96:97], v[104:105]
	v_pk_mul_f32 v[96:97], v[0:1], v[120:121]
	v_pk_mul_f32 v[118:119], v[118:119], v[130:131]
	v_pk_fma_f32 v[96:97], v[8:9], v[134:135], v[96:97]
	v_lshlrev_b32_e32 v110, 16, v106
	v_and_b32_e32 v111, 0xffff0000, v106
	v_pk_fma_f32 v[96:97], v[20:21], v[118:119], v[96:97]
	v_lshlrev_b32_e32 v102, 16, v103
	v_and_b32_e32 v103, 0xffff0000, v103
	v_lshlrev_b32_e32 v98, 16, v99
	v_and_b32_e32 v99, 0xffff0000, v99
	v_pk_mul_f32 v[110:111], v[96:97], v[110:111]
	v_pk_mul_f32 v[96:97], v[2:3], v[122:123]
	v_pk_mul_f32 v[102:103], v[102:103], v[98:99]
	v_pk_fma_f32 v[96:97], v[10:11], v[114:115], v[96:97]
	v_lshlrev_b32_e32 v106, 16, v107
	v_and_b32_e32 v107, 0xffff0000, v107
	v_pk_mul_f32 v[124:125], v[4:5], v[124:125]
	v_pk_fma_f32 v[96:97], v[22:23], v[102:103], v[96:97]
	v_pk_mul_f32 v[116:117], v[116:117], v[128:129]
	v_pk_fma_f32 v[124:125], v[12:13], v[160:161], v[124:125]
	v_pk_mul_f32 v[106:107], v[96:97], v[106:107]
	v_add_u32_e32 v96, -6, v144
	v_pk_fma_f32 v[124:125], v[16:17], v[116:117], v[124:125]
	v_ashrrev_i32_e32 v97, 31, v96
	v_pk_mul_f32 v[108:109], v[124:125], v[108:109]
	v_lshlrev_b64 v[96:97], 11, v[96:97]
	v_lshl_add_u64 v[120:121], v[142:143], 0, v[96:97]
	v_cvt_pk_bf16_f32 v96, v108, v109
	v_cvt_pk_bf16_f32 v97, v104, v105
	v_lshlrev_b32_e32 v104, 16, v88
	v_and_b32_e32 v105, 0xffff0000, v88
	v_lshlrev_b32_e32 v88, 16, v89
	v_and_b32_e32 v89, 0xffff0000, v89
	v_lshlrev_b32_e32 v108, 16, v84
	v_and_b32_e32 v109, 0xffff0000, v84
	v_lshlrev_b32_e32 v84, 16, v85
	v_and_b32_e32 v85, 0xffff0000, v85
	v_pk_mul_f32 v[88:89], v[88:89], v[84:85]
	v_pk_mul_f32 v[84:85], v[14:15], v[100:101]
	v_cvt_pk_bf16_f32 v98, v110, v111
	v_cvt_pk_bf16_f32 v99, v106, v107
	v_pk_fma_f32 v[84:85], v[6:7], v[112:113], v[84:85]
	global_store_dwordx4 v[120:121], v[96:99], off offset:1024 sc1
	v_pk_fma_f32 v[84:85], v[18:19], v[88:89], v[84:85]
	v_lshlrev_b32_e32 v106, 16, v90
	v_lshlrev_b32_e32 v96, 16, v92
	v_and_b32_e32 v97, 0xffff0000, v92
	v_lshlrev_b32_e32 v92, 16, v93
	v_and_b32_e32 v93, 0xffff0000, v93
	v_and_b32_e32 v107, 0xffff0000, v90
	v_lshlrev_b32_e32 v110, 16, v86
	v_and_b32_e32 v111, 0xffff0000, v86
	v_pk_mul_f32 v[92:93], v[84:85], v[92:93]
	v_pk_mul_f32 v[84:85], v[8:9], v[118:119]
	v_pk_mul_f32 v[106:107], v[106:107], v[110:111]
	v_pk_fma_f32 v[84:85], v[0:1], v[134:135], v[84:85]
	v_lshlrev_b32_e32 v98, 16, v94
	v_and_b32_e32 v99, 0xffff0000, v94
	v_pk_fma_f32 v[84:85], v[20:21], v[106:107], v[84:85]
	v_lshlrev_b32_e32 v90, 16, v91
; DI F8 unpack8(uint4 u) { F8 r; r.v[0] = lo16(u.x); r.v[1] = hi16(u.x); r.v[2] = lo16(u.y); r.v[3] = hi16(u.y); r.v[4] = lo16(u.z); r.v[5] = hi16(u.z); r.v[6] = lo16(u.w); r.v[7] = hi16(u.w); return r; }
; DI void stf8(float* p, const F8& f) { *(float4*)p = make_float4(f.v[0], f.v[1], f.v[2], f.v[3]); *(float4*)(p + 4) = make_float4(f.v[4], f.v[5], f.v[6], f.v[7]); }
; DI void stb8(bf16_t* p, const F8& f) { *(uint4*)p = pack8(f); }
; DI void even_elem(const Params& p, int e) {
;     ...
;             for (int t = 0; t < 8; ++t) {
;                 const F8 gb = unpack8(gbr[t]), gc = unpack8(gcr[t]), sh = unpack8(shr[t]);
;                 F8 a0, o;
; #pragma unroll
;                 for (int k = 0; k < 8; ++k) { a0.v[k] = gc.v[k] * sh.v[k]; o.v[k] = gb.v[k] * (w0.v[k] * a2.v[k] + w1.v[k] * a1.v[k] + w2.v[k] * a0.v[k]); }
;                 stb8(CAT + (size_t)(r0 + t) * 1024 + 512 + c, o);
;                 if (last && t >= 6) {
;                     float* so = sq < 4 ? p.out + O_PSC + (((size_t)e * 4 + sq) * 2 + (t - 6)) * 512 : p.out + O_SSC + (((size_t)e * 8 + (sq - 4)) * 2 + (t - 6)) * 512;
;                     stf8(so + c, a0);
;                 }
;                 a2 = a1; a1 = a0;
;             }
	v_and_b32_e32 v91, 0xffff0000, v91
	v_lshlrev_b32_e32 v86, 16, v87
	v_and_b32_e32 v87, 0xffff0000, v87
	v_pk_mul_f32 v[98:99], v[84:85], v[98:99]
	v_pk_mul_f32 v[84:85], v[10:11], v[102:103]
	v_pk_mul_f32 v[90:91], v[90:91], v[86:87]
	v_pk_fma_f32 v[84:85], v[2:3], v[114:115], v[84:85]
	v_lshlrev_b32_e32 v94, 16, v95
	v_and_b32_e32 v95, 0xffff0000, v95
	v_pk_mul_f32 v[104:105], v[104:105], v[108:109]
	v_pk_mul_f32 v[108:109], v[12:13], v[116:117]
	v_pk_fma_f32 v[84:85], v[22:23], v[90:91], v[84:85]
	v_pk_fma_f32 v[108:109], v[4:5], v[160:161], v[108:109]
	v_pk_mul_f32 v[94:95], v[84:85], v[94:95]
	v_add_u32_e32 v84, -5, v144
	v_pk_fma_f32 v[108:109], v[16:17], v[104:105], v[108:109]
	v_ashrrev_i32_e32 v85, 31, v84
	v_pk_mul_f32 v[96:97], v[108:109], v[96:97]
	v_lshlrev_b64 v[84:85], 11, v[84:85]
	v_lshl_add_u64 v[108:109], v[142:143], 0, v[84:85]
	v_cvt_pk_bf16_f32 v84, v96, v97
	v_cvt_pk_bf16_f32 v85, v92, v93
	v_lshlrev_b32_e32 v92, 16, v76
	v_and_b32_e32 v93, 0xffff0000, v76
	v_lshlrev_b32_e32 v76, 16, v77
	v_and_b32_e32 v77, 0xffff0000, v77
	v_lshlrev_b32_e32 v96, 16, v72
	v_and_b32_e32 v97, 0xffff0000, v72
	v_lshlrev_b32_e32 v72, 16, v73
	v_and_b32_e32 v73, 0xffff0000, v73
	v_pk_mul_f32 v[76:77], v[76:77], v[72:73]
	v_pk_mul_f32 v[72:73], v[14:15], v[88:89]
	v_cvt_pk_bf16_f32 v86, v98, v99
	v_cvt_pk_bf16_f32 v87, v94, v95
	v_pk_fma_f32 v[72:73], v[6:7], v[100:101], v[72:73]
	global_store_dwordx4 v[108:109], v[84:87], off offset:1024 sc1
	v_pk_fma_f32 v[72:73], v[18:19], v[76:77], v[72:73]
	v_lshlrev_b32_e32 v94, 16, v78
	v_lshlrev_b32_e32 v84, 16, v80
	v_and_b32_e32 v85, 0xffff0000, v80
	v_lshlrev_b32_e32 v80, 16, v81
	v_and_b32_e32 v81, 0xffff0000, v81
	v_and_b32_e32 v95, 0xffff0000, v78
	v_lshlrev_b32_e32 v98, 16, v74
	v_and_b32_e32 v99, 0xffff0000, v74
	v_pk_mul_f32 v[80:81], v[72:73], v[80:81]
	v_pk_mul_f32 v[72:73], v[8:9], v[106:107]
	v_pk_mul_f32 v[94:95], v[94:95], v[98:99]
	v_pk_fma_f32 v[72:73], v[0:1], v[118:119], v[72:73]
	v_lshlrev_b32_e32 v86, 16, v82
	v_and_b32_e32 v87, 0xffff0000, v82
	v_pk_fma_f32 v[72:73], v[20:21], v[94:95], v[72:73]
	v_lshlrev_b32_e32 v78, 16, v79
	v_and_b32_e32 v79, 0xffff0000, v79
	v_lshlrev_b32_e32 v74, 16, v75
	v_and_b32_e32 v75, 0xffff0000, v75
	v_pk_mul_f32 v[86:87], v[72:73], v[86:87]
	v_pk_mul_f32 v[72:73], v[10:11], v[90:91]
	v_pk_mul_f32 v[78:79], v[78:79], v[74:75]
	v_pk_fma_f32 v[72:73], v[2:3], v[102:103], v[72:73]
	v_lshlrev_b32_e32 v82, 16, v83
	v_and_b32_e32 v83, 0xffff0000, v83
	v_pk_mul_f32 v[92:93], v[92:93], v[96:97]
	v_pk_mul_f32 v[96:97], v[12:13], v[104:105]
	v_pk_fma_f32 v[72:73], v[22:23], v[78:79], v[72:73]
	v_pk_fma_f32 v[96:97], v[4:5], v[116:117], v[96:97]
	v_pk_mul_f32 v[82:83], v[72:73], v[82:83]
	v_add_u32_e32 v72, -4, v144
	v_pk_fma_f32 v[96:97], v[16:17], v[92:93], v[96:97]
	v_ashrrev_i32_e32 v73, 31, v72
	v_pk_mul_f32 v[84:85], v[96:97], v[84:85]
	v_lshlrev_b64 v[72:73], 11, v[72:73]
	v_lshl_add_u64 v[96:97], v[142:143], 0, v[72:73]
	v_cvt_pk_bf16_f32 v72, v84, v85
	v_cvt_pk_bf16_f32 v73, v80, v81
	v_lshlrev_b32_e32 v80, 16, v64
	v_and_b32_e32 v81, 0xffff0000, v64
	v_lshlrev_b32_e32 v64, 16, v65
	v_and_b32_e32 v65, 0xffff0000, v65
	v_lshlrev_b32_e32 v84, 16, v60
	v_and_b32_e32 v85, 0xffff0000, v60
	v_lshlrev_b32_e32 v60, 16, v61
	v_and_b32_e32 v61, 0xffff0000, v61
	v_pk_mul_f32 v[64:65], v[64:65], v[60:61]
	v_pk_mul_f32 v[60:61], v[14:15], v[76:77]
	v_cvt_pk_bf16_f32 v74, v86, v87
	v_cvt_pk_bf16_f32 v75, v82, v83
	v_pk_fma_f32 v[60:61], v[6:7], v[88:89], v[60:61]
	global_store_dwordx4 v[96:97], v[72:75], off offset:1024 sc1
	v_pk_fma_f32 v[60:61], v[18:19], v[64:65], v[60:61]
	v_lshlrev_b32_e32 v82, 16, v66
	v_lshlrev_b32_e32 v72, 16, v68
	v_and_b32_e32 v73, 0xffff0000, v68
	v_lshlrev_b32_e32 v68, 16, v69
	v_and_b32_e32 v69, 0xffff0000, v69
	v_and_b32_e32 v83, 0xffff0000, v66
	v_lshlrev_b32_e32 v86, 16, v62
	v_and_b32_e32 v87, 0xffff0000, v62
	v_pk_mul_f32 v[68:69], v[60:61], v[68:69]
	v_pk_mul_f32 v[60:61], v[8:9], v[94:95]
	v_pk_mul_f32 v[82:83], v[82:83], v[86:87]
	v_pk_fma_f32 v[60:61], v[0:1], v[106:107], v[60:61]
	v_lshlrev_b32_e32 v74, 16, v70
	v_and_b32_e32 v75, 0xffff0000, v70
	v_pk_fma_f32 v[60:61], v[20:21], v[82:83], v[60:61]
	v_lshlrev_b32_e32 v66, 16, v67
	v_and_b32_e32 v67, 0xffff0000, v67
	v_lshlrev_b32_e32 v62, 16, v63
	v_and_b32_e32 v63, 0xffff0000, v63
	v_pk_mul_f32 v[74:75], v[60:61], v[74:75]
	v_pk_mul_f32 v[60:61], v[10:11], v[78:79]
	v_pk_mul_f32 v[66:67], v[66:67], v[62:63]
	v_pk_fma_f32 v[60:61], v[2:3], v[90:91], v[60:61]
	v_lshlrev_b32_e32 v70, 16, v71
	v_and_b32_e32 v71, 0xffff0000, v71
	v_pk_mul_f32 v[80:81], v[80:81], v[84:85]
	v_pk_mul_f32 v[84:85], v[12:13], v[92:93]
	v_pk_fma_f32 v[60:61], v[22:23], v[66:67], v[60:61]
	v_pk_fma_f32 v[84:85], v[4:5], v[104:105], v[84:85]
	v_pk_mul_f32 v[70:71], v[60:61], v[70:71]
	v_add_u32_e32 v60, -3, v144
	v_pk_fma_f32 v[84:85], v[16:17], v[80:81], v[84:85]
	v_ashrrev_i32_e32 v61, 31, v60
	v_pk_mul_f32 v[72:73], v[84:85], v[72:73]
	v_lshlrev_b64 v[60:61], 11, v[60:61]
	v_lshl_add_u64 v[84:85], v[142:143], 0, v[60:61]
	v_cvt_pk_bf16_f32 v60, v72, v73
	v_cvt_pk_bf16_f32 v61, v68, v69
	v_cvt_pk_bf16_f32 v62, v74, v75
	v_cvt_pk_bf16_f32 v63, v70, v71
	global_store_dwordx4 v[84:85], v[60:63], off offset:1024 sc1
	v_lshlrev_b32_e32 v72, 16, v48
	v_and_b32_e32 v73, 0xffff0000, v48
	v_lshlrev_b32_e32 v60, 16, v52
	v_and_b32_e32 v61, 0xffff0000, v52
	v_lshlrev_b32_e32 v62, 16, v53
	v_and_b32_e32 v63, 0xffff0000, v53
	v_lshlrev_b32_e32 v52, 16, v56
	v_and_b32_e32 v53, 0xffff0000, v56
	v_lshlrev_b32_e32 v100, 16, v36
	v_and_b32_e32 v101, 0xffff0000, v36
	v_lshlrev_b32_e32 v102, 16, v37
; DI F8 unpack8(uint4 u) { F8 r; r.v[0] = lo16(u.x); r.v[1] = hi16(u.x); r.v[2] = lo16(u.y); r.v[3] = hi16(u.y); r.v[4] = lo16(u.z); r.v[5] = hi16(u.z); r.v[6] = lo16(u.w); r.v[7] = hi16(u.w); return r; }
; DI void stf8(float* p, const F8& f) { *(float4*)p = make_float4(f.v[0], f.v[1], f.v[2], f.v[3]); *(float4*)(p + 4) = make_float4(f.v[4], f.v[5], f.v[6], f.v[7]); }
; DI void stb8(bf16_t* p, const F8& f) { *(uint4*)p = pack8(f); }
; DI void even_elem(const Params& p, int e) {
;     ...
;             for (int t = 0; t < 8; ++t) {
;                 const F8 gb = unpack8(gbr[t]), gc = unpack8(gcr[t]), sh = unpack8(shr[t]);
;                 F8 a0, o;
; #pragma unroll
;                 for (int k = 0; k < 8; ++k) { a0.v[k] = gc.v[k] * sh.v[k]; o.v[k] = gb.v[k] * (w0.v[k] * a2.v[k] + w1.v[k] * a1.v[k] + w2.v[k] * a0.v[k]); }
;                 stb8(CAT + (size_t)(r0 + t) * 1024 + 512 + c, o);
;                 if (last && t >= 6) {
;                     float* so = sq < 4 ? p.out + O_PSC + (((size_t)e * 4 + sq) * 2 + (t - 6)) * 512 : p.out + O_SSC + (((size_t)e * 8 + (sq - 4)) * 2 + (t - 6)) * 512;
;                     stf8(so + c, a0);
;                 }
;                 a2 = a1; a1 = a0;
;             }
	v_and_b32_e32 v103, 0xffff0000, v37
	v_pk_mul_f32 v[36:37], v[12:13], v[80:81]
	v_lshlrev_b32_e32 v86, 16, v44
	v_and_b32_e32 v87, 0xffff0000, v44
	v_lshlrev_b32_e32 v88, 16, v45
	v_and_b32_e32 v89, 0xffff0000, v45
	v_pk_mul_f32 v[44:45], v[52:53], v[72:73]
	v_pk_fma_f32 v[36:37], v[4:5], v[92:93], v[36:37]
	v_lshlrev_b32_e32 v90, 16, v46
	v_pk_fma_f32 v[36:37], v[16:17], v[44:45], v[36:37]
	v_and_b32_e32 v91, 0xffff0000, v46
	v_lshlrev_b32_e32 v96, 16, v47
	v_and_b32_e32 v97, 0xffff0000, v47
	v_lshlrev_b32_e32 v46, 16, v40
	v_and_b32_e32 v47, 0xffff0000, v40
	v_lshlrev_b32_e32 v104, 16, v38
	v_and_b32_e32 v105, 0xffff0000, v38
	v_lshlrev_b32_e32 v106, 16, v39
	v_and_b32_e32 v107, 0xffff0000, v39
	v_pk_mul_f32 v[36:37], v[36:37], v[60:61]
	v_pk_mul_f32 v[38:39], v[12:13], v[44:45]
	v_cvt_pk_bf16_f32 v52, v36, v37
	v_pk_mul_f32 v[36:37], v[46:47], v[100:101]
	v_pk_fma_f32 v[38:39], v[4:5], v[80:81], v[38:39]
	v_lshlrev_b32_e32 v68, 16, v54
	v_pk_fma_f32 v[38:39], v[16:17], v[36:37], v[38:39]
	v_and_b32_e32 v69, 0xffff0000, v54
	v_lshlrev_b32_e32 v70, 16, v55
	v_and_b32_e32 v71, 0xffff0000, v55
	v_lshlrev_b32_e32 v54, 16, v57
	v_and_b32_e32 v55, 0xffff0000, v57
	v_lshlrev_b32_e32 v48, 16, v49
	v_and_b32_e32 v49, 0xffff0000, v49
	v_pk_mul_f32 v[60:61], v[38:39], v[86:87]
	v_pk_mul_f32 v[38:39], v[14:15], v[64:65]
	v_pk_mul_f32 v[46:47], v[54:55], v[48:49]
	v_pk_fma_f32 v[38:39], v[6:7], v[76:77], v[38:39]
	v_lshlrev_b32_e32 v40, 16, v41
	v_pk_fma_f32 v[38:39], v[18:19], v[46:47], v[38:39]
	v_and_b32_e32 v41, 0xffff0000, v41
	v_pk_mul_f32 v[38:39], v[38:39], v[62:63]
	v_lshlrev_b32_e32 v56, 16, v58
	v_cvt_pk_bf16_f32 v53, v38, v39
	v_pk_mul_f32 v[38:39], v[40:41], v[102:103]
	v_pk_mul_f32 v[40:41], v[14:15], v[46:47]
	v_and_b32_e32 v57, 0xffff0000, v58
	v_pk_fma_f32 v[40:41], v[6:7], v[64:65], v[40:41]
	v_lshlrev_b32_e32 v58, 16, v59
	v_and_b32_e32 v59, 0xffff0000, v59
	v_lshlrev_b32_e32 v74, 16, v50
	v_and_b32_e32 v75, 0xffff0000, v50
	v_lshlrev_b32_e32 v50, 16, v51
	v_and_b32_e32 v51, 0xffff0000, v51
	v_pk_fma_f32 v[40:41], v[18:19], v[38:39], v[40:41]
	v_pk_mul_f32 v[50:51], v[58:59], v[50:51]
	v_pk_mul_f32 v[62:63], v[40:41], v[88:89]
	v_pk_mul_f32 v[40:41], v[8:9], v[82:83]
	v_pk_mul_f32 v[58:59], v[10:11], v[66:67]
	v_add_u32_e32 v84, -2, v144
	v_pk_mul_f32 v[48:49], v[56:57], v[74:75]
	v_pk_fma_f32 v[40:41], v[0:1], v[94:95], v[40:41]
	v_pk_fma_f32 v[58:59], v[2:3], v[78:79], v[58:59]
	v_ashrrev_i32_e32 v85, 31, v84
	v_pk_fma_f32 v[40:41], v[20:21], v[48:49], v[40:41]
	v_pk_fma_f32 v[58:59], v[22:23], v[50:51], v[58:59]
	v_lshlrev_b64 v[84:85], 11, v[84:85]
	v_pk_mul_f32 v[40:41], v[40:41], v[68:69]
	v_pk_mul_f32 v[58:59], v[58:59], v[70:71]
	v_lshl_add_u64 v[84:85], v[142:143], 0, v[84:85]
	v_cvt_pk_bf16_f32 v54, v40, v41
	v_cvt_pk_bf16_f32 v55, v58, v59
	v_lshlrev_b32_e32 v98, 16, v42
	v_and_b32_e32 v99, 0xffff0000, v42
	v_lshlrev_b32_e32 v42, 16, v43
	v_and_b32_e32 v43, 0xffff0000, v43
	global_store_dwordx4 v[84:85], v[52:55], off offset:1024 sc1
	v_pk_mul_f32 v[42:43], v[42:43], v[106:107]
	v_pk_mul_f32 v[56:57], v[8:9], v[48:49]
	v_pk_mul_f32 v[52:53], v[10:11], v[50:51]
	v_pk_mul_f32 v[40:41], v[98:99], v[104:105]
	v_pk_fma_f32 v[52:53], v[2:3], v[66:67], v[52:53]
	v_pk_fma_f32 v[56:57], v[0:1], v[82:83], v[56:57]
	v_pk_fma_f32 v[52:53], v[22:23], v[42:43], v[52:53]
	v_pk_fma_f32 v[56:57], v[20:21], v[40:41], v[56:57]
	v_pk_mul_f32 v[58:59], v[52:53], v[96:97]
	v_add_u32_e32 v52, -1, v144
	v_ashrrev_i32_e32 v53, 31, v52
	v_add_u32_e32 v212, -4, v148
	v_ashrrev_i32_e32 v149, 31, v148
	v_pk_mul_f32 v[56:57], v[56:57], v[90:91]
	v_lshlrev_b64 v[52:53], 11, v[52:53]
	v_cmp_eq_u32_e64 s[40:41], v146, v145
	v_cmp_gt_i32_e32 vcc, 4, v148
	v_lshl_add_u64 v[146:147], v[212:213], 1, s[6:7]
	v_lshl_add_u64 v[148:149], v[148:149], 1, s[14:15]
	v_lshl_add_u64 v[64:65], v[142:143], 0, v[52:53]
	v_cvt_pk_bf16_f32 v52, v60, v61
	v_cvt_pk_bf16_f32 v53, v62, v63
	v_cvt_pk_bf16_f32 v54, v56, v57
	v_cvt_pk_bf16_f32 v55, v58, v59
	global_store_dwordx4 v[64:65], v[52:55], off offset:1024 sc1
	s_nop 1
	v_cndmask_b32_e32 v53, v147, v149, vcc
	v_cndmask_b32_e32 v52, v146, v148, vcc
	s_and_saveexec_b64 s[22:23], s[40:41]
	s_cbranch_execz .LBB0_659
	v_mov_b32_e32 v54, 0xcfc8000
	v_mov_b32_e32 v55, 0xca00000
	v_cndmask_b32_e32 v212, v54, v55, vcc
	v_lshl_add_u64 v[54:55], s[60:61], 0, v[212:213]
	v_lshlrev_b64 v[56:57], 11, v[52:53]
	v_lshl_add_u64 v[54:55], v[54:55], 0, v[56:57]
	v_lshl_add_u64 v[54:55], v[136:137], 2, v[54:55]
	global_store_dwordx4 v[54:55], v[36:39], off sc1
	global_store_dwordx4 v[54:55], v[40:43], off offset:16 sc1
; DI F8 unpack8(uint4 u) { F8 r; r.v[0] = lo16(u.x); r.v[1] = hi16(u.x); r.v[2] = lo16(u.y); r.v[3] = hi16(u.y); r.v[4] = lo16(u.z); r.v[5] = hi16(u.z); r.v[6] = lo16(u.w); r.v[7] = hi16(u.w); return r; }
; DI void stf8(float* p, const F8& f) { *(float4*)p = make_float4(f.v[0], f.v[1], f.v[2], f.v[3]); *(float4*)(p + 4) = make_float4(f.v[4], f.v[5], f.v[6], f.v[7]); }
; DI void stb8(bf16_t* p, const F8& f) { *(uint4*)p = pack8(f); }
; DI void even_elem(const Params& p, int e) {
;     ...
;             for (int t = 0; t < 8; ++t) {
;                 const F8 gb = unpack8(gbr[t]), gc = unpack8(gcr[t]), sh = unpack8(shr[t]);
;                 F8 a0, o;
; #pragma unroll
;                 for (int k = 0; k < 8; ++k) { a0.v[k] = gc.v[k] * sh.v[k]; o.v[k] = gb.v[k] * (w0.v[k] * a2.v[k] + w1.v[k] * a1.v[k] + w2.v[k] * a0.v[k]); }
;                 stb8(CAT + (size_t)(r0 + t) * 1024 + 512 + c, o);
;                 if (last && t >= 6) {
;                     float* so = sq < 4 ? p.out + O_PSC + (((size_t)e * 4 + sq) * 2 + (t - 6)) * 512 : p.out + O_SSC + (((size_t)e * 8 + (sq - 4)) * 2 + (t - 6)) * 512;
;                     stf8(so + c, a0);
;                 }
;                 a2 = a1; a1 = a0;
;             }
.LBB0_659:
	s_or_b64 exec, exec, s[22:23]
	v_lshlrev_b32_e32 v58, 16, v28
	v_and_b32_e32 v59, 0xffff0000, v28
	v_lshlrev_b32_e32 v62, 16, v24
	v_and_b32_e32 v63, 0xffff0000, v24
	v_lshlrev_b32_e32 v66, 16, v26
	v_and_b32_e32 v67, 0xffff0000, v26
	v_lshlrev_b32_e32 v68, 16, v27
	v_and_b32_e32 v69, 0xffff0000, v27
	v_pk_mul_f32 v[26:27], v[12:13], v[36:37]
	v_lshlrev_b32_e32 v64, 16, v25
	v_and_b32_e32 v65, 0xffff0000, v25
	v_pk_mul_f32 v[24:25], v[58:59], v[62:63]
	v_pk_fma_f32 v[26:27], v[4:5], v[44:45], v[26:27]
	v_lshlrev_b32_e32 v54, 16, v32
	v_and_b32_e32 v55, 0xffff0000, v32
	v_lshlrev_b32_e32 v28, 16, v29
	v_and_b32_e32 v29, 0xffff0000, v29
	v_pk_fma_f32 v[26:27], v[16:17], v[24:25], v[26:27]
	v_pk_mul_f32 v[38:39], v[14:15], v[38:39]
	v_pk_mul_f32 v[36:37], v[26:27], v[54:55]
	v_pk_mul_f32 v[26:27], v[28:29], v[64:65]
	v_pk_fma_f32 v[28:29], v[6:7], v[46:47], v[38:39]
	v_lshlrev_b32_e32 v32, 16, v33
	v_and_b32_e32 v33, 0xffff0000, v33
	v_pk_fma_f32 v[28:29], v[18:19], v[26:27], v[28:29]
	v_lshlrev_b32_e32 v60, 16, v30
	v_and_b32_e32 v61, 0xffff0000, v30
	v_pk_mul_f32 v[38:39], v[28:29], v[32:33]
	v_pk_mul_f32 v[32:33], v[8:9], v[40:41]
	v_pk_mul_f32 v[28:29], v[60:61], v[66:67]
	v_pk_fma_f32 v[32:33], v[0:1], v[48:49], v[32:33]
	v_lshlrev_b32_e32 v56, 16, v34
	v_and_b32_e32 v57, 0xffff0000, v34
	v_pk_fma_f32 v[32:33], v[20:21], v[28:29], v[32:33]
	v_lshlrev_b32_e32 v30, 16, v31
	v_and_b32_e32 v31, 0xffff0000, v31
	v_pk_mul_f32 v[40:41], v[32:33], v[56:57]
	v_pk_mul_f32 v[32:33], v[10:11], v[42:43]
	v_pk_mul_f32 v[30:31], v[30:31], v[68:69]
	v_pk_fma_f32 v[32:33], v[2:3], v[50:51], v[32:33]
	v_lshlrev_b32_e32 v34, 16, v35
	v_and_b32_e32 v35, 0xffff0000, v35
	v_pk_fma_f32 v[32:33], v[22:23], v[30:31], v[32:33]
	v_ashrrev_i32_e32 v145, 31, v144
	v_pk_mul_f32 v[42:43], v[32:33], v[34:35]
	v_lshlrev_b64 v[32:33], 11, v[144:145]
	v_lshl_add_u64 v[44:45], v[142:143], 0, v[32:33]
	v_cvt_pk_bf16_f32 v32, v36, v37
	v_cvt_pk_bf16_f32 v33, v38, v39
	v_cvt_pk_bf16_f32 v34, v40, v41
	v_cvt_pk_bf16_f32 v35, v42, v43
	global_store_dwordx4 v[44:45], v[32:35], off offset:1024 sc1
	s_and_saveexec_b64 s[22:23], s[40:41]
	s_cbranch_execz .LBB0_650
	v_mov_b32_e32 v32, 0xcfc8800
	v_mov_b32_e32 v33, 0xca00800
	v_cndmask_b32_e32 v212, v32, v33, vcc
	v_lshlrev_b64 v[32:33], 11, v[52:53]
	v_lshl_add_u64 v[34:35], s[60:61], 0, v[212:213]
	v_lshl_add_u64 v[32:33], v[34:35], 0, v[32:33]
	v_lshl_add_u64 v[32:33], v[136:137], 2, v[32:33]
	global_store_dwordx4 v[32:33], v[24:27], off sc1
	global_store_dwordx4 v[32:33], v[28:31], off offset:16 sc1
	s_branch .LBB0_650

; DI void stb8(bf16_t* p, const F8& f) { *(uint4*)p = pack8(f); }
; DI void rowinfo(int r, int& sq, int& pos, int& len) { if (r < MP) { sq = r >> 13; pos = r & 8191; len = 8192; } else { sq = 4 + ((r - MP) >> 6); pos = r & 63; len = 64; } }
; template <int MODE>
; DI void gemm_epilogue(const float* Cs, int m0, int n0, const Epi& ep) {
;     ...
;         for (int it = 0; it < 4; ++it) {
;             const int row = (tid >> 4) + 32 * it, cc = (tid & 15) * 8, col = n0 + cc, hc = col % 96;
;             F8 x = ldf8(Cs + row * LDC + cc);
;             if (hc >= 64) {
;                 int sq, pos, len; rowinfo(m0 + row, sq, pos, len); if (sq >= 4) pos += 2048;
;                 const bool first = hc < 80;
;                 const int j0 = first ? hc - 64 : hc - 80;
;                 F8 y = ldf8(Cs + row * LDC + (first ? cc + 16 : cc - 16));
;                 const float2* rp = ep.rope + pos * 16 + j0;
; #pragma unroll
;                 for (int e = 0; e < 8; ++e) { const float2 cs = rp[e]; x.v[e] = first ? x.v[e] * cs.x - y.v[e] * cs.y : x.v[e] * cs.x + y.v[e] * cs.y; }
;             }
; #pragma unroll
;             for (int e = 0; e < 8; ++e) x.v[e] *= qs;
;             stb8(ep.b0 + (size_t)(m0 + row) * 768 + col, x);
.LBB0_738:
	s_or_b64 exec, exec, s[0:1]
	s_waitcnt lgkmcnt(0)
	v_pk_mul_f32 v[12:13], v[0:1], s[74:75] op_sel_hi:[1,0]
	v_mov_b64_e32 v[0:1], s[76:77]
	v_pk_mul_f32 v[4:5], v[4:5], s[74:75] op_sel_hi:[1,0]
	v_pk_mul_f32 v[6:7], v[6:7], s[74:75] op_sel_hi:[1,0]
	v_pk_mul_f32 v[14:15], v[2:3], s[74:75] op_sel_hi:[1,0]
	v_mad_i64_i32 v[0:1], s[0:1], v11, s97, v[0:1]
	s_add_i32 s15, s15, s14
	v_lshl_add_u64 v[8:9], v[8:9], 1, v[0:1]
	v_cvt_pk_bf16_f32 v0, v4, v5
	v_cvt_pk_bf16_f32 v1, v6, v7
	v_cvt_pk_bf16_f32 v2, v12, v13
	v_cvt_pk_bf16_f32 v3, v14, v15
	s_cmpk_lt_i32 s15, 0x186
	global_store_dwordx4 v[8:9], v[0:3], off offset:256 sc1
	s_barrier
	s_cbranch_scc0 .LBB0_811

; DI void stb8(bf16_t* p, const F8& f) { *(uint4*)p = pack8(f); }
; DI void rowinfo(int r, int& sq, int& pos, int& len) { if (r < MP) { sq = r >> 13; pos = r & 8191; len = 8192; } else { sq = 4 + ((r - MP) >> 6); pos = r & 63; len = 64; } }
; template <int MODE>
; DI void gemm_epilogue(const float* Cs, int m0, int n0, const Epi& ep) {
;     ...
;         for (int it = 0; it < 4; ++it) {
;             const int row = (tid >> 4) + 32 * it, cc = (tid & 15) * 8, col = n0 + cc, hc = col % 96;
;             F8 x = ldf8(Cs + row * LDC + cc);
;             if (hc >= 64) {
;                 int sq, pos, len; rowinfo(m0 + row, sq, pos, len); if (sq >= 4) pos += 2048;
;                 const bool first = hc < 80;
;                 const int j0 = first ? hc - 64 : hc - 80;
;                 F8 y = ldf8(Cs + row * LDC + (first ? cc + 16 : cc - 16));
;                 const float2* rp = ep.rope + pos * 16 + j0;
; #pragma unroll
;                 for (int e = 0; e < 8; ++e) { const float2 cs = rp[e]; x.v[e] = first ? x.v[e] * cs.x - y.v[e] * cs.y : x.v[e] * cs.x + y.v[e] * cs.y; }
;             }
; #pragma unroll
;             for (int e = 0; e < 8; ++e) x.v[e] *= qs;
;             stb8(ep.b0 + (size_t)(m0 + row) * 768 + col, x);
.LBB0_751:
	s_or_b64 exec, exec, s[6:7]
	s_waitcnt lgkmcnt(0)
	v_pk_mul_f32 v[112:113], v[96:97], s[74:75] op_sel_hi:[1,0]
	v_mov_b64_e32 v[96:97], s[76:77]
	v_ashrrev_i32_e32 v105, 31, v104
	v_pk_mul_f32 v[100:101], v[100:101], s[74:75] op_sel_hi:[1,0]
	v_pk_mul_f32 v[102:103], v[102:103], s[74:75] op_sel_hi:[1,0]
	v_pk_mul_f32 v[114:115], v[98:99], s[74:75] op_sel_hi:[1,0]
	v_mad_i64_i32 v[96:97], s[6:7], v110, s97, v[96:97]
	v_lshl_add_u64 v[110:111], v[104:105], 1, v[96:97]
	v_cvt_pk_bf16_f32 v96, v100, v101
	v_cvt_pk_bf16_f32 v97, v102, v103
	v_cvt_pk_bf16_f32 v98, v112, v113
	v_cvt_pk_bf16_f32 v99, v114, v115
	v_add_u32_e32 v109, 0x4200, v109
	global_store_dwordx4 v[110:111], v[96:99], off sc1
	v_lshl_add_u32 v111, v108, 2, v109
	ds_read_b128 v[100:103], v111
	ds_read_b128 v[96:99], v111 offset:16
	v_add_u32_e32 v112, 32, v107
	v_add_u32_e32 v110, s30, v112
	s_and_saveexec_b64 s[6:7], s[40:41]
	s_xor_b64 s[6:7], exec, s[6:7]
	v_add_u32_e32 v110, s30, v112
	s_andn2_saveexec_b64 s[6:7], s[6:7]
	s_cbranch_execz .LBB0_755
	v_add_u32_e32 v112, 0xffff8000, v110
	v_cmp_gt_i32_e64 s[42:43], s53, v110
	v_lshrrev_b32_e32 v112, 6, v112
	v_mov_b32_e32 v114, 0x1fff
	v_add_u32_e32 v112, 4, v112
	v_ashrrev_i32_e32 v113, 13, v110
	v_cndmask_b32_e64 v114, 63, v114, s[42:43]
	v_cndmask_b32_e64 v112, v112, v113, s[42:43]
	v_and_b32_e32 v113, v114, v110
	v_cmp_lt_i32_e64 s[42:43], 3, v112
	v_lshlrev_b32_e32 v112, 4, v113
	v_add_u32_e32 v113, 0x8000, v112
	v_cndmask_b32_e64 v112, v112, v113, s[42:43]
	v_lshlrev_b32_e32 v112, 3, v112
	v_mov_b32_e32 v113, v213
	v_lshl_add_u64 v[112:113], s[80:81], 0, v[112:113]
	v_lshl_add_u32 v111, v106, 2, v111
	v_lshl_add_u64 v[156:157], v[212:213], 3, v[112:113]
	ds_read_b128 v[112:115], v111
	ds_read_b128 v[116:119], v111 offset:16
	global_load_dwordx4 v[120:123], v[156:157], off offset:48
	global_load_dwordx4 v[124:127], v[156:157], off offset:32
	global_load_dwordx4 v[136:139], v[156:157], off offset:16
	s_nop 0
	global_load_dwordx4 v[156:159], v[156:157], off
	s_waitcnt vmcnt(0)
	v_mov_b32_e32 v161, v158
	v_mov_b32_e32 v158, v157
	s_waitcnt lgkmcnt(1)
	v_pk_mul_f32 v[112:113], v[112:113], v[158:159]
	v_mov_b32_e32 v160, v156
	v_cndmask_b32_e64 v113, v113, -v113, vcc
	v_cndmask_b32_e64 v112, v112, -v112, vcc
	v_pk_fma_f32 v[100:101], v[100:101], v[160:161], v[112:113]
	v_mov_b32_e32 v113, v138
	v_mov_b32_e32 v138, v137
	v_pk_mul_f32 v[114:115], v[114:115], v[138:139]
	v_mov_b32_e32 v112, v136
	v_cndmask_b32_e64 v115, v115, -v115, vcc
	v_cndmask_b32_e64 v114, v114, -v114, vcc
	v_pk_fma_f32 v[102:103], v[102:103], v[112:113], v[114:115]
	v_mov_b32_e32 v113, v126
	v_mov_b32_e32 v126, v125
	s_waitcnt lgkmcnt(0)
	v_pk_mul_f32 v[114:115], v[116:117], v[126:127]
	v_mov_b32_e32 v112, v124
	v_cndmask_b32_e64 v115, v115, -v115, vcc
	v_cndmask_b32_e64 v114, v114, -v114, vcc
	v_pk_fma_f32 v[96:97], v[96:97], v[112:113], v[114:115]
	v_mov_b32_e32 v113, v122
	v_mov_b32_e32 v122, v121
	v_pk_mul_f32 v[114:115], v[118:119], v[122:123]
	v_mov_b32_e32 v112, v120
	v_cndmask_b32_e64 v115, v115, -v115, vcc
	v_cndmask_b32_e64 v114, v114, -v114, vcc
	v_pk_fma_f32 v[98:99], v[98:99], v[112:113], v[114:115]
.LBB0_755:
	s_or_b64 exec, exec, s[6:7]
	s_waitcnt lgkmcnt(0)
	v_pk_mul_f32 v[112:113], v[96:97], s[74:75] op_sel_hi:[1,0]
	v_mov_b64_e32 v[96:97], s[76:77]
	v_pk_mul_f32 v[100:101], v[100:101], s[74:75] op_sel_hi:[1,0]
	v_pk_mul_f32 v[102:103], v[102:103], s[74:75] op_sel_hi:[1,0]
	v_pk_mul_f32 v[114:115], v[98:99], s[74:75] op_sel_hi:[1,0]
	v_mad_i64_i32 v[96:97], s[6:7], v110, s97, v[96:97]
	v_lshl_add_u64 v[110:111], v[104:105], 1, v[96:97]
	v_cvt_pk_bf16_f32 v96, v100, v101
	v_cvt_pk_bf16_f32 v97, v102, v103
	v_cvt_pk_bf16_f32 v98, v112, v113
	v_cvt_pk_bf16_f32 v99, v114, v115
	global_store_dwordx4 v[110:111], v[96:99], off sc1
	v_add_u32_e32 v110, 64, v107
	s_nop 0
	v_add_u32_e32 v96, 0x4200, v109
	v_lshl_add_u32 v108, v108, 2, v96
	ds_read_b128 v[100:103], v108
	ds_read_b128 v[96:99], v108 offset:16
	v_add_u32_e32 v109, s30, v110
	s_and_saveexec_b64 s[6:7], s[40:41]
	s_xor_b64 s[6:7], exec, s[6:7]
	v_add_u32_e32 v109, s30, v110
	s_andn2_saveexec_b64 s[6:7], s[6:7]
	s_cbranch_execz .LBB0_759
	v_add_u32_e32 v110, 0xffff8000, v109
	v_cmp_gt_i32_e64 s[42:43], s53, v109
	v_lshrrev_b32_e32 v110, 6, v110
	v_mov_b32_e32 v112, 0x1fff
	v_add_u32_e32 v110, 4, v110
	v_ashrrev_i32_e32 v111, 13, v109
	v_cndmask_b32_e64 v112, 63, v112, s[42:43]
	v_cndmask_b32_e64 v110, v110, v111, s[42:43]
	v_and_b32_e32 v111, v112, v109
	v_cmp_lt_i32_e64 s[42:43], 3, v110
	v_lshlrev_b32_e32 v110, 4, v111
	v_add_u32_e32 v111, 0x8000, v110
	v_cndmask_b32_e64 v110, v110, v111, s[42:43]
	v_lshlrev_b32_e32 v110, 3, v110
	v_mov_b32_e32 v111, v213
	v_lshl_add_u64 v[110:111], s[80:81], 0, v[110:111]
	v_lshl_add_u32 v114, v106, 2, v108
	v_lshl_add_u64 v[126:127], v[212:213], 3, v[110:111]
	ds_read_b128 v[110:113], v114
	ds_read_b128 v[114:117], v114 offset:16
	global_load_dwordx4 v[118:121], v[126:127], off offset:48
	global_load_dwordx4 v[122:125], v[126:127], off offset:32
	global_load_dwordx4 v[136:139], v[126:127], off offset:16
	global_load_dwordx4 v[156:159], v[126:127], off
	s_waitcnt vmcnt(0)
	v_mov_b32_e32 v127, v158
	v_mov_b32_e32 v158, v157
	s_waitcnt lgkmcnt(1)
	v_pk_mul_f32 v[110:111], v[110:111], v[158:159]
	v_mov_b32_e32 v126, v156
	v_cndmask_b32_e64 v111, v111, -v111, vcc
	v_cndmask_b32_e64 v110, v110, -v110, vcc
	v_pk_fma_f32 v[100:101], v[100:101], v[126:127], v[110:111]
	v_mov_b32_e32 v111, v138
	v_mov_b32_e32 v138, v137
	v_pk_mul_f32 v[112:113], v[112:113], v[138:139]
	v_mov_b32_e32 v110, v136
	v_cndmask_b32_e64 v113, v113, -v113, vcc
	v_cndmask_b32_e64 v112, v112, -v112, vcc
	v_pk_fma_f32 v[102:103], v[102:103], v[110:111], v[112:113]
	v_mov_b32_e32 v111, v124
	v_mov_b32_e32 v124, v123
	s_waitcnt lgkmcnt(0)
	v_pk_mul_f32 v[112:113], v[114:115], v[124:125]
	v_mov_b32_e32 v110, v122
	v_cndmask_b32_e64 v113, v113, -v113, vcc
	v_cndmask_b32_e64 v112, v112, -v112, vcc
	v_pk_fma_f32 v[96:97], v[96:97], v[110:111], v[112:113]
	v_mov_b32_e32 v111, v120
	v_mov_b32_e32 v120, v119
	v_pk_mul_f32 v[112:113], v[116:117], v[120:121]
	v_mov_b32_e32 v110, v118
	v_cndmask_b32_e64 v113, v113, -v113, vcc
	v_cndmask_b32_e64 v112, v112, -v112, vcc
	v_pk_fma_f32 v[98:99], v[98:99], v[110:111], v[112:113]
; DI void stb8(bf16_t* p, const F8& f) { *(uint4*)p = pack8(f); }
; DI void rowinfo(int r, int& sq, int& pos, int& len) { if (r < MP) { sq = r >> 13; pos = r & 8191; len = 8192; } else { sq = 4 + ((r - MP) >> 6); pos = r & 63; len = 64; } }
; template <int MODE>
; DI void gemm_epilogue(const float* Cs, int m0, int n0, const Epi& ep) {
;     ...
;         for (int it = 0; it < 4; ++it) {
;             const int row = (tid >> 4) + 32 * it, cc = (tid & 15) * 8, col = n0 + cc, hc = col % 96;
;             F8 x = ldf8(Cs + row * LDC + cc);
;             if (hc >= 64) {
;                 int sq, pos, len; rowinfo(m0 + row, sq, pos, len); if (sq >= 4) pos += 2048;
;                 const bool first = hc < 80;
;                 const int j0 = first ? hc - 64 : hc - 80;
;                 F8 y = ldf8(Cs + row * LDC + (first ? cc + 16 : cc - 16));
;                 const float2* rp = ep.rope + pos * 16 + j0;
; #pragma unroll
;                 for (int e = 0; e < 8; ++e) { const float2 cs = rp[e]; x.v[e] = first ? x.v[e] * cs.x - y.v[e] * cs.y : x.v[e] * cs.x + y.v[e] * cs.y; }
;             }
; #pragma unroll
;             for (int e = 0; e < 8; ++e) x.v[e] *= qs;
;             stb8(ep.b0 + (size_t)(m0 + row) * 768 + col, x);
; template <int MODE>
; DI void gemm_phase(const bf16_t* __restrict__ A, const bf16_t* __restrict__ Bt, int M, int N, int K, const Epi& ep) {
;     ...
; #pragma unroll
;                 for (int m = 0; m < 4; ++m)
; #pragma unroll
;                     for (int n = 0; n < 2; ++n)
;                         *(f32x4*)(Cs + (wr * 64 + m * 16 + fr) * LDC + wc * 32 + n * 16 + fq * 4) = acc[ai][bj][m][n];
;                 __syncthreads();
;                 gemm_epilogue<MODE>(Cs, brow + ai * 128, bcol + bj * 128, ep);
.LBB0_759:
	s_or_b64 exec, exec, s[6:7]
	s_waitcnt lgkmcnt(0)
	v_pk_mul_f32 v[110:111], v[96:97], s[74:75] op_sel_hi:[1,0]
	v_mov_b64_e32 v[96:97], s[76:77]
	v_pk_mul_f32 v[100:101], v[100:101], s[74:75] op_sel_hi:[1,0]
	v_pk_mul_f32 v[102:103], v[102:103], s[74:75] op_sel_hi:[1,0]
	v_pk_mul_f32 v[112:113], v[98:99], s[74:75] op_sel_hi:[1,0]
	v_mad_i64_i32 v[96:97], s[6:7], v109, s97, v[96:97]
	v_lshl_add_u64 v[114:115], v[104:105], 1, v[96:97]
	v_cvt_pk_bf16_f32 v96, v100, v101
	v_cvt_pk_bf16_f32 v97, v102, v103
	v_cvt_pk_bf16_f32 v98, v110, v111
	v_cvt_pk_bf16_f32 v99, v112, v113
	global_store_dwordx4 v[114:115], v[96:99], off sc1
	ds_read_b128 v[100:103], v108 offset:16896
	ds_read_b128 v[96:99], v108 offset:16912
	v_add_u32_e32 v109, 0x60, v107
	v_add_u32_e32 v107, s30, v109
	s_and_saveexec_b64 s[6:7], s[40:41]
	s_xor_b64 s[6:7], exec, s[6:7]
	v_add_u32_e32 v107, s30, v109
	s_andn2_saveexec_b64 s[6:7], s[6:7]
	s_cbranch_execz .LBB0_763
	v_add_u32_e32 v109, 0xffff8000, v107
	v_cmp_gt_i32_e64 s[40:41], s53, v107
	v_lshrrev_b32_e32 v109, 6, v109
	v_mov_b32_e32 v111, 0x1fff
	v_add_u32_e32 v109, 4, v109
	v_ashrrev_i32_e32 v110, 13, v107
	v_cndmask_b32_e64 v111, 63, v111, s[40:41]
	v_add_u32_e32 v108, 0x4200, v108
	v_cndmask_b32_e64 v109, v109, v110, s[40:41]
	v_and_b32_e32 v110, v111, v107
	v_lshl_add_u32 v106, v106, 2, v108
	v_lshlrev_b32_e32 v108, 4, v110
	v_cmp_lt_i32_e64 s[40:41], 3, v109
	v_add_u32_e32 v109, 0x8000, v108
	s_nop 0
	v_cndmask_b32_e64 v108, v108, v109, s[40:41]
	v_lshlrev_b32_e32 v108, 3, v108
	v_mov_b32_e32 v109, v213
	v_lshl_add_u64 v[108:109], s[80:81], 0, v[108:109]
	v_lshl_add_u64 v[136:137], v[212:213], 3, v[108:109]
	ds_read_b128 v[108:111], v106
	ds_read_b128 v[112:115], v106 offset:16
	global_load_dwordx4 v[116:119], v[136:137], off offset:48
	global_load_dwordx4 v[120:123], v[136:137], off offset:32
	global_load_dwordx4 v[124:127], v[136:137], off offset:16
	s_nop 0
	global_load_dwordx4 v[136:139], v[136:137], off
	s_waitcnt vmcnt(0)
	v_mov_b32_e32 v157, v138
	v_mov_b32_e32 v138, v137
	s_waitcnt lgkmcnt(1)
	v_pk_mul_f32 v[108:109], v[108:109], v[138:139]
	v_mov_b32_e32 v156, v136
	v_cndmask_b32_e64 v109, v109, -v109, vcc
	v_cndmask_b32_e64 v108, v108, -v108, vcc
	v_pk_fma_f32 v[100:101], v[100:101], v[156:157], v[108:109]
	v_mov_b32_e32 v109, v126
	v_mov_b32_e32 v126, v125
	v_pk_mul_f32 v[110:111], v[110:111], v[126:127]
	v_mov_b32_e32 v108, v124
	v_cndmask_b32_e64 v111, v111, -v111, vcc
	v_cndmask_b32_e64 v110, v110, -v110, vcc
	v_pk_fma_f32 v[102:103], v[102:103], v[108:109], v[110:111]
	v_mov_b32_e32 v109, v122
	v_mov_b32_e32 v122, v121
	s_waitcnt lgkmcnt(0)
	v_pk_mul_f32 v[110:111], v[112:113], v[122:123]
	v_mov_b32_e32 v108, v120
	v_cndmask_b32_e64 v111, v111, -v111, vcc
	v_cndmask_b32_e64 v110, v110, -v110, vcc
	v_pk_fma_f32 v[96:97], v[96:97], v[108:109], v[110:111]
	v_mov_b32_e32 v109, v118
	v_mov_b32_e32 v118, v117
	v_pk_mul_f32 v[110:111], v[114:115], v[118:119]
	v_mov_b32_e32 v108, v116
	v_cndmask_b32_e64 v111, v111, -v111, vcc
	v_cndmask_b32_e64 v110, v110, -v110, vcc
	v_pk_fma_f32 v[98:99], v[98:99], v[108:109], v[110:111]
.LBB0_763:
	s_or_b64 exec, exec, s[6:7]
	s_waitcnt lgkmcnt(0)
	v_pk_mul_f32 v[108:109], v[96:97], s[74:75] op_sel_hi:[1,0]
	v_mov_b64_e32 v[96:97], s[76:77]
	v_pk_mul_f32 v[100:101], v[100:101], s[74:75] op_sel_hi:[1,0]
	v_pk_mul_f32 v[102:103], v[102:103], s[74:75] op_sel_hi:[1,0]
	v_pk_mul_f32 v[110:111], v[98:99], s[74:75] op_sel_hi:[1,0]
	v_mad_i64_i32 v[96:97], s[6:7], v107, s97, v[96:97]
	v_lshl_add_u64 v[104:105], v[104:105], 1, v[96:97]
	v_cvt_pk_bf16_f32 v96, v100, v101
	v_cvt_pk_bf16_f32 v97, v102, v103
	v_cvt_pk_bf16_f32 v98, v108, v109
	v_cvt_pk_bf16_f32 v99, v110, v111
	global_store_dwordx4 v[104:105], v[96:99], off sc1
	s_barrier
	ds_write_b128 v154, v[64:67]
	ds_write_b128 v154, v[68:71] offset:64
	ds_write_b128 v154, v[72:75] offset:8448
	ds_write_b128 v154, v[76:79] offset:8512
	ds_write_b128 v154, v[80:83] offset:16896
	ds_write_b128 v154, v[84:87] offset:16960
	ds_write_b128 v154, v[88:91] offset:25344
	ds_write_b128 v154, v[92:95] offset:25408
	v_mov_b32_e32 v64, v250
	s_waitcnt lgkmcnt(0)
	s_barrier
	s_nop 0
	v_ashrrev_i32_e32 v77, 4, v64
	v_lshlrev_b32_e32 v64, 3, v64
	v_and_b32_e32 v74, 0x78, v64
	v_or_b32_e32 v72, s27, v74
	v_mul_i32_i24_e32 v64, 0x2aab, v72
	v_lshrrev_b32_e32 v65, 31, v64
	v_lshrrev_b32_e32 v64, 20, v64
	v_add_u16_e32 v64, v64, v65
	v_mul_lo_u16_e32 v75, 0x60, v64
	v_mul_lo_u32 v64, v77, s35
	v_add_u32_e32 v78, 16, v64
	v_lshl_add_u32 v73, v74, 2, v78
	ds_read_b128 v[68:71], v73
	ds_read_b128 v[64:67], v73 offset:16
	v_sub_u16_e32 v75, v72, v75
	v_cmp_gt_i16_e64 s[40:41], 64, v75
	v_cmp_gt_u16_e32 vcc, s1, v75
	v_add_u32_e32 v72, s30, v77
	s_and_saveexec_b64 s[6:7], s[40:41]
	s_xor_b64 s[6:7], exec, s[6:7]
	v_add_u32_e32 v72, s30, v77
	s_or_saveexec_b64 s[6:7], s[6:7]
	v_mov_b32_e32 v76, 0xffffffb0
	v_not_b32_e32 v79, 63
	v_cndmask_b32_e32 v76, v76, v79, vcc
	v_add_u32_sdwa v212, v76, sext(v75) dst_sel:DWORD dst_unused:UNUSED_PAD src0_sel:DWORD src1_sel:WORD_0
	v_cndmask_b32_e64 v76, -16, 16, vcc
	s_xor_b64 exec, exec, s[6:7]
	s_cbranch_execz .LBB0_767
; DI void stb8(bf16_t* p, const F8& f) { *(uint4*)p = pack8(f); }
; DI void rowinfo(int r, int& sq, int& pos, int& len) { if (r < MP) { sq = r >> 13; pos = r & 8191; len = 8192; } else { sq = 4 + ((r - MP) >> 6); pos = r & 63; len = 64; } }
; template <int MODE>
; DI void gemm_epilogue(const float* Cs, int m0, int n0, const Epi& ep) {
;     ...
;         for (int it = 0; it < 4; ++it) {
;             const int row = (tid >> 4) + 32 * it, cc = (tid & 15) * 8, col = n0 + cc, hc = col % 96;
;             F8 x = ldf8(Cs + row * LDC + cc);
;             if (hc >= 64) {
;                 int sq, pos, len; rowinfo(m0 + row, sq, pos, len); if (sq >= 4) pos += 2048;
;                 const bool first = hc < 80;
;                 const int j0 = first ? hc - 64 : hc - 80;
;                 F8 y = ldf8(Cs + row * LDC + (first ? cc + 16 : cc - 16));
;                 const float2* rp = ep.rope + pos * 16 + j0;
; #pragma unroll
;                 for (int e = 0; e < 8; ++e) { const float2 cs = rp[e]; x.v[e] = first ? x.v[e] * cs.x - y.v[e] * cs.y : x.v[e] * cs.x + y.v[e] * cs.y; }
;             }
; #pragma unroll
;             for (int e = 0; e < 8; ++e) x.v[e] *= qs;
;             stb8(ep.b0 + (size_t)(m0 + row) * 768 + col, x);
	v_add_u32_e32 v75, 0xffff8000, v72
	v_cmp_gt_i32_e64 s[42:43], s53, v72
	v_lshrrev_b32_e32 v75, 6, v75
	v_mov_b32_e32 v80, 0x1fff
	v_add_u32_e32 v75, 4, v75
	v_ashrrev_i32_e32 v79, 13, v72
	v_cndmask_b32_e64 v80, 63, v80, s[42:43]
	v_cndmask_b32_e64 v75, v75, v79, s[42:43]
	v_and_b32_e32 v79, v80, v72
	v_cmp_lt_i32_e64 s[42:43], 3, v75
	v_lshlrev_b32_e32 v75, 4, v79
	v_add_u32_e32 v79, 0x8000, v75
	v_cndmask_b32_e64 v75, v75, v79, s[42:43]
	v_lshlrev_b32_e32 v80, 3, v75
	v_mov_b32_e32 v81, v213
	v_lshl_add_u64 v[80:81], s[80:81], 0, v[80:81]
	v_lshl_add_u32 v73, v76, 2, v73
	v_lshl_add_u64 v[100:101], v[212:213], 3, v[80:81]
	ds_read_b128 v[80:83], v73
	ds_read_b128 v[84:87], v73 offset:16
	global_load_dwordx4 v[88:91], v[100:101], off offset:48
	global_load_dwordx4 v[92:95], v[100:101], off offset:32
	global_load_dwordx4 v[96:99], v[100:101], off offset:16
	s_nop 0
	global_load_dwordx4 v[100:103], v[100:101], off
	s_waitcnt vmcnt(0)
	v_mov_b32_e32 v105, v102
	v_mov_b32_e32 v102, v101
	s_waitcnt lgkmcnt(1)
	v_pk_mul_f32 v[80:81], v[80:81], v[102:103]
	v_mov_b32_e32 v104, v100
	v_cndmask_b32_e64 v81, v81, -v81, vcc
	v_cndmask_b32_e64 v80, v80, -v80, vcc
	v_pk_fma_f32 v[68:69], v[68:69], v[104:105], v[80:81]
	v_mov_b32_e32 v81, v98
	v_mov_b32_e32 v98, v97
	v_pk_mul_f32 v[82:83], v[82:83], v[98:99]
	v_mov_b32_e32 v80, v96
	v_cndmask_b32_e64 v83, v83, -v83, vcc
	v_cndmask_b32_e64 v82, v82, -v82, vcc
	v_pk_fma_f32 v[70:71], v[70:71], v[80:81], v[82:83]
	v_mov_b32_e32 v81, v94
	v_mov_b32_e32 v94, v93
	s_waitcnt lgkmcnt(0)
	v_pk_mul_f32 v[82:83], v[84:85], v[94:95]
	v_mov_b32_e32 v80, v92
	v_cndmask_b32_e64 v83, v83, -v83, vcc
	v_cndmask_b32_e64 v82, v82, -v82, vcc
	v_pk_fma_f32 v[64:65], v[64:65], v[80:81], v[82:83]
	v_mov_b32_e32 v81, v90
	v_mov_b32_e32 v90, v89
	v_pk_mul_f32 v[82:83], v[86:87], v[90:91]
	v_mov_b32_e32 v80, v88
	v_cndmask_b32_e64 v83, v83, -v83, vcc
	v_cndmask_b32_e64 v82, v82, -v82, vcc
	v_pk_fma_f32 v[66:67], v[66:67], v[80:81], v[82:83]
.LBB0_767:
	s_or_b64 exec, exec, s[6:7]
	s_waitcnt lgkmcnt(0)
	v_pk_mul_f32 v[80:81], v[64:65], s[74:75] op_sel_hi:[1,0]
	v_mov_b64_e32 v[64:65], s[76:77]
	v_mov_b32_e32 v75, v213
	s_ashr_i32 s1, s0, 31
	v_pk_mul_f32 v[68:69], v[68:69], s[74:75] op_sel_hi:[1,0]
	v_pk_mul_f32 v[70:71], v[70:71], s[74:75] op_sel_hi:[1,0]
	v_pk_mul_f32 v[82:83], v[66:67], s[74:75] op_sel_hi:[1,0]
	v_mad_i64_i32 v[64:65], s[6:7], v72, s97, v[64:65]
	v_lshl_add_u64 v[72:73], v[74:75], 0, s[0:1]
	v_lshl_add_u64 v[84:85], v[72:73], 1, v[64:65]
	v_cvt_pk_bf16_f32 v64, v68, v69
	v_cvt_pk_bf16_f32 v65, v70, v71
	v_cvt_pk_bf16_f32 v66, v80, v81
	v_cvt_pk_bf16_f32 v67, v82, v83
	v_add_u32_e32 v75, 0x4200, v78
	global_store_dwordx4 v[84:85], v[64:67], off offset:256 sc1
	v_lshl_add_u32 v79, v74, 2, v75
	ds_read_b128 v[68:71], v79
	ds_read_b128 v[64:67], v79 offset:16
	v_add_u32_e32 v80, 32, v77
	v_add_u32_e32 v78, s30, v80
	s_and_saveexec_b64 s[6:7], s[40:41]
	s_xor_b64 s[6:7], exec, s[6:7]
	v_add_u32_e32 v78, s30, v80
	s_andn2_saveexec_b64 s[6:7], s[6:7]
	s_cbranch_execz .LBB0_771
	v_add_u32_e32 v80, 0xffff8000, v78
	v_cmp_gt_i32_e64 s[42:43], s53, v78
	v_lshrrev_b32_e32 v80, 6, v80
	v_mov_b32_e32 v82, 0x1fff
	v_add_u32_e32 v80, 4, v80
	v_ashrrev_i32_e32 v81, 13, v78
	v_cndmask_b32_e64 v82, 63, v82, s[42:43]
	v_cndmask_b32_e64 v80, v80, v81, s[42:43]
	v_and_b32_e32 v81, v82, v78
	v_cmp_lt_i32_e64 s[42:43], 3, v80
	v_lshlrev_b32_e32 v80, 4, v81
	v_add_u32_e32 v81, 0x8000, v80
	v_cndmask_b32_e64 v80, v80, v81, s[42:43]
	v_lshlrev_b32_e32 v80, 3, v80
	v_mov_b32_e32 v81, v213
	v_lshl_add_u64 v[80:81], s[80:81], 0, v[80:81]
	v_lshl_add_u32 v79, v76, 2, v79
	v_lshl_add_u64 v[100:101], v[212:213], 3, v[80:81]
	ds_read_b128 v[80:83], v79
	ds_read_b128 v[84:87], v79 offset:16
	global_load_dwordx4 v[88:91], v[100:101], off offset:48
	global_load_dwordx4 v[92:95], v[100:101], off offset:32
	global_load_dwordx4 v[96:99], v[100:101], off offset:16
	s_nop 0
	global_load_dwordx4 v[100:103], v[100:101], off
	s_waitcnt vmcnt(0)
	v_mov_b32_e32 v105, v102
	v_mov_b32_e32 v102, v101
	s_waitcnt lgkmcnt(1)
	v_pk_mul_f32 v[80:81], v[80:81], v[102:103]
	v_mov_b32_e32 v104, v100
	v_cndmask_b32_e64 v81, v81, -v81, vcc
	v_cndmask_b32_e64 v80, v80, -v80, vcc
	v_pk_fma_f32 v[68:69], v[68:69], v[104:105], v[80:81]
	v_mov_b32_e32 v81, v98
	v_mov_b32_e32 v98, v97
	v_pk_mul_f32 v[82:83], v[82:83], v[98:99]
	v_mov_b32_e32 v80, v96
	v_cndmask_b32_e64 v83, v83, -v83, vcc
	v_cndmask_b32_e64 v82, v82, -v82, vcc
	v_pk_fma_f32 v[70:71], v[70:71], v[80:81], v[82:83]
	v_mov_b32_e32 v81, v94
	v_mov_b32_e32 v94, v93
	s_waitcnt lgkmcnt(0)
	v_pk_mul_f32 v[82:83], v[84:85], v[94:95]
	v_mov_b32_e32 v80, v92
	v_cndmask_b32_e64 v83, v83, -v83, vcc
	v_cndmask_b32_e64 v82, v82, -v82, vcc
	v_pk_fma_f32 v[64:65], v[64:65], v[80:81], v[82:83]
	v_mov_b32_e32 v81, v90
	v_mov_b32_e32 v90, v89
	v_pk_mul_f32 v[82:83], v[86:87], v[90:91]
	v_mov_b32_e32 v80, v88
	v_cndmask_b32_e64 v83, v83, -v83, vcc
	v_cndmask_b32_e64 v82, v82, -v82, vcc
	v_pk_fma_f32 v[66:67], v[66:67], v[80:81], v[82:83]
; DI void stb8(bf16_t* p, const F8& f) { *(uint4*)p = pack8(f); }
; DI void rowinfo(int r, int& sq, int& pos, int& len) { if (r < MP) { sq = r >> 13; pos = r & 8191; len = 8192; } else { sq = 4 + ((r - MP) >> 6); pos = r & 63; len = 64; } }
; template <int MODE>
; DI void gemm_epilogue(const float* Cs, int m0, int n0, const Epi& ep) {
;     ...
;         for (int it = 0; it < 4; ++it) {
;             const int row = (tid >> 4) + 32 * it, cc = (tid & 15) * 8, col = n0 + cc, hc = col % 96;
;             F8 x = ldf8(Cs + row * LDC + cc);
;             if (hc >= 64) {
;                 int sq, pos, len; rowinfo(m0 + row, sq, pos, len); if (sq >= 4) pos += 2048;
;                 const bool first = hc < 80;
;                 const int j0 = first ? hc - 64 : hc - 80;
;                 F8 y = ldf8(Cs + row * LDC + (first ? cc + 16 : cc - 16));
;                 const float2* rp = ep.rope + pos * 16 + j0;
; #pragma unroll
;                 for (int e = 0; e < 8; ++e) { const float2 cs = rp[e]; x.v[e] = first ? x.v[e] * cs.x - y.v[e] * cs.y : x.v[e] * cs.x + y.v[e] * cs.y; }
;             }
; #pragma unroll
;             for (int e = 0; e < 8; ++e) x.v[e] *= qs;
;             stb8(ep.b0 + (size_t)(m0 + row) * 768 + col, x);
.LBB0_771:
	s_or_b64 exec, exec, s[6:7]
	s_waitcnt lgkmcnt(0)
	v_pk_mul_f32 v[80:81], v[64:65], s[74:75] op_sel_hi:[1,0]
	v_mov_b64_e32 v[64:65], s[76:77]
	v_pk_mul_f32 v[68:69], v[68:69], s[74:75] op_sel_hi:[1,0]
	v_pk_mul_f32 v[70:71], v[70:71], s[74:75] op_sel_hi:[1,0]
	v_pk_mul_f32 v[82:83], v[66:67], s[74:75] op_sel_hi:[1,0]
	v_mad_i64_i32 v[64:65], s[6:7], v78, s97, v[64:65]
	v_lshl_add_u64 v[78:79], v[72:73], 1, v[64:65]
	v_cvt_pk_bf16_f32 v64, v68, v69
	v_cvt_pk_bf16_f32 v65, v70, v71
	v_cvt_pk_bf16_f32 v66, v80, v81
	v_cvt_pk_bf16_f32 v67, v82, v83
	global_store_dwordx4 v[78:79], v[64:67], off offset:256 sc1
	v_add_u32_e32 v78, 64, v77
	s_nop 0
	v_add_u32_e32 v64, 0x4200, v75
	v_lshl_add_u32 v74, v74, 2, v64
	ds_read_b128 v[68:71], v74
	ds_read_b128 v[64:67], v74 offset:16
	v_add_u32_e32 v75, s30, v78
	s_and_saveexec_b64 s[6:7], s[40:41]
	s_xor_b64 s[6:7], exec, s[6:7]
	v_add_u32_e32 v75, s30, v78
	s_andn2_saveexec_b64 s[6:7], s[6:7]
	s_cbranch_execz .LBB0_775
	v_add_u32_e32 v78, 0xffff8000, v75
	v_cmp_gt_i32_e64 s[42:43], s53, v75
	v_lshrrev_b32_e32 v78, 6, v78
	v_mov_b32_e32 v80, 0x1fff
	v_add_u32_e32 v78, 4, v78
	v_ashrrev_i32_e32 v79, 13, v75
	v_cndmask_b32_e64 v80, 63, v80, s[42:43]
	v_cndmask_b32_e64 v78, v78, v79, s[42:43]
	v_and_b32_e32 v79, v80, v75
	v_cmp_lt_i32_e64 s[42:43], 3, v78
	v_lshlrev_b32_e32 v78, 4, v79
	v_add_u32_e32 v79, 0x8000, v78
	v_cndmask_b32_e64 v78, v78, v79, s[42:43]
	v_lshlrev_b32_e32 v78, 3, v78
	v_mov_b32_e32 v79, v213
	v_lshl_add_u64 v[78:79], s[80:81], 0, v[78:79]
	v_lshl_add_u32 v82, v76, 2, v74
	v_lshl_add_u64 v[98:99], v[212:213], 3, v[78:79]
	ds_read_b128 v[78:81], v82
	ds_read_b128 v[82:85], v82 offset:16
	global_load_dwordx4 v[86:89], v[98:99], off offset:48
	global_load_dwordx4 v[90:93], v[98:99], off offset:32
	global_load_dwordx4 v[94:97], v[98:99], off offset:16
	s_nop 0
	global_load_dwordx4 v[98:101], v[98:99], off
	s_waitcnt vmcnt(0)
	v_mov_b32_e32 v103, v100
	v_mov_b32_e32 v100, v99
	s_waitcnt lgkmcnt(1)
	v_pk_mul_f32 v[78:79], v[78:79], v[100:101]
	v_mov_b32_e32 v102, v98
	v_cndmask_b32_e64 v79, v79, -v79, vcc
	v_cndmask_b32_e64 v78, v78, -v78, vcc
	v_pk_fma_f32 v[68:69], v[68:69], v[102:103], v[78:79]
	v_mov_b32_e32 v79, v96
	v_mov_b32_e32 v96, v95
	v_pk_mul_f32 v[80:81], v[80:81], v[96:97]
	v_mov_b32_e32 v78, v94
	v_cndmask_b32_e64 v81, v81, -v81, vcc
	v_cndmask_b32_e64 v80, v80, -v80, vcc
	v_pk_fma_f32 v[70:71], v[70:71], v[78:79], v[80:81]
	v_mov_b32_e32 v79, v92
	v_mov_b32_e32 v92, v91
	s_waitcnt lgkmcnt(0)
	v_pk_mul_f32 v[80:81], v[82:83], v[92:93]
	v_mov_b32_e32 v78, v90
	v_cndmask_b32_e64 v81, v81, -v81, vcc
	v_cndmask_b32_e64 v80, v80, -v80, vcc
	v_pk_fma_f32 v[64:65], v[64:65], v[78:79], v[80:81]
	v_mov_b32_e32 v79, v88
	v_mov_b32_e32 v88, v87
	v_pk_mul_f32 v[80:81], v[84:85], v[88:89]
	v_mov_b32_e32 v78, v86
	v_cndmask_b32_e64 v81, v81, -v81, vcc
	v_cndmask_b32_e64 v80, v80, -v80, vcc
	v_pk_fma_f32 v[66:67], v[66:67], v[78:79], v[80:81]
.LBB0_775:
	s_or_b64 exec, exec, s[6:7]
	s_waitcnt lgkmcnt(0)
	v_pk_mul_f32 v[78:79], v[64:65], s[74:75] op_sel_hi:[1,0]
	v_mov_b64_e32 v[64:65], s[76:77]
	v_pk_mul_f32 v[68:69], v[68:69], s[74:75] op_sel_hi:[1,0]
	v_pk_mul_f32 v[70:71], v[70:71], s[74:75] op_sel_hi:[1,0]
	v_pk_mul_f32 v[80:81], v[66:67], s[74:75] op_sel_hi:[1,0]
	v_mad_i64_i32 v[64:65], s[6:7], v75, s97, v[64:65]
	v_lshl_add_u64 v[82:83], v[72:73], 1, v[64:65]
	v_cvt_pk_bf16_f32 v64, v68, v69
	v_cvt_pk_bf16_f32 v65, v70, v71
	v_cvt_pk_bf16_f32 v66, v78, v79
	v_cvt_pk_bf16_f32 v67, v80, v81
	global_store_dwordx4 v[82:83], v[64:67], off offset:256 sc1
	ds_read_b128 v[68:71], v74 offset:16896
	ds_read_b128 v[64:67], v74 offset:16912
	v_add_u32_e32 v77, 0x60, v77
	v_add_u32_e32 v75, s30, v77
	s_and_saveexec_b64 s[6:7], s[40:41]
	s_xor_b64 s[6:7], exec, s[6:7]
	v_add_u32_e32 v75, s30, v77
	s_andn2_saveexec_b64 s[6:7], s[6:7]
	s_cbranch_execz .LBB0_779
	v_add_u32_e32 v77, 0xffff8000, v75
	v_cmp_gt_i32_e64 s[40:41], s53, v75
	v_lshrrev_b32_e32 v77, 6, v77
	v_mov_b32_e32 v79, 0x1fff
	v_add_u32_e32 v77, 4, v77
	v_ashrrev_i32_e32 v78, 13, v75
	v_cndmask_b32_e64 v79, 63, v79, s[40:41]
	v_add_u32_e32 v74, 0x4200, v74
	v_cndmask_b32_e64 v77, v77, v78, s[40:41]
	v_and_b32_e32 v78, v79, v75
	v_lshl_add_u32 v74, v76, 2, v74
	v_lshlrev_b32_e32 v76, 4, v78
	v_cmp_lt_i32_e64 s[40:41], 3, v77
	v_add_u32_e32 v77, 0x8000, v76
	s_nop 0
	v_cndmask_b32_e64 v76, v76, v77, s[40:41]
	v_lshlrev_b32_e32 v76, 3, v76
	v_mov_b32_e32 v77, v213
	v_lshl_add_u64 v[76:77], s[80:81], 0, v[76:77]
	v_lshl_add_u64 v[96:97], v[212:213], 3, v[76:77]
	ds_read_b128 v[76:79], v74
	ds_read_b128 v[80:83], v74 offset:16
	global_load_dwordx4 v[84:87], v[96:97], off offset:48
	global_load_dwordx4 v[88:91], v[96:97], off offset:32
	global_load_dwordx4 v[92:95], v[96:97], off offset:16
	s_nop 0
	global_load_dwordx4 v[96:99], v[96:97], off
	s_waitcnt vmcnt(0)
	v_mov_b32_e32 v101, v98
	v_mov_b32_e32 v98, v97
	s_waitcnt lgkmcnt(1)
	v_pk_mul_f32 v[76:77], v[76:77], v[98:99]
	v_mov_b32_e32 v100, v96
	v_cndmask_b32_e64 v77, v77, -v77, vcc
	v_cndmask_b32_e64 v76, v76, -v76, vcc
	v_pk_fma_f32 v[68:69], v[68:69], v[100:101], v[76:77]
	v_mov_b32_e32 v77, v94
	v_mov_b32_e32 v94, v93
	v_pk_mul_f32 v[78:79], v[78:79], v[94:95]
	v_mov_b32_e32 v76, v92
	v_cndmask_b32_e64 v79, v79, -v79, vcc
	v_cndmask_b32_e64 v78, v78, -v78, vcc
	v_pk_fma_f32 v[70:71], v[70:71], v[76:77], v[78:79]
	v_mov_b32_e32 v77, v90
	v_mov_b32_e32 v90, v89
	s_waitcnt lgkmcnt(0)
	v_pk_mul_f32 v[78:79], v[80:81], v[90:91]
	v_mov_b32_e32 v76, v88
	v_cndmask_b32_e64 v79, v79, -v79, vcc
	v_cndmask_b32_e64 v78, v78, -v78, vcc
	v_pk_fma_f32 v[64:65], v[64:65], v[76:77], v[78:79]
	v_mov_b32_e32 v77, v86
	v_mov_b32_e32 v86, v85
	v_pk_mul_f32 v[78:79], v[82:83], v[86:87]
	v_mov_b32_e32 v76, v84
	v_cndmask_b32_e64 v79, v79, -v79, vcc
	v_cndmask_b32_e64 v78, v78, -v78, vcc
	v_pk_fma_f32 v[66:67], v[66:67], v[76:77], v[78:79]
; DI void stb8(bf16_t* p, const F8& f) { *(uint4*)p = pack8(f); }
; DI void rowinfo(int r, int& sq, int& pos, int& len) { if (r < MP) { sq = r >> 13; pos = r & 8191; len = 8192; } else { sq = 4 + ((r - MP) >> 6); pos = r & 63; len = 64; } }
; template <int MODE>
; DI void gemm_epilogue(const float* Cs, int m0, int n0, const Epi& ep) {
;     ...
;         for (int it = 0; it < 4; ++it) {
;             const int row = (tid >> 4) + 32 * it, cc = (tid & 15) * 8, col = n0 + cc, hc = col % 96;
;             F8 x = ldf8(Cs + row * LDC + cc);
;             if (hc >= 64) {
;                 int sq, pos, len; rowinfo(m0 + row, sq, pos, len); if (sq >= 4) pos += 2048;
;                 const bool first = hc < 80;
;                 const int j0 = first ? hc - 64 : hc - 80;
;                 F8 y = ldf8(Cs + row * LDC + (first ? cc + 16 : cc - 16));
;                 const float2* rp = ep.rope + pos * 16 + j0;
; #pragma unroll
;                 for (int e = 0; e < 8; ++e) { const float2 cs = rp[e]; x.v[e] = first ? x.v[e] * cs.x - y.v[e] * cs.y : x.v[e] * cs.x + y.v[e] * cs.y; }
;             }
; #pragma unroll
;             for (int e = 0; e < 8; ++e) x.v[e] *= qs;
;             stb8(ep.b0 + (size_t)(m0 + row) * 768 + col, x);
; template <int MODE>
; DI void gemm_phase(const bf16_t* __restrict__ A, const bf16_t* __restrict__ Bt, int M, int N, int K, const Epi& ep) {
;     ...
;                         *(f32x4*)(Cs + (wr * 64 + m * 16 + fr) * LDC + wc * 32 + n * 16 + fq * 4) = acc[ai][bj][m][n];
;                 __syncthreads();
;                 gemm_epilogue<MODE>(Cs, brow + ai * 128, bcol + bj * 128, ep);
.LBB0_779:
	s_or_b64 exec, exec, s[6:7]
	s_waitcnt lgkmcnt(0)
	v_pk_mul_f32 v[76:77], v[64:65], s[74:75] op_sel_hi:[1,0]
	v_mov_b64_e32 v[64:65], s[76:77]
	v_pk_mul_f32 v[68:69], v[68:69], s[74:75] op_sel_hi:[1,0]
	v_pk_mul_f32 v[70:71], v[70:71], s[74:75] op_sel_hi:[1,0]
	v_pk_mul_f32 v[78:79], v[66:67], s[74:75] op_sel_hi:[1,0]
	v_mad_i64_i32 v[64:65], s[6:7], v75, s97, v[64:65]
	v_lshl_add_u64 v[72:73], v[72:73], 1, v[64:65]
	v_cvt_pk_bf16_f32 v64, v68, v69
	v_cvt_pk_bf16_f32 v65, v70, v71
	v_cvt_pk_bf16_f32 v66, v76, v77
	v_cvt_pk_bf16_f32 v67, v78, v79
	global_store_dwordx4 v[72:73], v[64:67], off offset:256 sc1
	s_barrier
	ds_write_b128 v154, v[32:35]
	ds_write_b128 v154, v[36:39] offset:64
	ds_write_b128 v154, v[40:43] offset:8448
	ds_write_b128 v154, v[44:47] offset:8512
	ds_write_b128 v154, v[48:51] offset:16896
	ds_write_b128 v154, v[52:55] offset:16960
	ds_write_b128 v154, v[56:59] offset:25344
	ds_write_b128 v154, v[60:63] offset:25408
	v_mov_b32_e32 v32, v250
	s_waitcnt lgkmcnt(0)
	s_barrier
	s_movk_i32 s6, 0x50
	v_ashrrev_i32_e32 v43, 4, v32
	v_lshlrev_b32_e32 v32, 3, v32
	v_and_b32_e32 v44, 0x78, v32
	v_or_b32_e32 v40, s0, v44
	v_mul_i32_i24_e32 v32, 0x2aab, v40
	v_lshrrev_b32_e32 v33, 31, v32
	v_lshrrev_b32_e32 v32, 20, v32
	v_add_u16_e32 v32, v32, v33
	v_mul_lo_u16_e32 v42, 0x60, v32
	v_mul_lo_u32 v32, v43, s35
	v_add_u32_e32 v45, 16, v32
	v_lshl_add_u32 v41, v44, 2, v45
	ds_read_b128 v[36:39], v41
	ds_read_b128 v[32:35], v41 offset:16
	v_sub_u16_e32 v42, v40, v42
	v_cmp_gt_i16_e64 s[40:41], 64, v42
	v_cmp_gt_u16_e32 vcc, s6, v42
	v_add_u32_e32 v46, s26, v43
	s_and_saveexec_b64 s[6:7], s[40:41]
	s_xor_b64 s[6:7], exec, s[6:7]
	v_add_u32_e32 v46, s26, v43
	s_or_saveexec_b64 s[6:7], s[6:7]
	v_mov_b32_e32 v47, 0xffffffb0
	v_not_b32_e32 v48, 63
	v_cndmask_b32_e32 v47, v47, v48, vcc
	v_add_u32_sdwa v212, v47, sext(v42) dst_sel:DWORD dst_unused:UNUSED_PAD src0_sel:DWORD src1_sel:WORD_0
	v_cndmask_b32_e64 v42, -16, 16, vcc
	s_xor_b64 exec, exec, s[6:7]
	s_cbranch_execz .LBB0_783
	v_add_u32_e32 v47, 0xffff8000, v46
	v_cmp_gt_i32_e64 s[42:43], s53, v46
	v_lshrrev_b32_e32 v47, 6, v47
	v_mov_b32_e32 v49, 0x1fff
	v_add_u32_e32 v47, 4, v47
	v_ashrrev_i32_e32 v48, 13, v46
	v_cndmask_b32_e64 v49, 63, v49, s[42:43]
	v_cndmask_b32_e64 v47, v47, v48, s[42:43]
	v_and_b32_e32 v48, v49, v46
	v_cmp_lt_i32_e64 s[42:43], 3, v47
	v_lshlrev_b32_e32 v47, 4, v48
	v_add_u32_e32 v48, 0x8000, v47
	v_cndmask_b32_e64 v47, v47, v48, s[42:43]
	v_lshlrev_b32_e32 v48, 3, v47
	v_mov_b32_e32 v49, v213
	v_lshl_add_u64 v[48:49], s[80:81], 0, v[48:49]
	v_lshl_add_u32 v41, v42, 2, v41
	v_lshl_add_u64 v[68:69], v[212:213], 3, v[48:49]
	ds_read_b128 v[48:51], v41
	ds_read_b128 v[52:55], v41 offset:16
	global_load_dwordx4 v[56:59], v[68:69], off offset:48
	global_load_dwordx4 v[60:63], v[68:69], off offset:32
	global_load_dwordx4 v[64:67], v[68:69], off offset:16
	s_nop 0
	global_load_dwordx4 v[68:71], v[68:69], off
	s_waitcnt vmcnt(0)
	v_mov_b32_e32 v73, v70
	v_mov_b32_e32 v70, v69
	s_waitcnt lgkmcnt(1)
	v_pk_mul_f32 v[48:49], v[48:49], v[70:71]
	v_mov_b32_e32 v72, v68
	v_cndmask_b32_e64 v49, v49, -v49, vcc
	v_cndmask_b32_e64 v48, v48, -v48, vcc
	v_pk_fma_f32 v[36:37], v[36:37], v[72:73], v[48:49]
	v_mov_b32_e32 v49, v66
	v_mov_b32_e32 v66, v65
	v_pk_mul_f32 v[50:51], v[50:51], v[66:67]
	v_mov_b32_e32 v48, v64
	v_cndmask_b32_e64 v51, v51, -v51, vcc
	v_cndmask_b32_e64 v50, v50, -v50, vcc
	v_pk_fma_f32 v[38:39], v[38:39], v[48:49], v[50:51]
	v_mov_b32_e32 v49, v62
	v_mov_b32_e32 v62, v61
	s_waitcnt lgkmcnt(0)
	v_pk_mul_f32 v[50:51], v[52:53], v[62:63]
	v_mov_b32_e32 v48, v60
	v_cndmask_b32_e64 v51, v51, -v51, vcc
	v_cndmask_b32_e64 v50, v50, -v50, vcc
	v_pk_fma_f32 v[32:33], v[32:33], v[48:49], v[50:51]
	v_mov_b32_e32 v49, v58
	v_mov_b32_e32 v58, v57
	v_pk_mul_f32 v[50:51], v[54:55], v[58:59]
	v_mov_b32_e32 v48, v56
	v_cndmask_b32_e64 v51, v51, -v51, vcc
	v_cndmask_b32_e64 v50, v50, -v50, vcc
	v_pk_fma_f32 v[34:35], v[34:35], v[48:49], v[50:51]
.LBB0_783:
	s_or_b64 exec, exec, s[6:7]
	s_waitcnt lgkmcnt(0)
	v_pk_mul_f32 v[48:49], v[32:33], s[74:75] op_sel_hi:[1,0]
	v_mov_b64_e32 v[32:33], s[76:77]
	v_ashrrev_i32_e32 v41, 31, v40
	v_pk_mul_f32 v[36:37], v[36:37], s[74:75] op_sel_hi:[1,0]
	v_pk_mul_f32 v[38:39], v[38:39], s[74:75] op_sel_hi:[1,0]
	v_pk_mul_f32 v[50:51], v[34:35], s[74:75] op_sel_hi:[1,0]
	v_mad_i64_i32 v[32:33], s[6:7], v46, s97, v[32:33]
	v_lshl_add_u64 v[46:47], v[40:41], 1, v[32:33]
	v_cvt_pk_bf16_f32 v32, v36, v37
	v_cvt_pk_bf16_f32 v33, v38, v39
	v_cvt_pk_bf16_f32 v34, v48, v49
	v_cvt_pk_bf16_f32 v35, v50, v51
	v_add_u32_e32 v45, 0x4200, v45
	global_store_dwordx4 v[46:47], v[32:35], off sc1
	v_lshl_add_u32 v47, v44, 2, v45
	ds_read_b128 v[36:39], v47
	ds_read_b128 v[32:35], v47 offset:16
	v_add_u32_e32 v48, 32, v43
	v_add_u32_e32 v46, s26, v48
	s_and_saveexec_b64 s[6:7], s[40:41]
	s_xor_b64 s[6:7], exec, s[6:7]
	v_add_u32_e32 v46, s26, v48
	s_andn2_saveexec_b64 s[6:7], s[6:7]
	s_cbranch_execz .LBB0_787
	v_add_u32_e32 v48, 0xffff8000, v46
	v_cmp_gt_i32_e64 s[42:43], s53, v46
	v_lshrrev_b32_e32 v48, 6, v48
	v_mov_b32_e32 v50, 0x1fff
	v_add_u32_e32 v48, 4, v48
	v_ashrrev_i32_e32 v49, 13, v46
	v_cndmask_b32_e64 v50, 63, v50, s[42:43]
	v_cndmask_b32_e64 v48, v48, v49, s[42:43]
	v_and_b32_e32 v49, v50, v46
	v_cmp_lt_i32_e64 s[42:43], 3, v48
	v_lshlrev_b32_e32 v48, 4, v49
	v_add_u32_e32 v49, 0x8000, v48
	v_cndmask_b32_e64 v48, v48, v49, s[42:43]
	v_lshlrev_b32_e32 v48, 3, v48
	v_mov_b32_e32 v49, v213
	v_lshl_add_u64 v[48:49], s[80:81], 0, v[48:49]
	v_lshl_add_u32 v47, v42, 2, v47
	v_lshl_add_u64 v[68:69], v[212:213], 3, v[48:49]
	ds_read_b128 v[48:51], v47
	ds_read_b128 v[52:55], v47 offset:16
	global_load_dwordx4 v[56:59], v[68:69], off offset:48
	global_load_dwordx4 v[60:63], v[68:69], off offset:32
	global_load_dwordx4 v[64:67], v[68:69], off offset:16
	s_nop 0
	global_load_dwordx4 v[68:71], v[68:69], off
	s_waitcnt vmcnt(0)
	v_mov_b32_e32 v73, v70
	v_mov_b32_e32 v70, v69
	s_waitcnt lgkmcnt(1)
	v_pk_mul_f32 v[48:49], v[48:49], v[70:71]
	v_mov_b32_e32 v72, v68
	v_cndmask_b32_e64 v49, v49, -v49, vcc
	v_cndmask_b32_e64 v48, v48, -v48, vcc
	v_pk_fma_f32 v[36:37], v[36:37], v[72:73], v[48:49]
	v_mov_b32_e32 v49, v66
	v_mov_b32_e32 v66, v65
	v_pk_mul_f32 v[50:51], v[50:51], v[66:67]
	v_mov_b32_e32 v48, v64
	v_cndmask_b32_e64 v51, v51, -v51, vcc
	v_cndmask_b32_e64 v50, v50, -v50, vcc
	v_pk_fma_f32 v[38:39], v[38:39], v[48:49], v[50:51]
	v_mov_b32_e32 v49, v62
	v_mov_b32_e32 v62, v61
	s_waitcnt lgkmcnt(0)
	v_pk_mul_f32 v[50:51], v[52:53], v[62:63]
	v_mov_b32_e32 v48, v60
	v_cndmask_b32_e64 v51, v51, -v51, vcc
	v_cndmask_b32_e64 v50, v50, -v50, vcc
	v_pk_fma_f32 v[32:33], v[32:33], v[48:49], v[50:51]
	v_mov_b32_e32 v49, v58
	v_mov_b32_e32 v58, v57
	v_pk_mul_f32 v[50:51], v[54:55], v[58:59]
	v_mov_b32_e32 v48, v56
	v_cndmask_b32_e64 v51, v51, -v51, vcc
	v_cndmask_b32_e64 v50, v50, -v50, vcc
	v_pk_fma_f32 v[34:35], v[34:35], v[48:49], v[50:51]
; DI void stb8(bf16_t* p, const F8& f) { *(uint4*)p = pack8(f); }
; DI void rowinfo(int r, int& sq, int& pos, int& len) { if (r < MP) { sq = r >> 13; pos = r & 8191; len = 8192; } else { sq = 4 + ((r - MP) >> 6); pos = r & 63; len = 64; } }
; template <int MODE>
; DI void gemm_epilogue(const float* Cs, int m0, int n0, const Epi& ep) {
;     ...
;         for (int it = 0; it < 4; ++it) {
;             const int row = (tid >> 4) + 32 * it, cc = (tid & 15) * 8, col = n0 + cc, hc = col % 96;
;             F8 x = ldf8(Cs + row * LDC + cc);
;             if (hc >= 64) {
;                 int sq, pos, len; rowinfo(m0 + row, sq, pos, len); if (sq >= 4) pos += 2048;
;                 const bool first = hc < 80;
;                 const int j0 = first ? hc - 64 : hc - 80;
;                 F8 y = ldf8(Cs + row * LDC + (first ? cc + 16 : cc - 16));
;                 const float2* rp = ep.rope + pos * 16 + j0;
; #pragma unroll
;                 for (int e = 0; e < 8; ++e) { const float2 cs = rp[e]; x.v[e] = first ? x.v[e] * cs.x - y.v[e] * cs.y : x.v[e] * cs.x + y.v[e] * cs.y; }
;             }
; #pragma unroll
;             for (int e = 0; e < 8; ++e) x.v[e] *= qs;
;             stb8(ep.b0 + (size_t)(m0 + row) * 768 + col, x);
.LBB0_787:
	s_or_b64 exec, exec, s[6:7]
	s_waitcnt lgkmcnt(0)
	v_pk_mul_f32 v[48:49], v[32:33], s[74:75] op_sel_hi:[1,0]
	v_mov_b64_e32 v[32:33], s[76:77]
	v_pk_mul_f32 v[36:37], v[36:37], s[74:75] op_sel_hi:[1,0]
	v_pk_mul_f32 v[38:39], v[38:39], s[74:75] op_sel_hi:[1,0]
	v_pk_mul_f32 v[50:51], v[34:35], s[74:75] op_sel_hi:[1,0]
	v_mad_i64_i32 v[32:33], s[6:7], v46, s97, v[32:33]
	v_lshl_add_u64 v[46:47], v[40:41], 1, v[32:33]
	v_cvt_pk_bf16_f32 v32, v36, v37
	v_cvt_pk_bf16_f32 v33, v38, v39
	v_cvt_pk_bf16_f32 v34, v48, v49
	v_cvt_pk_bf16_f32 v35, v50, v51
	global_store_dwordx4 v[46:47], v[32:35], off sc1
	v_add_u32_e32 v46, 64, v43
	s_nop 0
	v_add_u32_e32 v32, 0x4200, v45
	v_lshl_add_u32 v44, v44, 2, v32
	ds_read_b128 v[36:39], v44
	ds_read_b128 v[32:35], v44 offset:16
	v_add_u32_e32 v45, s26, v46
	s_and_saveexec_b64 s[6:7], s[40:41]
	s_xor_b64 s[6:7], exec, s[6:7]
	v_add_u32_e32 v45, s26, v46
	s_andn2_saveexec_b64 s[6:7], s[6:7]
	s_cbranch_execz .LBB0_791
	v_add_u32_e32 v46, 0xffff8000, v45
	v_cmp_gt_i32_e64 s[42:43], s53, v45
	v_lshrrev_b32_e32 v46, 6, v46
	v_mov_b32_e32 v48, 0x1fff
	v_add_u32_e32 v46, 4, v46
	v_ashrrev_i32_e32 v47, 13, v45
	v_cndmask_b32_e64 v48, 63, v48, s[42:43]
	v_cndmask_b32_e64 v46, v46, v47, s[42:43]
	v_and_b32_e32 v47, v48, v45
	v_cmp_lt_i32_e64 s[42:43], 3, v46
	v_lshlrev_b32_e32 v46, 4, v47
	v_add_u32_e32 v47, 0x8000, v46
	v_cndmask_b32_e64 v46, v46, v47, s[42:43]
	v_lshlrev_b32_e32 v46, 3, v46
	v_mov_b32_e32 v47, v213
	v_lshl_add_u64 v[46:47], s[80:81], 0, v[46:47]
	v_lshl_add_u32 v50, v42, 2, v44
	v_lshl_add_u64 v[66:67], v[212:213], 3, v[46:47]
	ds_read_b128 v[46:49], v50
	ds_read_b128 v[50:53], v50 offset:16
	global_load_dwordx4 v[54:57], v[66:67], off offset:48
	global_load_dwordx4 v[58:61], v[66:67], off offset:32
	global_load_dwordx4 v[62:65], v[66:67], off offset:16
	s_nop 0
	global_load_dwordx4 v[66:69], v[66:67], off
	s_waitcnt vmcnt(0)
	v_mov_b32_e32 v71, v68
	v_mov_b32_e32 v68, v67
	s_waitcnt lgkmcnt(1)
	v_pk_mul_f32 v[46:47], v[46:47], v[68:69]
	v_mov_b32_e32 v70, v66
	v_cndmask_b32_e64 v47, v47, -v47, vcc
	v_cndmask_b32_e64 v46, v46, -v46, vcc
	v_pk_fma_f32 v[36:37], v[36:37], v[70:71], v[46:47]
	v_mov_b32_e32 v47, v64
	v_mov_b32_e32 v64, v63
	v_pk_mul_f32 v[48:49], v[48:49], v[64:65]
	v_mov_b32_e32 v46, v62
	v_cndmask_b32_e64 v49, v49, -v49, vcc
	v_cndmask_b32_e64 v48, v48, -v48, vcc
	v_pk_fma_f32 v[38:39], v[38:39], v[46:47], v[48:49]
	v_mov_b32_e32 v47, v60
	v_mov_b32_e32 v60, v59
	s_waitcnt lgkmcnt(0)
	v_pk_mul_f32 v[48:49], v[50:51], v[60:61]
	v_mov_b32_e32 v46, v58
	v_cndmask_b32_e64 v49, v49, -v49, vcc
	v_cndmask_b32_e64 v48, v48, -v48, vcc
	v_pk_fma_f32 v[32:33], v[32:33], v[46:47], v[48:49]
	v_mov_b32_e32 v47, v56
	v_mov_b32_e32 v56, v55
	v_pk_mul_f32 v[48:49], v[52:53], v[56:57]
	v_mov_b32_e32 v46, v54
	v_cndmask_b32_e64 v49, v49, -v49, vcc
	v_cndmask_b32_e64 v48, v48, -v48, vcc
	v_pk_fma_f32 v[34:35], v[34:35], v[46:47], v[48:49]
.LBB0_791:
	s_or_b64 exec, exec, s[6:7]
	s_waitcnt lgkmcnt(0)
	v_pk_mul_f32 v[46:47], v[32:33], s[74:75] op_sel_hi:[1,0]
	v_mov_b64_e32 v[32:33], s[76:77]
	v_pk_mul_f32 v[36:37], v[36:37], s[74:75] op_sel_hi:[1,0]
	v_pk_mul_f32 v[38:39], v[38:39], s[74:75] op_sel_hi:[1,0]
	v_pk_mul_f32 v[48:49], v[34:35], s[74:75] op_sel_hi:[1,0]
	v_mad_i64_i32 v[32:33], s[6:7], v45, s97, v[32:33]
	v_lshl_add_u64 v[50:51], v[40:41], 1, v[32:33]
	v_cvt_pk_bf16_f32 v32, v36, v37
	v_cvt_pk_bf16_f32 v33, v38, v39
	v_cvt_pk_bf16_f32 v34, v46, v47
	v_cvt_pk_bf16_f32 v35, v48, v49
	global_store_dwordx4 v[50:51], v[32:35], off sc1
	ds_read_b128 v[36:39], v44 offset:16896
	ds_read_b128 v[32:35], v44 offset:16912
	v_add_u32_e32 v45, 0x60, v43
	v_add_u32_e32 v43, s26, v45
	s_and_saveexec_b64 s[6:7], s[40:41]
	s_xor_b64 s[6:7], exec, s[6:7]
	v_add_u32_e32 v43, s26, v45
	s_andn2_saveexec_b64 s[6:7], s[6:7]
	s_cbranch_execz .LBB0_795
	v_add_u32_e32 v45, 0xffff8000, v43
	v_cmp_gt_i32_e64 s[40:41], s53, v43
	v_lshrrev_b32_e32 v45, 6, v45
	v_mov_b32_e32 v47, 0x1fff
	v_add_u32_e32 v45, 4, v45
	v_ashrrev_i32_e32 v46, 13, v43
	v_cndmask_b32_e64 v47, 63, v47, s[40:41]
	v_add_u32_e32 v44, 0x4200, v44
	v_cndmask_b32_e64 v45, v45, v46, s[40:41]
	v_and_b32_e32 v46, v47, v43
	v_lshl_add_u32 v42, v42, 2, v44
	v_lshlrev_b32_e32 v44, 4, v46
	v_cmp_lt_i32_e64 s[40:41], 3, v45
	v_add_u32_e32 v45, 0x8000, v44
	s_nop 0
	v_cndmask_b32_e64 v44, v44, v45, s[40:41]
	v_lshlrev_b32_e32 v44, 3, v44
	v_mov_b32_e32 v45, v213
	v_lshl_add_u64 v[44:45], s[80:81], 0, v[44:45]
	v_lshl_add_u64 v[64:65], v[212:213], 3, v[44:45]
	ds_read_b128 v[44:47], v42
	ds_read_b128 v[48:51], v42 offset:16
	global_load_dwordx4 v[52:55], v[64:65], off offset:48
	global_load_dwordx4 v[56:59], v[64:65], off offset:32
	global_load_dwordx4 v[60:63], v[64:65], off offset:16
	s_nop 0
	global_load_dwordx4 v[64:67], v[64:65], off
	s_waitcnt vmcnt(0)
	v_mov_b32_e32 v69, v66
	v_mov_b32_e32 v66, v65
	s_waitcnt lgkmcnt(1)
	v_pk_mul_f32 v[44:45], v[44:45], v[66:67]
	v_mov_b32_e32 v68, v64
	v_cndmask_b32_e64 v45, v45, -v45, vcc
	v_cndmask_b32_e64 v44, v44, -v44, vcc
	v_pk_fma_f32 v[36:37], v[36:37], v[68:69], v[44:45]
	v_mov_b32_e32 v45, v62
	v_mov_b32_e32 v62, v61
	v_pk_mul_f32 v[46:47], v[46:47], v[62:63]
	v_mov_b32_e32 v44, v60
	v_cndmask_b32_e64 v47, v47, -v47, vcc
	v_cndmask_b32_e64 v46, v46, -v46, vcc
	v_pk_fma_f32 v[38:39], v[38:39], v[44:45], v[46:47]
	v_mov_b32_e32 v45, v58
	v_mov_b32_e32 v58, v57
	s_waitcnt lgkmcnt(0)
	v_pk_mul_f32 v[46:47], v[48:49], v[58:59]
	v_mov_b32_e32 v44, v56
	v_cndmask_b32_e64 v47, v47, -v47, vcc
	v_cndmask_b32_e64 v46, v46, -v46, vcc
	v_pk_fma_f32 v[32:33], v[32:33], v[44:45], v[46:47]
	v_mov_b32_e32 v45, v54
	v_mov_b32_e32 v54, v53
	v_pk_mul_f32 v[46:47], v[50:51], v[54:55]
	v_mov_b32_e32 v44, v52
	v_cndmask_b32_e64 v47, v47, -v47, vcc
	v_cndmask_b32_e64 v46, v46, -v46, vcc
	v_pk_fma_f32 v[34:35], v[34:35], v[44:45], v[46:47]
; DI void stb8(bf16_t* p, const F8& f) { *(uint4*)p = pack8(f); }
; DI void rowinfo(int r, int& sq, int& pos, int& len) { if (r < MP) { sq = r >> 13; pos = r & 8191; len = 8192; } else { sq = 4 + ((r - MP) >> 6); pos = r & 63; len = 64; } }
; template <int MODE>
; DI void gemm_epilogue(const float* Cs, int m0, int n0, const Epi& ep) {
;     ...
;         for (int it = 0; it < 4; ++it) {
;             const int row = (tid >> 4) + 32 * it, cc = (tid & 15) * 8, col = n0 + cc, hc = col % 96;
;             F8 x = ldf8(Cs + row * LDC + cc);
;             if (hc >= 64) {
;                 int sq, pos, len; rowinfo(m0 + row, sq, pos, len); if (sq >= 4) pos += 2048;
;                 const bool first = hc < 80;
;                 const int j0 = first ? hc - 64 : hc - 80;
;                 F8 y = ldf8(Cs + row * LDC + (first ? cc + 16 : cc - 16));
;                 const float2* rp = ep.rope + pos * 16 + j0;
; #pragma unroll
;                 for (int e = 0; e < 8; ++e) { const float2 cs = rp[e]; x.v[e] = first ? x.v[e] * cs.x - y.v[e] * cs.y : x.v[e] * cs.x + y.v[e] * cs.y; }
;             }
; #pragma unroll
;             for (int e = 0; e < 8; ++e) x.v[e] *= qs;
;             stb8(ep.b0 + (size_t)(m0 + row) * 768 + col, x);
; template <int MODE>
; DI void gemm_phase(const bf16_t* __restrict__ A, const bf16_t* __restrict__ Bt, int M, int N, int K, const Epi& ep) {
;     ...
;                         *(f32x4*)(Cs + (wr * 64 + m * 16 + fr) * LDC + wc * 32 + n * 16 + fq * 4) = acc[ai][bj][m][n];
;                 __syncthreads();
;                 gemm_epilogue<MODE>(Cs, brow + ai * 128, bcol + bj * 128, ep);
.LBB0_795:
	s_or_b64 exec, exec, s[6:7]
	s_waitcnt lgkmcnt(0)
	v_pk_mul_f32 v[44:45], v[32:33], s[74:75] op_sel_hi:[1,0]
	v_mov_b64_e32 v[32:33], s[76:77]
	v_pk_mul_f32 v[36:37], v[36:37], s[74:75] op_sel_hi:[1,0]
	v_pk_mul_f32 v[38:39], v[38:39], s[74:75] op_sel_hi:[1,0]
	v_pk_mul_f32 v[46:47], v[34:35], s[74:75] op_sel_hi:[1,0]
	v_mad_i64_i32 v[32:33], s[6:7], v43, s97, v[32:33]
	v_lshl_add_u64 v[40:41], v[40:41], 1, v[32:33]
	v_cvt_pk_bf16_f32 v32, v36, v37
	v_cvt_pk_bf16_f32 v33, v38, v39
	v_cvt_pk_bf16_f32 v34, v44, v45
	v_cvt_pk_bf16_f32 v35, v46, v47
	global_store_dwordx4 v[40:41], v[32:35], off sc1
	s_barrier
	ds_write_b128 v154, v[0:3]
	ds_write_b128 v154, v[4:7] offset:64
	ds_write_b128 v154, v[8:11] offset:8448
	ds_write_b128 v154, v[12:15] offset:8512
	ds_write_b128 v154, v[16:19] offset:16896
	ds_write_b128 v154, v[20:23] offset:16960
	ds_write_b128 v154, v[24:27] offset:25344
	ds_write_b128 v154, v[28:31] offset:25408
	v_mov_b32_e32 v0, v250
	s_waitcnt lgkmcnt(0)
	s_barrier
	s_movk_i32 s6, 0x50
	v_ashrrev_i32_e32 v13, 4, v0
	v_lshlrev_b32_e32 v0, 3, v0
	v_and_b32_e32 v10, 0x78, v0
	v_or_b32_e32 v8, s27, v10
	v_mul_i32_i24_e32 v0, 0x2aab, v8
	v_lshrrev_b32_e32 v1, 31, v0
	v_lshrrev_b32_e32 v0, 20, v0
	v_add_u16_e32 v0, v0, v1
	v_mul_lo_u16_e32 v11, 0x60, v0
	v_mul_lo_u32 v0, v13, s35
	v_add_u32_e32 v14, 16, v0
	v_lshl_add_u32 v9, v10, 2, v14
	ds_read_b128 v[4:7], v9
	ds_read_b128 v[0:3], v9 offset:16
	v_sub_u16_e32 v11, v8, v11
	v_cmp_gt_i16_e64 s[40:41], 64, v11
	v_cmp_gt_u16_e32 vcc, s6, v11
	v_add_u32_e32 v8, s26, v13
	s_and_saveexec_b64 s[6:7], s[40:41]
	s_xor_b64 s[6:7], exec, s[6:7]
	v_add_u32_e32 v8, s26, v13
	s_or_saveexec_b64 s[6:7], s[6:7]
	v_mov_b32_e32 v12, 0xffffffb0
	v_not_b32_e32 v15, 63
	v_cndmask_b32_e32 v12, v12, v15, vcc
	v_add_u32_sdwa v212, v12, sext(v11) dst_sel:DWORD dst_unused:UNUSED_PAD src0_sel:DWORD src1_sel:WORD_0
	v_cndmask_b32_e64 v12, -16, 16, vcc
	s_xor_b64 exec, exec, s[6:7]
	s_cbranch_execz .LBB0_799
	v_add_u32_e32 v11, 0xffff8000, v8
	v_cmp_gt_i32_e64 s[42:43], s53, v8
	v_lshrrev_b32_e32 v11, 6, v11
	v_mov_b32_e32 v16, 0x1fff
	v_add_u32_e32 v11, 4, v11
	v_ashrrev_i32_e32 v15, 13, v8
	v_cndmask_b32_e64 v16, 63, v16, s[42:43]
	v_cndmask_b32_e64 v11, v11, v15, s[42:43]
	v_and_b32_e32 v15, v16, v8
	v_cmp_lt_i32_e64 s[42:43], 3, v11
	v_lshlrev_b32_e32 v11, 4, v15
	v_add_u32_e32 v15, 0x8000, v11
	v_cndmask_b32_e64 v11, v11, v15, s[42:43]
	v_lshlrev_b32_e32 v16, 3, v11
	v_mov_b32_e32 v17, v213
	v_lshl_add_u64 v[16:17], s[80:81], 0, v[16:17]
	v_lshl_add_u32 v9, v12, 2, v9
	v_lshl_add_u64 v[36:37], v[212:213], 3, v[16:17]
	ds_read_b128 v[16:19], v9
	ds_read_b128 v[20:23], v9 offset:16
	global_load_dwordx4 v[24:27], v[36:37], off offset:48
	global_load_dwordx4 v[28:31], v[36:37], off offset:32
	global_load_dwordx4 v[32:35], v[36:37], off offset:16
	s_nop 0
	global_load_dwordx4 v[36:39], v[36:37], off
	s_waitcnt vmcnt(0)
	v_mov_b32_e32 v41, v38
	v_mov_b32_e32 v38, v37
	s_waitcnt lgkmcnt(1)
	v_pk_mul_f32 v[16:17], v[16:17], v[38:39]
	v_mov_b32_e32 v40, v36
	v_cndmask_b32_e64 v17, v17, -v17, vcc
	v_cndmask_b32_e64 v16, v16, -v16, vcc
	v_pk_fma_f32 v[4:5], v[4:5], v[40:41], v[16:17]
	v_mov_b32_e32 v17, v34
	v_mov_b32_e32 v34, v33
	v_pk_mul_f32 v[18:19], v[18:19], v[34:35]
	v_mov_b32_e32 v16, v32
	v_cndmask_b32_e64 v19, v19, -v19, vcc
	v_cndmask_b32_e64 v18, v18, -v18, vcc
	v_pk_fma_f32 v[6:7], v[6:7], v[16:17], v[18:19]
	v_mov_b32_e32 v17, v30
	v_mov_b32_e32 v30, v29
	s_waitcnt lgkmcnt(0)
	v_pk_mul_f32 v[18:19], v[20:21], v[30:31]
	v_mov_b32_e32 v16, v28
	v_cndmask_b32_e64 v19, v19, -v19, vcc
	v_cndmask_b32_e64 v18, v18, -v18, vcc
	v_pk_fma_f32 v[0:1], v[0:1], v[16:17], v[18:19]
	v_mov_b32_e32 v17, v26
	v_mov_b32_e32 v26, v25
	v_pk_mul_f32 v[18:19], v[22:23], v[26:27]
	v_mov_b32_e32 v16, v24
	v_cndmask_b32_e64 v19, v19, -v19, vcc
	v_cndmask_b32_e64 v18, v18, -v18, vcc
	v_pk_fma_f32 v[2:3], v[2:3], v[16:17], v[18:19]
.LBB0_799:
	s_or_b64 exec, exec, s[6:7]
	s_waitcnt lgkmcnt(0)
	v_pk_mul_f32 v[16:17], v[0:1], s[74:75] op_sel_hi:[1,0]
	v_mov_b64_e32 v[0:1], s[76:77]
	v_mov_b32_e32 v11, v213
	v_pk_mul_f32 v[4:5], v[4:5], s[74:75] op_sel_hi:[1,0]
	v_pk_mul_f32 v[6:7], v[6:7], s[74:75] op_sel_hi:[1,0]
	v_pk_mul_f32 v[18:19], v[2:3], s[74:75] op_sel_hi:[1,0]
	v_mad_i64_i32 v[0:1], s[6:7], v8, s97, v[0:1]
	v_lshl_add_u64 v[8:9], v[10:11], 0, s[0:1]
	v_lshl_add_u64 v[20:21], v[8:9], 1, v[0:1]
	v_cvt_pk_bf16_f32 v0, v4, v5
	v_cvt_pk_bf16_f32 v1, v6, v7
	v_cvt_pk_bf16_f32 v2, v16, v17
	v_cvt_pk_bf16_f32 v3, v18, v19
	v_add_u32_e32 v11, 0x4200, v14
	global_store_dwordx4 v[20:21], v[0:3], off offset:256 sc1
	v_lshl_add_u32 v15, v10, 2, v11
	ds_read_b128 v[4:7], v15
	ds_read_b128 v[0:3], v15 offset:16
	v_add_u32_e32 v16, 32, v13
	v_add_u32_e32 v14, s26, v16
	s_and_saveexec_b64 s[0:1], s[40:41]
	s_xor_b64 s[0:1], exec, s[0:1]
	v_add_u32_e32 v14, s26, v16
	s_andn2_saveexec_b64 s[0:1], s[0:1]
	s_cbranch_execz .LBB0_803
	v_add_u32_e32 v16, 0xffff8000, v14
	v_cmp_gt_i32_e64 s[42:43], s53, v14
	v_lshrrev_b32_e32 v16, 6, v16
	v_mov_b32_e32 v18, 0x1fff
	v_add_u32_e32 v16, 4, v16
	v_ashrrev_i32_e32 v17, 13, v14
	v_cndmask_b32_e64 v18, 63, v18, s[42:43]
	v_cndmask_b32_e64 v16, v16, v17, s[42:43]
	v_and_b32_e32 v17, v18, v14
	v_cmp_lt_i32_e64 s[42:43], 3, v16
	v_lshlrev_b32_e32 v16, 4, v17
	v_add_u32_e32 v17, 0x8000, v16
	v_cndmask_b32_e64 v16, v16, v17, s[42:43]
	v_lshlrev_b32_e32 v16, 3, v16
	v_mov_b32_e32 v17, v213
	v_lshl_add_u64 v[16:17], s[80:81], 0, v[16:17]
	v_lshl_add_u32 v15, v12, 2, v15
	v_lshl_add_u64 v[36:37], v[212:213], 3, v[16:17]
	ds_read_b128 v[16:19], v15
	ds_read_b128 v[20:23], v15 offset:16
	global_load_dwordx4 v[24:27], v[36:37], off offset:48
	global_load_dwordx4 v[28:31], v[36:37], off offset:32
	global_load_dwordx4 v[32:35], v[36:37], off offset:16
	s_nop 0
	global_load_dwordx4 v[36:39], v[36:37], off
	s_waitcnt vmcnt(0)
	v_mov_b32_e32 v41, v38
	v_mov_b32_e32 v38, v37
	s_waitcnt lgkmcnt(1)
	v_pk_mul_f32 v[16:17], v[16:17], v[38:39]
	v_mov_b32_e32 v40, v36
	v_cndmask_b32_e64 v17, v17, -v17, vcc
	v_cndmask_b32_e64 v16, v16, -v16, vcc
	v_pk_fma_f32 v[4:5], v[4:5], v[40:41], v[16:17]
	v_mov_b32_e32 v17, v34
	v_mov_b32_e32 v34, v33
	v_pk_mul_f32 v[18:19], v[18:19], v[34:35]
	v_mov_b32_e32 v16, v32
	v_cndmask_b32_e64 v19, v19, -v19, vcc
	v_cndmask_b32_e64 v18, v18, -v18, vcc
	v_pk_fma_f32 v[6:7], v[6:7], v[16:17], v[18:19]
	v_mov_b32_e32 v17, v30
	v_mov_b32_e32 v30, v29
	s_waitcnt lgkmcnt(0)
	v_pk_mul_f32 v[18:19], v[20:21], v[30:31]
	v_mov_b32_e32 v16, v28
	v_cndmask_b32_e64 v19, v19, -v19, vcc
	v_cndmask_b32_e64 v18, v18, -v18, vcc
	v_pk_fma_f32 v[0:1], v[0:1], v[16:17], v[18:19]
	v_mov_b32_e32 v17, v26
	v_mov_b32_e32 v26, v25
	v_pk_mul_f32 v[18:19], v[22:23], v[26:27]
	v_mov_b32_e32 v16, v24
	v_cndmask_b32_e64 v19, v19, -v19, vcc
	v_cndmask_b32_e64 v18, v18, -v18, vcc
	v_pk_fma_f32 v[2:3], v[2:3], v[16:17], v[18:19]
; DI void stb8(bf16_t* p, const F8& f) { *(uint4*)p = pack8(f); }
; DI void rowinfo(int r, int& sq, int& pos, int& len) { if (r < MP) { sq = r >> 13; pos = r & 8191; len = 8192; } else { sq = 4 + ((r - MP) >> 6); pos = r & 63; len = 64; } }
; template <int MODE>
; DI void gemm_epilogue(const float* Cs, int m0, int n0, const Epi& ep) {
;     ...
;         for (int it = 0; it < 4; ++it) {
;             const int row = (tid >> 4) + 32 * it, cc = (tid & 15) * 8, col = n0 + cc, hc = col % 96;
;             F8 x = ldf8(Cs + row * LDC + cc);
;             if (hc >= 64) {
;                 int sq, pos, len; rowinfo(m0 + row, sq, pos, len); if (sq >= 4) pos += 2048;
;                 const bool first = hc < 80;
;                 const int j0 = first ? hc - 64 : hc - 80;
;                 F8 y = ldf8(Cs + row * LDC + (first ? cc + 16 : cc - 16));
;                 const float2* rp = ep.rope + pos * 16 + j0;
; #pragma unroll
;                 for (int e = 0; e < 8; ++e) { const float2 cs = rp[e]; x.v[e] = first ? x.v[e] * cs.x - y.v[e] * cs.y : x.v[e] * cs.x + y.v[e] * cs.y; }
;             }
; #pragma unroll
;             for (int e = 0; e < 8; ++e) x.v[e] *= qs;
;             stb8(ep.b0 + (size_t)(m0 + row) * 768 + col, x);
.LBB0_803:
	s_or_b64 exec, exec, s[0:1]
	s_waitcnt lgkmcnt(0)
	v_pk_mul_f32 v[16:17], v[0:1], s[74:75] op_sel_hi:[1,0]
	v_mov_b64_e32 v[0:1], s[76:77]
	v_pk_mul_f32 v[4:5], v[4:5], s[74:75] op_sel_hi:[1,0]
	v_pk_mul_f32 v[6:7], v[6:7], s[74:75] op_sel_hi:[1,0]
	v_pk_mul_f32 v[18:19], v[2:3], s[74:75] op_sel_hi:[1,0]
	v_mad_i64_i32 v[0:1], s[0:1], v14, s97, v[0:1]
	v_lshl_add_u64 v[14:15], v[8:9], 1, v[0:1]
	v_cvt_pk_bf16_f32 v0, v4, v5
	v_cvt_pk_bf16_f32 v1, v6, v7
	v_cvt_pk_bf16_f32 v2, v16, v17
	v_cvt_pk_bf16_f32 v3, v18, v19
	global_store_dwordx4 v[14:15], v[0:3], off offset:256 sc1
	v_add_u32_e32 v14, 64, v13
	s_nop 0
	v_add_u32_e32 v0, 0x4200, v11
	v_lshl_add_u32 v10, v10, 2, v0
	ds_read_b128 v[4:7], v10
	ds_read_b128 v[0:3], v10 offset:16
	v_add_u32_e32 v11, s26, v14
	s_and_saveexec_b64 s[0:1], s[40:41]
	s_xor_b64 s[0:1], exec, s[0:1]
	v_add_u32_e32 v11, s26, v14
	s_andn2_saveexec_b64 s[0:1], s[0:1]
	s_cbranch_execz .LBB0_807
	v_add_u32_e32 v14, 0xffff8000, v11
	v_cmp_gt_i32_e64 s[42:43], s53, v11
	v_lshrrev_b32_e32 v14, 6, v14
	v_mov_b32_e32 v16, 0x1fff
	v_add_u32_e32 v14, 4, v14
	v_ashrrev_i32_e32 v15, 13, v11
	v_cndmask_b32_e64 v16, 63, v16, s[42:43]
	v_cndmask_b32_e64 v14, v14, v15, s[42:43]
	v_and_b32_e32 v15, v16, v11
	v_cmp_lt_i32_e64 s[42:43], 3, v14
	v_lshlrev_b32_e32 v14, 4, v15
	v_add_u32_e32 v15, 0x8000, v14
	v_cndmask_b32_e64 v14, v14, v15, s[42:43]
	v_lshlrev_b32_e32 v14, 3, v14
	v_mov_b32_e32 v15, v213
	v_lshl_add_u64 v[14:15], s[80:81], 0, v[14:15]
	v_lshl_add_u32 v18, v12, 2, v10
	v_lshl_add_u64 v[34:35], v[212:213], 3, v[14:15]
	ds_read_b128 v[14:17], v18
	ds_read_b128 v[18:21], v18 offset:16
	global_load_dwordx4 v[22:25], v[34:35], off offset:48
	global_load_dwordx4 v[26:29], v[34:35], off offset:32
	global_load_dwordx4 v[30:33], v[34:35], off offset:16
	s_nop 0
	global_load_dwordx4 v[34:37], v[34:35], off
	s_waitcnt vmcnt(0)
	v_mov_b32_e32 v39, v36
	v_mov_b32_e32 v36, v35
	s_waitcnt lgkmcnt(1)
	v_pk_mul_f32 v[14:15], v[14:15], v[36:37]
	v_mov_b32_e32 v38, v34
	v_cndmask_b32_e64 v15, v15, -v15, vcc
	v_cndmask_b32_e64 v14, v14, -v14, vcc
	v_pk_fma_f32 v[4:5], v[4:5], v[38:39], v[14:15]
	v_mov_b32_e32 v15, v32
	v_mov_b32_e32 v32, v31
	v_pk_mul_f32 v[16:17], v[16:17], v[32:33]
	v_mov_b32_e32 v14, v30
	v_cndmask_b32_e64 v17, v17, -v17, vcc
	v_cndmask_b32_e64 v16, v16, -v16, vcc
	v_pk_fma_f32 v[6:7], v[6:7], v[14:15], v[16:17]
	v_mov_b32_e32 v15, v28
	v_mov_b32_e32 v28, v27
	s_waitcnt lgkmcnt(0)
	v_pk_mul_f32 v[16:17], v[18:19], v[28:29]
	v_mov_b32_e32 v14, v26
	v_cndmask_b32_e64 v17, v17, -v17, vcc
	v_cndmask_b32_e64 v16, v16, -v16, vcc
	v_pk_fma_f32 v[0:1], v[0:1], v[14:15], v[16:17]
	v_mov_b32_e32 v15, v24
	v_mov_b32_e32 v24, v23
	v_pk_mul_f32 v[16:17], v[20:21], v[24:25]
	v_mov_b32_e32 v14, v22
	v_cndmask_b32_e64 v17, v17, -v17, vcc
	v_cndmask_b32_e64 v16, v16, -v16, vcc
	v_pk_fma_f32 v[2:3], v[2:3], v[14:15], v[16:17]
.LBB0_807:
	s_or_b64 exec, exec, s[0:1]
	s_waitcnt lgkmcnt(0)
	v_pk_mul_f32 v[14:15], v[0:1], s[74:75] op_sel_hi:[1,0]
	v_mov_b64_e32 v[0:1], s[76:77]
	v_pk_mul_f32 v[4:5], v[4:5], s[74:75] op_sel_hi:[1,0]
	v_pk_mul_f32 v[6:7], v[6:7], s[74:75] op_sel_hi:[1,0]
	v_pk_mul_f32 v[16:17], v[2:3], s[74:75] op_sel_hi:[1,0]
	v_mad_i64_i32 v[0:1], s[0:1], v11, s97, v[0:1]
	v_lshl_add_u64 v[18:19], v[8:9], 1, v[0:1]
	v_cvt_pk_bf16_f32 v0, v4, v5
	v_cvt_pk_bf16_f32 v1, v6, v7
	v_cvt_pk_bf16_f32 v2, v14, v15
	v_cvt_pk_bf16_f32 v3, v16, v17
	global_store_dwordx4 v[18:19], v[0:3], off offset:256 sc1
	ds_read_b128 v[4:7], v10 offset:16896
	ds_read_b128 v[0:3], v10 offset:16912
	v_add_u32_e32 v13, 0x60, v13
	v_add_u32_e32 v11, s26, v13
	s_and_saveexec_b64 s[0:1], s[40:41]
	s_xor_b64 s[0:1], exec, s[0:1]
	v_add_u32_e32 v11, s26, v13
	s_andn2_saveexec_b64 s[0:1], s[0:1]
	s_cbranch_execz .LBB0_738
	v_add_u32_e32 v13, 0xffff8000, v11
	v_cmp_gt_i32_e64 s[40:41], s53, v11
	v_lshrrev_b32_e32 v13, 6, v13
	v_mov_b32_e32 v15, 0x1fff
	v_add_u32_e32 v13, 4, v13
	v_ashrrev_i32_e32 v14, 13, v11
	v_cndmask_b32_e64 v15, 63, v15, s[40:41]
	v_add_u32_e32 v10, 0x4200, v10
	v_cndmask_b32_e64 v13, v13, v14, s[40:41]
	v_and_b32_e32 v14, v15, v11
	v_lshl_add_u32 v10, v12, 2, v10
	v_lshlrev_b32_e32 v12, 4, v14
	v_cmp_lt_i32_e64 s[40:41], 3, v13
	v_add_u32_e32 v13, 0x8000, v12
	s_nop 0
	v_cndmask_b32_e64 v12, v12, v13, s[40:41]
	v_lshlrev_b32_e32 v12, 3, v12
	v_mov_b32_e32 v13, v213
	v_lshl_add_u64 v[12:13], s[80:81], 0, v[12:13]
	v_lshl_add_u64 v[32:33], v[212:213], 3, v[12:13]
	ds_read_b128 v[12:15], v10
	ds_read_b128 v[16:19], v10 offset:16
	global_load_dwordx4 v[20:23], v[32:33], off offset:48
	global_load_dwordx4 v[24:27], v[32:33], off offset:32
	global_load_dwordx4 v[28:31], v[32:33], off offset:16
	s_nop 0
	global_load_dwordx4 v[32:35], v[32:33], off
	s_waitcnt vmcnt(0)
	v_mov_b32_e32 v37, v34
	v_mov_b32_e32 v34, v33
	s_waitcnt lgkmcnt(1)
	v_pk_mul_f32 v[12:13], v[12:13], v[34:35]
	v_mov_b32_e32 v36, v32
	v_cndmask_b32_e64 v13, v13, -v13, vcc
	v_cndmask_b32_e64 v12, v12, -v12, vcc
	v_pk_fma_f32 v[4:5], v[4:5], v[36:37], v[12:13]
	v_mov_b32_e32 v13, v30
	v_mov_b32_e32 v30, v29
	v_pk_mul_f32 v[14:15], v[14:15], v[30:31]
	v_mov_b32_e32 v12, v28
	v_cndmask_b32_e64 v15, v15, -v15, vcc
	v_cndmask_b32_e64 v14, v14, -v14, vcc
	v_pk_fma_f32 v[6:7], v[6:7], v[12:13], v[14:15]
	v_mov_b32_e32 v13, v26
	v_mov_b32_e32 v26, v25
	s_waitcnt lgkmcnt(0)
	v_pk_mul_f32 v[14:15], v[16:17], v[26:27]
	v_mov_b32_e32 v12, v24
	v_cndmask_b32_e64 v15, v15, -v15, vcc
	v_cndmask_b32_e64 v14, v14, -v14, vcc
	v_pk_fma_f32 v[0:1], v[0:1], v[12:13], v[14:15]
	v_mov_b32_e32 v13, v22
	v_mov_b32_e32 v22, v21
	v_pk_mul_f32 v[14:15], v[18:19], v[22:23]
	v_mov_b32_e32 v12, v20
	v_cndmask_b32_e64 v15, v15, -v15, vcc
	v_cndmask_b32_e64 v14, v14, -v14, vcc
	v_pk_fma_f32 v[2:3], v[2:3], v[12:13], v[14:15]
	s_branch .LBB0_738

; DI void stb8(bf16_t* p, const F8& f) { *(uint4*)p = pack8(f); }
; template <int MODE>
; DI void gemm_epilogue(const float* Cs, int m0, int n0, const Epi& ep) {
;     ...
;             if (kvr < MP) { vb = (size_t)(kvr >> 13) * (512 * 8192); Ts = 8192; t = kvr & 8191; }
;             else { const int s = (kvr - MP) / 2112; vb = (size_t)4 * 512 * 8192 + (size_t)s * (512 * 2112); Ts = 2112; t = kvr - MP - s * 2112; }
;             F8 x;
; #pragma unroll
;             for (int e = 0; e < 8; ++e) x.v[e] = Cs[(t8 + e) * LDC + 64 + dv];
;             stb8(ep.b1 + vb + (size_t)(h * 64 + dv) * Ts + t, x);
.LBB0_813:
	s_or_b64 exec, exec, s[6:7]
	v_add_u32_e32 v1, 0x8400, v8
	ds_read2_b32 v[10:11], v1 offset0:64 offset1:196
	v_add_u32_e32 v1, 0x8800, v8
	ds_read2_b32 v[12:13], v1 offset0:72 offset1:204
	v_add_u32_e32 v1, 0x8c00, v8
	ds_read2_b32 v[14:15], v1 offset0:80 offset1:212
	v_add_u32_e32 v1, 0x9000, v8
	ds_read2_b32 v[8:9], v1 offset0:88 offset1:220
	v_readlane_b32 s0, v254, 20
	v_readlane_b32 s1, v254, 21
	v_ashrrev_i32_e32 v1, 31, v0
	s_add_i32 s23, s23, s22
	v_lshl_add_u64 v[2:3], v[2:3], 1, s[0:1]
	v_mad_i64_i32 v[4:5], s[0:1], v4, v7, 0
	v_lshl_add_u64 v[2:3], v[4:5], 1, v[2:3]
	v_lshl_add_u64 v[4:5], v[0:1], 1, v[2:3]
	s_waitcnt lgkmcnt(3)
	v_cvt_pk_bf16_f32 v0, v10, v11
	s_waitcnt lgkmcnt(2)
	v_cvt_pk_bf16_f32 v1, v12, v13
	s_waitcnt lgkmcnt(1)
	v_cvt_pk_bf16_f32 v2, v14, v15
	s_waitcnt lgkmcnt(0)
	v_cvt_pk_bf16_f32 v3, v8, v9
	s_cmpk_lt_i32 s23, 0x308
	global_store_dwordx4 v[4:5], v[0:3], off sc1
	s_barrier
	s_cbranch_scc0 .LBB0_850

; DI void stb8(bf16_t* p, const F8& f) { *(uint4*)p = pack8(f); }
; template <int MODE>
; DI void gemm_epilogue(const float* Cs, int m0, int n0, const Epi& ep) {
;     ...
;         for (int it = 0; it < 2; ++it) {
;             const int row = (tid >> 3) + 64 * it, cc = (tid & 7) * 8;
;             stb8(ep.b0 + (size_t)(m0 + row) * 768 + h * 96 + cc, ldf8(Cs + row * LDC + cc));
;         }
;         const int dv = tid >> 3;
; #pragma unroll
;         for (int jj = 0; jj < 2; ++jj) {
;             const int t8 = ((tid & 7) + 8 * jj) * 8, kvr = m0 + t8;
;             size_t vb; int Ts, t;
;             if (kvr < MP) { vb = (size_t)(kvr >> 13) * (512 * 8192); Ts = 8192; t = kvr & 8191; }
;             else { const int s = (kvr - MP) / 2112; vb = (size_t)4 * 512 * 8192 + (size_t)s * (512 * 2112); Ts = 2112; t = kvr - MP - s * 2112; }
;             F8 x;
; #pragma unroll
;             for (int e = 0; e < 8; ++e) x.v[e] = Cs[(t8 + e) * LDC + 64 + dv];
;             stb8(ep.b1 + vb + (size_t)(h * 64 + dv) * Ts + t, x);
; template <int MODE>
; DI void gemm_phase(const bf16_t* __restrict__ A, const bf16_t* __restrict__ Bt, int M, int N, int K, const Epi& ep) {
;     ...
;                         *(f32x4*)(Cs + (wr * 64 + m * 16 + fr) * LDC + wc * 32 + n * 16 + fq * 4) = acc[ai][bj][m][n];
;                 __syncthreads();
;                 gemm_epilogue<MODE>(Cs, brow + ai * 128, bcol + bj * 128, ep);
.LBB0_818:
	s_or_b64 exec, exec, s[0:1]
	s_waitcnt vmcnt(0)
	s_barrier
	ds_write_b128 v154, v[96:99]
	ds_write_b128 v154, v[100:103] offset:64
	ds_write_b128 v154, v[104:107] offset:8448
	ds_write_b128 v154, v[108:111] offset:8512
	ds_write_b128 v154, v[112:115] offset:16896
	ds_write_b128 v154, v[116:119] offset:16960
	ds_write_b128 v154, v[120:123] offset:25344
	ds_write_b128 v154, v[124:127] offset:25408
	v_mov_b32_e32 v96, v250
	s_waitcnt lgkmcnt(0)
	s_barrier
	v_readlane_b32 s6, v254, 18
	s_lshl_b32 s26, s19, 8
	v_ashrrev_i32_e32 v99, 3, v96
	v_lshlrev_b32_e32 v96, 3, v96
	v_readlane_b32 s7, v254, 19
	v_and_b32_e32 v97, 56, v96
	s_mul_i32 s0, s18, 0xc0
	v_add_u32_e32 v98, s26, v99
	v_mov_b64_e32 v[108:109], s[6:7]
	s_movk_i32 s14, 0x600
	s_ashr_i32 s1, s0, 31
	v_lshl_add_u32 v96, v97, 2, 16
	v_mad_i64_i32 v[104:105], s[6:7], v98, s14, v[108:109]
	s_lshl_b64 s[6:7], s[0:1], 1
	v_mad_u64_u32 v[110:111], s[0:1], v99, s35, v[96:97]
	ds_read_b128 v[100:103], v110
	v_lshl_add_u64 v[112:113], v[104:105], 0, s[6:7]
	ds_read_b128 v[104:107], v110 offset:16
	v_lshlrev_b32_e32 v212, 1, v97
	v_lshl_add_u64 v[112:113], v[112:113], 0, v[212:213]
	s_waitcnt lgkmcnt(1)
	v_cvt_pk_bf16_f32 v100, v100, v101
	v_cvt_pk_bf16_f32 v101, v102, v103
	s_waitcnt lgkmcnt(0)
	v_cvt_pk_bf16_f32 v102, v104, v105
	v_cvt_pk_bf16_f32 v103, v106, v107
	global_store_dwordx4 v[112:113], v[100:103], off sc1
	ds_read_b128 v[100:103], v110 offset:33792
	ds_read_b128 v[104:107], v110 offset:33808
	v_add_u32_e32 v98, 64, v98
	v_mad_i64_i32 v[108:109], s[0:1], v98, s14, v[108:109]
	v_lshl_add_u64 v[108:109], v[108:109], 0, s[6:7]
	s_waitcnt lgkmcnt(1)
	v_cvt_pk_bf16_f32 v100, v100, v101
	v_cvt_pk_bf16_f32 v101, v102, v103
	s_waitcnt lgkmcnt(0)
	v_cvt_pk_bf16_f32 v102, v104, v105
	v_or_b32_e32 v104, s26, v97
	s_movk_i32 s0, 0x7fff
	v_lshl_add_u64 v[108:109], v[108:109], 0, v[212:213]
	v_cvt_pk_bf16_f32 v103, v106, v107
	v_cmp_lt_i32_e64 s[38:39], s0, v104
	global_store_dwordx4 v[108:109], v[100:103], off sc1
	s_and_saveexec_b64 s[0:1], s[38:39]
	s_xor_b64 s[0:1], exec, s[0:1]
	v_add_u32_e32 v98, 0xffff8000, v104
	s_mov_b32 s14, 0xf83f
	v_mul_u32_u24_sdwa v100, v98, s14 dst_sel:DWORD dst_unused:UNUSED_PAD src0_sel:WORD_0 src1_sel:DWORD
	v_lshrrev_b32_e32 v102, 27, v100
	s_mov_b32 s14, 0x108000
	v_mov_b64_e32 v[100:101], 0x1000000
	v_mad_u64_u32 v[100:101], s[14:15], v102, s14, v[100:101]
	s_movk_i32 s14, 0xf7c0
	s_nop 0
	v_mad_i32_i24 v98, v102, s14, v98
	s_or_saveexec_b64 s[14:15], s[0:1]
	s_ashr_i32 s0, s19, 5
	s_ashr_i32 s1, s0, 31
	s_lshl_b64 s[0:1], s[0:1], 22
	v_mov_b64_e32 v[102:103], 0x840
	s_xor_b64 exec, exec, s[14:15]
	v_and_b32_e32 v98, 0x1f38, v104
	v_mov_b64_e32 v[102:103], 0x2000
	v_mov_b64_e32 v[100:101], s[0:1]
	s_or_b64 exec, exec, s[14:15]
	s_movk_i32 s14, 0x20c
	v_mad_u32_u24 v96, v97, s14, v96
	v_lshl_add_u32 v104, v99, 2, v96
	v_add_u32_e32 v96, 0x400, v104
	ds_read2_b32 v[108:109], v96 offset0:72 offset1:204
	v_add_u32_e32 v96, 0x800, v104
	ds_read2_b32 v[110:111], v96 offset0:80 offset1:212
	v_add_u32_e32 v96, 0xc00, v104
	ds_read2_b32 v[106:107], v104 offset0:64 offset1:196
	ds_read2_b32 v[112:113], v96 offset0:88 offset1:220
	s_lshl_b32 s27, s18, 7
	v_readlane_b32 s14, v254, 20
	v_add_u32_e32 v103, s27, v99
	v_readlane_b32 s15, v254, 21
	v_ashrrev_i32_e32 v99, 31, v98
	v_or3_b32 v97, v97, s26, 64
	v_lshl_add_u64 v[100:101], v[100:101], 1, s[14:15]
	v_mad_i64_i32 v[114:115], s[14:15], v102, v103, 0
	v_lshl_add_u64 v[100:101], v[114:115], 1, v[100:101]
	s_movk_i32 s14, 0x7fff
	v_lshl_add_u64 v[114:115], v[98:99], 1, v[100:101]
	s_waitcnt lgkmcnt(1)
	v_cvt_pk_bf16_f32 v98, v106, v107
	v_cvt_pk_bf16_f32 v99, v108, v109
	v_cvt_pk_bf16_f32 v100, v110, v111
	s_waitcnt lgkmcnt(0)
	v_cvt_pk_bf16_f32 v101, v112, v113
	v_cmp_lt_i32_e64 s[38:39], s14, v97
	global_store_dwordx4 v[114:115], v[98:101], off sc1
	s_and_saveexec_b64 s[14:15], s[38:39]
	s_xor_b64 s[14:15], exec, s[14:15]
	v_add_u32_e32 v96, 0xffff8000, v97
	s_mov_b32 s19, 0xf83f
	v_mul_u32_u24_sdwa v97, v96, s19 dst_sel:DWORD dst_unused:UNUSED_PAD src0_sel:WORD_0 src1_sel:DWORD
	v_lshrrev_b32_e32 v97, 27, v97
	s_mov_b32 s19, 0x108000
	v_mov_b64_e32 v[98:99], 0x1000000
	v_mad_u64_u32 v[98:99], s[30:31], v97, s19, v[98:99]
	s_movk_i32 s19, 0xf7c0
	v_mad_i32_i24 v96, v97, s19, v96
	s_or_saveexec_b64 s[14:15], s[14:15]
	v_mov_b64_e32 v[100:101], 0x840
	s_xor_b64 exec, exec, s[14:15]
	v_and_b32_e32 v96, 0x1f78, v97
	v_mov_b64_e32 v[100:101], 0x2000
	v_mov_b64_e32 v[98:99], s[0:1]
	s_or_b64 exec, exec, s[14:15]
	v_add_u32_e32 v97, 0x8400, v104
	ds_read2_b32 v[106:107], v97 offset0:64 offset1:196
	v_add_u32_e32 v97, 0x8800, v104
	ds_read2_b32 v[108:109], v97 offset0:72 offset1:204
	v_add_u32_e32 v97, 0x8c00, v104
	ds_read2_b32 v[110:111], v97 offset0:80 offset1:212
	v_add_u32_e32 v97, 0x9000, v104
	ds_read2_b32 v[104:105], v97 offset0:88 offset1:220
	v_readlane_b32 s14, v254, 20
	v_readlane_b32 s15, v254, 21
	v_ashrrev_i32_e32 v97, 31, v96
	s_lshl_b32 s30, s18, 8
	v_lshl_add_u64 v[98:99], v[98:99], 1, s[14:15]
	v_mad_i64_i32 v[100:101], s[14:15], v100, v103, 0
	v_lshl_add_u64 v[98:99], v[100:101], 1, v[98:99]
	v_lshl_add_u64 v[100:101], v[96:97], 1, v[98:99]
	s_waitcnt lgkmcnt(3)
	v_cvt_pk_bf16_f32 v96, v106, v107
	s_waitcnt lgkmcnt(2)
	v_cvt_pk_bf16_f32 v97, v108, v109
	s_waitcnt lgkmcnt(1)
	v_cvt_pk_bf16_f32 v98, v110, v111
	s_waitcnt lgkmcnt(0)
	v_cvt_pk_bf16_f32 v99, v104, v105
	global_store_dwordx4 v[100:101], v[96:99], off sc1
	s_barrier
; DI void stb8(bf16_t* p, const F8& f) { *(uint4*)p = pack8(f); }
; template <int MODE>
; DI void gemm_epilogue(const float* Cs, int m0, int n0, const Epi& ep) {
;     ...
;         for (int it = 0; it < 2; ++it) {
;             const int row = (tid >> 3) + 64 * it, cc = (tid & 7) * 8;
;             stb8(ep.b0 + (size_t)(m0 + row) * 768 + h * 96 + cc, ldf8(Cs + row * LDC + cc));
;         }
;         const int dv = tid >> 3;
; #pragma unroll
;         for (int jj = 0; jj < 2; ++jj) {
;             const int t8 = ((tid & 7) + 8 * jj) * 8, kvr = m0 + t8;
;             size_t vb; int Ts, t;
;             if (kvr < MP) { vb = (size_t)(kvr >> 13) * (512 * 8192); Ts = 8192; t = kvr & 8191; }
;             else { const int s = (kvr - MP) / 2112; vb = (size_t)4 * 512 * 8192 + (size_t)s * (512 * 2112); Ts = 2112; t = kvr - MP - s * 2112; }
;             F8 x;
; #pragma unroll
;             for (int e = 0; e < 8; ++e) x.v[e] = Cs[(t8 + e) * LDC + 64 + dv];
;             stb8(ep.b1 + vb + (size_t)(h * 64 + dv) * Ts + t, x);
; template <int MODE>
; DI void gemm_phase(const bf16_t* __restrict__ A, const bf16_t* __restrict__ Bt, int M, int N, int K, const Epi& ep) {
;     ...
;                         *(f32x4*)(Cs + (wr * 64 + m * 16 + fr) * LDC + wc * 32 + n * 16 + fq * 4) = acc[ai][bj][m][n];
;                 __syncthreads();
;                 gemm_epilogue<MODE>(Cs, brow + ai * 128, bcol + bj * 128, ep);
	ds_write_b128 v154, v[64:67]
	ds_write_b128 v154, v[68:71] offset:64
	ds_write_b128 v154, v[72:75] offset:8448
	ds_write_b128 v154, v[76:79] offset:8512
	ds_write_b128 v154, v[80:83] offset:16896
	ds_write_b128 v154, v[84:87] offset:16960
	ds_write_b128 v154, v[88:91] offset:25344
	ds_write_b128 v154, v[92:95] offset:25408
	v_mov_b32_e32 v64, v250
	s_waitcnt lgkmcnt(0)
	s_barrier
	s_bitset1_b32 s30, 7
	s_ashr_i32 s14, s30, 7
	v_ashrrev_i32_e32 v67, 3, v64
	v_lshlrev_b32_e32 v64, 3, v64
	v_readlane_b32 s18, v254, 18
	v_and_b32_e32 v65, 56, v64
	s_mulk_i32 s14, 0x60
	v_readlane_b32 s19, v254, 19
	s_ashr_i32 s15, s14, 31
	v_lshl_add_u32 v64, v65, 2, 16
	v_add_u32_e32 v66, s26, v67
	v_mov_b64_e32 v[76:77], s[18:19]
	s_movk_i32 s31, 0x600
	v_mad_i64_i32 v[72:73], s[18:19], v66, s31, v[76:77]
	s_lshl_b64 s[14:15], s[14:15], 1
	v_mad_u64_u32 v[78:79], s[18:19], v67, s35, v[64:65]
	ds_read_b128 v[68:71], v78
	v_lshl_add_u64 v[80:81], v[72:73], 0, s[14:15]
	ds_read_b128 v[72:75], v78 offset:16
	v_lshlrev_b32_e32 v212, 1, v65
	v_lshl_add_u64 v[80:81], v[80:81], 0, v[212:213]
	s_waitcnt lgkmcnt(1)
	v_cvt_pk_bf16_f32 v68, v68, v69
	v_cvt_pk_bf16_f32 v69, v70, v71
	s_waitcnt lgkmcnt(0)
	v_cvt_pk_bf16_f32 v70, v72, v73
	v_cvt_pk_bf16_f32 v71, v74, v75
	global_store_dwordx4 v[80:81], v[68:71], off sc1
	ds_read_b128 v[68:71], v78 offset:33792
	ds_read_b128 v[72:75], v78 offset:33808
	v_add_u32_e32 v66, 64, v66
	v_mad_i64_i32 v[76:77], s[18:19], v66, s31, v[76:77]
	v_lshl_add_u64 v[76:77], v[76:77], 0, s[14:15]
	s_waitcnt lgkmcnt(1)
	v_cvt_pk_bf16_f32 v68, v68, v69
	v_cvt_pk_bf16_f32 v69, v70, v71
	s_waitcnt lgkmcnt(0)
	v_cvt_pk_bf16_f32 v70, v72, v73
	v_or_b32_e32 v72, s26, v65
	s_movk_i32 s18, 0x7fff
	v_lshl_add_u64 v[76:77], v[76:77], 0, v[212:213]
	v_cvt_pk_bf16_f32 v71, v74, v75
	v_cmp_lt_i32_e64 s[38:39], s18, v72
	global_store_dwordx4 v[76:77], v[68:71], off sc1
	s_and_saveexec_b64 s[18:19], s[38:39]
	s_xor_b64 s[18:19], exec, s[18:19]
	v_add_u32_e32 v66, 0xffff8000, v72
	s_mov_b32 s31, 0xf83f
	v_mul_u32_u24_sdwa v68, v66, s31 dst_sel:DWORD dst_unused:UNUSED_PAD src0_sel:WORD_0 src1_sel:DWORD
	v_lshrrev_b32_e32 v70, 27, v68
	s_mov_b32 s31, 0x108000
	v_mov_b64_e32 v[68:69], 0x1000000
	v_mad_u64_u32 v[68:69], s[38:39], v70, s31, v[68:69]
	s_movk_i32 s31, 0xf7c0
	v_mad_i32_i24 v66, v70, s31, v66
	s_or_saveexec_b64 s[18:19], s[18:19]
	v_mov_b64_e32 v[70:71], 0x840
	s_xor_b64 exec, exec, s[18:19]
	v_and_b32_e32 v66, 0x1f38, v72
	v_mov_b64_e32 v[70:71], 0x2000
	v_mov_b64_e32 v[68:69], s[0:1]
	s_or_b64 exec, exec, s[18:19]
	s_movk_i32 s18, 0x20c
	v_mad_u32_u24 v64, v65, s18, v64
	v_lshl_add_u32 v72, v67, 2, v64
	v_add_u32_e32 v64, 0x400, v72
	ds_read2_b32 v[76:77], v64 offset0:72 offset1:204
	v_add_u32_e32 v64, 0x800, v72
	ds_read2_b32 v[78:79], v64 offset0:80 offset1:212
	v_add_u32_e32 v64, 0xc00, v72
	ds_read2_b32 v[74:75], v72 offset0:64 offset1:196
	ds_read2_b32 v[80:81], v64 offset0:88 offset1:220
	s_ashr_i32 s30, s30, 1
	v_readlane_b32 s18, v254, 20
	v_add_u32_e32 v71, s30, v67
	v_readlane_b32 s19, v254, 21
	v_ashrrev_i32_e32 v67, 31, v66
	v_or3_b32 v65, v65, s26, 64
	v_lshl_add_u64 v[68:69], v[68:69], 1, s[18:19]
	v_mad_i64_i32 v[82:83], s[18:19], v70, v71, 0
	v_lshl_add_u64 v[68:69], v[82:83], 1, v[68:69]
	s_movk_i32 s18, 0x7fff
	v_lshl_add_u64 v[82:83], v[66:67], 1, v[68:69]
	s_waitcnt lgkmcnt(1)
	v_cvt_pk_bf16_f32 v66, v74, v75
	v_cvt_pk_bf16_f32 v67, v76, v77
	v_cvt_pk_bf16_f32 v68, v78, v79
	s_waitcnt lgkmcnt(0)
	v_cvt_pk_bf16_f32 v69, v80, v81
	v_cmp_lt_i32_e64 s[38:39], s18, v65
	global_store_dwordx4 v[82:83], v[66:69], off sc1
	s_and_saveexec_b64 s[18:19], s[38:39]
	s_xor_b64 s[18:19], exec, s[18:19]
	v_add_u32_e32 v64, 0xffff8000, v65
	s_mov_b32 s31, 0xf83f
	v_mul_u32_u24_sdwa v65, v64, s31 dst_sel:DWORD dst_unused:UNUSED_PAD src0_sel:WORD_0 src1_sel:DWORD
	v_lshrrev_b32_e32 v65, 27, v65
	s_mov_b32 s31, 0x108000
	v_mov_b64_e32 v[66:67], 0x1000000
	v_mad_u64_u32 v[66:67], s[38:39], v65, s31, v[66:67]
	s_movk_i32 s31, 0xf7c0
	v_mad_i32_i24 v64, v65, s31, v64
	s_or_saveexec_b64 s[18:19], s[18:19]
	v_mov_b64_e32 v[68:69], 0x840
	s_xor_b64 exec, exec, s[18:19]
	v_and_b32_e32 v64, 0x1f78, v65
	v_mov_b64_e32 v[68:69], 0x2000
	v_mov_b64_e32 v[66:67], s[0:1]
	s_or_b64 exec, exec, s[18:19]
	v_add_u32_e32 v65, 0x8400, v72
	ds_read2_b32 v[74:75], v65 offset0:64 offset1:196
	v_add_u32_e32 v65, 0x8800, v72
	ds_read2_b32 v[76:77], v65 offset0:72 offset1:204
	v_add_u32_e32 v65, 0x8c00, v72
	ds_read2_b32 v[78:79], v65 offset0:80 offset1:212
	v_add_u32_e32 v65, 0x9000, v72
	ds_read2_b32 v[72:73], v65 offset0:88 offset1:220
	v_readlane_b32 s18, v254, 20
	v_readlane_b32 s19, v254, 21
	v_ashrrev_i32_e32 v65, 31, v64
	s_bitset1_b32 s26, 7
	v_lshl_add_u64 v[66:67], v[66:67], 1, s[18:19]
	v_mad_i64_i32 v[68:69], s[18:19], v68, v71, 0
	v_lshl_add_u64 v[66:67], v[68:69], 1, v[66:67]
	v_lshl_add_u64 v[68:69], v[64:65], 1, v[66:67]
	s_waitcnt lgkmcnt(3)
	v_cvt_pk_bf16_f32 v64, v74, v75
	s_waitcnt lgkmcnt(2)
	v_cvt_pk_bf16_f32 v65, v76, v77
	s_waitcnt lgkmcnt(1)
	v_cvt_pk_bf16_f32 v66, v78, v79
	s_waitcnt lgkmcnt(0)
	v_cvt_pk_bf16_f32 v67, v72, v73
	global_store_dwordx4 v[68:69], v[64:67], off sc1
	s_barrier
	ds_write_b128 v154, v[32:35]
	ds_write_b128 v154, v[36:39] offset:64
	ds_write_b128 v154, v[40:43] offset:8448
	ds_write_b128 v154, v[44:47] offset:8512
	ds_write_b128 v154, v[48:51] offset:16896
	ds_write_b128 v154, v[52:55] offset:16960
	ds_write_b128 v154, v[56:59] offset:25344
	ds_write_b128 v154, v[60:63] offset:25408
	v_mov_b32_e32 v32, v250
	s_waitcnt lgkmcnt(0)
	s_barrier
; DI void stb8(bf16_t* p, const F8& f) { *(uint4*)p = pack8(f); }
; template <int MODE>
; DI void gemm_epilogue(const float* Cs, int m0, int n0, const Epi& ep) {
;     ...
;         for (int it = 0; it < 2; ++it) {
;             const int row = (tid >> 3) + 64 * it, cc = (tid & 7) * 8;
;             stb8(ep.b0 + (size_t)(m0 + row) * 768 + h * 96 + cc, ldf8(Cs + row * LDC + cc));
;         }
;         const int dv = tid >> 3;
; #pragma unroll
;         for (int jj = 0; jj < 2; ++jj) {
;             const int t8 = ((tid & 7) + 8 * jj) * 8, kvr = m0 + t8;
;             size_t vb; int Ts, t;
;             if (kvr < MP) { vb = (size_t)(kvr >> 13) * (512 * 8192); Ts = 8192; t = kvr & 8191; }
;             else { const int s = (kvr - MP) / 2112; vb = (size_t)4 * 512 * 8192 + (size_t)s * (512 * 2112); Ts = 2112; t = kvr - MP - s * 2112; }
;             F8 x;
; #pragma unroll
;             for (int e = 0; e < 8; ++e) x.v[e] = Cs[(t8 + e) * LDC + 64 + dv];
;             stb8(ep.b1 + vb + (size_t)(h * 64 + dv) * Ts + t, x);
	v_readlane_b32 s18, v254, 18
	v_ashrrev_i32_e32 v35, 3, v32
	v_lshlrev_b32_e32 v32, 3, v32
	v_and_b32_e32 v33, 56, v32
	v_readlane_b32 s19, v254, 19
	v_lshl_add_u32 v32, v33, 2, 16
	v_add_u32_e32 v34, s26, v35
	v_mov_b64_e32 v[44:45], s[18:19]
	s_movk_i32 s31, 0x600
	v_mad_i64_i32 v[40:41], s[18:19], v34, s31, v[44:45]
	v_mad_u64_u32 v[46:47], s[18:19], v35, s35, v[32:33]
	ds_read_b128 v[36:39], v46
	v_lshl_add_u64 v[48:49], v[40:41], 0, s[6:7]
	ds_read_b128 v[40:43], v46 offset:16
	v_lshlrev_b32_e32 v212, 1, v33
	v_lshl_add_u64 v[48:49], v[48:49], 0, v[212:213]
	s_waitcnt lgkmcnt(1)
	v_cvt_pk_bf16_f32 v36, v36, v37
	v_cvt_pk_bf16_f32 v37, v38, v39
	s_waitcnt lgkmcnt(0)
	v_cvt_pk_bf16_f32 v38, v40, v41
	v_cvt_pk_bf16_f32 v39, v42, v43
	global_store_dwordx4 v[48:49], v[36:39], off sc1
	ds_read_b128 v[36:39], v46 offset:33792
	ds_read_b128 v[40:43], v46 offset:33808
	v_add_u32_e32 v34, 64, v34
	v_mad_i64_i32 v[44:45], s[18:19], v34, s31, v[44:45]
	v_lshl_add_u64 v[44:45], v[44:45], 0, s[6:7]
	s_waitcnt lgkmcnt(1)
	v_cvt_pk_bf16_f32 v36, v36, v37
	v_cvt_pk_bf16_f32 v37, v38, v39
	s_waitcnt lgkmcnt(0)
	v_cvt_pk_bf16_f32 v38, v40, v41
	v_or_b32_e32 v40, s26, v33
	s_movk_i32 s6, 0x7fff
	v_lshl_add_u64 v[44:45], v[44:45], 0, v[212:213]
	v_cvt_pk_bf16_f32 v39, v42, v43
	v_cmp_lt_i32_e64 s[38:39], s6, v40
	global_store_dwordx4 v[44:45], v[36:39], off sc1
	s_and_saveexec_b64 s[6:7], s[38:39]
	s_xor_b64 s[6:7], exec, s[6:7]
	v_add_u32_e32 v34, 0xffff8000, v40
	s_mov_b32 s18, 0xf83f
	v_mul_u32_u24_sdwa v36, v34, s18 dst_sel:DWORD dst_unused:UNUSED_PAD src0_sel:WORD_0 src1_sel:DWORD
	v_lshrrev_b32_e32 v38, 27, v36
	s_mov_b32 s18, 0x108000
	v_mov_b64_e32 v[36:37], 0x1000000
	v_mad_u64_u32 v[36:37], s[18:19], v38, s18, v[36:37]
	s_movk_i32 s18, 0xf7c0
	s_nop 0
	v_mad_i32_i24 v34, v38, s18, v34
	s_or_saveexec_b64 s[6:7], s[6:7]
	v_mov_b64_e32 v[38:39], 0x840
	s_xor_b64 exec, exec, s[6:7]
	v_and_b32_e32 v34, 0x1fb8, v40
	v_mov_b64_e32 v[38:39], 0x2000
	v_mov_b64_e32 v[36:37], s[0:1]
	s_or_b64 exec, exec, s[6:7]
	s_movk_i32 s6, 0x20c
	v_mad_u32_u24 v32, v33, s6, v32
	v_lshl_add_u32 v40, v35, 2, v32
	v_add_u32_e32 v32, 0x400, v40
	ds_read2_b32 v[44:45], v32 offset0:72 offset1:204
	v_add_u32_e32 v32, 0x800, v40
	ds_read2_b32 v[46:47], v32 offset0:80 offset1:212
	v_add_u32_e32 v32, 0xc00, v40
	ds_read2_b32 v[42:43], v40 offset0:64 offset1:196
	ds_read2_b32 v[48:49], v32 offset0:88 offset1:220
	v_readlane_b32 s6, v254, 20
	v_add_u32_e32 v39, s27, v35
	v_readlane_b32 s7, v254, 21
	v_ashrrev_i32_e32 v35, 31, v34
	v_or3_b32 v33, v33, s26, 64
	v_lshl_add_u64 v[36:37], v[36:37], 1, s[6:7]
	v_mad_i64_i32 v[50:51], s[6:7], v38, v39, 0
	v_lshl_add_u64 v[36:37], v[50:51], 1, v[36:37]
	s_movk_i32 s6, 0x7fff
	v_lshl_add_u64 v[50:51], v[34:35], 1, v[36:37]
	s_waitcnt lgkmcnt(1)
	v_cvt_pk_bf16_f32 v34, v42, v43
	v_cvt_pk_bf16_f32 v35, v44, v45
	v_cvt_pk_bf16_f32 v36, v46, v47
	s_waitcnt lgkmcnt(0)
	v_cvt_pk_bf16_f32 v37, v48, v49
	v_cmp_lt_i32_e64 s[38:39], s6, v33
	global_store_dwordx4 v[50:51], v[34:37], off sc1
	s_and_saveexec_b64 s[6:7], s[38:39]
	s_xor_b64 s[6:7], exec, s[6:7]
	v_add_u32_e32 v32, 0xffff8000, v33
	s_mov_b32 s18, 0xf83f
	v_mul_u32_u24_sdwa v33, v32, s18 dst_sel:DWORD dst_unused:UNUSED_PAD src0_sel:WORD_0 src1_sel:DWORD
	v_lshrrev_b32_e32 v33, 27, v33
	s_mov_b32 s18, 0x108000
	v_mov_b64_e32 v[34:35], 0x1000000
	v_mad_u64_u32 v[34:35], s[18:19], v33, s18, v[34:35]
	s_movk_i32 s18, 0xf7c0
	s_nop 0
	v_mad_i32_i24 v32, v33, s18, v32
	s_or_saveexec_b64 s[6:7], s[6:7]
	v_mov_b64_e32 v[36:37], 0x840
	s_xor_b64 exec, exec, s[6:7]
	v_and_b32_e32 v32, 0x1ff8, v33
	v_mov_b64_e32 v[36:37], 0x2000
	v_mov_b64_e32 v[34:35], s[0:1]
	s_or_b64 exec, exec, s[6:7]
	v_add_u32_e32 v33, 0x8400, v40
	ds_read2_b32 v[42:43], v33 offset0:64 offset1:196
	v_add_u32_e32 v33, 0x8800, v40
	ds_read2_b32 v[44:45], v33 offset0:72 offset1:204
	v_add_u32_e32 v33, 0x8c00, v40
	ds_read2_b32 v[46:47], v33 offset0:80 offset1:212
	v_add_u32_e32 v33, 0x9000, v40
	ds_read2_b32 v[40:41], v33 offset0:88 offset1:220
	v_readlane_b32 s6, v254, 20
	v_readlane_b32 s7, v254, 21
	v_ashrrev_i32_e32 v33, 31, v32
	s_movk_i32 s18, 0x600
	v_lshl_add_u64 v[34:35], v[34:35], 1, s[6:7]
	v_mad_i64_i32 v[36:37], s[6:7], v36, v39, 0
	v_lshl_add_u64 v[34:35], v[36:37], 1, v[34:35]
	v_lshl_add_u64 v[36:37], v[32:33], 1, v[34:35]
	s_waitcnt lgkmcnt(3)
	v_cvt_pk_bf16_f32 v32, v42, v43
	s_waitcnt lgkmcnt(2)
	v_cvt_pk_bf16_f32 v33, v44, v45
	s_waitcnt lgkmcnt(1)
	v_cvt_pk_bf16_f32 v34, v46, v47
	s_waitcnt lgkmcnt(0)
	v_cvt_pk_bf16_f32 v35, v40, v41
	global_store_dwordx4 v[36:37], v[32:35], off sc1
	s_barrier
; DI void stb8(bf16_t* p, const F8& f) { *(uint4*)p = pack8(f); }
; template <int MODE>
; DI void gemm_epilogue(const float* Cs, int m0, int n0, const Epi& ep) {
;     ...
;         for (int it = 0; it < 2; ++it) {
;             const int row = (tid >> 3) + 64 * it, cc = (tid & 7) * 8;
;             stb8(ep.b0 + (size_t)(m0 + row) * 768 + h * 96 + cc, ldf8(Cs + row * LDC + cc));
;         }
;         const int dv = tid >> 3;
; #pragma unroll
;         for (int jj = 0; jj < 2; ++jj) {
;             const int t8 = ((tid & 7) + 8 * jj) * 8, kvr = m0 + t8;
;             size_t vb; int Ts, t;
;             if (kvr < MP) { vb = (size_t)(kvr >> 13) * (512 * 8192); Ts = 8192; t = kvr & 8191; }
;             else { const int s = (kvr - MP) / 2112; vb = (size_t)4 * 512 * 8192 + (size_t)s * (512 * 2112); Ts = 2112; t = kvr - MP - s * 2112; }
;             F8 x;
; #pragma unroll
;             for (int e = 0; e < 8; ++e) x.v[e] = Cs[(t8 + e) * LDC + 64 + dv];
;             stb8(ep.b1 + vb + (size_t)(h * 64 + dv) * Ts + t, x);
	ds_write_b128 v154, v[0:3]
	ds_write_b128 v154, v[4:7] offset:64
	ds_write_b128 v154, v[8:11] offset:8448
	ds_write_b128 v154, v[12:15] offset:8512
	ds_write_b128 v154, v[16:19] offset:16896
	ds_write_b128 v154, v[20:23] offset:16960
	ds_write_b128 v154, v[24:27] offset:25344
	ds_write_b128 v154, v[28:31] offset:25408
	v_mov_b32_e32 v0, v250
	s_waitcnt lgkmcnt(0)
	s_barrier
	v_readlane_b32 s6, v254, 18
	v_ashrrev_i32_e32 v3, 3, v0
	v_lshlrev_b32_e32 v0, 3, v0
	v_and_b32_e32 v1, 56, v0
	v_readlane_b32 s7, v254, 19
	v_lshl_add_u32 v0, v1, 2, 16
	v_add_u32_e32 v2, s26, v3
	v_mov_b64_e32 v[12:13], s[6:7]
	v_mad_i64_i32 v[8:9], s[6:7], v2, s18, v[12:13]
	v_mad_u64_u32 v[14:15], s[6:7], v3, s35, v[0:1]
	ds_read_b128 v[4:7], v14
	v_lshl_add_u64 v[16:17], v[8:9], 0, s[14:15]
	ds_read_b128 v[8:11], v14 offset:16
	v_lshlrev_b32_e32 v212, 1, v1
	v_lshl_add_u64 v[16:17], v[16:17], 0, v[212:213]
	s_waitcnt lgkmcnt(1)
	v_cvt_pk_bf16_f32 v4, v4, v5
	v_cvt_pk_bf16_f32 v5, v6, v7
	s_waitcnt lgkmcnt(0)
	v_cvt_pk_bf16_f32 v6, v8, v9
	v_cvt_pk_bf16_f32 v7, v10, v11
	global_store_dwordx4 v[16:17], v[4:7], off sc1
	ds_read_b128 v[4:7], v14 offset:33792
	ds_read_b128 v[8:11], v14 offset:33808
	v_add_u32_e32 v2, 64, v2
	v_mad_i64_i32 v[12:13], s[6:7], v2, s18, v[12:13]
	v_lshl_add_u64 v[12:13], v[12:13], 0, s[14:15]
	s_waitcnt lgkmcnt(1)
	v_cvt_pk_bf16_f32 v4, v4, v5
	v_cvt_pk_bf16_f32 v5, v6, v7
	s_waitcnt lgkmcnt(0)
	v_cvt_pk_bf16_f32 v6, v8, v9
	v_or_b32_e32 v8, s26, v1
	s_movk_i32 s6, 0x7fff
	s_movk_i32 s97, 0x600
	v_lshl_add_u64 v[12:13], v[12:13], 0, v[212:213]
	v_cvt_pk_bf16_f32 v7, v10, v11
	v_cmp_lt_i32_e64 s[38:39], s6, v8
	global_store_dwordx4 v[12:13], v[4:7], off sc1
	s_and_saveexec_b64 s[6:7], s[38:39]
	s_xor_b64 s[6:7], exec, s[6:7]
	v_add_u32_e32 v2, 0xffff8000, v8
	s_mov_b32 s14, 0xf83f
	v_mul_u32_u24_sdwa v4, v2, s14 dst_sel:DWORD dst_unused:UNUSED_PAD src0_sel:WORD_0 src1_sel:DWORD
	v_lshrrev_b32_e32 v6, 27, v4
	s_mov_b32 s14, 0x108000
	v_mov_b64_e32 v[4:5], 0x1000000
	v_mad_u64_u32 v[4:5], s[14:15], v6, s14, v[4:5]
	s_movk_i32 s14, 0xf7c0
	s_nop 0
	v_mad_i32_i24 v2, v6, s14, v2
	s_or_saveexec_b64 s[6:7], s[6:7]
	v_mov_b64_e32 v[6:7], 0x840
	s_xor_b64 exec, exec, s[6:7]
	v_and_b32_e32 v2, 0x1fb8, v8
	v_mov_b64_e32 v[6:7], 0x2000
	v_mov_b64_e32 v[4:5], s[0:1]
	s_or_b64 exec, exec, s[6:7]
	s_movk_i32 s6, 0x20c
	v_mad_u32_u24 v0, v1, s6, v0
	v_lshl_add_u32 v8, v3, 2, v0
	v_add_u32_e32 v0, 0x400, v8
	ds_read2_b32 v[12:13], v0 offset0:72 offset1:204
	v_add_u32_e32 v0, 0x800, v8
	ds_read2_b32 v[14:15], v0 offset0:80 offset1:212
	v_add_u32_e32 v0, 0xc00, v8
	ds_read2_b32 v[10:11], v8 offset0:64 offset1:196
	ds_read2_b32 v[16:17], v0 offset0:88 offset1:220
	v_readlane_b32 s6, v254, 20
	v_add_u32_e32 v7, s30, v3
	v_readlane_b32 s7, v254, 21
	v_ashrrev_i32_e32 v3, 31, v2
	v_or3_b32 v1, v1, s26, 64
	v_lshl_add_u64 v[4:5], v[4:5], 1, s[6:7]
	v_mad_i64_i32 v[18:19], s[6:7], v6, v7, 0
	v_lshl_add_u64 v[4:5], v[18:19], 1, v[4:5]
	s_movk_i32 s6, 0x7fff
	v_lshl_add_u64 v[18:19], v[2:3], 1, v[4:5]
	s_waitcnt lgkmcnt(1)
	v_cvt_pk_bf16_f32 v2, v10, v11
	v_cvt_pk_bf16_f32 v3, v12, v13
	v_cvt_pk_bf16_f32 v4, v14, v15
	s_waitcnt lgkmcnt(0)
	v_cvt_pk_bf16_f32 v5, v16, v17
	v_cmp_lt_i32_e64 s[38:39], s6, v1
	global_store_dwordx4 v[18:19], v[2:5], off sc1
	s_and_saveexec_b64 s[6:7], s[38:39]
	s_xor_b64 s[6:7], exec, s[6:7]
	v_add_u32_e32 v0, 0xffff8000, v1
	s_mov_b32 s14, 0xf83f
	v_mul_u32_u24_sdwa v1, v0, s14 dst_sel:DWORD dst_unused:UNUSED_PAD src0_sel:WORD_0 src1_sel:DWORD
	v_lshrrev_b32_e32 v1, 27, v1
	s_mov_b32 s14, 0x108000
	v_mov_b64_e32 v[2:3], 0x1000000
	v_mad_u64_u32 v[2:3], s[14:15], v1, s14, v[2:3]
	s_movk_i32 s14, 0xf7c0
	s_nop 0
	v_mad_i32_i24 v0, v1, s14, v0
	s_or_saveexec_b64 s[6:7], s[6:7]
	v_mov_b64_e32 v[4:5], 0x840
	s_xor_b64 exec, exec, s[6:7]
	s_cbranch_execz .LBB0_813
	v_and_b32_e32 v0, 0x1ff8, v1
	v_mov_b64_e32 v[4:5], 0x2000
	v_mov_b64_e32 v[2:3], s[0:1]
	s_branch .LBB0_813

; DI void stb8(bf16_t* p, const F8& f) { *(uint4*)p = pack8(f); }
; template <int MODE>
; DI void gemm_epilogue(const float* Cs, int m0, int n0, const Epi& ep) {
;     ...
; #pragma unroll
;         for (int it = 0; it < 4; ++it) {
;             const int row = (tid >> 4) + 32 * it, cc = (tid & 15) * 8;
;             stb8(ep.b0 + (size_t)(m0 + row) * ep.ld + n0 + cc, ldf8(Cs + row * LDC + cc));
;         }
; template <int MODE>
; DI void gemm_phase(const bf16_t* __restrict__ A, const bf16_t* __restrict__ Bt, int M, int N, int K, const Epi& ep) {
;     ...
;                         *(f32x4*)(Cs + (wr * 64 + m * 16 + fr) * LDC + wc * 32 + n * 16 + fq * 4) = acc[ai][bj][m][n];
;                 __syncthreads();
;                 gemm_epilogue<MODE>(Cs, brow + ai * 128, bcol + bj * 128, ep);
.LBB0_1015:
	s_or_b64 exec, exec, s[6:7]
	v_mov_b32_e32 v64, v250
	s_waitcnt vmcnt(0)
	s_barrier
	ds_write_b128 v146, v[96:99]
	ds_write_b128 v146, v[100:103] offset:64
	ds_write_b128 v146, v[104:107] offset:8448
	ds_write_b128 v146, v[108:111] offset:8512
	ds_write_b128 v146, v[112:115] offset:16896
	ds_write_b128 v146, v[116:119] offset:16960
	ds_write_b128 v146, v[120:123] offset:25344
	ds_write_b128 v146, v[124:127] offset:25408
	s_waitcnt lgkmcnt(0)
	s_barrier
	s_lshl_b64 s[0:1], s[0:1], 1
	v_ashrrev_i32_e32 v66, 4, v64
	v_add_u32_e32 v100, s30, v66
	v_lshlrev_b32_e32 v64, 3, v64
	v_ashrrev_i32_e32 v101, 31, v100
	v_and_b32_e32 v104, 0x78, v64
	v_lshlrev_b64 v[64:65], 11, v[100:101]
	v_lshlrev_b32_e32 v67, 2, v104
	v_lshl_add_u64 v[96:97], s[76:77], 0, v[64:65]
	v_mul_lo_u32 v64, v66, s35
	v_add3_u32 v105, 16, v67, v64
	ds_read_b128 v[64:67], v105
	v_lshl_add_u64 v[102:103], v[96:97], 0, s[0:1]
	ds_read_b128 v[96:99], v105 offset:16
	v_lshlrev_b32_e32 v212, 1, v104
	v_lshl_add_u64 v[102:103], v[102:103], 0, v[212:213]
	s_waitcnt lgkmcnt(1)
	v_cvt_pk_bf16_f32 v64, v64, v65
	v_cvt_pk_bf16_f32 v65, v66, v67
	s_waitcnt lgkmcnt(0)
	v_cvt_pk_bf16_f32 v66, v96, v97
	v_cvt_pk_bf16_f32 v67, v98, v99
	global_store_dwordx4 v[102:103], v[64:67], off sc1
	s_add_i32 s22, s22, 1
	s_nop 0
	v_add_u32_e32 v64, 32, v100
	v_ashrrev_i32_e32 v65, 31, v64
	v_lshlrev_b64 v[96:97], 11, v[64:65]
	ds_read_b128 v[64:67], v105 offset:16896
	v_lshl_add_u64 v[102:103], s[76:77], 0, v[96:97]
	ds_read_b128 v[96:99], v105 offset:16912
	v_lshl_add_u64 v[102:103], v[102:103], 0, s[0:1]
	v_lshl_add_u64 v[102:103], v[102:103], 0, v[212:213]
	s_waitcnt lgkmcnt(1)
	v_cvt_pk_bf16_f32 v64, v64, v65
	v_cvt_pk_bf16_f32 v65, v66, v67
	s_waitcnt lgkmcnt(0)
	v_cvt_pk_bf16_f32 v66, v96, v97
	v_cvt_pk_bf16_f32 v67, v98, v99
	global_store_dwordx4 v[102:103], v[64:67], off sc1
	s_nop 1
	v_add_u32_e32 v64, 64, v100
	v_ashrrev_i32_e32 v65, 31, v64
	v_lshlrev_b64 v[96:97], 11, v[64:65]
	ds_read_b128 v[64:67], v105 offset:33792
	v_lshl_add_u64 v[102:103], s[76:77], 0, v[96:97]
	ds_read_b128 v[96:99], v105 offset:33808
	v_lshl_add_u64 v[102:103], v[102:103], 0, s[0:1]
	v_lshl_add_u64 v[102:103], v[102:103], 0, v[212:213]
	s_waitcnt lgkmcnt(1)
	v_cvt_pk_bf16_f32 v64, v64, v65
	v_cvt_pk_bf16_f32 v65, v66, v67
	s_waitcnt lgkmcnt(0)
	v_cvt_pk_bf16_f32 v66, v96, v97
	v_cvt_pk_bf16_f32 v67, v98, v99
	global_store_dwordx4 v[102:103], v[64:67], off sc1
	s_nop 1
	v_add_u32_e32 v64, 0x60, v100
	v_ashrrev_i32_e32 v65, 31, v64
	v_lshlrev_b64 v[96:97], 11, v[64:65]
	ds_read_b128 v[64:67], v105 offset:50688
	v_lshl_add_u64 v[100:101], s[76:77], 0, v[96:97]
	ds_read_b128 v[96:99], v105 offset:50704
	v_lshl_add_u64 v[100:101], v[100:101], 0, s[0:1]
	v_lshl_add_u64 v[100:101], v[100:101], 0, v[212:213]
	s_waitcnt lgkmcnt(1)
	v_cvt_pk_bf16_f32 v64, v64, v65
	v_cvt_pk_bf16_f32 v65, v66, v67
	s_waitcnt lgkmcnt(0)
	v_cvt_pk_bf16_f32 v66, v96, v97
	v_cvt_pk_bf16_f32 v67, v98, v99
	global_store_dwordx4 v[100:101], v[64:67], off sc1
	s_barrier
	s_nop 0
	v_mov_b32_e32 v64, v250
	ds_write_b128 v146, v[222:225]
	ds_write_b128 v146, v[68:71] offset:64
	ds_write_b128 v146, v[72:75] offset:8448
	ds_write_b128 v146, v[76:79] offset:8512
	ds_write_b128 v146, v[80:83] offset:16896
	ds_write_b128 v146, v[84:87] offset:16960
	ds_write_b128 v146, v[88:91] offset:25344
	ds_write_b128 v146, v[92:95] offset:25408
	s_waitcnt lgkmcnt(0)
	s_barrier
	s_nop 0
	v_ashrrev_i32_e32 v66, 4, v64
	v_add_u32_e32 v72, s30, v66
	v_lshlrev_b32_e32 v64, 3, v64
	v_ashrrev_i32_e32 v73, 31, v72
	v_and_b32_e32 v76, 0x78, v64
	v_lshlrev_b64 v[64:65], 11, v[72:73]
	v_lshlrev_b32_e32 v67, 2, v76
	v_lshl_add_u64 v[68:69], s[76:77], 0, v[64:65]
	v_mul_lo_u32 v64, v66, s35
	v_add3_u32 v77, 16, v67, v64
	ds_read_b128 v[64:67], v77
	v_lshl_add_u64 v[74:75], v[68:69], 0, s[0:1]
	ds_read_b128 v[68:71], v77 offset:16
	v_lshlrev_b32_e32 v212, 1, v76
	v_lshl_add_u64 v[74:75], v[74:75], 0, v[212:213]
	s_waitcnt lgkmcnt(1)
	v_cvt_pk_bf16_f32 v64, v64, v65
	v_cvt_pk_bf16_f32 v65, v66, v67
	s_waitcnt lgkmcnt(0)
	v_cvt_pk_bf16_f32 v66, v68, v69
	v_cvt_pk_bf16_f32 v67, v70, v71
	global_store_dwordx4 v[74:75], v[64:67], off offset:256 sc1
	s_nop 1
	v_add_u32_e32 v64, 32, v72
	v_ashrrev_i32_e32 v65, 31, v64
	v_lshlrev_b64 v[68:69], 11, v[64:65]
	ds_read_b128 v[64:67], v77 offset:16896
	v_lshl_add_u64 v[74:75], s[76:77], 0, v[68:69]
	ds_read_b128 v[68:71], v77 offset:16912
	v_lshl_add_u64 v[74:75], v[74:75], 0, s[0:1]
	v_lshl_add_u64 v[74:75], v[74:75], 0, v[212:213]
	s_waitcnt lgkmcnt(1)
	v_cvt_pk_bf16_f32 v64, v64, v65
	v_cvt_pk_bf16_f32 v65, v66, v67
	s_waitcnt lgkmcnt(0)
	v_cvt_pk_bf16_f32 v66, v68, v69
	v_cvt_pk_bf16_f32 v67, v70, v71
	global_store_dwordx4 v[74:75], v[64:67], off offset:256 sc1
	s_nop 1
	v_add_u32_e32 v64, 64, v72
	v_ashrrev_i32_e32 v65, 31, v64
	v_lshlrev_b64 v[68:69], 11, v[64:65]
	ds_read_b128 v[64:67], v77 offset:33792
	v_lshl_add_u64 v[74:75], s[76:77], 0, v[68:69]
	ds_read_b128 v[68:71], v77 offset:33808
	v_lshl_add_u64 v[74:75], v[74:75], 0, s[0:1]
	v_lshl_add_u64 v[74:75], v[74:75], 0, v[212:213]
	s_waitcnt lgkmcnt(1)
	v_cvt_pk_bf16_f32 v64, v64, v65
	v_cvt_pk_bf16_f32 v65, v66, v67
	s_waitcnt lgkmcnt(0)
	v_cvt_pk_bf16_f32 v66, v68, v69
	v_cvt_pk_bf16_f32 v67, v70, v71
	global_store_dwordx4 v[74:75], v[64:67], off offset:256 sc1
	s_nop 1
	v_add_u32_e32 v64, 0x60, v72
	v_ashrrev_i32_e32 v65, 31, v64
	v_lshlrev_b64 v[68:69], 11, v[64:65]
	ds_read_b128 v[64:67], v77 offset:50688
	v_lshl_add_u64 v[72:73], s[76:77], 0, v[68:69]
	ds_read_b128 v[68:71], v77 offset:50704
	v_lshl_add_u64 v[72:73], v[72:73], 0, s[0:1]
	v_lshl_add_u64 v[72:73], v[72:73], 0, v[212:213]
	s_waitcnt lgkmcnt(1)
	v_cvt_pk_bf16_f32 v64, v64, v65
	v_cvt_pk_bf16_f32 v65, v66, v67
	s_waitcnt lgkmcnt(0)
	v_cvt_pk_bf16_f32 v66, v68, v69
	v_cvt_pk_bf16_f32 v67, v70, v71
	global_store_dwordx4 v[72:73], v[64:67], off offset:256 sc1
	s_barrier
; DI void stb8(bf16_t* p, const F8& f) { *(uint4*)p = pack8(f); }
; template <int MODE>
; DI void gemm_epilogue(const float* Cs, int m0, int n0, const Epi& ep) {
;     ...
; #pragma unroll
;         for (int it = 0; it < 4; ++it) {
;             const int row = (tid >> 4) + 32 * it, cc = (tid & 15) * 8;
;             stb8(ep.b0 + (size_t)(m0 + row) * ep.ld + n0 + cc, ldf8(Cs + row * LDC + cc));
;         }
; template <int MODE>
; DI void gemm_phase(const bf16_t* __restrict__ A, const bf16_t* __restrict__ Bt, int M, int N, int K, const Epi& ep) {
;     ...
;     for (int round = 0;; ++round) {
;         const int L = round * G + bid;
;         if (L >= nwg) break;
;     ...
;                         *(f32x4*)(Cs + (wr * 64 + m * 16 + fr) * LDC + wc * 32 + n * 16 + fq * 4) = acc[ai][bj][m][n];
;                 __syncthreads();
;                 gemm_epilogue<MODE>(Cs, brow + ai * 128, bcol + bj * 128, ep);
	ds_write_b128 v146, v[32:35]
	ds_write_b128 v146, v[36:39] offset:64
	ds_write_b128 v146, v[40:43] offset:8448
	ds_write_b128 v146, v[44:47] offset:8512
	ds_write_b128 v146, v[48:51] offset:16896
	ds_write_b128 v146, v[52:55] offset:16960
	ds_write_b128 v146, v[56:59] offset:25344
	ds_write_b128 v146, v[60:63] offset:25408
	v_mov_b32_e32 v32, v250
	s_waitcnt lgkmcnt(0)
	s_barrier
	s_nop 0
	v_ashrrev_i32_e32 v34, 4, v32
	v_add_u32_e32 v40, s23, v34
	v_lshlrev_b32_e32 v32, 3, v32
	v_ashrrev_i32_e32 v41, 31, v40
	v_and_b32_e32 v44, 0x78, v32
	v_lshlrev_b64 v[32:33], 11, v[40:41]
	v_lshlrev_b32_e32 v35, 2, v44
	v_lshl_add_u64 v[36:37], s[76:77], 0, v[32:33]
	v_mul_lo_u32 v32, v34, s35
	v_add3_u32 v45, 16, v35, v32
	ds_read_b128 v[32:35], v45
	v_lshl_add_u64 v[42:43], v[36:37], 0, s[0:1]
	ds_read_b128 v[36:39], v45 offset:16
	v_lshlrev_b32_e32 v212, 1, v44
	v_lshl_add_u64 v[42:43], v[42:43], 0, v[212:213]
	s_waitcnt lgkmcnt(1)
	v_cvt_pk_bf16_f32 v32, v32, v33
	v_cvt_pk_bf16_f32 v33, v34, v35
	s_waitcnt lgkmcnt(0)
	v_cvt_pk_bf16_f32 v34, v36, v37
	v_cvt_pk_bf16_f32 v35, v38, v39
	global_store_dwordx4 v[42:43], v[32:35], off sc1
	s_nop 1
	v_add_u32_e32 v32, 32, v40
	v_ashrrev_i32_e32 v33, 31, v32
	v_lshlrev_b64 v[36:37], 11, v[32:33]
	ds_read_b128 v[32:35], v45 offset:16896
	v_lshl_add_u64 v[42:43], s[76:77], 0, v[36:37]
	ds_read_b128 v[36:39], v45 offset:16912
	v_lshl_add_u64 v[42:43], v[42:43], 0, s[0:1]
	v_lshl_add_u64 v[42:43], v[42:43], 0, v[212:213]
	s_waitcnt lgkmcnt(1)
	v_cvt_pk_bf16_f32 v32, v32, v33
	v_cvt_pk_bf16_f32 v33, v34, v35
	s_waitcnt lgkmcnt(0)
	v_cvt_pk_bf16_f32 v34, v36, v37
	v_cvt_pk_bf16_f32 v35, v38, v39
	global_store_dwordx4 v[42:43], v[32:35], off sc1
	s_nop 1
	v_add_u32_e32 v32, 64, v40
	v_ashrrev_i32_e32 v33, 31, v32
	v_lshlrev_b64 v[36:37], 11, v[32:33]
	ds_read_b128 v[32:35], v45 offset:33792
	v_lshl_add_u64 v[42:43], s[76:77], 0, v[36:37]
	ds_read_b128 v[36:39], v45 offset:33808
	v_lshl_add_u64 v[42:43], v[42:43], 0, s[0:1]
	v_lshl_add_u64 v[42:43], v[42:43], 0, v[212:213]
	s_waitcnt lgkmcnt(1)
	v_cvt_pk_bf16_f32 v32, v32, v33
	v_cvt_pk_bf16_f32 v33, v34, v35
	s_waitcnt lgkmcnt(0)
	v_cvt_pk_bf16_f32 v34, v36, v37
	v_cvt_pk_bf16_f32 v35, v38, v39
	global_store_dwordx4 v[42:43], v[32:35], off sc1
	s_nop 1
	v_add_u32_e32 v32, 0x60, v40
	v_ashrrev_i32_e32 v33, 31, v32
	v_lshlrev_b64 v[36:37], 11, v[32:33]
	ds_read_b128 v[32:35], v45 offset:50688
	v_lshl_add_u64 v[40:41], s[76:77], 0, v[36:37]
	ds_read_b128 v[36:39], v45 offset:50704
	v_lshl_add_u64 v[40:41], v[40:41], 0, s[0:1]
	v_lshl_add_u64 v[40:41], v[40:41], 0, v[212:213]
	s_waitcnt lgkmcnt(1)
	v_cvt_pk_bf16_f32 v32, v32, v33
	v_cvt_pk_bf16_f32 v33, v34, v35
	s_waitcnt lgkmcnt(0)
	v_cvt_pk_bf16_f32 v34, v36, v37
	v_cvt_pk_bf16_f32 v35, v38, v39
	global_store_dwordx4 v[40:41], v[32:35], off sc1
	s_barrier
	ds_write_b128 v146, v[0:3]
	ds_write_b128 v146, v[4:7] offset:64
	ds_write_b128 v146, v[8:11] offset:8448
	ds_write_b128 v146, v[12:15] offset:8512
	ds_write_b128 v146, v[16:19] offset:16896
	ds_write_b128 v146, v[20:23] offset:16960
	ds_write_b128 v146, v[24:27] offset:25344
	ds_write_b128 v146, v[28:31] offset:25408
	v_mov_b32_e32 v0, v250
	s_waitcnt lgkmcnt(0)
	s_barrier
	s_nop 0
	v_ashrrev_i32_e32 v2, 4, v0
	v_add_u32_e32 v8, s23, v2
	v_lshlrev_b32_e32 v0, 3, v0
	v_ashrrev_i32_e32 v9, 31, v8
	v_and_b32_e32 v12, 0x78, v0
	v_lshlrev_b64 v[0:1], 11, v[8:9]
	v_lshlrev_b32_e32 v3, 2, v12
	v_lshl_add_u64 v[4:5], s[76:77], 0, v[0:1]
	v_mul_lo_u32 v0, v2, s35
	v_add3_u32 v13, 16, v3, v0
	ds_read_b128 v[0:3], v13
	v_lshl_add_u64 v[10:11], v[4:5], 0, s[0:1]
	ds_read_b128 v[4:7], v13 offset:16
	v_lshlrev_b32_e32 v212, 1, v12
	v_lshl_add_u64 v[10:11], v[10:11], 0, v[212:213]
	s_waitcnt lgkmcnt(1)
	v_cvt_pk_bf16_f32 v0, v0, v1
	v_cvt_pk_bf16_f32 v1, v2, v3
	s_waitcnt lgkmcnt(0)
	v_cvt_pk_bf16_f32 v2, v4, v5
	v_cvt_pk_bf16_f32 v3, v6, v7
	global_store_dwordx4 v[10:11], v[0:3], off offset:256 sc1
	s_nop 1
	v_add_u32_e32 v0, 32, v8
	v_ashrrev_i32_e32 v1, 31, v0
	v_lshlrev_b64 v[4:5], 11, v[0:1]
	ds_read_b128 v[0:3], v13 offset:16896
	v_lshl_add_u64 v[10:11], s[76:77], 0, v[4:5]
	ds_read_b128 v[4:7], v13 offset:16912
	v_lshl_add_u64 v[10:11], v[10:11], 0, s[0:1]
	v_lshl_add_u64 v[10:11], v[10:11], 0, v[212:213]
	s_waitcnt lgkmcnt(1)
	v_cvt_pk_bf16_f32 v0, v0, v1
	v_cvt_pk_bf16_f32 v1, v2, v3
	s_waitcnt lgkmcnt(0)
	v_cvt_pk_bf16_f32 v2, v4, v5
	v_cvt_pk_bf16_f32 v3, v6, v7
	global_store_dwordx4 v[10:11], v[0:3], off offset:256 sc1
	s_nop 1
	v_add_u32_e32 v0, 64, v8
	v_ashrrev_i32_e32 v1, 31, v0
	v_lshlrev_b64 v[4:5], 11, v[0:1]
	ds_read_b128 v[0:3], v13 offset:33792
	v_lshl_add_u64 v[10:11], s[76:77], 0, v[4:5]
	ds_read_b128 v[4:7], v13 offset:33808
	v_lshl_add_u64 v[10:11], v[10:11], 0, s[0:1]
	v_lshl_add_u64 v[10:11], v[10:11], 0, v[212:213]
	s_waitcnt lgkmcnt(1)
	v_cvt_pk_bf16_f32 v0, v0, v1
	v_cvt_pk_bf16_f32 v1, v2, v3
	s_waitcnt lgkmcnt(0)
	v_cvt_pk_bf16_f32 v2, v4, v5
	v_cvt_pk_bf16_f32 v3, v6, v7
	global_store_dwordx4 v[10:11], v[0:3], off offset:256 sc1
	s_nop 1
	v_add_u32_e32 v0, 0x60, v8
	v_ashrrev_i32_e32 v1, 31, v0
	v_lshlrev_b64 v[4:5], 11, v[0:1]
	ds_read_b128 v[0:3], v13 offset:50688
	v_lshl_add_u64 v[8:9], s[76:77], 0, v[4:5]
	ds_read_b128 v[4:7], v13 offset:50704
	v_lshl_add_u64 v[8:9], v[8:9], 0, s[0:1]
	s_mul_i32 s0, s22, s18
	s_add_i32 s0, s0, s19
	v_lshl_add_u64 v[8:9], v[8:9], 0, v[212:213]
	s_waitcnt lgkmcnt(1)
	v_cvt_pk_bf16_f32 v0, v0, v1
	v_cvt_pk_bf16_f32 v1, v2, v3
	s_waitcnt lgkmcnt(0)
	v_cvt_pk_bf16_f32 v2, v4, v5
	v_cvt_pk_bf16_f32 v3, v6, v7
	s_cmpk_lt_i32 s0, 0x200
	global_store_dwordx4 v[8:9], v[0:3], off offset:256 sc1
	s_barrier
	s_cbranch_scc0 .LBB0_1026

; DI F8 unpack8(uint4 u) { F8 r; r.v[0] = lo16(u.x); r.v[1] = hi16(u.x); r.v[2] = lo16(u.y); r.v[3] = hi16(u.y); r.v[4] = lo16(u.z); r.v[5] = hi16(u.z); r.v[6] = lo16(u.w); r.v[7] = hi16(u.w); return r; }
; DI float wsum(float v) { v += __shfl_xor(v, 32); v += __shfl_xor(v, 16); v += __shfl_xor(v, 8); v += __shfl_xor(v, 4); v += __shfl_xor(v, 2); v += __shfl_xor(v, 1); return v; }
; DI void ln_phase(const Params& p, const bf16_t* __restrict__ Y, const float* __restrict__ g, const float* __restrict__ b, bool final_out) {
;     ...
;     for (int r0 = gw; r0 < MT; r0 += 2 * nw) {
;         const int r1 = r0 + nw; const bool two = r1 < MT; const int rr[2] = {r0, two ? r1 : r0};
;         uint4 xr[2][2], yr[2][2];
; #pragma unroll
;         for (int q = 0; q < 2; ++q)
; #pragma unroll
;             for (int it = 0; it < 2; ++it) { const size_t off = (size_t)rr[q] * 1024 + it * 512 + lane * 8; xr[q][it] = *(const uint4*)(XB + off); yr[q][it] = *(const uint4*)(Y + off); }
;         float v[2][16];
; #pragma unroll
;         for (int q = 0; q < 2; ++q)
; #pragma unroll
;             for (int it = 0; it < 2; ++it) { const F8 x = unpack8(xr[q][it]), y = unpack8(yr[q][it]);
; #pragma unroll
;                 for (int e = 0; e < 8; ++e) v[q][it * 8 + e] = ALPHA * x.v[e] + y.v[e]; }
;         float s0 = 0.f, s1 = 0.f;
; #pragma unroll
;         for (int e = 0; e < 16; ++e) { s0 += v[0][e]; s1 += v[1][e]; }
;         const float mu0 = wsum(s0) * (1.f / 1024.f), mu1 = wsum(s1) * (1.f / 1024.f);
.LBB0_1085:
	v_add_u32_e32 v32, s26, v40
	s_mov_b32 s7, 0x8200
	v_cmp_gt_i32_e64 s[36:37], s7, v32
	global_load_dwordx4 v[54:57], v[46:47], off
	s_waitcnt lgkmcnt(0)
	global_load_dwordx4 v[60:63], v[46:47], off offset:1024
	v_cndmask_b32_e64 v36, v40, v32, s[36:37]
	v_ashrrev_i32_e32 v37, 31, v36
	v_lshlrev_b64 v[48:49], 11, v[36:37]
	v_lshl_or_b32 v36, v42, 1, v48
	v_mov_b32_e32 v37, v49
	v_lshl_add_u64 v[38:39], s[82:83], 0, v[36:37]
	global_load_dwordx4 v[64:67], v[38:39], off
	v_lshl_add_u64 v[38:39], s[76:77], 0, v[36:37]
	v_or_b32_e32 v36, 0x400, v36
	global_load_dwordx4 v[70:73], v[38:39], off
	v_lshl_add_u64 v[38:39], s[82:83], 0, v[36:37]
	global_load_dwordx4 v[74:77], v[38:39], off
	v_lshl_add_u64 v[36:37], s[76:77], 0, v[36:37]
	global_load_dwordx4 v[94:97], v[36:37], off
	v_add_co_u32_e32 v50, vcc, 0xee400000, v46
	s_waitcnt vmcnt(5)
	v_lshlrev_b32_e32 v82, 16, v54
	v_addc_co_u32_e32 v51, vcc, -1, v47, vcc
	v_add_co_u32_e32 v52, vcc, 0xee401000, v46
	global_load_dwordx4 v[32:35], v[50:51], off
	s_nop 0
	v_addc_co_u32_e32 v53, vcc, -1, v47, vcc
	global_load_dwordx4 v[36:39], v[52:53], off offset:-3072
	v_and_b32_e32 v83, 0xffff0000, v54
	v_lshlrev_b32_e32 v78, 16, v55
	v_and_b32_e32 v79, 0xffff0000, v55
	s_waitcnt vmcnt(6)
	v_lshlrev_b32_e32 v58, 16, v60
	v_and_b32_e32 v59, 0xffff0000, v60
	v_lshlrev_b32_e32 v54, 16, v61
	v_and_b32_e32 v55, 0xffff0000, v61
	s_waitcnt vmcnt(5)
	v_lshlrev_b32_e32 v60, 16, v64
	v_and_b32_e32 v61, 0xffff0000, v64
	s_waitcnt vmcnt(4)
	v_lshlrev_b32_e32 v98, 16, v70
	v_and_b32_e32 v99, 0xffff0000, v70
	s_waitcnt vmcnt(3)
	v_lshlrev_b32_e32 v108, 16, v76
	v_and_b32_e32 v109, 0xffff0000, v76
	v_lshlrev_b32_e32 v110, 16, v77
	v_and_b32_e32 v111, 0xffff0000, v77
	v_pk_fma_f32 v[76:77], v[60:61], s[52:53], v[98:99] op_sel_hi:[1,0,1]
	v_lshlrev_b32_e32 v81, 16, v62
	v_and_b32_e32 v80, 0xffff0000, v62
	v_lshlrev_b32_e32 v85, 16, v63
	v_and_b32_e32 v84, 0xffff0000, v63
	v_lshlrev_b32_e32 v62, 16, v65
	v_and_b32_e32 v63, 0xffff0000, v65
	v_lshlrev_b32_e32 v70, 16, v71
	v_and_b32_e32 v71, 0xffff0000, v71
	v_add_f32_e32 v41, 0, v76
	v_lshlrev_b32_e32 v104, 16, v74
	v_and_b32_e32 v105, 0xffff0000, v74
	v_lshlrev_b32_e32 v106, 16, v75
	v_and_b32_e32 v107, 0xffff0000, v75
	v_pk_fma_f32 v[74:75], v[62:63], s[52:53], v[70:71] op_sel_hi:[1,0,1]
	v_add_f32_e32 v41, v77, v41
	v_lshlrev_b32_e32 v64, 16, v66
	v_and_b32_e32 v65, 0xffff0000, v66
	v_lshlrev_b32_e32 v100, 16, v72
	v_and_b32_e32 v101, 0xffff0000, v72
	v_add_f32_e32 v41, v74, v41
	v_lshlrev_b32_e32 v102, 16, v73
	v_and_b32_e32 v103, 0xffff0000, v73
	v_pk_fma_f32 v[72:73], v[64:65], s[52:53], v[100:101] op_sel_hi:[1,0,1]
	v_add_f32_e32 v41, v75, v41
	v_lshlrev_b32_e32 v66, 16, v67
	v_and_b32_e32 v67, 0xffff0000, v67
	v_add_f32_e32 v41, v72, v41
	v_pk_fma_f32 v[70:71], v[66:67], s[52:53], v[102:103] op_sel_hi:[1,0,1]
	v_add_f32_e32 v41, v73, v41
	s_waitcnt vmcnt(2)
	v_lshlrev_b32_e32 v112, 16, v94
	v_and_b32_e32 v113, 0xffff0000, v94
	v_add_f32_e32 v41, v70, v41
	v_pk_fma_f32 v[66:67], v[104:105], s[52:53], v[112:113] op_sel_hi:[1,0,1]
	v_add_f32_e32 v41, v71, v41
	v_lshlrev_b32_e32 v94, 16, v95
	v_and_b32_e32 v95, 0xffff0000, v95
	v_add_f32_e32 v41, v41, v66
	v_pk_fma_f32 v[64:65], v[106:107], s[52:53], v[94:95] op_sel_hi:[1,0,1]
	v_add_f32_e32 v41, v67, v41
	v_lshlrev_b32_e32 v114, 16, v96
	v_and_b32_e32 v115, 0xffff0000, v96
	v_add_f32_e32 v41, v64, v41
	v_pk_fma_f32 v[62:63], v[108:109], s[52:53], v[114:115] op_sel_hi:[1,0,1]
	v_add_f32_e32 v41, v65, v41
	v_lshlrev_b32_e32 v96, 16, v97
	v_and_b32_e32 v97, 0xffff0000, v97
	v_add_f32_e32 v41, v62, v41
	v_pk_fma_f32 v[60:61], v[110:111], s[52:53], v[96:97] op_sel_hi:[1,0,1]
	v_add_f32_e32 v41, v63, v41
	v_add_f32_e32 v41, v60, v41
	v_add_f32_e32 v41, v61, v41
	v_mov_b32_e32 v93, v41
	v_lshlrev_b32_e32 v68, 16, v56
	v_and_b32_e32 v69, 0xffff0000, v56
	v_lshlrev_b32_e32 v56, 16, v57
	v_and_b32_e32 v57, 0xffff0000, v57
	s_waitcnt lgkmcnt(0)
	s_nop 1
	v_permlane32_swap_b32_e32 v41, v93
	v_add_f32_e32 v41, v41, v93
	v_mov_b32_e32 v93, v41
	s_waitcnt vmcnt(1)
	v_lshlrev_b32_e32 v86, 16, v32
	v_and_b32_e32 v87, 0xffff0000, v32
	s_waitcnt lgkmcnt(0)
	s_nop 1
	v_permlane16_swap_b32_e32 v41, v93
	v_add_f32_e32 v41, v41, v93
	s_waitcnt vmcnt(0)
	v_lshlrev_b32_e32 v99, 16, v38
	v_and_b32_e32 v98, 0xffff0000, v38
	v_lshlrev_b32_e32 v101, 16, v39
	v_and_b32_e32 v100, 0xffff0000, v39
	s_waitcnt lgkmcnt(0)
	s_nop 1
	v_add_f32_dpp v41, v41, v41 row_ror:8 row_mask:0xf bank_mask:0xf
	v_lshlrev_b32_e32 v32, 16, v33
	v_and_b32_e32 v33, 0xffff0000, v33
	v_pk_fma_f32 v[78:79], v[32:33], s[52:53], v[78:79] op_sel_hi:[1,0,1]
	v_pk_fma_f32 v[82:83], v[86:87], s[52:53], v[82:83] op_sel_hi:[1,0,1]
	s_waitcnt lgkmcnt(0)
	s_nop 1
	v_add_f32_dpp v38, v41, v41 row_ror:4 row_mask:0xf bank_mask:0xf
	v_lshlrev_b32_e32 v94, 16, v34
	v_and_b32_e32 v95, 0xffff0000, v34
	v_pk_fma_f32 v[86:87], v[94:95], s[52:53], v[68:69] op_sel_hi:[1,0,1]
	v_lshlrev_b32_e32 v34, 16, v35
	s_waitcnt lgkmcnt(0)
	s_nop 1
	v_add_f32_dpp v32, v38, v38 row_ror:2 row_mask:0xf bank_mask:0xf
	v_add_f32_e32 v38, 0, v82
	v_add_f32_e32 v38, v83, v38
	v_add_f32_e32 v38, v78, v38
	v_add_f32_e32 v39, v79, v38
	s_waitcnt lgkmcnt(0)
; DI float wsum(float v) { v += __shfl_xor(v, 32); v += __shfl_xor(v, 16); v += __shfl_xor(v, 8); v += __shfl_xor(v, 4); v += __shfl_xor(v, 2); v += __shfl_xor(v, 1); return v; }
; DI void ln_phase(const Params& p, const bf16_t* __restrict__ Y, const float* __restrict__ g, const float* __restrict__ b, bool final_out) {
;     ...
;         float s0 = 0.f, s1 = 0.f;
; #pragma unroll
;         for (int e = 0; e < 16; ++e) { s0 += v[0][e]; s1 += v[1][e]; }
;         const float mu0 = wsum(s0) * (1.f / 1024.f), mu1 = wsum(s1) * (1.f / 1024.f);
;         float q0 = 0.f, q1 = 0.f;
; #pragma unroll
;         for (int e = 0; e < 16; ++e) { const float d0 = v[0][e] - mu0, d1 = v[1][e] - mu1; q0 += d0 * d0; q1 += d1 * d1; }
;         const float rs0 = rsqrtf(wsum(q0) * (1.f / 1024.f) + EPS), rs1 = rsqrtf(wsum(q1) * (1.f / 1024.f) + EPS);
	s_nop 1
	v_add_f32_dpp v32, v32, v32 row_ror:1 row_mask:0xf bank_mask:0xf
	v_and_b32_e32 v35, 0xffff0000, v35
	v_mul_f32_e32 v38, 0x3a800000, v32
	v_add_f32_e32 v32, v86, v39
	v_add_f32_e32 v32, v87, v32
	v_pk_fma_f32 v[94:95], v[34:35], s[52:53], v[56:57] op_sel_hi:[1,0,1]
	v_lshlrev_b32_e32 v96, 16, v36
	v_and_b32_e32 v97, 0xffff0000, v36
	v_add_f32_e32 v32, v94, v32
	v_add_f32_e32 v32, v95, v32
	v_pk_fma_f32 v[96:97], v[96:97], s[52:53], v[58:59] op_sel_hi:[1,0,1]
	v_lshlrev_b32_e32 v36, 16, v37
	v_and_b32_e32 v37, 0xffff0000, v37
	v_add_f32_e32 v32, v32, v96
	v_pk_fma_f32 v[80:81], v[98:99], s[52:53], v[80:81] op_sel_hi:[1,0,1]
	v_add_f32_e32 v32, v97, v32
	v_pk_fma_f32 v[98:99], v[36:37], s[52:53], v[54:55] op_sel_hi:[1,0,1]
	v_pk_fma_f32 v[84:85], v[100:101], s[52:53], v[84:85] op_sel_hi:[1,0,1]
	v_add_f32_e32 v32, v98, v32
	v_add_f32_e32 v32, v99, v32
	v_add_f32_e32 v32, v81, v32
	v_add_f32_e32 v32, v80, v32
	v_add_f32_e32 v32, v85, v32
	v_add_f32_e32 v32, v84, v32
	v_mov_b32_e32 v33, v32
	v_pk_add_f32 v[54:55], v[76:77], v[38:39] op_sel_hi:[1,0] neg_lo:[0,1] neg_hi:[0,1]
	v_pk_add_f32 v[56:57], v[74:75], v[38:39] op_sel_hi:[1,0] neg_lo:[0,1] neg_hi:[0,1]
	v_pk_mul_f32 v[76:77], v[54:55], v[54:55]
	v_pk_mul_f32 v[74:75], v[56:57], v[56:57]
	s_waitcnt lgkmcnt(0)
	s_nop 1
	v_permlane32_swap_b32_e32 v32, v33
	v_add_f32_e32 v32, v32, v33
	v_mov_b32_e32 v33, v32
	v_add_f32_e32 v76, v76, v77
	v_pk_add_f32 v[58:59], v[72:73], v[38:39] op_sel_hi:[1,0] neg_lo:[0,1] neg_hi:[0,1]
	v_add_f32_e32 v74, v74, v76
	v_pk_mul_f32 v[72:73], v[58:59], v[58:59]
	s_waitcnt lgkmcnt(0)
	s_nop 1
	v_permlane16_swap_b32_e32 v32, v33
	v_add_f32_e32 v36, v32, v33
	v_add_f32_e32 v74, v75, v74
	v_add_f32_e32 v72, v72, v74
	v_pk_add_f32 v[68:69], v[70:71], v[38:39] op_sel_hi:[1,0] neg_lo:[0,1] neg_hi:[0,1]
	v_add_f32_e32 v72, v73, v72
	s_waitcnt lgkmcnt(0)
	s_nop 1
	v_add_f32_dpp v41, v36, v36 row_ror:8 row_mask:0xf bank_mask:0xf
	v_pk_mul_f32 v[70:71], v[68:69], v[68:69]
	v_pk_add_f32 v[32:33], v[66:67], v[38:39] op_sel_hi:[1,0] neg_lo:[0,1] neg_hi:[0,1]
	v_add_f32_e32 v70, v70, v72
	v_pk_mul_f32 v[66:67], v[32:33], v[32:33]
	s_waitcnt lgkmcnt(0)
	s_nop 1
	v_add_f32_dpp v41, v41, v41 row_ror:4 row_mask:0xf bank_mask:0xf
	v_add_f32_e32 v70, v71, v70
	v_pk_add_f32 v[34:35], v[64:65], v[38:39] op_sel_hi:[1,0] neg_lo:[0,1] neg_hi:[0,1]
	v_pk_add_f32 v[36:37], v[62:63], v[38:39] op_sel_hi:[1,0] neg_lo:[0,1] neg_hi:[0,1]
	v_pk_mul_f32 v[64:65], v[34:35], v[34:35]
	s_waitcnt lgkmcnt(0)
	s_nop 1
	v_add_f32_dpp v41, v41, v41 row_ror:2 row_mask:0xf bank_mask:0xf
	v_add_f32_e32 v93, v66, v70
	v_pk_mul_f32 v[62:63], v[36:37], v[36:37]
	v_pk_add_f32 v[38:39], v[60:61], v[38:39] op_sel_hi:[1,0] neg_lo:[0,1] neg_hi:[0,1]
	s_waitcnt lgkmcnt(0)
	s_nop 1
	v_add_f32_dpp v41, v41, v41 row_ror:1 row_mask:0xf bank_mask:0xf
	v_mul_f32_e32 v66, 0x3a800000, v41
	v_pk_add_f32 v[70:71], v[82:83], v[66:67] op_sel_hi:[1,0] neg_lo:[0,1] neg_hi:[0,1]
	v_pk_add_f32 v[74:75], v[78:79], v[66:67] op_sel_hi:[1,0] neg_lo:[0,1] neg_hi:[0,1]
	v_pk_mul_f32 v[72:73], v[70:71], v[70:71]
	v_pk_mul_f32 v[76:77], v[74:75], v[74:75]
	v_add_f32_e32 v41, v72, v73
	v_pk_add_f32 v[78:79], v[86:87], v[66:67] op_sel_hi:[1,0] neg_lo:[0,1] neg_hi:[0,1]
	v_add_f32_e32 v41, v76, v41
	v_pk_mul_f32 v[82:83], v[78:79], v[78:79]
	v_add_f32_e32 v41, v77, v41
	v_pk_add_f32 v[86:87], v[94:95], v[66:67] op_sel_hi:[1,0] neg_lo:[0,1] neg_hi:[0,1]
	v_add_f32_e32 v41, v82, v41
	v_pk_mul_f32 v[94:95], v[86:87], v[86:87]
	v_add_f32_e32 v41, v83, v41
	v_pk_add_f32 v[96:97], v[96:97], v[66:67] op_sel_hi:[1,0] neg_lo:[0,1] neg_hi:[0,1]
	v_add_f32_e32 v41, v94, v41
	v_pk_mul_f32 v[100:101], v[96:97], v[96:97]
	v_add_f32_e32 v41, v95, v41
	v_pk_add_f32 v[98:99], v[98:99], v[66:67] op_sel_hi:[1,0] neg_lo:[0,1] neg_hi:[0,1]
	v_add_f32_e32 v41, v100, v41
	v_pk_mul_f32 v[102:103], v[98:99], v[98:99]
	v_add_f32_e32 v41, v101, v41
	v_pk_add_f32 v[80:81], v[80:81], v[66:67] op_sel_hi:[1,0] neg_lo:[0,1] neg_hi:[0,1]
	v_add_f32_e32 v41, v102, v41
	v_pk_mul_f32 v[104:105], v[80:81], v[80:81]
	v_add_f32_e32 v41, v103, v41
	v_pk_add_f32 v[84:85], v[84:85], v[66:67] op_sel_hi:[1,0] neg_lo:[0,1] neg_hi:[0,1]
	v_add_f32_e32 v41, v105, v41
	v_pk_mul_f32 v[106:107], v[84:85], v[84:85]
	v_add_f32_e32 v41, v104, v41
	v_add_f32_e32 v41, v107, v41
	v_add_f32_e32 v41, v106, v41
	v_mov_b32_e32 v66, v41
	v_add_f32_e32 v67, v67, v93
	v_add_f32_e32 v64, v64, v67
	v_add_f32_e32 v64, v65, v64
	v_add_f32_e32 v62, v62, v64
	s_waitcnt lgkmcnt(0)
; DI void stf8(float* p, const F8& f) { *(float4*)p = make_float4(f.v[0], f.v[1], f.v[2], f.v[3]); *(float4*)(p + 4) = make_float4(f.v[4], f.v[5], f.v[6], f.v[7]); }
; DI void stb8(bf16_t* p, const F8& f) { *(uint4*)p = pack8(f); }
; DI float wsum(float v) { v += __shfl_xor(v, 32); v += __shfl_xor(v, 16); v += __shfl_xor(v, 8); v += __shfl_xor(v, 4); v += __shfl_xor(v, 2); v += __shfl_xor(v, 1); return v; }
; DI void ln_phase(const Params& p, const bf16_t* __restrict__ Y, const float* __restrict__ g, const float* __restrict__ b, bool final_out) {
;     ...
;         const float rs0 = rsqrtf(wsum(q0) * (1.f / 1024.f) + EPS), rs1 = rsqrtf(wsum(q1) * (1.f / 1024.f) + EPS);
; #pragma unroll
;         for (int q = 0; q < 2; ++q) {
;             if (q == 1 && !two) break;
;             const float mu = q ? mu1 : mu0, rs = q ? rs1 : rs0;
; #pragma unroll
;             for (int it = 0; it < 2; ++it) {
;                 const int c = it * 512 + lane * 8;
;                 F8 o;
; #pragma unroll
;                 for (int e = 0; e < 8; ++e) o.v[e] = (v[q][it * 8 + e] - mu) * rs * gg[it].v[e] + bb[it].v[e];
;                 if (final_out) stf8(p.out + (size_t)rr[q] * 1024 + c, o);
;                 else stb8(XB + (size_t)rr[q] * 1024 + c, o);
;             }
	s_nop 1
	v_permlane32_swap_b32_e32 v41, v66
	v_add_f32_e32 v41, v41, v66
	v_mov_b32_e32 v64, v41
	v_pk_mul_f32 v[60:61], v[38:39], v[38:39]
	v_add_f32_e32 v62, v63, v62
	v_add_f32_e32 v60, v60, v62
	v_add_f32_e32 v60, v61, v60
	s_waitcnt lgkmcnt(0)
	s_nop 1
	v_permlane16_swap_b32_e32 v41, v64
	v_add_f32_e32 v41, v41, v64
	v_mov_b32_e32 v61, v60
	s_waitcnt lgkmcnt(1)
	s_nop 1
	v_add_f32_dpp v41, v41, v41 row_ror:8 row_mask:0xf bank_mask:0xf
	s_waitcnt lgkmcnt(1)
	s_nop 1
	v_permlane32_swap_b32_e32 v60, v61
	v_add_f32_e32 v60, v60, v61
	v_mov_b32_e32 v61, v60
	s_waitcnt lgkmcnt(1)
	s_nop 1
	v_add_f32_dpp v41, v41, v41 row_ror:4 row_mask:0xf bank_mask:0xf
	s_waitcnt lgkmcnt(1)
	s_nop 1
	v_permlane16_swap_b32_e32 v60, v61
	v_add_f32_e32 v60, v60, v61
	s_waitcnt lgkmcnt(1)
	s_nop 1
	v_add_f32_dpp v41, v41, v41 row_ror:2 row_mask:0xf bank_mask:0xf
	s_waitcnt lgkmcnt(1)
	s_nop 1
	v_add_f32_dpp v60, v60, v60 row_ror:8 row_mask:0xf bank_mask:0xf
	s_waitcnt lgkmcnt(1)
	s_nop 1
	v_add_f32_dpp v41, v41, v41 row_ror:1 row_mask:0xf bank_mask:0xf
	v_mov_b32_e32 v62, 0x358637bd
	v_fmamk_f32 v41, v41, 0x3a800000, v62
	s_waitcnt lgkmcnt(0)
	s_nop 1
	v_add_f32_dpp v60, v60, v60 row_ror:4 row_mask:0xf bank_mask:0xf
	v_mul_f32_e32 v62, 0x4b800000, v41
	v_cmp_gt_f32_e32 vcc, s2, v41
	s_nop 0
	v_cndmask_b32_e32 v41, v41, v62, vcc
	v_rsq_f32_e32 v62, v41
	s_waitcnt lgkmcnt(0)
	s_nop 1
	v_add_f32_dpp v41, v60, v60 row_ror:2 row_mask:0xf bank_mask:0xf
	ds_bpermute_b32 v60, v92, v41
	v_mul_f32_e32 v61, 0x45800000, v62
	v_cndmask_b32_e32 v66, v62, v61, vcc
	v_pk_mul_f32 v[62:63], v[70:71], v[66:67] op_sel_hi:[1,0]
	v_pk_mul_f32 v[64:65], v[74:75], v[66:67] op_sel_hi:[1,0]
	v_pk_mul_f32 v[70:71], v[78:79], v[66:67] op_sel_hi:[1,0]
	v_pk_mul_f32 v[72:73], v[86:87], v[66:67] op_sel_hi:[1,0]
	v_pk_fma_f32 v[62:63], v[4:5], v[62:63], v[12:13]
	v_pk_fma_f32 v[64:65], v[6:7], v[64:65], v[14:15]
	v_pk_fma_f32 v[70:71], v[0:1], v[70:71], v[8:9]
	v_pk_fma_f32 v[72:73], v[2:3], v[72:73], v[10:11]
	v_cvt_pk_bf16_f32 v62, v62, v63
	v_cvt_pk_bf16_f32 v63, v64, v65
	v_cvt_pk_bf16_f32 v64, v70, v71
	v_cvt_pk_bf16_f32 v65, v72, v73
	global_store_dwordx4 v[50:51], v[62:65], off sc1
	v_pk_mul_f32 v[50:51], v[96:97], v[66:67] op_sel_hi:[1,0]
	s_nop 0
	v_pk_mul_f32 v[62:63], v[98:99], v[66:67] op_sel_hi:[1,0]
	v_pk_fma_f32 v[50:51], v[20:21], v[50:51], v[28:29]
	v_pk_fma_f32 v[64:65], v[22:23], v[62:63], v[30:31]
	v_pk_mul_f32 v[62:63], v[80:81], v[66:67] op_sel_hi:[1,0]
	s_nop 0
	v_pk_fma_f32 v[70:71], v[16:17], v[62:63], v[24:25] op_sel:[0,1,0] op_sel_hi:[1,0,1]
	v_pk_mul_f32 v[62:63], v[84:85], v[66:67] op_sel_hi:[1,0]
	s_nop 0
	v_pk_fma_f32 v[66:67], v[18:19], v[62:63], v[26:27] op_sel:[0,1,0] op_sel_hi:[1,0,1]
	v_cvt_pk_bf16_f32 v62, v50, v51
	v_cvt_pk_bf16_f32 v63, v64, v65
	v_cvt_pk_bf16_f32 v64, v70, v71
	v_cvt_pk_bf16_f32 v65, v66, v67
	global_store_dwordx4 v[52:53], v[62:65], off offset:-3072 sc1
	s_and_saveexec_b64 s[22:23], s[36:37]
	s_cbranch_execz .LBB0_1084
	s_waitcnt lgkmcnt(0)
	v_add_f32_e32 v41, v41, v60
	v_mov_b32_e32 v50, 0x358637bd
	v_fmamk_f32 v41, v41, 0x3a800000, v50
	v_mul_f32_e32 v50, 0x4b800000, v41
	v_cmp_gt_f32_e32 vcc, s2, v41
	v_lshl_add_u64 v[60:61], v[44:45], 0, v[48:49]
	s_nop 0
	v_cndmask_b32_e32 v41, v41, v50, vcc
	v_rsq_f32_e32 v41, v41
	s_nop 0
	v_mul_f32_e32 v50, 0x45800000, v41
	v_cndmask_b32_e32 v52, v41, v50, vcc
	v_pk_mul_f32 v[50:51], v[54:55], v[52:53] op_sel_hi:[1,0]
	v_pk_mul_f32 v[54:55], v[56:57], v[52:53] op_sel_hi:[1,0]
	v_pk_mul_f32 v[56:57], v[58:59], v[52:53] op_sel_hi:[1,0]
	v_pk_mul_f32 v[58:59], v[68:69], v[52:53] op_sel_hi:[1,0]
	v_pk_mul_f32 v[32:33], v[32:33], v[52:53] op_sel_hi:[1,0]
	v_pk_mul_f32 v[34:35], v[34:35], v[52:53] op_sel_hi:[1,0]
	v_pk_mul_f32 v[36:37], v[36:37], v[52:53] op_sel_hi:[1,0]
	v_pk_mul_f32 v[38:39], v[38:39], v[52:53] op_sel_hi:[1,0]
	v_pk_fma_f32 v[50:51], v[4:5], v[50:51], v[12:13]
	v_pk_fma_f32 v[54:55], v[6:7], v[54:55], v[14:15]
	v_pk_fma_f32 v[56:57], v[0:1], v[56:57], v[8:9]
	v_pk_fma_f32 v[58:59], v[2:3], v[58:59], v[10:11]
	v_pk_fma_f32 v[32:33], v[20:21], v[32:33], v[28:29]
	v_pk_fma_f32 v[34:35], v[22:23], v[34:35], v[30:31]
	v_pk_fma_f32 v[36:37], v[16:17], v[36:37], v[24:25]
	v_pk_fma_f32 v[38:39], v[18:19], v[38:39], v[26:27]
	v_cvt_pk_bf16_f32 v48, v50, v51
	v_cvt_pk_bf16_f32 v49, v54, v55
	v_cvt_pk_bf16_f32 v50, v56, v57
	v_cvt_pk_bf16_f32 v51, v58, v59
	v_cvt_pk_bf16_f32 v32, v32, v33
	v_cvt_pk_bf16_f32 v33, v34, v35
	v_cvt_pk_bf16_f32 v34, v36, v37
	v_cvt_pk_bf16_f32 v35, v38, v39
	global_store_dwordx4 v[60:61], v[48:51], off sc1
	global_store_dwordx4 v[60:61], v[32:35], off offset:1024 sc1
	s_branch .LBB0_1084

; DI void stf8(float* p, const F8& f) { *(float4*)p = make_float4(f.v[0], f.v[1], f.v[2], f.v[3]); *(float4*)(p + 4) = make_float4(f.v[4], f.v[5], f.v[6], f.v[7]); }
; DI void stb8(bf16_t* p, const F8& f) { *(uint4*)p = pack8(f); }
; DI float siluf(float x) { return x / (1.f + __expf(-x)); }
; template <int MODE>
; DI void gemm_epilogue(const float* Cs, int m0, int n0, const Epi& ep) {
;     ...
;         const int mt = m0 >> 7, ch0 = (n0 >> 7) * 64, c8 = (tid & 7) * 8, ch = ch0 + c8;
;         const float* cw = ep.c0;
;         const F8 w0 = ldf8(cw + ch), w1 = ldf8(cw + 2816 + ch), w2 = ldf8(cw + 2 * 2816 + ch);
;         const bool defer01 = (m0 < MP) && ((m0 & 8191) != 0);
; #pragma unroll
;         for (int it = 0; it < 2; ++it) {
;             const int i = (tid >> 3) + 64 * it, r = m0 + i;
;             int sq, pos, len; rowinfo(r, sq, pos, len);
;             const F8 g0 = ldf8(Cs + i * LDC + c8), up = ldf8(Cs + i * LDC + 64 + c8);
;             if (i >= 126) stf8(ep.f0 + ((size_t)mt * 2 + (i - 126)) * 2816 + ch, g0);
;             if (i < 2) { stf8(ep.f1 + ((size_t)mt * 2 + i) * 2816 + ch, g0); stf8(ep.f2 + ((size_t)mt * 2 + i) * 2816 + ch, up); }
;             if (pos >= len - 2) {
;                 float* so = sq < 4 ? ep.out + O_PFF + (((size_t)ep.layer * 4 + sq) * 2 + (pos - (len - 2))) * 2816
;                                    : ep.out + O_SFF + (((size_t)ep.layer * 8 + (sq - 4)) * 2 + (pos - (len - 2))) * 2816;
;                 stf8(so + ch, g0);
;             }
;             if (i < 2 && defer01) continue;
;             F8 g1, g2;
;             const float* hist = sq >= 4 ? ep.c1 + ((size_t)ep.layer * 8 + (sq - 4)) * 2 * 2816 + ch : nullptr;
;             if (pos >= 1) g1 = ldf8(Cs + (i - 1) * LDC + c8);
;             else if (hist) g1 = ldf8(hist + 2816);
;             else { for (int e = 0; e < 8; ++e) g1.v[e] = 0.f; }
;             if (pos >= 2) g2 = ldf8(Cs + (i - 2) * LDC + c8);
;             else if (hist) g2 = ldf8(hist + (size_t)pos * 2816);
;             else { for (int e = 0; e < 8; ++e) g2.v[e] = 0.f; }
;             F8 o;
; #pragma unroll
;             for (int e = 0; e < 8; ++e) o.v[e] = siluf(w0.v[e] * g2.v[e] + w1.v[e] * g1.v[e] + w2.v[e] * g0.v[e]) * up.v[e];
;             stb8(ep.b0 + (size_t)r * 2816 + ch, o);
.Lffn_fast:
	s_lshl_b32 s54, s27, 8
	s_lshl_b32 s30, s26, 7
	s_lshl_b32 s31, s27, 2
	v_lshrrev_b32_e32 v195, 3, v250
	v_and_b32_e32 v212, 7, v250
	v_lshlrev_b32_e32 v212, 3, v212
	v_add_u32_e32 v64, s30, v212
	v_add_u32_e32 v65, s54, v195
	s_movk_i32 s0, 0x1600
	v_add_u32_e32 v66, s31, v195
	v_mul_lo_u32 v65, v65, s0
	v_mul_lo_u32 v66, v66, s3
	v_mul_u32_u24_e32 v197, 0x210, v195
	v_lshl_add_u32 v65, v64, 1, v65
	v_lshlrev_b32_e32 v64, 2, v64
	v_lshl_add_u32 v67, v212, 2, 16
	v_add_u32_e32 v66, v66, v64
	v_add_u32_e32 v197, v197, v67
	v_cmp_lt_u32_e64 s[40:41], 1, v195
	v_cmp_gt_u32_e64 s[42:43], 2, v195
	v_cmp_lt_u32_e64 s[44:45], 61, v195
	v_add_u32_e32 v196, 0xfffffbe0, v197
	v_max_i32_e32 v196, v196, v67
	s_mov_b32 s30, 0xbfb8aa3b
	s_mov_b32 s31, 0xbfb8aa3b
	global_load_dwordx4 v[128:131], v64, s[6:7] offset:0
	global_load_dwordx4 v[132:135], v64, s[6:7] offset:16
	global_load_dwordx4 v[136:139], v64, s[14:15] offset:0
	global_load_dwordx4 v[140:143], v64, s[14:15] offset:16
	global_load_dwordx4 v[144:147], v64, s[18:19] offset:0
	global_load_dwordx4 v[148:151], v64, s[18:19] offset:16
	ds_write_b128 v194, v[96:99]
	ds_write_b128 v194, v[100:103] offset:64
	ds_write_b128 v194, v[104:107] offset:8448
	ds_write_b128 v194, v[108:111] offset:8512
	ds_write_b128 v194, v[112:115] offset:16896
	ds_write_b128 v194, v[116:119] offset:16960
	ds_write_b128 v194, v[120:123] offset:25344
	ds_write_b128 v194, v[124:127] offset:25408
	s_waitcnt lgkmcnt(0)
	s_barrier
	ds_read_b128 v[96:99], v197
	ds_read_b128 v[100:103], v197 offset:16
	ds_read_b128 v[104:107], v197 offset:256
	ds_read_b128 v[108:111], v197 offset:272
	ds_read_b128 v[112:115], v196 offset:528
	ds_read_b128 v[116:119], v196 offset:544
	ds_read_b128 v[120:123], v196
	ds_read_b128 v[124:127], v196 offset:16
	s_waitcnt vmcnt(0)
	s_mov_b64 exec, s[42:43]
	s_cbranch_execz .Lffn_f1
	s_waitcnt lgkmcnt(4)
	global_store_dwordx4 v66, v[96:99], s[80:81] offset:0 sc1
	global_store_dwordx4 v66, v[100:103], s[80:81] offset:16 sc1
	global_store_dwordx4 v66, v[104:107], s[82:83] offset:0 sc1
	global_store_dwordx4 v66, v[108:111], s[82:83] offset:16 sc1
.Lffn_f1:
	s_mov_b64 exec, -1
	s_waitcnt lgkmcnt(0)
	v_pk_mul_f32 v[120:121], v[128:129], v[120:121]
	v_pk_mul_f32 v[122:123], v[130:131], v[122:123]
	v_pk_mul_f32 v[124:125], v[132:133], v[124:125]
	v_pk_mul_f32 v[126:127], v[134:135], v[126:127]
	v_pk_fma_f32 v[120:121], v[136:137], v[112:113], v[120:121]
	v_pk_fma_f32 v[122:123], v[138:139], v[114:115], v[122:123]
	v_pk_fma_f32 v[124:125], v[140:141], v[116:117], v[124:125]
	v_pk_fma_f32 v[126:127], v[142:143], v[118:119], v[126:127]
	v_pk_fma_f32 v[120:121], v[144:145], v[96:97], v[120:121]
	v_pk_fma_f32 v[122:123], v[146:147], v[98:99], v[122:123]
	v_pk_fma_f32 v[124:125], v[148:149], v[100:101], v[124:125]
	v_pk_fma_f32 v[126:127], v[150:151], v[102:103], v[126:127]
	v_pk_mul_f32 v[152:153], v[120:121], s[30:31]
	v_pk_mul_f32 v[154:155], v[122:123], s[30:31]
	v_pk_mul_f32 v[164:165], v[124:125], s[30:31]
	v_pk_mul_f32 v[166:167], v[126:127], s[30:31]
	v_pk_mul_f32 v[120:121], v[104:105], v[120:121]
	v_pk_mul_f32 v[122:123], v[106:107], v[122:123]
	v_pk_mul_f32 v[124:125], v[108:109], v[124:125]
	v_pk_mul_f32 v[126:127], v[110:111], v[126:127]
	v_exp_f32_e32 v152, v152
	v_exp_f32_e32 v153, v153
	v_exp_f32_e32 v154, v154
	v_exp_f32_e32 v155, v155
	v_exp_f32_e32 v164, v164
	v_exp_f32_e32 v165, v165
	v_exp_f32_e32 v166, v166
	v_exp_f32_e32 v167, v167
	v_pk_add_f32 v[152:153], v[152:153], 1.0 op_sel_hi:[1,0]
	v_pk_add_f32 v[154:155], v[154:155], 1.0 op_sel_hi:[1,0]
	v_pk_add_f32 v[164:165], v[164:165], 1.0 op_sel_hi:[1,0]
	v_pk_add_f32 v[166:167], v[166:167], 1.0 op_sel_hi:[1,0]
	v_rcp_f32_e32 v152, v152
	v_rcp_f32_e32 v153, v153
	v_rcp_f32_e32 v154, v154
	v_rcp_f32_e32 v155, v155
	v_rcp_f32_e32 v164, v164
	v_rcp_f32_e32 v165, v165
	v_rcp_f32_e32 v166, v166
	v_rcp_f32_e32 v167, v167
	v_pk_mul_f32 v[120:121], v[120:121], v[152:153]
	v_pk_mul_f32 v[122:123], v[122:123], v[154:155]
	v_pk_mul_f32 v[124:125], v[124:125], v[164:165]
	v_pk_mul_f32 v[126:127], v[126:127], v[166:167]
	v_cvt_pk_bf16_f32 v152, v120, v121
	v_cvt_pk_bf16_f32 v153, v122, v123
	v_cvt_pk_bf16_f32 v154, v124, v125
	v_cvt_pk_bf16_f32 v155, v126, v127
	s_mov_b64 exec, s[40:41]
	global_store_dwordx4 v65, v[152:155], s[84:85] offset:0 sc1
	s_mov_b64 exec, -1
	ds_read_b128 v[96:99], v197 offset:33792
	ds_read_b128 v[100:103], v197 offset:33808
	ds_read_b128 v[104:107], v197 offset:34048
	ds_read_b128 v[108:111], v197 offset:34064
	ds_read_b128 v[112:115], v197 offset:33264
	ds_read_b128 v[116:119], v197 offset:33280
	ds_read_b128 v[120:123], v197 offset:32736
	ds_read_b128 v[124:127], v197 offset:32752
	v_add_u32_e32 v67, 0x58000, v65
	s_mov_b64 exec, s[44:45]
	s_cbranch_execz .Lffn_f2
	v_add_u32_e32 v212, 0xfff55800, v66
	s_waitcnt lgkmcnt(6)
	global_store_dwordx4 v212, v[96:99], s[72:73] offset:0 sc1
	global_store_dwordx4 v212, v[100:103], s[72:73] offset:16 sc1
; DI void stf8(float* p, const F8& f) { *(float4*)p = make_float4(f.v[0], f.v[1], f.v[2], f.v[3]); *(float4*)(p + 4) = make_float4(f.v[4], f.v[5], f.v[6], f.v[7]); }
; DI void stb8(bf16_t* p, const F8& f) { *(uint4*)p = pack8(f); }
; DI float siluf(float x) { return x / (1.f + __expf(-x)); }
; template <int MODE>
; DI void gemm_epilogue(const float* Cs, int m0, int n0, const Epi& ep) {
;     ...
;         const int mt = m0 >> 7, ch0 = (n0 >> 7) * 64, c8 = (tid & 7) * 8, ch = ch0 + c8;
;         const float* cw = ep.c0;
;         const F8 w0 = ldf8(cw + ch), w1 = ldf8(cw + 2816 + ch), w2 = ldf8(cw + 2 * 2816 + ch);
;         const bool defer01 = (m0 < MP) && ((m0 & 8191) != 0);
; #pragma unroll
;         for (int it = 0; it < 2; ++it) {
;             const int i = (tid >> 3) + 64 * it, r = m0 + i;
;             int sq, pos, len; rowinfo(r, sq, pos, len);
;             const F8 g0 = ldf8(Cs + i * LDC + c8), up = ldf8(Cs + i * LDC + 64 + c8);
;             if (i >= 126) stf8(ep.f0 + ((size_t)mt * 2 + (i - 126)) * 2816 + ch, g0);
;             if (i < 2) { stf8(ep.f1 + ((size_t)mt * 2 + i) * 2816 + ch, g0); stf8(ep.f2 + ((size_t)mt * 2 + i) * 2816 + ch, up); }
;             if (pos >= len - 2) {
;                 float* so = sq < 4 ? ep.out + O_PFF + (((size_t)ep.layer * 4 + sq) * 2 + (pos - (len - 2))) * 2816
;                                    : ep.out + O_SFF + (((size_t)ep.layer * 8 + (sq - 4)) * 2 + (pos - (len - 2))) * 2816;
;                 stf8(so + ch, g0);
;             }
;             if (i < 2 && defer01) continue;
;             F8 g1, g2;
;             const float* hist = sq >= 4 ? ep.c1 + ((size_t)ep.layer * 8 + (sq - 4)) * 2 * 2816 + ch : nullptr;
;             if (pos >= 1) g1 = ldf8(Cs + (i - 1) * LDC + c8);
;             else if (hist) g1 = ldf8(hist + 2816);
;             else { for (int e = 0; e < 8; ++e) g1.v[e] = 0.f; }
;             if (pos >= 2) g2 = ldf8(Cs + (i - 2) * LDC + c8);
;             else if (hist) g2 = ldf8(hist + (size_t)pos * 2816);
;             else { for (int e = 0; e < 8; ++e) g2.v[e] = 0.f; }
;             F8 o;
; #pragma unroll
;             for (int e = 0; e < 8; ++e) o.v[e] = siluf(w0.v[e] * g2.v[e] + w1.v[e] * g1.v[e] + w2.v[e] * g0.v[e]) * up.v[e];
;             stb8(ep.b0 + (size_t)r * 2816 + ch, o);
.Lffn_f2:
	s_mov_b64 exec, -1
	s_waitcnt lgkmcnt(0)
	v_pk_mul_f32 v[120:121], v[128:129], v[120:121]
	v_pk_mul_f32 v[122:123], v[130:131], v[122:123]
	v_pk_mul_f32 v[124:125], v[132:133], v[124:125]
	v_pk_mul_f32 v[126:127], v[134:135], v[126:127]
	v_pk_fma_f32 v[120:121], v[136:137], v[112:113], v[120:121]
	v_pk_fma_f32 v[122:123], v[138:139], v[114:115], v[122:123]
	v_pk_fma_f32 v[124:125], v[140:141], v[116:117], v[124:125]
	v_pk_fma_f32 v[126:127], v[142:143], v[118:119], v[126:127]
	v_pk_fma_f32 v[120:121], v[144:145], v[96:97], v[120:121]
	v_pk_fma_f32 v[122:123], v[146:147], v[98:99], v[122:123]
	v_pk_fma_f32 v[124:125], v[148:149], v[100:101], v[124:125]
	v_pk_fma_f32 v[126:127], v[150:151], v[102:103], v[126:127]
	v_pk_mul_f32 v[152:153], v[120:121], s[30:31]
	v_pk_mul_f32 v[154:155], v[122:123], s[30:31]
	v_pk_mul_f32 v[164:165], v[124:125], s[30:31]
	v_pk_mul_f32 v[166:167], v[126:127], s[30:31]
	v_pk_mul_f32 v[120:121], v[104:105], v[120:121]
	v_pk_mul_f32 v[122:123], v[106:107], v[122:123]
	v_pk_mul_f32 v[124:125], v[108:109], v[124:125]
	v_pk_mul_f32 v[126:127], v[110:111], v[126:127]
	v_exp_f32_e32 v152, v152
	v_exp_f32_e32 v153, v153
	v_exp_f32_e32 v154, v154
	v_exp_f32_e32 v155, v155
	v_exp_f32_e32 v164, v164
	v_exp_f32_e32 v165, v165
	v_exp_f32_e32 v166, v166
	v_exp_f32_e32 v167, v167
	v_pk_add_f32 v[152:153], v[152:153], 1.0 op_sel_hi:[1,0]
	v_pk_add_f32 v[154:155], v[154:155], 1.0 op_sel_hi:[1,0]
	v_pk_add_f32 v[164:165], v[164:165], 1.0 op_sel_hi:[1,0]
	v_pk_add_f32 v[166:167], v[166:167], 1.0 op_sel_hi:[1,0]
	v_rcp_f32_e32 v152, v152
	v_rcp_f32_e32 v153, v153
	v_rcp_f32_e32 v154, v154
	v_rcp_f32_e32 v155, v155
	v_rcp_f32_e32 v164, v164
	v_rcp_f32_e32 v165, v165
	v_rcp_f32_e32 v166, v166
	v_rcp_f32_e32 v167, v167
	v_pk_mul_f32 v[120:121], v[120:121], v[152:153]
	v_pk_mul_f32 v[122:123], v[122:123], v[154:155]
	v_pk_mul_f32 v[124:125], v[124:125], v[164:165]
	v_pk_mul_f32 v[126:127], v[126:127], v[166:167]
	v_cvt_pk_bf16_f32 v152, v120, v121
	v_cvt_pk_bf16_f32 v153, v122, v123
	v_cvt_pk_bf16_f32 v154, v124, v125
	v_cvt_pk_bf16_f32 v155, v126, v127
	global_store_dwordx4 v67, v[152:155], s[84:85] offset:0 sc1
	global_load_dwordx4 v[128:131], v64, s[6:7] offset:256
	global_load_dwordx4 v[132:135], v64, s[6:7] offset:272
	global_load_dwordx4 v[136:139], v64, s[14:15] offset:256
	global_load_dwordx4 v[140:143], v64, s[14:15] offset:272
	global_load_dwordx4 v[144:147], v64, s[18:19] offset:256
	global_load_dwordx4 v[148:151], v64, s[18:19] offset:272
	s_barrier
	ds_write_b128 v194, v[222:225]
	ds_write_b128 v194, v[68:71] offset:64
	ds_write_b128 v194, v[72:75] offset:8448
	ds_write_b128 v194, v[76:79] offset:8512
	ds_write_b128 v194, v[80:83] offset:16896
	ds_write_b128 v194, v[84:87] offset:16960
	ds_write_b128 v194, v[88:91] offset:25344
	ds_write_b128 v194, v[92:95] offset:25408
	s_waitcnt lgkmcnt(0)
	s_barrier
	ds_read_b128 v[96:99], v197
	ds_read_b128 v[100:103], v197 offset:16
	ds_read_b128 v[104:107], v197 offset:256
	ds_read_b128 v[108:111], v197 offset:272
	ds_read_b128 v[112:115], v196 offset:528
	ds_read_b128 v[116:119], v196 offset:544
	ds_read_b128 v[120:123], v196
	ds_read_b128 v[124:127], v196 offset:16
	s_waitcnt vmcnt(0)
	s_mov_b64 exec, s[42:43]
	s_cbranch_execz .Lffn_f3
	s_waitcnt lgkmcnt(4)
	global_store_dwordx4 v66, v[96:99], s[80:81] offset:256 sc1
	global_store_dwordx4 v66, v[100:103], s[80:81] offset:272 sc1
	global_store_dwordx4 v66, v[104:107], s[82:83] offset:256 sc1
	global_store_dwordx4 v66, v[108:111], s[82:83] offset:272 sc1
.Lffn_f3:
	s_mov_b64 exec, -1
	s_waitcnt lgkmcnt(0)
	v_pk_mul_f32 v[120:121], v[128:129], v[120:121]
	v_pk_mul_f32 v[122:123], v[130:131], v[122:123]
	v_pk_mul_f32 v[124:125], v[132:133], v[124:125]
	v_pk_mul_f32 v[126:127], v[134:135], v[126:127]
	v_pk_fma_f32 v[120:121], v[136:137], v[112:113], v[120:121]
	v_pk_fma_f32 v[122:123], v[138:139], v[114:115], v[122:123]
	v_pk_fma_f32 v[124:125], v[140:141], v[116:117], v[124:125]
	v_pk_fma_f32 v[126:127], v[142:143], v[118:119], v[126:127]
	v_pk_fma_f32 v[120:121], v[144:145], v[96:97], v[120:121]
	v_pk_fma_f32 v[122:123], v[146:147], v[98:99], v[122:123]
	v_pk_fma_f32 v[124:125], v[148:149], v[100:101], v[124:125]
	v_pk_fma_f32 v[126:127], v[150:151], v[102:103], v[126:127]
	v_pk_mul_f32 v[152:153], v[120:121], s[30:31]
	v_pk_mul_f32 v[154:155], v[122:123], s[30:31]
	v_pk_mul_f32 v[164:165], v[124:125], s[30:31]
	v_pk_mul_f32 v[166:167], v[126:127], s[30:31]
	v_pk_mul_f32 v[120:121], v[104:105], v[120:121]
	v_pk_mul_f32 v[122:123], v[106:107], v[122:123]
	v_pk_mul_f32 v[124:125], v[108:109], v[124:125]
	v_pk_mul_f32 v[126:127], v[110:111], v[126:127]
	v_exp_f32_e32 v152, v152
	v_exp_f32_e32 v153, v153
	v_exp_f32_e32 v154, v154
	v_exp_f32_e32 v155, v155
	v_exp_f32_e32 v164, v164
	v_exp_f32_e32 v165, v165
	v_exp_f32_e32 v166, v166
	v_exp_f32_e32 v167, v167
	v_pk_add_f32 v[152:153], v[152:153], 1.0 op_sel_hi:[1,0]
	v_pk_add_f32 v[154:155], v[154:155], 1.0 op_sel_hi:[1,0]
	v_pk_add_f32 v[164:165], v[164:165], 1.0 op_sel_hi:[1,0]
	v_pk_add_f32 v[166:167], v[166:167], 1.0 op_sel_hi:[1,0]
	v_rcp_f32_e32 v152, v152
	v_rcp_f32_e32 v153, v153
	v_rcp_f32_e32 v154, v154
	v_rcp_f32_e32 v155, v155
	v_rcp_f32_e32 v164, v164
	v_rcp_f32_e32 v165, v165
	v_rcp_f32_e32 v166, v166
	v_rcp_f32_e32 v167, v167
	v_pk_mul_f32 v[120:121], v[120:121], v[152:153]
	v_pk_mul_f32 v[122:123], v[122:123], v[154:155]
	v_pk_mul_f32 v[124:125], v[124:125], v[164:165]
	v_pk_mul_f32 v[126:127], v[126:127], v[166:167]
	v_cvt_pk_bf16_f32 v152, v120, v121
	v_cvt_pk_bf16_f32 v153, v122, v123
	v_cvt_pk_bf16_f32 v154, v124, v125
	v_cvt_pk_bf16_f32 v155, v126, v127
	s_mov_b64 exec, s[40:41]
	global_store_dwordx4 v65, v[152:155], s[84:85] offset:128 sc1
	s_mov_b64 exec, -1
	ds_read_b128 v[96:99], v197 offset:33792
	ds_read_b128 v[100:103], v197 offset:33808
	ds_read_b128 v[104:107], v197 offset:34048
	ds_read_b128 v[108:111], v197 offset:34064
	ds_read_b128 v[112:115], v197 offset:33264
	ds_read_b128 v[116:119], v197 offset:33280
	ds_read_b128 v[120:123], v197 offset:32736
	ds_read_b128 v[124:127], v197 offset:32752
	v_add_u32_e32 v67, 0x58000, v65
	s_mov_b64 exec, s[44:45]
	s_cbranch_execz .Lffn_f4
	v_add_u32_e32 v212, 0xfff55800, v66
	s_waitcnt lgkmcnt(6)
	global_store_dwordx4 v212, v[96:99], s[72:73] offset:256 sc1
	global_store_dwordx4 v212, v[100:103], s[72:73] offset:272 sc1
; DI void stf8(float* p, const F8& f) { *(float4*)p = make_float4(f.v[0], f.v[1], f.v[2], f.v[3]); *(float4*)(p + 4) = make_float4(f.v[4], f.v[5], f.v[6], f.v[7]); }
; DI void stb8(bf16_t* p, const F8& f) { *(uint4*)p = pack8(f); }
; DI float siluf(float x) { return x / (1.f + __expf(-x)); }
; template <int MODE>
; DI void gemm_epilogue(const float* Cs, int m0, int n0, const Epi& ep) {
;     ...
;         const int mt = m0 >> 7, ch0 = (n0 >> 7) * 64, c8 = (tid & 7) * 8, ch = ch0 + c8;
;         const float* cw = ep.c0;
;         const F8 w0 = ldf8(cw + ch), w1 = ldf8(cw + 2816 + ch), w2 = ldf8(cw + 2 * 2816 + ch);
;         const bool defer01 = (m0 < MP) && ((m0 & 8191) != 0);
; #pragma unroll
;         for (int it = 0; it < 2; ++it) {
;             const int i = (tid >> 3) + 64 * it, r = m0 + i;
;             int sq, pos, len; rowinfo(r, sq, pos, len);
;             const F8 g0 = ldf8(Cs + i * LDC + c8), up = ldf8(Cs + i * LDC + 64 + c8);
;             if (i >= 126) stf8(ep.f0 + ((size_t)mt * 2 + (i - 126)) * 2816 + ch, g0);
;             if (i < 2) { stf8(ep.f1 + ((size_t)mt * 2 + i) * 2816 + ch, g0); stf8(ep.f2 + ((size_t)mt * 2 + i) * 2816 + ch, up); }
;             if (pos >= len - 2) {
;                 float* so = sq < 4 ? ep.out + O_PFF + (((size_t)ep.layer * 4 + sq) * 2 + (pos - (len - 2))) * 2816
;                                    : ep.out + O_SFF + (((size_t)ep.layer * 8 + (sq - 4)) * 2 + (pos - (len - 2))) * 2816;
;                 stf8(so + ch, g0);
;             }
;             if (i < 2 && defer01) continue;
;             F8 g1, g2;
;             const float* hist = sq >= 4 ? ep.c1 + ((size_t)ep.layer * 8 + (sq - 4)) * 2 * 2816 + ch : nullptr;
;             if (pos >= 1) g1 = ldf8(Cs + (i - 1) * LDC + c8);
;             else if (hist) g1 = ldf8(hist + 2816);
;             else { for (int e = 0; e < 8; ++e) g1.v[e] = 0.f; }
;             if (pos >= 2) g2 = ldf8(Cs + (i - 2) * LDC + c8);
;             else if (hist) g2 = ldf8(hist + (size_t)pos * 2816);
;             else { for (int e = 0; e < 8; ++e) g2.v[e] = 0.f; }
;             F8 o;
; #pragma unroll
;             for (int e = 0; e < 8; ++e) o.v[e] = siluf(w0.v[e] * g2.v[e] + w1.v[e] * g1.v[e] + w2.v[e] * g0.v[e]) * up.v[e];
;             stb8(ep.b0 + (size_t)r * 2816 + ch, o);
.Lffn_f4:
	s_mov_b64 exec, -1
	s_waitcnt lgkmcnt(0)
	v_pk_mul_f32 v[120:121], v[128:129], v[120:121]
	v_pk_mul_f32 v[122:123], v[130:131], v[122:123]
	v_pk_mul_f32 v[124:125], v[132:133], v[124:125]
	v_pk_mul_f32 v[126:127], v[134:135], v[126:127]
	v_pk_fma_f32 v[120:121], v[136:137], v[112:113], v[120:121]
	v_pk_fma_f32 v[122:123], v[138:139], v[114:115], v[122:123]
	v_pk_fma_f32 v[124:125], v[140:141], v[116:117], v[124:125]
	v_pk_fma_f32 v[126:127], v[142:143], v[118:119], v[126:127]
	v_pk_fma_f32 v[120:121], v[144:145], v[96:97], v[120:121]
	v_pk_fma_f32 v[122:123], v[146:147], v[98:99], v[122:123]
	v_pk_fma_f32 v[124:125], v[148:149], v[100:101], v[124:125]
	v_pk_fma_f32 v[126:127], v[150:151], v[102:103], v[126:127]
	v_pk_mul_f32 v[152:153], v[120:121], s[30:31]
	v_pk_mul_f32 v[154:155], v[122:123], s[30:31]
	v_pk_mul_f32 v[164:165], v[124:125], s[30:31]
	v_pk_mul_f32 v[166:167], v[126:127], s[30:31]
	v_pk_mul_f32 v[120:121], v[104:105], v[120:121]
	v_pk_mul_f32 v[122:123], v[106:107], v[122:123]
	v_pk_mul_f32 v[124:125], v[108:109], v[124:125]
	v_pk_mul_f32 v[126:127], v[110:111], v[126:127]
	v_exp_f32_e32 v152, v152
	v_exp_f32_e32 v153, v153
	v_exp_f32_e32 v154, v154
	v_exp_f32_e32 v155, v155
	v_exp_f32_e32 v164, v164
	v_exp_f32_e32 v165, v165
	v_exp_f32_e32 v166, v166
	v_exp_f32_e32 v167, v167
	v_pk_add_f32 v[152:153], v[152:153], 1.0 op_sel_hi:[1,0]
	v_pk_add_f32 v[154:155], v[154:155], 1.0 op_sel_hi:[1,0]
	v_pk_add_f32 v[164:165], v[164:165], 1.0 op_sel_hi:[1,0]
	v_pk_add_f32 v[166:167], v[166:167], 1.0 op_sel_hi:[1,0]
	v_rcp_f32_e32 v152, v152
	v_rcp_f32_e32 v153, v153
	v_rcp_f32_e32 v154, v154
	v_rcp_f32_e32 v155, v155
	v_rcp_f32_e32 v164, v164
	v_rcp_f32_e32 v165, v165
	v_rcp_f32_e32 v166, v166
	v_rcp_f32_e32 v167, v167
	v_pk_mul_f32 v[120:121], v[120:121], v[152:153]
	v_pk_mul_f32 v[122:123], v[122:123], v[154:155]
	v_pk_mul_f32 v[124:125], v[124:125], v[164:165]
	v_pk_mul_f32 v[126:127], v[126:127], v[166:167]
	v_cvt_pk_bf16_f32 v152, v120, v121
	v_cvt_pk_bf16_f32 v153, v122, v123
	v_cvt_pk_bf16_f32 v154, v124, v125
	v_cvt_pk_bf16_f32 v155, v126, v127
	global_store_dwordx4 v67, v[152:155], s[84:85] offset:128 sc1
	global_load_dwordx4 v[128:131], v64, s[6:7] offset:0
	global_load_dwordx4 v[132:135], v64, s[6:7] offset:16
	global_load_dwordx4 v[136:139], v64, s[14:15] offset:0
	global_load_dwordx4 v[140:143], v64, s[14:15] offset:16
	global_load_dwordx4 v[144:147], v64, s[18:19] offset:0
	global_load_dwordx4 v[148:151], v64, s[18:19] offset:16
	s_barrier
	ds_write_b128 v194, v[32:35]
	ds_write_b128 v194, v[36:39] offset:64
	ds_write_b128 v194, v[40:43] offset:8448
	ds_write_b128 v194, v[44:47] offset:8512
	ds_write_b128 v194, v[48:51] offset:16896
	ds_write_b128 v194, v[52:55] offset:16960
	ds_write_b128 v194, v[56:59] offset:25344
	ds_write_b128 v194, v[60:63] offset:25408
	s_waitcnt lgkmcnt(0)
	s_barrier
	ds_read_b128 v[96:99], v197
	ds_read_b128 v[100:103], v197 offset:16
	ds_read_b128 v[104:107], v197 offset:256
	ds_read_b128 v[108:111], v197 offset:272
	ds_read_b128 v[112:115], v196 offset:528
	ds_read_b128 v[116:119], v196 offset:544
	ds_read_b128 v[120:123], v196
	ds_read_b128 v[124:127], v196 offset:16
	v_add_u32_e32 v67, 0xb0000, v65
	s_waitcnt vmcnt(0)
	s_mov_b64 exec, s[42:43]
	s_cbranch_execz .Lffn_f5
	v_add_u32_e32 v212, 0x5800, v66
	s_waitcnt lgkmcnt(4)
	global_store_dwordx4 v212, v[96:99], s[80:81] offset:0 sc1
	global_store_dwordx4 v212, v[100:103], s[80:81] offset:16 sc1
	global_store_dwordx4 v212, v[104:107], s[82:83] offset:0 sc1
	global_store_dwordx4 v212, v[108:111], s[82:83] offset:16 sc1
.Lffn_f5:
	s_mov_b64 exec, -1
	s_waitcnt lgkmcnt(0)
	v_pk_mul_f32 v[120:121], v[128:129], v[120:121]
	v_pk_mul_f32 v[122:123], v[130:131], v[122:123]
	v_pk_mul_f32 v[124:125], v[132:133], v[124:125]
	v_pk_mul_f32 v[126:127], v[134:135], v[126:127]
	v_pk_fma_f32 v[120:121], v[136:137], v[112:113], v[120:121]
	v_pk_fma_f32 v[122:123], v[138:139], v[114:115], v[122:123]
	v_pk_fma_f32 v[124:125], v[140:141], v[116:117], v[124:125]
	v_pk_fma_f32 v[126:127], v[142:143], v[118:119], v[126:127]
	v_pk_fma_f32 v[120:121], v[144:145], v[96:97], v[120:121]
	v_pk_fma_f32 v[122:123], v[146:147], v[98:99], v[122:123]
	v_pk_fma_f32 v[124:125], v[148:149], v[100:101], v[124:125]
	v_pk_fma_f32 v[126:127], v[150:151], v[102:103], v[126:127]
	v_pk_mul_f32 v[152:153], v[120:121], s[30:31]
	v_pk_mul_f32 v[154:155], v[122:123], s[30:31]
	v_pk_mul_f32 v[164:165], v[124:125], s[30:31]
	v_pk_mul_f32 v[166:167], v[126:127], s[30:31]
	v_pk_mul_f32 v[120:121], v[104:105], v[120:121]
	v_pk_mul_f32 v[122:123], v[106:107], v[122:123]
	v_pk_mul_f32 v[124:125], v[108:109], v[124:125]
	v_pk_mul_f32 v[126:127], v[110:111], v[126:127]
	v_exp_f32_e32 v152, v152
	v_exp_f32_e32 v153, v153
	v_exp_f32_e32 v154, v154
	v_exp_f32_e32 v155, v155
	v_exp_f32_e32 v164, v164
	v_exp_f32_e32 v165, v165
	v_exp_f32_e32 v166, v166
	v_exp_f32_e32 v167, v167
	v_pk_add_f32 v[152:153], v[152:153], 1.0 op_sel_hi:[1,0]
	v_pk_add_f32 v[154:155], v[154:155], 1.0 op_sel_hi:[1,0]
	v_pk_add_f32 v[164:165], v[164:165], 1.0 op_sel_hi:[1,0]
	v_pk_add_f32 v[166:167], v[166:167], 1.0 op_sel_hi:[1,0]
	v_rcp_f32_e32 v152, v152
	v_rcp_f32_e32 v153, v153
	v_rcp_f32_e32 v154, v154
	v_rcp_f32_e32 v155, v155
	v_rcp_f32_e32 v164, v164
	v_rcp_f32_e32 v165, v165
	v_rcp_f32_e32 v166, v166
	v_rcp_f32_e32 v167, v167
	v_pk_mul_f32 v[120:121], v[120:121], v[152:153]
	v_pk_mul_f32 v[122:123], v[122:123], v[154:155]
	v_pk_mul_f32 v[124:125], v[124:125], v[164:165]
	v_pk_mul_f32 v[126:127], v[126:127], v[166:167]
	v_cvt_pk_bf16_f32 v152, v120, v121
	v_cvt_pk_bf16_f32 v153, v122, v123
	v_cvt_pk_bf16_f32 v154, v124, v125
	v_cvt_pk_bf16_f32 v155, v126, v127
	s_mov_b64 exec, s[40:41]
	global_store_dwordx4 v67, v[152:155], s[84:85] offset:0 sc1
	s_mov_b64 exec, -1
	ds_read_b128 v[96:99], v197 offset:33792
	ds_read_b128 v[100:103], v197 offset:33808
	ds_read_b128 v[104:107], v197 offset:34048
	ds_read_b128 v[108:111], v197 offset:34064
	ds_read_b128 v[112:115], v197 offset:33264
	ds_read_b128 v[116:119], v197 offset:33280
	ds_read_b128 v[120:123], v197 offset:32736
	ds_read_b128 v[124:127], v197 offset:32752
	v_add_u32_e32 v67, 0x108000, v65
	s_mov_b64 exec, s[44:45]
	s_cbranch_execz .Lffn_f6
	v_add_u32_e32 v212, 0xfff5b000, v66
	s_waitcnt lgkmcnt(6)
	global_store_dwordx4 v212, v[96:99], s[72:73] offset:0 sc1
	global_store_dwordx4 v212, v[100:103], s[72:73] offset:16 sc1
; DI void stf8(float* p, const F8& f) { *(float4*)p = make_float4(f.v[0], f.v[1], f.v[2], f.v[3]); *(float4*)(p + 4) = make_float4(f.v[4], f.v[5], f.v[6], f.v[7]); }
; DI void stb8(bf16_t* p, const F8& f) { *(uint4*)p = pack8(f); }
; DI float siluf(float x) { return x / (1.f + __expf(-x)); }
; template <int MODE>
; DI void gemm_epilogue(const float* Cs, int m0, int n0, const Epi& ep) {
;     ...
;         const int mt = m0 >> 7, ch0 = (n0 >> 7) * 64, c8 = (tid & 7) * 8, ch = ch0 + c8;
;         const float* cw = ep.c0;
;         const F8 w0 = ldf8(cw + ch), w1 = ldf8(cw + 2816 + ch), w2 = ldf8(cw + 2 * 2816 + ch);
;         const bool defer01 = (m0 < MP) && ((m0 & 8191) != 0);
; #pragma unroll
;         for (int it = 0; it < 2; ++it) {
;             const int i = (tid >> 3) + 64 * it, r = m0 + i;
;             int sq, pos, len; rowinfo(r, sq, pos, len);
;             const F8 g0 = ldf8(Cs + i * LDC + c8), up = ldf8(Cs + i * LDC + 64 + c8);
;             if (i >= 126) stf8(ep.f0 + ((size_t)mt * 2 + (i - 126)) * 2816 + ch, g0);
;             if (i < 2) { stf8(ep.f1 + ((size_t)mt * 2 + i) * 2816 + ch, g0); stf8(ep.f2 + ((size_t)mt * 2 + i) * 2816 + ch, up); }
;             if (pos >= len - 2) {
;                 float* so = sq < 4 ? ep.out + O_PFF + (((size_t)ep.layer * 4 + sq) * 2 + (pos - (len - 2))) * 2816
;                                    : ep.out + O_SFF + (((size_t)ep.layer * 8 + (sq - 4)) * 2 + (pos - (len - 2))) * 2816;
;                 stf8(so + ch, g0);
;             }
;             if (i < 2 && defer01) continue;
;             F8 g1, g2;
;             const float* hist = sq >= 4 ? ep.c1 + ((size_t)ep.layer * 8 + (sq - 4)) * 2 * 2816 + ch : nullptr;
;             if (pos >= 1) g1 = ldf8(Cs + (i - 1) * LDC + c8);
;             else if (hist) g1 = ldf8(hist + 2816);
;             else { for (int e = 0; e < 8; ++e) g1.v[e] = 0.f; }
;             if (pos >= 2) g2 = ldf8(Cs + (i - 2) * LDC + c8);
;             else if (hist) g2 = ldf8(hist + (size_t)pos * 2816);
;             else { for (int e = 0; e < 8; ++e) g2.v[e] = 0.f; }
;             F8 o;
; #pragma unroll
;             for (int e = 0; e < 8; ++e) o.v[e] = siluf(w0.v[e] * g2.v[e] + w1.v[e] * g1.v[e] + w2.v[e] * g0.v[e]) * up.v[e];
;             stb8(ep.b0 + (size_t)r * 2816 + ch, o);
.Lffn_f6:
	s_mov_b64 exec, -1
	s_waitcnt lgkmcnt(0)
	v_pk_mul_f32 v[120:121], v[128:129], v[120:121]
	v_pk_mul_f32 v[122:123], v[130:131], v[122:123]
	v_pk_mul_f32 v[124:125], v[132:133], v[124:125]
	v_pk_mul_f32 v[126:127], v[134:135], v[126:127]
	v_pk_fma_f32 v[120:121], v[136:137], v[112:113], v[120:121]
	v_pk_fma_f32 v[122:123], v[138:139], v[114:115], v[122:123]
	v_pk_fma_f32 v[124:125], v[140:141], v[116:117], v[124:125]
	v_pk_fma_f32 v[126:127], v[142:143], v[118:119], v[126:127]
	v_pk_fma_f32 v[120:121], v[144:145], v[96:97], v[120:121]
	v_pk_fma_f32 v[122:123], v[146:147], v[98:99], v[122:123]
	v_pk_fma_f32 v[124:125], v[148:149], v[100:101], v[124:125]
	v_pk_fma_f32 v[126:127], v[150:151], v[102:103], v[126:127]
	v_pk_mul_f32 v[152:153], v[120:121], s[30:31]
	v_pk_mul_f32 v[154:155], v[122:123], s[30:31]
	v_pk_mul_f32 v[164:165], v[124:125], s[30:31]
	v_pk_mul_f32 v[166:167], v[126:127], s[30:31]
	v_pk_mul_f32 v[120:121], v[104:105], v[120:121]
	v_pk_mul_f32 v[122:123], v[106:107], v[122:123]
	v_pk_mul_f32 v[124:125], v[108:109], v[124:125]
	v_pk_mul_f32 v[126:127], v[110:111], v[126:127]
	v_exp_f32_e32 v152, v152
	v_exp_f32_e32 v153, v153
	v_exp_f32_e32 v154, v154
	v_exp_f32_e32 v155, v155
	v_exp_f32_e32 v164, v164
	v_exp_f32_e32 v165, v165
	v_exp_f32_e32 v166, v166
	v_exp_f32_e32 v167, v167
	v_pk_add_f32 v[152:153], v[152:153], 1.0 op_sel_hi:[1,0]
	v_pk_add_f32 v[154:155], v[154:155], 1.0 op_sel_hi:[1,0]
	v_pk_add_f32 v[164:165], v[164:165], 1.0 op_sel_hi:[1,0]
	v_pk_add_f32 v[166:167], v[166:167], 1.0 op_sel_hi:[1,0]
	v_rcp_f32_e32 v152, v152
	v_rcp_f32_e32 v153, v153
	v_rcp_f32_e32 v154, v154
	v_rcp_f32_e32 v155, v155
	v_rcp_f32_e32 v164, v164
	v_rcp_f32_e32 v165, v165
	v_rcp_f32_e32 v166, v166
	v_rcp_f32_e32 v167, v167
	v_pk_mul_f32 v[120:121], v[120:121], v[152:153]
	v_pk_mul_f32 v[122:123], v[122:123], v[154:155]
	v_pk_mul_f32 v[124:125], v[124:125], v[164:165]
	v_pk_mul_f32 v[126:127], v[126:127], v[166:167]
	v_cvt_pk_bf16_f32 v152, v120, v121
	v_cvt_pk_bf16_f32 v153, v122, v123
	v_cvt_pk_bf16_f32 v154, v124, v125
	v_cvt_pk_bf16_f32 v155, v126, v127
	global_store_dwordx4 v67, v[152:155], s[84:85] offset:0 sc1
	global_load_dwordx4 v[128:131], v64, s[6:7] offset:256
	global_load_dwordx4 v[132:135], v64, s[6:7] offset:272
	global_load_dwordx4 v[136:139], v64, s[14:15] offset:256
	global_load_dwordx4 v[140:143], v64, s[14:15] offset:272
	global_load_dwordx4 v[144:147], v64, s[18:19] offset:256
	global_load_dwordx4 v[148:151], v64, s[18:19] offset:272
	s_barrier
	ds_write_b128 v194, v[0:3]
	ds_write_b128 v194, v[4:7] offset:64
	ds_write_b128 v194, v[8:11] offset:8448
	ds_write_b128 v194, v[12:15] offset:8512
	ds_write_b128 v194, v[16:19] offset:16896
	ds_write_b128 v194, v[20:23] offset:16960
	ds_write_b128 v194, v[24:27] offset:25344
	ds_write_b128 v194, v[28:31] offset:25408
	s_waitcnt lgkmcnt(0)
	s_barrier
	ds_read_b128 v[96:99], v197
	ds_read_b128 v[100:103], v197 offset:16
	ds_read_b128 v[104:107], v197 offset:256
	ds_read_b128 v[108:111], v197 offset:272
	ds_read_b128 v[112:115], v196 offset:528
	ds_read_b128 v[116:119], v196 offset:544
	ds_read_b128 v[120:123], v196
	ds_read_b128 v[124:127], v196 offset:16
	v_add_u32_e32 v67, 0xb0000, v65
	s_waitcnt vmcnt(0)
	s_mov_b64 exec, s[42:43]
	s_cbranch_execz .Lffn_f7
	v_add_u32_e32 v212, 0x5800, v66
	s_waitcnt lgkmcnt(4)
	global_store_dwordx4 v212, v[96:99], s[80:81] offset:256 sc1
	global_store_dwordx4 v212, v[100:103], s[80:81] offset:272 sc1
	global_store_dwordx4 v212, v[104:107], s[82:83] offset:256 sc1
	global_store_dwordx4 v212, v[108:111], s[82:83] offset:272 sc1
.Lffn_f7:
	s_mov_b64 exec, -1
	s_waitcnt lgkmcnt(0)
	v_pk_mul_f32 v[120:121], v[128:129], v[120:121]
	v_pk_mul_f32 v[122:123], v[130:131], v[122:123]
	v_pk_mul_f32 v[124:125], v[132:133], v[124:125]
	v_pk_mul_f32 v[126:127], v[134:135], v[126:127]
	v_pk_fma_f32 v[120:121], v[136:137], v[112:113], v[120:121]
	v_pk_fma_f32 v[122:123], v[138:139], v[114:115], v[122:123]
	v_pk_fma_f32 v[124:125], v[140:141], v[116:117], v[124:125]
	v_pk_fma_f32 v[126:127], v[142:143], v[118:119], v[126:127]
	v_pk_fma_f32 v[120:121], v[144:145], v[96:97], v[120:121]
	v_pk_fma_f32 v[122:123], v[146:147], v[98:99], v[122:123]
	v_pk_fma_f32 v[124:125], v[148:149], v[100:101], v[124:125]
	v_pk_fma_f32 v[126:127], v[150:151], v[102:103], v[126:127]
	v_pk_mul_f32 v[152:153], v[120:121], s[30:31]
	v_pk_mul_f32 v[154:155], v[122:123], s[30:31]
	v_pk_mul_f32 v[164:165], v[124:125], s[30:31]
	v_pk_mul_f32 v[166:167], v[126:127], s[30:31]
	v_pk_mul_f32 v[120:121], v[104:105], v[120:121]
	v_pk_mul_f32 v[122:123], v[106:107], v[122:123]
	v_pk_mul_f32 v[124:125], v[108:109], v[124:125]
	v_pk_mul_f32 v[126:127], v[110:111], v[126:127]
	v_exp_f32_e32 v152, v152
	v_exp_f32_e32 v153, v153
	v_exp_f32_e32 v154, v154
	v_exp_f32_e32 v155, v155
	v_exp_f32_e32 v164, v164
	v_exp_f32_e32 v165, v165
	v_exp_f32_e32 v166, v166
	v_exp_f32_e32 v167, v167
	v_pk_add_f32 v[152:153], v[152:153], 1.0 op_sel_hi:[1,0]
	v_pk_add_f32 v[154:155], v[154:155], 1.0 op_sel_hi:[1,0]
	v_pk_add_f32 v[164:165], v[164:165], 1.0 op_sel_hi:[1,0]
	v_pk_add_f32 v[166:167], v[166:167], 1.0 op_sel_hi:[1,0]
	v_rcp_f32_e32 v152, v152
	v_rcp_f32_e32 v153, v153
	v_rcp_f32_e32 v154, v154
	v_rcp_f32_e32 v155, v155
	v_rcp_f32_e32 v164, v164
	v_rcp_f32_e32 v165, v165
	v_rcp_f32_e32 v166, v166
	v_rcp_f32_e32 v167, v167
	v_pk_mul_f32 v[120:121], v[120:121], v[152:153]
	v_pk_mul_f32 v[122:123], v[122:123], v[154:155]
	v_pk_mul_f32 v[124:125], v[124:125], v[164:165]
	v_pk_mul_f32 v[126:127], v[126:127], v[166:167]
	v_cvt_pk_bf16_f32 v152, v120, v121
	v_cvt_pk_bf16_f32 v153, v122, v123
	v_cvt_pk_bf16_f32 v154, v124, v125
	v_cvt_pk_bf16_f32 v155, v126, v127
	s_mov_b64 exec, s[40:41]
	global_store_dwordx4 v67, v[152:155], s[84:85] offset:128 sc1
	s_mov_b64 exec, -1
	ds_read_b128 v[96:99], v197 offset:33792
	ds_read_b128 v[100:103], v197 offset:33808
	ds_read_b128 v[104:107], v197 offset:34048
	ds_read_b128 v[108:111], v197 offset:34064
	ds_read_b128 v[112:115], v197 offset:33264
	ds_read_b128 v[116:119], v197 offset:33280
	ds_read_b128 v[120:123], v197 offset:32736
	ds_read_b128 v[124:127], v197 offset:32752
	v_add_u32_e32 v67, 0x108000, v65
	s_mov_b64 exec, s[44:45]
	s_cbranch_execz .Lffn_f8
	v_add_u32_e32 v212, 0xfff5b000, v66
	s_waitcnt lgkmcnt(6)
	global_store_dwordx4 v212, v[96:99], s[72:73] offset:256 sc1
	global_store_dwordx4 v212, v[100:103], s[72:73] offset:272 sc1
; DI void stf8(float* p, const F8& f) { *(float4*)p = make_float4(f.v[0], f.v[1], f.v[2], f.v[3]); *(float4*)(p + 4) = make_float4(f.v[4], f.v[5], f.v[6], f.v[7]); }
; DI void stb8(bf16_t* p, const F8& f) { *(uint4*)p = pack8(f); }
; DI float siluf(float x) { return x / (1.f + __expf(-x)); }
; template <int MODE>
; DI void gemm_epilogue(const float* Cs, int m0, int n0, const Epi& ep) {
;     ...
;         const int mt = m0 >> 7, ch0 = (n0 >> 7) * 64, c8 = (tid & 7) * 8, ch = ch0 + c8;
;         const float* cw = ep.c0;
;         const F8 w0 = ldf8(cw + ch), w1 = ldf8(cw + 2816 + ch), w2 = ldf8(cw + 2 * 2816 + ch);
;         const bool defer01 = (m0 < MP) && ((m0 & 8191) != 0);
; #pragma unroll
;         for (int it = 0; it < 2; ++it) {
;             const int i = (tid >> 3) + 64 * it, r = m0 + i;
;             int sq, pos, len; rowinfo(r, sq, pos, len);
;             const F8 g0 = ldf8(Cs + i * LDC + c8), up = ldf8(Cs + i * LDC + 64 + c8);
;             if (i >= 126) stf8(ep.f0 + ((size_t)mt * 2 + (i - 126)) * 2816 + ch, g0);
;             if (i < 2) { stf8(ep.f1 + ((size_t)mt * 2 + i) * 2816 + ch, g0); stf8(ep.f2 + ((size_t)mt * 2 + i) * 2816 + ch, up); }
;             if (pos >= len - 2) {
;                 float* so = sq < 4 ? ep.out + O_PFF + (((size_t)ep.layer * 4 + sq) * 2 + (pos - (len - 2))) * 2816
;                                    : ep.out + O_SFF + (((size_t)ep.layer * 8 + (sq - 4)) * 2 + (pos - (len - 2))) * 2816;
;                 stf8(so + ch, g0);
;             }
;             if (i < 2 && defer01) continue;
;             F8 g1, g2;
;             const float* hist = sq >= 4 ? ep.c1 + ((size_t)ep.layer * 8 + (sq - 4)) * 2 * 2816 + ch : nullptr;
;             if (pos >= 1) g1 = ldf8(Cs + (i - 1) * LDC + c8);
;             else if (hist) g1 = ldf8(hist + 2816);
;             else { for (int e = 0; e < 8; ++e) g1.v[e] = 0.f; }
;             if (pos >= 2) g2 = ldf8(Cs + (i - 2) * LDC + c8);
;             else if (hist) g2 = ldf8(hist + (size_t)pos * 2816);
;             else { for (int e = 0; e < 8; ++e) g2.v[e] = 0.f; }
;             F8 o;
; #pragma unroll
;             for (int e = 0; e < 8; ++e) o.v[e] = siluf(w0.v[e] * g2.v[e] + w1.v[e] * g1.v[e] + w2.v[e] * g0.v[e]) * up.v[e];
;             stb8(ep.b0 + (size_t)r * 2816 + ch, o);
.Lffn_f8:
	s_mov_b64 exec, -1
	s_waitcnt lgkmcnt(0)
	v_pk_mul_f32 v[120:121], v[128:129], v[120:121]
	v_pk_mul_f32 v[122:123], v[130:131], v[122:123]
	v_pk_mul_f32 v[124:125], v[132:133], v[124:125]
	v_pk_mul_f32 v[126:127], v[134:135], v[126:127]
	v_pk_fma_f32 v[120:121], v[136:137], v[112:113], v[120:121]
	v_pk_fma_f32 v[122:123], v[138:139], v[114:115], v[122:123]
	v_pk_fma_f32 v[124:125], v[140:141], v[116:117], v[124:125]
	v_pk_fma_f32 v[126:127], v[142:143], v[118:119], v[126:127]
	v_pk_fma_f32 v[120:121], v[144:145], v[96:97], v[120:121]
	v_pk_fma_f32 v[122:123], v[146:147], v[98:99], v[122:123]
	v_pk_fma_f32 v[124:125], v[148:149], v[100:101], v[124:125]
	v_pk_fma_f32 v[126:127], v[150:151], v[102:103], v[126:127]
	v_pk_mul_f32 v[152:153], v[120:121], s[30:31]
	v_pk_mul_f32 v[154:155], v[122:123], s[30:31]
	v_pk_mul_f32 v[164:165], v[124:125], s[30:31]
	v_pk_mul_f32 v[166:167], v[126:127], s[30:31]
	v_pk_mul_f32 v[120:121], v[104:105], v[120:121]
	v_pk_mul_f32 v[122:123], v[106:107], v[122:123]
	v_pk_mul_f32 v[124:125], v[108:109], v[124:125]
	v_pk_mul_f32 v[126:127], v[110:111], v[126:127]
	v_exp_f32_e32 v152, v152
	v_exp_f32_e32 v153, v153
	v_exp_f32_e32 v154, v154
	v_exp_f32_e32 v155, v155
	v_exp_f32_e32 v164, v164
	v_exp_f32_e32 v165, v165
	v_exp_f32_e32 v166, v166
	v_exp_f32_e32 v167, v167
	v_pk_add_f32 v[152:153], v[152:153], 1.0 op_sel_hi:[1,0]
	v_pk_add_f32 v[154:155], v[154:155], 1.0 op_sel_hi:[1,0]
	v_pk_add_f32 v[164:165], v[164:165], 1.0 op_sel_hi:[1,0]
	v_pk_add_f32 v[166:167], v[166:167], 1.0 op_sel_hi:[1,0]
	v_rcp_f32_e32 v152, v152
	v_rcp_f32_e32 v153, v153
	v_rcp_f32_e32 v154, v154
	v_rcp_f32_e32 v155, v155
	v_rcp_f32_e32 v164, v164
	v_rcp_f32_e32 v165, v165
	v_rcp_f32_e32 v166, v166
	v_rcp_f32_e32 v167, v167
	v_pk_mul_f32 v[120:121], v[120:121], v[152:153]
	v_pk_mul_f32 v[122:123], v[122:123], v[154:155]
	v_pk_mul_f32 v[124:125], v[124:125], v[164:165]
	v_pk_mul_f32 v[126:127], v[126:127], v[166:167]
	v_cvt_pk_bf16_f32 v152, v120, v121
	v_cvt_pk_bf16_f32 v153, v122, v123
	v_cvt_pk_bf16_f32 v154, v124, v125
	v_cvt_pk_bf16_f32 v155, v126, v127
	global_store_dwordx4 v67, v[152:155], s[84:85] offset:128 sc1
	s_mov_b64 s[0:1], -1
	s_branch .LBB0_1142
.LBB0_1141:
	s_or_b64 exec, exec, s[26:27]
	s_waitcnt vmcnt(0) lgkmcnt(1)
	v_pk_mul_f32 v[12:13], v[12:13], v[52:53]
	v_pk_mul_f32 v[14:15], v[14:15], v[54:55]
	v_pk_fma_f32 v[12:13], v[16:17], v[48:49], v[12:13]
	v_pk_fma_f32 v[14:15], v[18:19], v[50:51], v[14:15]
	v_pk_fma_f32 v[12:13], v[20:21], v[40:41], v[12:13]
	v_pk_fma_f32 v[14:15], v[22:23], v[42:43], v[14:15]
	v_mul_f32_e32 v16, 0xbfb8aa3b, v12
	v_mul_f32_e32 v17, 0xbfb8aa3b, v13
	v_exp_f32_e32 v16, v16
	v_exp_f32_e32 v17, v17
	s_waitcnt lgkmcnt(0)
	v_pk_mul_f32 v[0:1], v[0:1], v[44:45]
	v_pk_add_f32 v[16:17], v[16:17], 1.0 op_sel_hi:[1,0]
	s_nop 0
	v_pk_fma_f32 v[0:1], v[4:5], v[36:37], v[0:1]
	v_rcp_f32_e32 v20, v17
	s_nop 0
	v_mul_f32_e32 v13, v13, v20
	v_pk_fma_f32 v[0:1], v[8:9], v[28:29], v[0:1]
	v_rcp_f32_e32 v17, v16
	s_nop 0
	v_mul_f32_e32 v12, v12, v17
	v_mul_f32_e32 v16, 0xbfb8aa3b, v14
	v_mul_f32_e32 v17, 0xbfb8aa3b, v15
	v_exp_f32_e32 v16, v16
	v_exp_f32_e32 v17, v17
	v_mul_f32_e32 v4, 0xbfb8aa3b, v0
	v_mul_f32_e32 v5, 0xbfb8aa3b, v1
	v_exp_f32_e32 v4, v4
	v_pk_add_f32 v[16:17], v[16:17], 1.0 op_sel_hi:[1,0]
	v_exp_f32_e32 v5, v5
	s_nop 0
	v_pk_add_f32 v[4:5], v[4:5], 1.0 op_sel_hi:[1,0]
	v_pk_mul_f32 v[12:13], v[32:33], v[12:13]
	v_rcp_f32_e32 v18, v17
	s_nop 0
	v_mul_f32_e32 v15, v15, v18
	v_rcp_f32_e32 v17, v16
	s_nop 0
	v_mul_f32_e32 v14, v14, v17
	v_rcp_f32_e32 v8, v5
	s_nop 0
	v_mul_f32_e32 v1, v1, v8
	v_pk_mul_f32 v[14:15], v[34:35], v[14:15]
	v_rcp_f32_e32 v5, v4
	s_nop 0
	v_mul_f32_e32 v0, v0, v5
	v_pk_mul_f32 v[4:5], v[24:25], v[0:1]
	v_pk_mul_f32 v[0:1], v[2:3], v[46:47]
	s_nop 0
	v_pk_fma_f32 v[0:1], v[6:7], v[38:39], v[0:1]
	s_nop 0
	v_pk_fma_f32 v[0:1], v[10:11], v[30:31], v[0:1]
	s_nop 0
	v_mul_f32_e32 v2, 0xbfb8aa3b, v0
	v_mul_f32_e32 v3, 0xbfb8aa3b, v1
	v_exp_f32_e32 v2, v2
	v_exp_f32_e32 v3, v3
	s_nop 0
	v_pk_add_f32 v[2:3], v[2:3], 1.0 op_sel_hi:[1,0]
	s_nop 0
	v_rcp_f32_e32 v6, v3
	s_nop 0
	v_mul_f32_e32 v1, v1, v6
	v_rcp_f32_e32 v3, v2
	s_nop 0
	v_mul_f32_e32 v0, v0, v3
	v_pk_mul_f32 v[6:7], v[26:27], v[0:1]
	v_mov_b64_e32 v[0:1], s[84:85]
	v_mad_i64_i32 v[0:1], s[26:27], v60, s89, v[0:1]
	v_lshl_add_u64 v[8:9], v[56:57], 1, v[0:1]
	v_cvt_pk_bf16_f32 v0, v12, v13
	v_cvt_pk_bf16_f32 v1, v14, v15
	v_cvt_pk_bf16_f32 v2, v4, v5
	v_cvt_pk_bf16_f32 v3, v6, v7
	global_store_dwordx4 v[8:9], v[0:3], off offset:128 sc1

; DI void stf8(float* p, const F8& f) { *(float4*)p = make_float4(f.v[0], f.v[1], f.v[2], f.v[3]); *(float4*)(p + 4) = make_float4(f.v[4], f.v[5], f.v[6], f.v[7]); }
; DI void rowinfo(int r, int& sq, int& pos, int& len) { if (r < MP) { sq = r >> 13; pos = r & 8191; len = 8192; } else { sq = 4 + ((r - MP) >> 6); pos = r & 63; len = 64; } }
; #define BAR __builtin_amdgcn_s_barrier()
; template <int MODE>
; DI void gemm_epilogue(const float* Cs, int m0, int n0, const Epi& ep) {
;     ...
;         const int mt = m0 >> 7, ch0 = (n0 >> 7) * 64, c8 = (tid & 7) * 8, ch = ch0 + c8;
;         const float* cw = ep.c0;
;         const F8 w0 = ldf8(cw + ch), w1 = ldf8(cw + 2816 + ch), w2 = ldf8(cw + 2 * 2816 + ch);
;         const bool defer01 = (m0 < MP) && ((m0 & 8191) != 0);
; #pragma unroll
;         for (int it = 0; it < 2; ++it) {
;             const int i = (tid >> 3) + 64 * it, r = m0 + i;
;             int sq, pos, len; rowinfo(r, sq, pos, len);
;             const F8 g0 = ldf8(Cs + i * LDC + c8), up = ldf8(Cs + i * LDC + 64 + c8);
;             if (i >= 126) stf8(ep.f0 + ((size_t)mt * 2 + (i - 126)) * 2816 + ch, g0);
;             if (i < 2) { stf8(ep.f1 + ((size_t)mt * 2 + i) * 2816 + ch, g0); stf8(ep.f2 + ((size_t)mt * 2 + i) * 2816 + ch, up); }
;             if (pos >= len - 2) {
;                 float* so = sq < 4 ? ep.out + O_PFF + (((size_t)ep.layer * 4 + sq) * 2 + (pos - (len - 2))) * 2816
;                                    : ep.out + O_SFF + (((size_t)ep.layer * 8 + (sq - 4)) * 2 + (pos - (len - 2))) * 2816;
;                 stf8(so + ch, g0);
;             }
; template <int MODE>
; DI void gemm_phase(const bf16_t* __restrict__ A, const bf16_t* __restrict__ Bt, int M, int N, int K, const Epi& ep) {
;     ...
;         if (wr == 0) BAR;
;         __syncthreads();
; #pragma unroll
;         for (int ai = 0; ai < 2; ++ai)
; #pragma unroll
;             for (int bj = 0; bj < 2; ++bj) {
; #pragma unroll
;                 for (int m = 0; m < 4; ++m)
; #pragma unroll
;                     for (int n = 0; n < 2; ++n)
;                         *(f32x4*)(Cs + (wr * 64 + m * 16 + fr) * LDC + wc * 32 + n * 16 + fq * 4) = acc[ai][bj][m][n];
;                 __syncthreads();
;                 gemm_epilogue<MODE>(Cs, brow + ai * 128, bcol + bj * 128, ep);
.LBB0_1153:
	s_or_b64 exec, exec, s[0:1]
	s_waitcnt vmcnt(0)
	s_barrier
	s_and_b32 s0, s27, 31
	s_add_i32 s0, s0, -1
	s_cmp_lt_u32 s0, 30
	s_cselect_b32 s0, 1, 0
	s_cmp_lt_u32 s27, 0x80
	s_cselect_b32 s1, 1, 0
	s_and_b32 s0, s0, s1
	s_cmp_lg_u32 s0, 0
	s_cbranch_scc1 .Lffn_fast
	ds_write_b128 v194, v[96:99]
	ds_write_b128 v194, v[100:103] offset:64
	ds_write_b128 v194, v[104:107] offset:8448
	ds_write_b128 v194, v[108:111] offset:8512
	ds_write_b128 v194, v[112:115] offset:16896
	ds_write_b128 v194, v[116:119] offset:16960
	ds_write_b128 v194, v[120:123] offset:25344
	ds_write_b128 v194, v[124:127] offset:25408
	v_mov_b32_e32 v120, v250
	s_waitcnt lgkmcnt(0)
	s_barrier
	s_lshl_b32 s26, s26, 7
	v_lshlrev_b32_e32 v64, 3, v120
	v_and_b32_e32 v195, 56, v64
	v_or_b32_e32 v152, s26, v195
	v_ashrrev_i32_e32 v153, 31, v152
	v_lshlrev_b64 v[154:155], 2, v[152:153]
	v_lshl_add_u64 v[64:65], s[6:7], 0, v[154:155]
	v_lshl_add_u64 v[116:117], s[18:19], 0, v[154:155]
	v_lshl_add_u64 v[66:67], s[14:15], 0, v[154:155]
	global_load_dwordx4 v[96:99], v[64:65], off offset:16
	global_load_dwordx4 v[108:111], v[64:65], off
	global_load_dwordx4 v[100:103], v[66:67], off offset:16
	global_load_dwordx4 v[112:115], v[66:67], off
	global_load_dwordx4 v[104:107], v[116:117], off offset:16
	s_nop 0
	global_load_dwordx4 v[116:119], v[116:117], off
	v_ashrrev_i32_e32 v164, 3, v120
	v_mul_lo_u32 v64, v164, s35
	v_add_u32_e32 v196, 16, v64
	v_lshl_add_u32 v64, v195, 2, v196
	ds_read_b128 v[132:135], v64
	ds_read_b128 v[124:127], v64 offset:16
	ds_read_b128 v[128:131], v64 offset:256
	ds_read_b128 v[120:123], v64 offset:272
	s_lshl_b32 s0, s27, 1
	s_ashr_i32 s1, s0, 31
	s_lshl_b64 s[30:31], s[0:1], 1
	v_cmp_lt_i32_e32 vcc, s71, v164
	s_and_saveexec_b64 s[0:1], vcc
	s_cbranch_execz .LBB0_1155
	v_add_u32_e32 v212, 0xffffff82, v164
	v_lshl_add_u64 v[64:65], s[30:31], 0, v[212:213]
	v_mov_b64_e32 v[66:67], s[72:73]
	v_mad_u64_u32 v[66:67], s[40:41], v64, s3, v[66:67]
	v_mad_i32_i24 v67, v65, s3, v67
	v_lshl_add_u64 v[64:65], v[152:153], 2, v[66:67]
	s_waitcnt lgkmcnt(3)
	global_store_dwordx4 v[64:65], v[132:135], off sc1
	s_waitcnt lgkmcnt(2)
	global_store_dwordx4 v[64:65], v[124:127], off offset:16 sc1
.LBB0_1155:
	s_or_b64 exec, exec, s[0:1]
	v_cmp_gt_i32_e32 vcc, 2, v164
	s_and_saveexec_b64 s[0:1], vcc
	s_cbranch_execz .LBB0_1157
	v_ashrrev_i32_e32 v165, 31, v164
	v_lshl_add_u64 v[64:65], s[30:31], 0, v[164:165]
	v_mov_b64_e32 v[66:67], s[80:81]
	v_mad_u64_u32 v[66:67], s[40:41], v64, s3, v[66:67]
	v_mad_i32_i24 v67, v65, s3, v67
	v_lshl_add_u64 v[66:67], v[66:67], 0, v[154:155]
	s_waitcnt lgkmcnt(3)
	global_store_dwordx4 v[66:67], v[132:135], off sc1
	s_waitcnt lgkmcnt(2)
	global_store_dwordx4 v[66:67], v[124:127], off offset:16 sc1
	v_mov_b64_e32 v[66:67], s[82:83]
	v_mad_u64_u32 v[66:67], s[40:41], v64, s3, v[66:67]
	v_mad_i32_i24 v67, v65, s3, v67
	v_lshl_add_u64 v[64:65], v[66:67], 0, v[154:155]
	s_waitcnt lgkmcnt(1)
	global_store_dwordx4 v[64:65], v[128:131], off sc1
	s_waitcnt lgkmcnt(0)
	global_store_dwordx4 v[64:65], v[120:123], off offset:16 sc1
.LBB0_1157:
	s_or_b64 exec, exec, s[0:1]
	s_lshl_b32 s54, s27, 8
	v_add_u32_e32 v165, s54, v164
	v_add_u32_e32 v64, 0xffff8000, v165
	v_lshrrev_b32_e32 v64, 6, v64
	v_add_u32_e32 v64, 4, v64
	v_ashrrev_i32_e32 v65, 13, v165
	v_cmp_gt_i32_e64 s[0:1], s53, v165
	v_mov_b32_e32 v66, 0x1fff
	s_nop 0
	v_cndmask_b32_e64 v66, 63, v66, s[0:1]
	v_cndmask_b32_e64 v136, v64, v65, s[0:1]
	v_mov_b32_e32 v64, 0x1ffe
	v_and_b32_e32 v197, v66, v165
	v_cndmask_b32_e64 v137, 62, v64, s[0:1]
	v_cmp_ge_u32_e64 s[0:1], v197, v137
	s_and_saveexec_b64 s[40:41], s[0:1]
	s_cbranch_execz .LBB0_1159
	v_add_u32_e32 v64, -4, v136
	v_ashrrev_i32_e32 v65, 31, v136
	v_cmp_gt_i32_e64 s[0:1], 4, v136
	v_mov_b32_e32 v66, 0xd868000
	v_mov_b32_e32 v67, 0xce50000
	v_cndmask_b32_e64 v65, 0, v65, s[0:1]
	v_cndmask_b32_e64 v64, v64, v136, s[0:1]
	v_cndmask_b32_e64 v212, v66, v67, s[0:1]
	v_cndmask_b32_e64 v138, 4, 3, s[0:1]
	v_readlane_b32 s0, v255, 13
	v_readlane_b32 s1, v255, 14
	v_lshl_add_u64 v[66:67], s[60:61], 0, v[212:213]
	v_sub_u32_e32 v212, v197, v137
	v_lshlrev_b64 v[138:139], v138, s[0:1]
	v_lshl_add_u64 v[138:139], v[138:139], 0, v[212:213]
	v_lshl_add_u64 v[64:65], v[64:65], 1, v[138:139]
	v_mad_u64_u32 v[66:67], s[0:1], v64, s3, v[66:67]
	v_mad_i32_i24 v67, v65, s3, v67
	v_lshl_add_u64 v[64:65], v[152:153], 2, v[66:67]
	s_waitcnt lgkmcnt(3)
	global_store_dwordx4 v[64:65], v[132:135], off sc1
	s_waitcnt lgkmcnt(2)
	global_store_dwordx4 v[64:65], v[124:127], off offset:16 sc1

; DI void stf8(float* p, const F8& f) { *(float4*)p = make_float4(f.v[0], f.v[1], f.v[2], f.v[3]); *(float4*)(p + 4) = make_float4(f.v[4], f.v[5], f.v[6], f.v[7]); }
; DI void stb8(bf16_t* p, const F8& f) { *(uint4*)p = pack8(f); }
; DI float siluf(float x) { return x / (1.f + __expf(-x)); }
; template <int MODE>
; DI void gemm_epilogue(const float* Cs, int m0, int n0, const Epi& ep) {
;     ...
;         const int mt = m0 >> 7, ch0 = (n0 >> 7) * 64, c8 = (tid & 7) * 8, ch = ch0 + c8;
;         const float* cw = ep.c0;
;         const F8 w0 = ldf8(cw + ch), w1 = ldf8(cw + 2816 + ch), w2 = ldf8(cw + 2 * 2816 + ch);
;         const bool defer01 = (m0 < MP) && ((m0 & 8191) != 0);
; #pragma unroll
;         for (int it = 0; it < 2; ++it) {
;             const int i = (tid >> 3) + 64 * it, r = m0 + i;
;             int sq, pos, len; rowinfo(r, sq, pos, len);
;             const F8 g0 = ldf8(Cs + i * LDC + c8), up = ldf8(Cs + i * LDC + 64 + c8);
;             if (i >= 126) stf8(ep.f0 + ((size_t)mt * 2 + (i - 126)) * 2816 + ch, g0);
;             if (i < 2) { stf8(ep.f1 + ((size_t)mt * 2 + i) * 2816 + ch, g0); stf8(ep.f2 + ((size_t)mt * 2 + i) * 2816 + ch, up); }
;             if (pos >= len - 2) {
;                 float* so = sq < 4 ? ep.out + O_PFF + (((size_t)ep.layer * 4 + sq) * 2 + (pos - (len - 2))) * 2816
;                                    : ep.out + O_SFF + (((size_t)ep.layer * 8 + (sq - 4)) * 2 + (pos - (len - 2))) * 2816;
;                 stf8(so + ch, g0);
;             }
;             if (i < 2 && defer01) continue;
;             F8 g1, g2;
;             const float* hist = sq >= 4 ? ep.c1 + ((size_t)ep.layer * 8 + (sq - 4)) * 2 * 2816 + ch : nullptr;
;             if (pos >= 1) g1 = ldf8(Cs + (i - 1) * LDC + c8);
;             else if (hist) g1 = ldf8(hist + 2816);
;             else { for (int e = 0; e < 8; ++e) g1.v[e] = 0.f; }
;             if (pos >= 2) g2 = ldf8(Cs + (i - 2) * LDC + c8);
;             else if (hist) g2 = ldf8(hist + (size_t)pos * 2816);
;             else { for (int e = 0; e < 8; ++e) g2.v[e] = 0.f; }
;             F8 o;
; #pragma unroll
;             for (int e = 0; e < 8; ++e) o.v[e] = siluf(w0.v[e] * g2.v[e] + w1.v[e] * g1.v[e] + w2.v[e] * g0.v[e]) * up.v[e];
;             stb8(ep.b0 + (size_t)r * 2816 + ch, o);
.LBB0_1174:
	s_or_b64 exec, exec, s[42:43]
	s_waitcnt vmcnt(0) lgkmcnt(1)
	v_pk_mul_f32 v[64:65], v[108:109], v[148:149]
	s_nop 0
	v_pk_fma_f32 v[64:65], v[112:113], v[144:145], v[64:65]
	s_nop 0
	v_pk_fma_f32 v[64:65], v[116:117], v[132:133], v[64:65]
	s_nop 0
	v_mul_f32_e32 v66, 0xbfb8aa3b, v64
	v_mul_f32_e32 v67, 0xbfb8aa3b, v65
	v_exp_f32_e32 v66, v66
	v_exp_f32_e32 v67, v67
	s_nop 0
	v_pk_add_f32 v[66:67], v[66:67], 1.0 op_sel_hi:[1,0]
	s_nop 0
	v_rcp_f32_e32 v132, v67
	s_nop 0
	v_mul_f32_e32 v65, v65, v132
	v_rcp_f32_e32 v67, v66
	s_nop 0
	v_mul_f32_e32 v64, v64, v67
	v_pk_mul_f32 v[128:129], v[128:129], v[64:65]
	v_pk_mul_f32 v[64:65], v[110:111], v[150:151]
	s_nop 0
	v_pk_fma_f32 v[64:65], v[114:115], v[146:147], v[64:65]
	s_nop 0
	v_pk_fma_f32 v[64:65], v[118:119], v[134:135], v[64:65]
	s_nop 0
	v_mul_f32_e32 v66, 0xbfb8aa3b, v64
	v_mul_f32_e32 v67, 0xbfb8aa3b, v65
	v_exp_f32_e32 v66, v66
	v_exp_f32_e32 v67, v67
	s_nop 0
	v_pk_add_f32 v[66:67], v[66:67], 1.0 op_sel_hi:[1,0]
	s_nop 0
	v_rcp_f32_e32 v132, v67
	s_nop 0
	v_mul_f32_e32 v65, v65, v132
	v_rcp_f32_e32 v67, v66
	s_nop 0
	v_mul_f32_e32 v64, v64, v67
	v_pk_mul_f32 v[66:67], v[130:131], v[64:65]
	s_waitcnt lgkmcnt(0)
	v_pk_mul_f32 v[64:65], v[96:97], v[140:141]
	s_nop 0
	v_pk_fma_f32 v[64:65], v[100:101], v[136:137], v[64:65]
	s_nop 0
	v_pk_fma_f32 v[64:65], v[104:105], v[124:125], v[64:65]
	s_nop 0
	v_mul_f32_e32 v124, 0xbfb8aa3b, v64
	v_mul_f32_e32 v125, 0xbfb8aa3b, v65
	v_exp_f32_e32 v124, v124
	v_exp_f32_e32 v125, v125
	s_nop 0
	v_pk_add_f32 v[124:125], v[124:125], 1.0 op_sel_hi:[1,0]
	s_nop 0
	v_rcp_f32_e32 v130, v125
	s_nop 0
	v_mul_f32_e32 v65, v65, v130
	v_rcp_f32_e32 v125, v124
	s_nop 0
	v_mul_f32_e32 v64, v64, v125
	v_pk_mul_f32 v[120:121], v[120:121], v[64:65]
	v_pk_mul_f32 v[64:65], v[98:99], v[142:143]
	s_nop 0
	v_pk_fma_f32 v[64:65], v[102:103], v[138:139], v[64:65]
	s_nop 0
	v_pk_fma_f32 v[64:65], v[106:107], v[126:127], v[64:65]
	s_nop 0
	v_mul_f32_e32 v124, 0xbfb8aa3b, v64
	v_mul_f32_e32 v125, 0xbfb8aa3b, v65
	v_exp_f32_e32 v124, v124
	v_exp_f32_e32 v125, v125
	s_nop 0
	v_pk_add_f32 v[124:125], v[124:125], 1.0 op_sel_hi:[1,0]
	s_nop 0
	v_rcp_f32_e32 v126, v125
	s_nop 0
	v_mul_f32_e32 v65, v65, v126
	v_rcp_f32_e32 v125, v124
	s_nop 0
	v_mul_f32_e32 v64, v64, v125
	v_pk_mul_f32 v[122:123], v[122:123], v[64:65]
	v_mov_b64_e32 v[64:65], s[84:85]
	v_mad_i64_i32 v[64:65], s[42:43], v165, s89, v[64:65]
	v_lshl_add_u64 v[124:125], v[152:153], 1, v[64:65]
	v_cvt_pk_bf16_f32 v64, v128, v129
	v_cvt_pk_bf16_f32 v65, v66, v67
	v_cvt_pk_bf16_f32 v66, v120, v121
	v_cvt_pk_bf16_f32 v67, v122, v123
	global_store_dwordx4 v[124:125], v[64:67], off sc1
.LBB0_1175:
	s_or_b64 exec, exec, s[0:1]
	s_waitcnt lgkmcnt(3)
	v_add_u32_e32 v132, 64, v164
	v_mul_lo_u32 v64, v132, s35
	v_add_u32_e32 v165, 16, v64
	v_lshl_add_u32 v64, v195, 2, v165
	ds_read_b128 v[136:139], v64
	s_waitcnt lgkmcnt(3)
	ds_read_b128 v[124:127], v64 offset:16
	s_waitcnt lgkmcnt(3)
	ds_read_b128 v[128:131], v64 offset:256
	s_waitcnt lgkmcnt(3)
	ds_read_b128 v[120:123], v64 offset:272
	v_cmp_lt_i32_e32 vcc, 61, v164
	s_and_saveexec_b64 s[0:1], vcc
	s_cbranch_execz .LBB0_1177
	v_subrev_u32_e32 v212, 62, v164
	v_lshl_add_u64 v[64:65], s[30:31], 0, v[212:213]
	v_mov_b64_e32 v[66:67], s[72:73]
	v_mad_u64_u32 v[66:67], s[42:43], v64, s3, v[66:67]
	v_mad_i32_i24 v67, v65, s3, v67
	v_lshl_add_u64 v[64:65], v[152:153], 2, v[66:67]
	s_waitcnt lgkmcnt(3)
	global_store_dwordx4 v[64:65], v[136:139], off sc1
	s_waitcnt lgkmcnt(2)
	global_store_dwordx4 v[64:65], v[124:127], off offset:16 sc1
.LBB0_1177:
	s_or_b64 exec, exec, s[0:1]
	v_cmp_gt_i32_e32 vcc, s90, v164
	s_and_saveexec_b64 s[0:1], vcc
	s_cbranch_execz .LBB0_1179
	v_ashrrev_i32_e32 v133, 31, v132
	v_lshl_add_u64 v[64:65], s[30:31], 0, v[132:133]
	v_mov_b64_e32 v[66:67], s[80:81]
	v_mad_u64_u32 v[66:67], s[42:43], v64, s3, v[66:67]
	v_mad_i32_i24 v67, v65, s3, v67
	v_lshl_add_u64 v[66:67], v[66:67], 0, v[154:155]
	s_waitcnt lgkmcnt(3)
	global_store_dwordx4 v[66:67], v[136:139], off sc1
	s_waitcnt lgkmcnt(2)
	global_store_dwordx4 v[66:67], v[124:127], off offset:16 sc1
	v_mov_b64_e32 v[66:67], s[82:83]
	v_mad_u64_u32 v[66:67], s[42:43], v64, s3, v[66:67]
	v_mad_i32_i24 v67, v65, s3, v67
	v_lshl_add_u64 v[64:65], v[66:67], 0, v[154:155]
	s_waitcnt lgkmcnt(1)
	global_store_dwordx4 v[64:65], v[128:131], off sc1
	s_waitcnt lgkmcnt(0)
	global_store_dwordx4 v[64:65], v[120:123], off offset:16 sc1
.LBB0_1179:
	s_or_b64 exec, exec, s[0:1]
	v_add_u32_e32 v164, s54, v132
	v_add_u32_e32 v64, 0xffff8000, v164
	v_lshrrev_b32_e32 v64, 6, v64
	v_add_u32_e32 v64, 4, v64
	v_ashrrev_i32_e32 v65, 13, v164
	v_cmp_gt_i32_e64 s[0:1], s53, v164
	v_mov_b32_e32 v66, 0x1fff
	s_nop 0
	v_cndmask_b32_e64 v66, 63, v66, s[0:1]
	v_cndmask_b32_e64 v132, v64, v65, s[0:1]
	v_mov_b32_e32 v64, 0x1ffe
	v_and_b32_e32 v166, v66, v164
	v_cndmask_b32_e64 v133, 62, v64, s[0:1]
	v_cmp_ge_u32_e64 s[0:1], v166, v133
	s_and_saveexec_b64 s[42:43], s[0:1]
	s_cbranch_execz .LBB0_1181
	v_ashrrev_i32_e32 v64, 31, v132
	v_add_u32_e32 v66, -4, v132
	v_cmp_gt_i32_e64 s[0:1], 4, v132
	v_mov_b32_e32 v67, 0xce50000
	s_nop 0
	v_cndmask_b32_e64 v65, 0, v64, s[0:1]
	v_cndmask_b32_e64 v64, v66, v132, s[0:1]
	v_mov_b32_e32 v66, 0xd868000
	v_cndmask_b32_e64 v212, v66, v67, s[0:1]
	v_cndmask_b32_e64 v134, 4, 3, s[0:1]
	v_readlane_b32 s0, v255, 13
	v_readlane_b32 s1, v255, 14
	v_lshl_add_u64 v[66:67], s[60:61], 0, v[212:213]
	v_sub_u32_e32 v212, v166, v133
	v_lshlrev_b64 v[134:135], v134, s[0:1]
	v_lshl_add_u64 v[134:135], v[134:135], 0, v[212:213]
	v_lshl_add_u64 v[64:65], v[64:65], 1, v[134:135]
	v_mad_u64_u32 v[66:67], s[0:1], v64, s3, v[66:67]
	v_mad_i32_i24 v67, v65, s3, v67
	v_lshl_add_u64 v[64:65], v[152:153], 2, v[66:67]
	s_waitcnt lgkmcnt(3)
	global_store_dwordx4 v[64:65], v[136:139], off sc1
	s_waitcnt lgkmcnt(2)
	global_store_dwordx4 v[64:65], v[124:127], off offset:16 sc1

; DI void stb8(bf16_t* p, const F8& f) { *(uint4*)p = pack8(f); }
; DI float siluf(float x) { return x / (1.f + __expf(-x)); }
; template <int MODE>
; DI void gemm_epilogue(const float* Cs, int m0, int n0, const Epi& ep) {
;     ...
;             F8 o;
; #pragma unroll
;             for (int e = 0; e < 8; ++e) o.v[e] = siluf(w0.v[e] * g2.v[e] + w1.v[e] * g1.v[e] + w2.v[e] * g0.v[e]) * up.v[e];
;             stb8(ep.b0 + (size_t)r * 2816 + ch, o);
.LBB0_1196:
	s_or_b64 exec, exec, s[42:43]
	s_waitcnt vmcnt(0) lgkmcnt(1)
	v_pk_mul_f32 v[64:65], v[108:109], v[148:149]
	s_nop 0
	v_pk_fma_f32 v[64:65], v[112:113], v[144:145], v[64:65]
	s_nop 0
	v_pk_fma_f32 v[64:65], v[116:117], v[136:137], v[64:65]
	s_nop 0
	v_mul_f32_e32 v66, 0xbfb8aa3b, v64
	v_mul_f32_e32 v67, 0xbfb8aa3b, v65
	v_exp_f32_e32 v66, v66
	v_exp_f32_e32 v67, v67
	s_nop 0
	v_pk_add_f32 v[66:67], v[66:67], 1.0 op_sel_hi:[1,0]
	s_nop 0
	v_rcp_f32_e32 v108, v67
	s_nop 0
	v_mul_f32_e32 v65, v65, v108
	v_rcp_f32_e32 v67, v66
	s_nop 0
	v_mul_f32_e32 v64, v64, v67
	v_pk_mul_f32 v[108:109], v[128:129], v[64:65]
	v_pk_mul_f32 v[64:65], v[110:111], v[150:151]
	s_nop 0
	v_pk_fma_f32 v[64:65], v[114:115], v[146:147], v[64:65]
	s_nop 0
	v_pk_fma_f32 v[64:65], v[118:119], v[138:139], v[64:65]
	s_nop 0
	v_mul_f32_e32 v66, 0xbfb8aa3b, v64
	v_mul_f32_e32 v67, 0xbfb8aa3b, v65
	v_exp_f32_e32 v66, v66
	v_exp_f32_e32 v67, v67
	s_nop 0
	v_pk_add_f32 v[66:67], v[66:67], 1.0 op_sel_hi:[1,0]
	s_nop 0
	v_rcp_f32_e32 v110, v67
	s_nop 0
	v_mul_f32_e32 v65, v65, v110
	v_rcp_f32_e32 v67, v66
	s_nop 0
	v_mul_f32_e32 v64, v64, v67
	v_pk_mul_f32 v[66:67], v[130:131], v[64:65]
	s_waitcnt lgkmcnt(0)
	v_pk_mul_f32 v[64:65], v[96:97], v[140:141]
	s_nop 0
	v_pk_fma_f32 v[64:65], v[100:101], v[132:133], v[64:65]
	s_nop 0
	v_pk_fma_f32 v[64:65], v[104:105], v[124:125], v[64:65]
	s_nop 0
	v_mul_f32_e32 v96, 0xbfb8aa3b, v64
	v_mul_f32_e32 v97, 0xbfb8aa3b, v65
	v_exp_f32_e32 v96, v96
	v_exp_f32_e32 v97, v97
	s_nop 0
	v_pk_add_f32 v[96:97], v[96:97], 1.0 op_sel_hi:[1,0]
	s_nop 0
	v_rcp_f32_e32 v100, v97
	s_nop 0
	v_mul_f32_e32 v65, v65, v100
	v_rcp_f32_e32 v97, v96
	s_nop 0
	v_mul_f32_e32 v64, v64, v97
	v_pk_mul_f32 v[96:97], v[120:121], v[64:65]
	v_pk_mul_f32 v[64:65], v[98:99], v[142:143]
	s_nop 0
	v_pk_fma_f32 v[64:65], v[102:103], v[134:135], v[64:65]
	s_nop 0
	v_pk_fma_f32 v[64:65], v[106:107], v[126:127], v[64:65]
	s_nop 0
	v_mul_f32_e32 v98, 0xbfb8aa3b, v64
	v_mul_f32_e32 v99, 0xbfb8aa3b, v65
	v_exp_f32_e32 v98, v98
	v_exp_f32_e32 v99, v99
	s_nop 0
	v_pk_add_f32 v[98:99], v[98:99], 1.0 op_sel_hi:[1,0]
	s_nop 0
	v_rcp_f32_e32 v100, v99
	s_nop 0
	v_mul_f32_e32 v65, v65, v100
	v_rcp_f32_e32 v99, v98
	s_nop 0
	v_mul_f32_e32 v64, v64, v99
	v_pk_mul_f32 v[98:99], v[122:123], v[64:65]
	v_mov_b64_e32 v[64:65], s[84:85]
	v_mad_i64_i32 v[64:65], s[42:43], v164, s89, v[64:65]
	v_lshl_add_u64 v[100:101], v[152:153], 1, v[64:65]
	v_cvt_pk_bf16_f32 v64, v108, v109
	v_cvt_pk_bf16_f32 v65, v66, v67
	v_cvt_pk_bf16_f32 v66, v96, v97
	v_cvt_pk_bf16_f32 v67, v98, v99
	global_store_dwordx4 v[100:101], v[64:67], off sc1
; DI void stf8(float* p, const F8& f) { *(float4*)p = make_float4(f.v[0], f.v[1], f.v[2], f.v[3]); *(float4*)(p + 4) = make_float4(f.v[4], f.v[5], f.v[6], f.v[7]); }
; DI void rowinfo(int r, int& sq, int& pos, int& len) { if (r < MP) { sq = r >> 13; pos = r & 8191; len = 8192; } else { sq = 4 + ((r - MP) >> 6); pos = r & 63; len = 64; } }
; template <int MODE>
; DI void gemm_epilogue(const float* Cs, int m0, int n0, const Epi& ep) {
;     ...
;         const int mt = m0 >> 7, ch0 = (n0 >> 7) * 64, c8 = (tid & 7) * 8, ch = ch0 + c8;
;         const float* cw = ep.c0;
;         const F8 w0 = ldf8(cw + ch), w1 = ldf8(cw + 2816 + ch), w2 = ldf8(cw + 2 * 2816 + ch);
;         const bool defer01 = (m0 < MP) && ((m0 & 8191) != 0);
; #pragma unroll
;         for (int it = 0; it < 2; ++it) {
;             const int i = (tid >> 3) + 64 * it, r = m0 + i;
;             int sq, pos, len; rowinfo(r, sq, pos, len);
;             const F8 g0 = ldf8(Cs + i * LDC + c8), up = ldf8(Cs + i * LDC + 64 + c8);
;             if (i >= 126) stf8(ep.f0 + ((size_t)mt * 2 + (i - 126)) * 2816 + ch, g0);
;             if (i < 2) { stf8(ep.f1 + ((size_t)mt * 2 + i) * 2816 + ch, g0); stf8(ep.f2 + ((size_t)mt * 2 + i) * 2816 + ch, up); }
;             if (pos >= len - 2) {
;                 float* so = sq < 4 ? ep.out + O_PFF + (((size_t)ep.layer * 4 + sq) * 2 + (pos - (len - 2))) * 2816
;                                    : ep.out + O_SFF + (((size_t)ep.layer * 8 + (sq - 4)) * 2 + (pos - (len - 2))) * 2816;
;                 stf8(so + ch, g0);
;             }
; template <int MODE>
; DI void gemm_phase(const bf16_t* __restrict__ A, const bf16_t* __restrict__ Bt, int M, int N, int K, const Epi& ep) {
;     ...
;                         *(f32x4*)(Cs + (wr * 64 + m * 16 + fr) * LDC + wc * 32 + n * 16 + fq * 4) = acc[ai][bj][m][n];
;                 __syncthreads();
.LBB0_1197:
	s_or_b64 exec, exec, s[0:1]
	s_waitcnt lgkmcnt(0)
	s_barrier
	ds_write_b128 v194, v[222:225]
	ds_write_b128 v194, v[68:71] offset:64
	ds_write_b128 v194, v[72:75] offset:8448
	ds_write_b128 v194, v[76:79] offset:8512
	ds_write_b128 v194, v[80:83] offset:16896
	ds_write_b128 v194, v[84:87] offset:16960
	ds_write_b128 v194, v[88:91] offset:25344
	ds_write_b128 v194, v[92:95] offset:25408
	v_mov_b32_e32 v88, v250
	s_waitcnt lgkmcnt(0)
	s_barrier
	s_or_b32 s49, s26, 64
	v_lshlrev_b32_e32 v64, 3, v88
	v_and_b32_e32 v212, 56, v64
	v_or_b32_e32 v64, s49, v212
	v_ashrrev_i32_e32 v65, 31, v64
	s_ashr_i32 s27, s26, 31
	v_lshl_add_u64 v[120:121], v[212:213], 0, s[26:27]
	v_lshlrev_b64 v[64:65], 2, v[64:65]
	v_lshl_add_u64 v[68:69], v[120:121], 2, s[6:7]
	v_lshl_add_u64 v[72:73], s[14:15], 0, v[64:65]
	v_lshl_add_u64 v[84:85], s[18:19], 0, v[64:65]
	global_load_dwordx4 v[64:67], v[68:69], off offset:272
	global_load_dwordx4 v[76:79], v[68:69], off offset:256
	s_nop 0
	global_load_dwordx4 v[68:71], v[72:73], off offset:16
	global_load_dwordx4 v[80:83], v[72:73], off
	s_nop 0
	global_load_dwordx4 v[72:75], v[84:85], off offset:16
	s_nop 0
	global_load_dwordx4 v[84:87], v[84:85], off
	v_ashrrev_i32_e32 v122, 3, v88
	v_mul_lo_u32 v88, v122, s35
	v_add_u32_e32 v128, 16, v88
	v_lshl_add_u32 v88, v212, 2, v128
	s_waitcnt vmcnt(7)
	ds_read_b128 v[104:107], v88
	ds_read_b128 v[92:95], v88 offset:16
	ds_read_b128 v[96:99], v88 offset:256
	ds_read_b128 v[88:91], v88 offset:272
	v_cmp_lt_i32_e32 vcc, s71, v122
	s_and_saveexec_b64 s[0:1], vcc
	s_cbranch_execz .LBB0_1199
	v_add_u32_e32 v100, 0xffffff82, v122
	v_mov_b32_e32 v101, v213
	v_lshl_add_u64 v[100:101], s[30:31], 0, v[100:101]
	v_mov_b64_e32 v[102:103], s[72:73]
	v_mad_u64_u32 v[102:103], s[42:43], v100, s3, v[102:103]
	v_mad_i32_i24 v103, v101, s3, v103
	v_lshl_add_u64 v[100:101], v[120:121], 2, v[102:103]
	s_waitcnt lgkmcnt(3)
	global_store_dwordx4 v[100:101], v[104:107], off offset:256 sc1
	s_waitcnt lgkmcnt(2)
	global_store_dwordx4 v[100:101], v[92:95], off offset:272 sc1
.LBB0_1199:
	s_or_b64 exec, exec, s[0:1]
	v_cmp_gt_i32_e32 vcc, 2, v122
	v_lshlrev_b64 v[124:125], 2, v[120:121]
	s_and_saveexec_b64 s[0:1], vcc
	s_cbranch_execz .LBB0_1201
	v_ashrrev_i32_e32 v123, 31, v122
	v_lshl_add_u64 v[100:101], s[30:31], 0, v[122:123]
	v_mov_b64_e32 v[102:103], s[80:81]
	v_mad_u64_u32 v[102:103], s[42:43], v100, s3, v[102:103]
	v_mad_i32_i24 v103, v101, s3, v103
	v_lshl_add_u64 v[102:103], v[102:103], 0, v[124:125]
	s_waitcnt lgkmcnt(3)
	global_store_dwordx4 v[102:103], v[104:107], off offset:256 sc1
	s_waitcnt lgkmcnt(2)
	global_store_dwordx4 v[102:103], v[92:95], off offset:272 sc1
	v_mov_b64_e32 v[102:103], s[82:83]
	v_mad_u64_u32 v[102:103], s[42:43], v100, s3, v[102:103]
	v_mad_i32_i24 v103, v101, s3, v103
	v_lshl_add_u64 v[100:101], v[102:103], 0, v[124:125]
	s_waitcnt lgkmcnt(1)
	global_store_dwordx4 v[100:101], v[96:99], off offset:256 sc1
	s_waitcnt lgkmcnt(0)
	global_store_dwordx4 v[100:101], v[88:91], off offset:272 sc1
.LBB0_1201:
	s_or_b64 exec, exec, s[0:1]
	v_add_u32_e32 v123, s54, v122
	v_add_u32_e32 v100, 0xffff8000, v123
	v_lshrrev_b32_e32 v100, 6, v100
	v_add_u32_e32 v100, 4, v100
	v_ashrrev_i32_e32 v101, 13, v123
	v_cmp_gt_i32_e64 s[0:1], s53, v123
	v_mov_b32_e32 v102, 0x1fff
	s_nop 0
	v_cndmask_b32_e64 v102, 63, v102, s[0:1]
	v_cndmask_b32_e64 v100, v100, v101, s[0:1]
	v_mov_b32_e32 v101, 0x1ffe
	v_and_b32_e32 v129, v102, v123
	v_cndmask_b32_e64 v101, 62, v101, s[0:1]
	v_cmp_ge_u32_e64 s[0:1], v129, v101
	s_and_saveexec_b64 s[42:43], s[0:1]
	s_cbranch_execz .LBB0_1203
	v_add_u32_e32 v102, -4, v100
	v_ashrrev_i32_e32 v103, 31, v100
	v_cmp_gt_i32_e64 s[0:1], 4, v100
	v_mov_b32_e32 v108, 0xd868000
	v_mov_b32_e32 v109, 0xce50000
	v_cndmask_b32_e64 v103, 0, v103, s[0:1]
	v_cndmask_b32_e64 v102, v102, v100, s[0:1]
	v_cndmask_b32_e64 v108, v108, v109, s[0:1]
	v_cndmask_b32_e64 v110, 4, 3, s[0:1]
	v_readlane_b32 s0, v255, 13
	v_readlane_b32 s1, v255, 14
	v_sub_u32_e32 v112, v129, v101
	v_mov_b32_e32 v113, v213
	v_lshlrev_b64 v[110:111], v110, s[0:1]
	v_mov_b32_e32 v109, v213
	v_lshl_add_u64 v[110:111], v[110:111], 0, v[112:113]
	v_lshl_add_u64 v[108:109], s[60:61], 0, v[108:109]
	v_lshl_add_u64 v[102:103], v[102:103], 1, v[110:111]
	v_mad_u64_u32 v[108:109], s[0:1], v102, s3, v[108:109]
	v_mad_i32_i24 v109, v103, s3, v109
	v_lshl_add_u64 v[102:103], v[120:121], 2, v[108:109]
	s_waitcnt lgkmcnt(3)
	global_store_dwordx4 v[102:103], v[104:107], off offset:256 sc1
	s_waitcnt lgkmcnt(2)
	global_store_dwordx4 v[102:103], v[92:95], off offset:272 sc1

; DI void stf8(float* p, const F8& f) { *(float4*)p = make_float4(f.v[0], f.v[1], f.v[2], f.v[3]); *(float4*)(p + 4) = make_float4(f.v[4], f.v[5], f.v[6], f.v[7]); }
; DI void stb8(bf16_t* p, const F8& f) { *(uint4*)p = pack8(f); }
; DI float siluf(float x) { return x / (1.f + __expf(-x)); }
; DI void rowinfo(int r, int& sq, int& pos, int& len) { if (r < MP) { sq = r >> 13; pos = r & 8191; len = 8192; } else { sq = 4 + ((r - MP) >> 6); pos = r & 63; len = 64; } }
; template <int MODE>
; DI void gemm_epilogue(const float* Cs, int m0, int n0, const Epi& ep) {
;     ...
;         for (int it = 0; it < 2; ++it) {
;             const int i = (tid >> 3) + 64 * it, r = m0 + i;
;             int sq, pos, len; rowinfo(r, sq, pos, len);
;             const F8 g0 = ldf8(Cs + i * LDC + c8), up = ldf8(Cs + i * LDC + 64 + c8);
;             if (i >= 126) stf8(ep.f0 + ((size_t)mt * 2 + (i - 126)) * 2816 + ch, g0);
;             if (i < 2) { stf8(ep.f1 + ((size_t)mt * 2 + i) * 2816 + ch, g0); stf8(ep.f2 + ((size_t)mt * 2 + i) * 2816 + ch, up); }
;             if (pos >= len - 2) {
;                 float* so = sq < 4 ? ep.out + O_PFF + (((size_t)ep.layer * 4 + sq) * 2 + (pos - (len - 2))) * 2816
;                                    : ep.out + O_SFF + (((size_t)ep.layer * 8 + (sq - 4)) * 2 + (pos - (len - 2))) * 2816;
;                 stf8(so + ch, g0);
;             }
;             if (i < 2 && defer01) continue;
;             F8 g1, g2;
;             const float* hist = sq >= 4 ? ep.c1 + ((size_t)ep.layer * 8 + (sq - 4)) * 2 * 2816 + ch : nullptr;
;             if (pos >= 1) g1 = ldf8(Cs + (i - 1) * LDC + c8);
;             else if (hist) g1 = ldf8(hist + 2816);
;             else { for (int e = 0; e < 8; ++e) g1.v[e] = 0.f; }
;             if (pos >= 2) g2 = ldf8(Cs + (i - 2) * LDC + c8);
;             else if (hist) g2 = ldf8(hist + (size_t)pos * 2816);
;             else { for (int e = 0; e < 8; ++e) g2.v[e] = 0.f; }
;             F8 o;
; #pragma unroll
;             for (int e = 0; e < 8; ++e) o.v[e] = siluf(w0.v[e] * g2.v[e] + w1.v[e] * g1.v[e] + w2.v[e] * g0.v[e]) * up.v[e];
;             stb8(ep.b0 + (size_t)r * 2816 + ch, o);
.LBB0_1218:
	s_or_b64 exec, exec, s[42:43]
	s_waitcnt vmcnt(0) lgkmcnt(1)
	v_pk_mul_f32 v[116:117], v[76:77], v[116:117]
	s_nop 0
	v_pk_fma_f32 v[112:113], v[80:81], v[112:113], v[116:117]
	s_nop 0
	v_pk_fma_f32 v[104:105], v[84:85], v[104:105], v[112:113]
	s_nop 0
	v_mul_f32_e32 v112, 0xbfb8aa3b, v104
	v_mul_f32_e32 v113, 0xbfb8aa3b, v105
	v_exp_f32_e32 v112, v112
	v_exp_f32_e32 v113, v113
	s_nop 0
	v_pk_add_f32 v[112:113], v[112:113], 1.0 op_sel_hi:[1,0]
	s_nop 0
	v_rcp_f32_e32 v116, v113
	s_nop 0
	v_mul_f32_e32 v105, v105, v116
	v_rcp_f32_e32 v113, v112
	s_nop 0
	v_mul_f32_e32 v104, v104, v113
	v_pk_mul_f32 v[96:97], v[96:97], v[104:105]
	v_pk_mul_f32 v[104:105], v[78:79], v[118:119]
	s_nop 0
	v_pk_fma_f32 v[104:105], v[82:83], v[114:115], v[104:105]
	s_nop 0
	v_pk_fma_f32 v[104:105], v[86:87], v[106:107], v[104:105]
	s_nop 0
	v_mul_f32_e32 v106, 0xbfb8aa3b, v104
	v_mul_f32_e32 v107, 0xbfb8aa3b, v105
	v_exp_f32_e32 v106, v106
	v_exp_f32_e32 v107, v107
	s_nop 0
	v_pk_add_f32 v[106:107], v[106:107], 1.0 op_sel_hi:[1,0]
	s_nop 0
	v_rcp_f32_e32 v112, v107
	s_nop 0
	v_mul_f32_e32 v105, v105, v112
	v_rcp_f32_e32 v107, v106
	s_nop 0
	v_mul_f32_e32 v104, v104, v107
	v_pk_mul_f32 v[98:99], v[98:99], v[104:105]
	s_waitcnt lgkmcnt(0)
	v_pk_mul_f32 v[104:105], v[64:65], v[108:109]
	s_nop 0
	v_pk_fma_f32 v[100:101], v[68:69], v[100:101], v[104:105]
	s_nop 0
	v_pk_fma_f32 v[92:93], v[72:73], v[92:93], v[100:101]
	s_nop 0
	v_mul_f32_e32 v100, 0xbfb8aa3b, v92
	v_mul_f32_e32 v101, 0xbfb8aa3b, v93
	v_exp_f32_e32 v100, v100
	v_exp_f32_e32 v101, v101
	s_nop 0
	v_pk_add_f32 v[100:101], v[100:101], 1.0 op_sel_hi:[1,0]
	s_nop 0
	v_rcp_f32_e32 v104, v101
	s_nop 0
	v_mul_f32_e32 v93, v93, v104
	v_rcp_f32_e32 v101, v100
	s_nop 0
	v_mul_f32_e32 v92, v92, v101
	v_pk_mul_f32 v[92:93], v[88:89], v[92:93]
	v_pk_mul_f32 v[88:89], v[66:67], v[110:111]
	s_nop 0
	v_pk_fma_f32 v[88:89], v[70:71], v[102:103], v[88:89]
	s_nop 0
	v_pk_fma_f32 v[88:89], v[74:75], v[94:95], v[88:89]
	s_nop 0
	v_mul_f32_e32 v94, 0xbfb8aa3b, v88
	v_mul_f32_e32 v95, 0xbfb8aa3b, v89
	v_exp_f32_e32 v94, v94
	v_exp_f32_e32 v95, v95
	s_nop 0
	v_pk_add_f32 v[94:95], v[94:95], 1.0 op_sel_hi:[1,0]
	s_nop 0
	v_rcp_f32_e32 v100, v95
	s_nop 0
	v_mul_f32_e32 v89, v89, v100
	v_rcp_f32_e32 v95, v94
	s_nop 0
	v_mul_f32_e32 v88, v88, v95
	v_pk_mul_f32 v[94:95], v[90:91], v[88:89]
	v_mov_b64_e32 v[88:89], s[84:85]
	v_mad_i64_i32 v[88:89], s[42:43], v123, s89, v[88:89]
	v_lshl_add_u64 v[100:101], v[120:121], 1, v[88:89]
	v_cvt_pk_bf16_f32 v88, v96, v97
	v_cvt_pk_bf16_f32 v89, v98, v99
	v_cvt_pk_bf16_f32 v90, v92, v93
	v_cvt_pk_bf16_f32 v91, v94, v95
	global_store_dwordx4 v[100:101], v[88:91], off offset:128 sc1
.LBB0_1219:
	s_or_b64 exec, exec, s[0:1]
	v_add_u32_e32 v100, 64, v122
	s_waitcnt lgkmcnt(0)
	v_mul_lo_u32 v88, v100, s35
	v_add_u32_e32 v126, 16, v88
	v_lshl_add_u32 v88, v212, 2, v126
	ds_read_b128 v[104:107], v88
	ds_read_b128 v[92:95], v88 offset:16
	ds_read_b128 v[96:99], v88 offset:256
	ds_read_b128 v[88:91], v88 offset:272
	v_cmp_lt_i32_e32 vcc, 61, v122
	s_and_saveexec_b64 s[0:1], vcc
	s_cbranch_execz .LBB0_1221
	v_subrev_u32_e32 v102, 62, v122
	v_mov_b32_e32 v103, v213
	v_lshl_add_u64 v[102:103], s[30:31], 0, v[102:103]
	v_mov_b64_e32 v[108:109], s[72:73]
	v_mad_u64_u32 v[108:109], s[42:43], v102, s3, v[108:109]
	v_mad_i32_i24 v109, v103, s3, v109
	v_lshl_add_u64 v[102:103], v[120:121], 2, v[108:109]
	s_waitcnt lgkmcnt(3)
	global_store_dwordx4 v[102:103], v[104:107], off offset:256 sc1
	s_waitcnt lgkmcnt(2)
	global_store_dwordx4 v[102:103], v[92:95], off offset:272 sc1
.LBB0_1221:
	s_or_b64 exec, exec, s[0:1]
	v_cmp_gt_i32_e32 vcc, s90, v122
	s_and_saveexec_b64 s[0:1], vcc
	s_cbranch_execz .LBB0_1223
	v_ashrrev_i32_e32 v101, 31, v100
	v_lshl_add_u64 v[102:103], s[30:31], 0, v[100:101]
	v_mov_b64_e32 v[108:109], s[80:81]
	v_mad_u64_u32 v[108:109], s[30:31], v102, s3, v[108:109]
	v_mad_i32_i24 v109, v103, s3, v109
	v_lshl_add_u64 v[108:109], v[108:109], 0, v[124:125]
	s_waitcnt lgkmcnt(3)
	global_store_dwordx4 v[108:109], v[104:107], off offset:256 sc1
	s_waitcnt lgkmcnt(2)
	global_store_dwordx4 v[108:109], v[92:95], off offset:272 sc1
	v_mov_b64_e32 v[108:109], s[82:83]
	v_mad_u64_u32 v[108:109], s[30:31], v102, s3, v[108:109]
	v_mad_i32_i24 v109, v103, s3, v109
	v_lshl_add_u64 v[102:103], v[108:109], 0, v[124:125]
	s_waitcnt lgkmcnt(1)
	global_store_dwordx4 v[102:103], v[96:99], off offset:256 sc1
	s_waitcnt lgkmcnt(0)
	global_store_dwordx4 v[102:103], v[88:91], off offset:272 sc1
.LBB0_1223:
	s_or_b64 exec, exec, s[0:1]
	v_add_u32_e32 v124, s54, v100
	v_add_u32_e32 v100, 0xffff8000, v124
	v_lshrrev_b32_e32 v100, 6, v100
	v_add_u32_e32 v100, 4, v100
	v_ashrrev_i32_e32 v101, 13, v124
	v_cmp_gt_i32_e64 s[0:1], s53, v124
	v_mov_b32_e32 v102, 0x1fff
	s_nop 0
	v_cndmask_b32_e64 v102, 63, v102, s[0:1]
	v_cndmask_b32_e64 v100, v100, v101, s[0:1]
	v_mov_b32_e32 v101, 0x1ffe
	v_and_b32_e32 v125, v102, v124
	v_cndmask_b32_e64 v101, 62, v101, s[0:1]
	v_cmp_ge_u32_e64 s[0:1], v125, v101
	s_and_saveexec_b64 s[30:31], s[0:1]
	s_cbranch_execz .LBB0_1225
	v_ashrrev_i32_e32 v102, 31, v100
	v_add_u32_e32 v108, -4, v100
	v_cmp_gt_i32_e64 s[0:1], 4, v100
	v_mov_b32_e32 v109, 0xce50000
	v_sub_u32_e32 v112, v125, v101
	v_cndmask_b32_e64 v103, 0, v102, s[0:1]
	v_cndmask_b32_e64 v102, v108, v100, s[0:1]
	v_mov_b32_e32 v108, 0xd868000
	v_cndmask_b32_e64 v108, v108, v109, s[0:1]
	v_cndmask_b32_e64 v110, 4, 3, s[0:1]
	v_readlane_b32 s0, v255, 13
	v_readlane_b32 s1, v255, 14
	v_mov_b32_e32 v113, v213
	v_mov_b32_e32 v109, v213
	v_lshlrev_b64 v[110:111], v110, s[0:1]
	v_lshl_add_u64 v[110:111], v[110:111], 0, v[112:113]
	v_lshl_add_u64 v[108:109], s[60:61], 0, v[108:109]
	v_lshl_add_u64 v[102:103], v[102:103], 1, v[110:111]
	v_mad_u64_u32 v[108:109], s[0:1], v102, s3, v[108:109]
	v_mad_i32_i24 v109, v103, s3, v109
	v_lshl_add_u64 v[102:103], v[120:121], 2, v[108:109]
	s_waitcnt lgkmcnt(3)
	global_store_dwordx4 v[102:103], v[104:107], off offset:256 sc1
	s_waitcnt lgkmcnt(2)
	global_store_dwordx4 v[102:103], v[92:95], off offset:272 sc1

; DI void stb8(bf16_t* p, const F8& f) { *(uint4*)p = pack8(f); }
; template <int MODE>
; DI void gemm_epilogue(const float* Cs, int m0, int n0, const Epi& ep) {
;     ...
;         const int mt = m0 >> 7, ch0 = (n0 >> 7) * 64, c8 = (tid & 7) * 8, ch = ch0 + c8;
;         const float* cw = ep.c0;
;         const F8 w0 = ldf8(cw + ch), w1 = ldf8(cw + 2816 + ch), w2 = ldf8(cw + 2 * 2816 + ch);
;         const bool defer01 = (m0 < MP) && ((m0 & 8191) != 0);
; #pragma unroll
;         for (int it = 0; it < 2; ++it) {
;             const int i = (tid >> 3) + 64 * it, r = m0 + i;
;             int sq, pos, len; rowinfo(r, sq, pos, len);
;             const F8 g0 = ldf8(Cs + i * LDC + c8), up = ldf8(Cs + i * LDC + 64 + c8);
;             if (i >= 126) stf8(ep.f0 + ((size_t)mt * 2 + (i - 126)) * 2816 + ch, g0);
;             if (i < 2) { stf8(ep.f1 + ((size_t)mt * 2 + i) * 2816 + ch, g0); stf8(ep.f2 + ((size_t)mt * 2 + i) * 2816 + ch, up); }
;             if (pos >= len - 2) {
;                 float* so = sq < 4 ? ep.out + O_PFF + (((size_t)ep.layer * 4 + sq) * 2 + (pos - (len - 2))) * 2816
;                                    : ep.out + O_SFF + (((size_t)ep.layer * 8 + (sq - 4)) * 2 + (pos - (len - 2))) * 2816;
;                 stf8(so + ch, g0);
;             }
;             if (i < 2 && defer01) continue;
;             F8 g1, g2;
;             const float* hist = sq >= 4 ? ep.c1 + ((size_t)ep.layer * 8 + (sq - 4)) * 2 * 2816 + ch : nullptr;
;             if (pos >= 1) g1 = ldf8(Cs + (i - 1) * LDC + c8);
;             else if (hist) g1 = ldf8(hist + 2816);
;             else { for (int e = 0; e < 8; ++e) g1.v[e] = 0.f; }
;             if (pos >= 2) g2 = ldf8(Cs + (i - 2) * LDC + c8);
;             else if (hist) g2 = ldf8(hist + (size_t)pos * 2816);
;             else { for (int e = 0; e < 8; ++e) g2.v[e] = 0.f; }
;             F8 o;
; #pragma unroll
;             for (int e = 0; e < 8; ++e) o.v[e] = siluf(w0.v[e] * g2.v[e] + w1.v[e] * g1.v[e] + w2.v[e] * g0.v[e]) * up.v[e];
;             stb8(ep.b0 + (size_t)r * 2816 + ch, o);
; template <int MODE>
; DI void gemm_phase(const bf16_t* __restrict__ A, const bf16_t* __restrict__ Bt, int M, int N, int K, const Epi& ep) {
;     ...
;                         *(f32x4*)(Cs + (wr * 64 + m * 16 + fr) * LDC + wc * 32 + n * 16 + fq * 4) = acc[ai][bj][m][n];
;                 __syncthreads();
.LBB0_1240:
	s_or_b64 exec, exec, s[30:31]
	s_waitcnt vmcnt(0) lgkmcnt(1)
	v_pk_mul_f32 v[76:77], v[76:77], v[116:117]
	v_pk_mul_f32 v[78:79], v[78:79], v[118:119]
	v_pk_fma_f32 v[76:77], v[80:81], v[112:113], v[76:77]
	v_pk_fma_f32 v[78:79], v[82:83], v[114:115], v[78:79]
	v_pk_fma_f32 v[76:77], v[84:85], v[104:105], v[76:77]
	v_pk_fma_f32 v[78:79], v[86:87], v[106:107], v[78:79]
	v_mul_f32_e32 v80, 0xbfb8aa3b, v76
	v_mul_f32_e32 v81, 0xbfb8aa3b, v77
	v_exp_f32_e32 v80, v80
	v_exp_f32_e32 v81, v81
	s_waitcnt lgkmcnt(0)
	v_pk_mul_f32 v[64:65], v[64:65], v[108:109]
	v_pk_add_f32 v[80:81], v[80:81], 1.0 op_sel_hi:[1,0]
	s_nop 0
	v_pk_fma_f32 v[64:65], v[68:69], v[100:101], v[64:65]
	v_rcp_f32_e32 v84, v81
	s_nop 0
	v_mul_f32_e32 v77, v77, v84
	v_pk_fma_f32 v[64:65], v[72:73], v[92:93], v[64:65]
	v_rcp_f32_e32 v81, v80
	s_nop 0
	v_mul_f32_e32 v76, v76, v81
	v_mul_f32_e32 v80, 0xbfb8aa3b, v78
	v_mul_f32_e32 v81, 0xbfb8aa3b, v79
	v_exp_f32_e32 v80, v80
	v_exp_f32_e32 v81, v81
	v_mul_f32_e32 v68, 0xbfb8aa3b, v64
	v_mul_f32_e32 v69, 0xbfb8aa3b, v65
	v_exp_f32_e32 v68, v68
	v_pk_add_f32 v[80:81], v[80:81], 1.0 op_sel_hi:[1,0]
	v_exp_f32_e32 v69, v69
	s_nop 0
	v_pk_add_f32 v[68:69], v[68:69], 1.0 op_sel_hi:[1,0]
	v_pk_mul_f32 v[76:77], v[96:97], v[76:77]
	v_rcp_f32_e32 v82, v81
	s_nop 0
	v_mul_f32_e32 v79, v79, v82
	v_rcp_f32_e32 v81, v80
	s_nop 0
	v_mul_f32_e32 v78, v78, v81
	v_rcp_f32_e32 v72, v69
	s_nop 0
	v_mul_f32_e32 v65, v65, v72
	v_pk_mul_f32 v[78:79], v[98:99], v[78:79]
	v_rcp_f32_e32 v69, v68
	s_nop 0
	v_mul_f32_e32 v64, v64, v69
	v_pk_mul_f32 v[68:69], v[88:89], v[64:65]
	v_pk_mul_f32 v[64:65], v[66:67], v[110:111]
	s_nop 0
	v_pk_fma_f32 v[64:65], v[70:71], v[102:103], v[64:65]
	s_nop 0
	v_pk_fma_f32 v[64:65], v[74:75], v[94:95], v[64:65]
	s_nop 0
	v_mul_f32_e32 v66, 0xbfb8aa3b, v64
	v_mul_f32_e32 v67, 0xbfb8aa3b, v65
	v_exp_f32_e32 v66, v66
	v_exp_f32_e32 v67, v67
	s_nop 0
	v_pk_add_f32 v[66:67], v[66:67], 1.0 op_sel_hi:[1,0]
	s_nop 0
	v_rcp_f32_e32 v70, v67
	s_nop 0
	v_mul_f32_e32 v65, v65, v70
	v_rcp_f32_e32 v67, v66
	s_nop 0
	v_mul_f32_e32 v64, v64, v67
	v_pk_mul_f32 v[70:71], v[90:91], v[64:65]
	v_mov_b64_e32 v[64:65], s[84:85]
	v_mad_i64_i32 v[64:65], s[30:31], v124, s89, v[64:65]
	v_lshl_add_u64 v[72:73], v[120:121], 1, v[64:65]
	v_cvt_pk_bf16_f32 v64, v76, v77
	v_cvt_pk_bf16_f32 v65, v78, v79
	v_cvt_pk_bf16_f32 v66, v68, v69
	v_cvt_pk_bf16_f32 v67, v70, v71
	global_store_dwordx4 v[72:73], v[64:67], off offset:128 sc1
.LBB0_1241:
	s_or_b64 exec, exec, s[0:1]
	s_waitcnt lgkmcnt(0)
	s_barrier
	ds_write_b128 v194, v[32:35]
	ds_write_b128 v194, v[36:39] offset:64
	ds_write_b128 v194, v[40:43] offset:8448
	ds_write_b128 v194, v[44:47] offset:8512
	ds_write_b128 v194, v[48:51] offset:16896
	ds_write_b128 v194, v[52:55] offset:16960
	ds_write_b128 v194, v[56:59] offset:25344
	ds_write_b128 v194, v[60:63] offset:25408
	v_mov_b32_e32 v56, v250
	s_waitcnt lgkmcnt(0)
	s_barrier
	s_bitset1_b32 s54, 7
	v_lshlrev_b32_e32 v32, 3, v56
	v_and_b32_e32 v94, 56, v32
	v_or_b32_e32 v88, s26, v94
	v_ashrrev_i32_e32 v89, 31, v88
	v_lshlrev_b64 v[90:91], 2, v[88:89]
	v_lshl_add_u64 v[36:37], s[6:7], 0, v[90:91]
	v_lshl_add_u64 v[40:41], s[14:15], 0, v[90:91]
	v_lshl_add_u64 v[52:53], s[18:19], 0, v[90:91]
	global_load_dwordx4 v[32:35], v[36:37], off offset:16
	global_load_dwordx4 v[44:47], v[36:37], off
	s_nop 0
	global_load_dwordx4 v[36:39], v[40:41], off offset:16
	global_load_dwordx4 v[48:51], v[40:41], off
	s_nop 0
	global_load_dwordx4 v[40:43], v[52:53], off offset:16
	s_nop 0
	global_load_dwordx4 v[52:55], v[52:53], off
	v_ashrrev_i32_e32 v95, 3, v56
	v_mul_lo_u32 v56, v95, s35
	v_add_u32_e32 v97, 16, v56
	v_lshl_add_u32 v56, v94, 2, v97
	s_waitcnt vmcnt(7)
	ds_read_b128 v[72:75], v56
	ds_read_b128 v[60:63], v56 offset:16
	ds_read_b128 v[64:67], v56 offset:256
	ds_read_b128 v[56:59], v56 offset:272
	s_ashr_i32 s0, s54, 7
	s_ashr_i32 s1, s0, 31
	s_lshl_b64 s[30:31], s[0:1], 1
	v_cmp_lt_i32_e32 vcc, s71, v95
	s_and_saveexec_b64 s[0:1], vcc
	s_cbranch_execz .LBB0_1243
	v_add_u32_e32 v212, 0xffffff82, v95
	v_lshl_add_u64 v[68:69], s[30:31], 0, v[212:213]
	v_mov_b64_e32 v[70:71], s[72:73]
	v_mad_u64_u32 v[70:71], s[40:41], v68, s3, v[70:71]
	v_mad_i32_i24 v71, v69, s3, v71
	v_lshl_add_u64 v[68:69], v[88:89], 2, v[70:71]
	s_waitcnt lgkmcnt(3)
	global_store_dwordx4 v[68:69], v[72:75], off sc1
	s_waitcnt lgkmcnt(2)
	global_store_dwordx4 v[68:69], v[60:63], off offset:16 sc1
.LBB0_1243:
	s_or_b64 exec, exec, s[0:1]
	v_cmp_gt_i32_e32 vcc, 2, v95
	s_and_saveexec_b64 s[0:1], vcc
	s_cbranch_execz .LBB0_1245
	v_add_u32_e32 v70, s30, v95
	v_mov_b64_e32 v[68:69], s[80:81]
	v_mad_i64_i32 v[68:69], s[40:41], v70, s3, v[68:69]
	v_lshl_add_u64 v[68:69], v[68:69], 0, v[90:91]
	s_waitcnt lgkmcnt(3)
	global_store_dwordx4 v[68:69], v[72:75], off sc1
	s_waitcnt lgkmcnt(2)
	global_store_dwordx4 v[68:69], v[60:63], off offset:16 sc1
	v_mov_b64_e32 v[68:69], s[82:83]
	v_mad_i64_i32 v[68:69], s[40:41], v70, s3, v[68:69]
	v_lshl_add_u64 v[68:69], v[68:69], 0, v[90:91]
	s_waitcnt lgkmcnt(1)
	global_store_dwordx4 v[68:69], v[64:67], off sc1
	s_waitcnt lgkmcnt(0)
	global_store_dwordx4 v[68:69], v[56:59], off offset:16 sc1
.LBB0_1245:
	s_or_b64 exec, exec, s[0:1]
	v_add_u32_e32 v96, s54, v95
	v_add_u32_e32 v68, 0xffff8000, v96
	v_lshrrev_b32_e32 v68, 6, v68
	v_add_u32_e32 v68, 4, v68
	v_ashrrev_i32_e32 v69, 13, v96
	v_cmp_gt_i32_e64 s[0:1], s53, v96
	v_mov_b32_e32 v70, 0x1fff
	s_nop 0
	v_cndmask_b32_e64 v70, 63, v70, s[0:1]
	v_cndmask_b32_e64 v68, v68, v69, s[0:1]
	v_mov_b32_e32 v69, 0x1ffe
	v_and_b32_e32 v98, v70, v96
	v_cndmask_b32_e64 v69, 62, v69, s[0:1]
	v_cmp_ge_u32_e64 s[0:1], v98, v69
	s_and_saveexec_b64 s[40:41], s[0:1]
	s_cbranch_execz .LBB0_1247
	v_add_u32_e32 v70, -4, v68
	v_ashrrev_i32_e32 v71, 31, v68
	v_cmp_gt_i32_e64 s[0:1], 4, v68
	v_mov_b32_e32 v76, 0xd868000
	v_mov_b32_e32 v77, 0xce50000
	v_cndmask_b32_e64 v71, 0, v71, s[0:1]
	v_cndmask_b32_e64 v70, v70, v68, s[0:1]
	v_cndmask_b32_e64 v212, v76, v77, s[0:1]
	v_cndmask_b32_e64 v78, 4, 3, s[0:1]
	v_readlane_b32 s0, v255, 13
	v_readlane_b32 s1, v255, 14
	v_lshl_add_u64 v[76:77], s[60:61], 0, v[212:213]
	v_sub_u32_e32 v212, v98, v69
	v_lshlrev_b64 v[78:79], v78, s[0:1]
	v_lshl_add_u64 v[78:79], v[78:79], 0, v[212:213]
	v_lshl_add_u64 v[70:71], v[70:71], 1, v[78:79]
	v_mad_u64_u32 v[76:77], s[0:1], v70, s3, v[76:77]
	v_mad_i32_i24 v77, v71, s3, v77
	v_lshl_add_u64 v[70:71], v[88:89], 2, v[76:77]
	s_waitcnt lgkmcnt(3)
	global_store_dwordx4 v[70:71], v[72:75], off sc1
	s_waitcnt lgkmcnt(2)
	global_store_dwordx4 v[70:71], v[60:63], off offset:16 sc1

; DI void stf8(float* p, const F8& f) { *(float4*)p = make_float4(f.v[0], f.v[1], f.v[2], f.v[3]); *(float4*)(p + 4) = make_float4(f.v[4], f.v[5], f.v[6], f.v[7]); }
; DI void stb8(bf16_t* p, const F8& f) { *(uint4*)p = pack8(f); }
; DI float siluf(float x) { return x / (1.f + __expf(-x)); }
; DI void rowinfo(int r, int& sq, int& pos, int& len) { if (r < MP) { sq = r >> 13; pos = r & 8191; len = 8192; } else { sq = 4 + ((r - MP) >> 6); pos = r & 63; len = 64; } }
; template <int MODE>
; DI void gemm_epilogue(const float* Cs, int m0, int n0, const Epi& ep) {
;     ...
;         for (int it = 0; it < 2; ++it) {
;             const int i = (tid >> 3) + 64 * it, r = m0 + i;
;             int sq, pos, len; rowinfo(r, sq, pos, len);
;             const F8 g0 = ldf8(Cs + i * LDC + c8), up = ldf8(Cs + i * LDC + 64 + c8);
;             if (i >= 126) stf8(ep.f0 + ((size_t)mt * 2 + (i - 126)) * 2816 + ch, g0);
;             if (i < 2) { stf8(ep.f1 + ((size_t)mt * 2 + i) * 2816 + ch, g0); stf8(ep.f2 + ((size_t)mt * 2 + i) * 2816 + ch, up); }
;             if (pos >= len - 2) {
;                 float* so = sq < 4 ? ep.out + O_PFF + (((size_t)ep.layer * 4 + sq) * 2 + (pos - (len - 2))) * 2816
;                                    : ep.out + O_SFF + (((size_t)ep.layer * 8 + (sq - 4)) * 2 + (pos - (len - 2))) * 2816;
;                 stf8(so + ch, g0);
;             }
;             if (i < 2 && defer01) continue;
;             F8 g1, g2;
;             const float* hist = sq >= 4 ? ep.c1 + ((size_t)ep.layer * 8 + (sq - 4)) * 2 * 2816 + ch : nullptr;
;             if (pos >= 1) g1 = ldf8(Cs + (i - 1) * LDC + c8);
;             else if (hist) g1 = ldf8(hist + 2816);
;             else { for (int e = 0; e < 8; ++e) g1.v[e] = 0.f; }
;             if (pos >= 2) g2 = ldf8(Cs + (i - 2) * LDC + c8);
;             else if (hist) g2 = ldf8(hist + (size_t)pos * 2816);
;             else { for (int e = 0; e < 8; ++e) g2.v[e] = 0.f; }
;             F8 o;
; #pragma unroll
;             for (int e = 0; e < 8; ++e) o.v[e] = siluf(w0.v[e] * g2.v[e] + w1.v[e] * g1.v[e] + w2.v[e] * g0.v[e]) * up.v[e];
;             stb8(ep.b0 + (size_t)r * 2816 + ch, o);
.LBB0_1262:
	s_or_b64 exec, exec, s[42:43]
	s_waitcnt vmcnt(0) lgkmcnt(1)
	v_pk_mul_f32 v[84:85], v[44:45], v[84:85]
	s_nop 0
	v_pk_fma_f32 v[80:81], v[48:49], v[80:81], v[84:85]
	s_nop 0
	v_pk_fma_f32 v[72:73], v[52:53], v[72:73], v[80:81]
	s_nop 0
	v_mul_f32_e32 v80, 0xbfb8aa3b, v72
	v_mul_f32_e32 v81, 0xbfb8aa3b, v73
	v_exp_f32_e32 v80, v80
	v_exp_f32_e32 v81, v81
	s_nop 0
	v_pk_add_f32 v[80:81], v[80:81], 1.0 op_sel_hi:[1,0]
	s_nop 0
	v_rcp_f32_e32 v84, v81
	s_nop 0
	v_mul_f32_e32 v73, v73, v84
	v_rcp_f32_e32 v81, v80
	s_nop 0
	v_mul_f32_e32 v72, v72, v81
	v_pk_mul_f32 v[64:65], v[64:65], v[72:73]
	v_pk_mul_f32 v[72:73], v[46:47], v[86:87]
	s_nop 0
	v_pk_fma_f32 v[72:73], v[50:51], v[82:83], v[72:73]
	s_nop 0
	v_pk_fma_f32 v[72:73], v[54:55], v[74:75], v[72:73]
	s_nop 0
	v_mul_f32_e32 v74, 0xbfb8aa3b, v72
	v_mul_f32_e32 v75, 0xbfb8aa3b, v73
	v_exp_f32_e32 v74, v74
	v_exp_f32_e32 v75, v75
	s_nop 0
	v_pk_add_f32 v[74:75], v[74:75], 1.0 op_sel_hi:[1,0]
	s_nop 0
	v_rcp_f32_e32 v80, v75
	s_nop 0
	v_mul_f32_e32 v73, v73, v80
	v_rcp_f32_e32 v75, v74
	s_nop 0
	v_mul_f32_e32 v72, v72, v75
	v_pk_mul_f32 v[66:67], v[66:67], v[72:73]
	s_waitcnt lgkmcnt(0)
	v_pk_mul_f32 v[72:73], v[32:33], v[76:77]
	s_nop 0
	v_pk_fma_f32 v[68:69], v[36:37], v[68:69], v[72:73]
	s_nop 0
	v_pk_fma_f32 v[60:61], v[40:41], v[60:61], v[68:69]
	s_nop 0
	v_mul_f32_e32 v68, 0xbfb8aa3b, v60
	v_mul_f32_e32 v69, 0xbfb8aa3b, v61
	v_exp_f32_e32 v68, v68
	v_exp_f32_e32 v69, v69
	s_nop 0
	v_pk_add_f32 v[68:69], v[68:69], 1.0 op_sel_hi:[1,0]
	s_nop 0
	v_rcp_f32_e32 v72, v69
	s_nop 0
	v_mul_f32_e32 v61, v61, v72
	v_rcp_f32_e32 v69, v68
	s_nop 0
	v_mul_f32_e32 v60, v60, v69
	v_pk_mul_f32 v[60:61], v[56:57], v[60:61]
	v_pk_mul_f32 v[56:57], v[34:35], v[78:79]
	s_nop 0
	v_pk_fma_f32 v[56:57], v[38:39], v[70:71], v[56:57]
	s_nop 0
	v_pk_fma_f32 v[56:57], v[42:43], v[62:63], v[56:57]
	s_nop 0
	v_mul_f32_e32 v62, 0xbfb8aa3b, v56
	v_mul_f32_e32 v63, 0xbfb8aa3b, v57
	v_exp_f32_e32 v62, v62
	v_exp_f32_e32 v63, v63
	s_nop 0
	v_pk_add_f32 v[62:63], v[62:63], 1.0 op_sel_hi:[1,0]
	s_nop 0
	v_rcp_f32_e32 v68, v63
	s_nop 0
	v_mul_f32_e32 v57, v57, v68
	v_rcp_f32_e32 v63, v62
	s_nop 0
	v_mul_f32_e32 v56, v56, v63
	v_pk_mul_f32 v[62:63], v[58:59], v[56:57]
	v_mov_b64_e32 v[56:57], s[84:85]
	v_mad_i64_i32 v[56:57], s[42:43], v96, s89, v[56:57]
	v_lshl_add_u64 v[68:69], v[88:89], 1, v[56:57]
	v_cvt_pk_bf16_f32 v56, v64, v65
	v_cvt_pk_bf16_f32 v57, v66, v67
	v_cvt_pk_bf16_f32 v58, v60, v61
	v_cvt_pk_bf16_f32 v59, v62, v63
	global_store_dwordx4 v[68:69], v[56:59], off sc1
.LBB0_1263:
	s_or_b64 exec, exec, s[0:1]
	v_add_u32_e32 v68, 64, v95
	s_waitcnt lgkmcnt(0)
	v_mul_lo_u32 v56, v68, s35
	v_add_u32_e32 v93, 16, v56
	v_lshl_add_u32 v56, v94, 2, v93
	ds_read_b128 v[72:75], v56
	ds_read_b128 v[60:63], v56 offset:16
	ds_read_b128 v[64:67], v56 offset:256
	ds_read_b128 v[56:59], v56 offset:272
	v_cmp_lt_i32_e32 vcc, 61, v95
	s_and_saveexec_b64 s[0:1], vcc
	s_cbranch_execz .LBB0_1265
	v_subrev_u32_e32 v212, 62, v95
	v_lshl_add_u64 v[70:71], s[30:31], 0, v[212:213]
	v_mov_b64_e32 v[76:77], s[72:73]
	v_mad_u64_u32 v[76:77], s[42:43], v70, s3, v[76:77]
	v_mad_i32_i24 v77, v71, s3, v77
	v_lshl_add_u64 v[70:71], v[88:89], 2, v[76:77]
	s_waitcnt lgkmcnt(3)
	global_store_dwordx4 v[70:71], v[72:75], off sc1
	s_waitcnt lgkmcnt(2)
	global_store_dwordx4 v[70:71], v[60:63], off offset:16 sc1
.LBB0_1265:
	s_or_b64 exec, exec, s[0:1]
	v_cmp_gt_i32_e32 vcc, s90, v95
	s_and_saveexec_b64 s[0:1], vcc
	s_cbranch_execz .LBB0_1267
	v_add_u32_e32 v69, s30, v68
	v_mov_b64_e32 v[70:71], s[80:81]
	v_mad_i64_i32 v[70:71], s[42:43], v69, s3, v[70:71]
	v_lshl_add_u64 v[70:71], v[70:71], 0, v[90:91]
	s_waitcnt lgkmcnt(3)
	global_store_dwordx4 v[70:71], v[72:75], off sc1
	s_waitcnt lgkmcnt(2)
	global_store_dwordx4 v[70:71], v[60:63], off offset:16 sc1
	v_mov_b64_e32 v[70:71], s[82:83]
	v_mad_i64_i32 v[70:71], s[42:43], v69, s3, v[70:71]
	v_lshl_add_u64 v[70:71], v[70:71], 0, v[90:91]
	s_waitcnt lgkmcnt(1)
	global_store_dwordx4 v[70:71], v[64:67], off sc1
	s_waitcnt lgkmcnt(0)
	global_store_dwordx4 v[70:71], v[56:59], off offset:16 sc1
.LBB0_1267:
	s_or_b64 exec, exec, s[0:1]
	v_add_u32_e32 v92, s54, v68
	v_add_u32_e32 v68, 0xffff8000, v92
	v_lshrrev_b32_e32 v68, 6, v68
	v_add_u32_e32 v68, 4, v68
	v_ashrrev_i32_e32 v69, 13, v92
	v_cmp_gt_i32_e64 s[0:1], s53, v92
	v_mov_b32_e32 v70, 0x1fff
	s_nop 0
	v_cndmask_b32_e64 v70, 63, v70, s[0:1]
	v_cndmask_b32_e64 v68, v68, v69, s[0:1]
	v_mov_b32_e32 v69, 0x1ffe
	v_and_b32_e32 v95, v70, v92
	v_cndmask_b32_e64 v69, 62, v69, s[0:1]
	v_cmp_ge_u32_e64 s[0:1], v95, v69
	s_and_saveexec_b64 s[42:43], s[0:1]
	s_cbranch_execz .LBB0_1269
	v_ashrrev_i32_e32 v70, 31, v68
	v_add_u32_e32 v76, -4, v68
	v_cmp_gt_i32_e64 s[0:1], 4, v68
	v_mov_b32_e32 v77, 0xce50000
	s_nop 0
	v_cndmask_b32_e64 v71, 0, v70, s[0:1]
	v_cndmask_b32_e64 v70, v76, v68, s[0:1]
	v_mov_b32_e32 v76, 0xd868000
	v_cndmask_b32_e64 v212, v76, v77, s[0:1]
	v_cndmask_b32_e64 v78, 4, 3, s[0:1]
	v_readlane_b32 s0, v255, 13
	v_readlane_b32 s1, v255, 14
	v_lshl_add_u64 v[76:77], s[60:61], 0, v[212:213]
	v_sub_u32_e32 v212, v95, v69
	v_lshlrev_b64 v[78:79], v78, s[0:1]
	v_lshl_add_u64 v[78:79], v[78:79], 0, v[212:213]
	v_lshl_add_u64 v[70:71], v[70:71], 1, v[78:79]
	v_mad_u64_u32 v[76:77], s[0:1], v70, s3, v[76:77]
	v_mad_i32_i24 v77, v71, s3, v77
	v_lshl_add_u64 v[70:71], v[88:89], 2, v[76:77]
	s_waitcnt lgkmcnt(3)
	global_store_dwordx4 v[70:71], v[72:75], off sc1
	s_waitcnt lgkmcnt(2)
	global_store_dwordx4 v[70:71], v[60:63], off offset:16 sc1

; DI void stb8(bf16_t* p, const F8& f) { *(uint4*)p = pack8(f); }
; template <int MODE>
; DI void gemm_epilogue(const float* Cs, int m0, int n0, const Epi& ep) {
;     ...
;         const int mt = m0 >> 7, ch0 = (n0 >> 7) * 64, c8 = (tid & 7) * 8, ch = ch0 + c8;
;         const float* cw = ep.c0;
;         const F8 w0 = ldf8(cw + ch), w1 = ldf8(cw + 2816 + ch), w2 = ldf8(cw + 2 * 2816 + ch);
;         const bool defer01 = (m0 < MP) && ((m0 & 8191) != 0);
; #pragma unroll
;         for (int it = 0; it < 2; ++it) {
;             const int i = (tid >> 3) + 64 * it, r = m0 + i;
;             int sq, pos, len; rowinfo(r, sq, pos, len);
;             const F8 g0 = ldf8(Cs + i * LDC + c8), up = ldf8(Cs + i * LDC + 64 + c8);
;             if (i >= 126) stf8(ep.f0 + ((size_t)mt * 2 + (i - 126)) * 2816 + ch, g0);
;             if (i < 2) { stf8(ep.f1 + ((size_t)mt * 2 + i) * 2816 + ch, g0); stf8(ep.f2 + ((size_t)mt * 2 + i) * 2816 + ch, up); }
;             if (pos >= len - 2) {
;                 float* so = sq < 4 ? ep.out + O_PFF + (((size_t)ep.layer * 4 + sq) * 2 + (pos - (len - 2))) * 2816
;                                    : ep.out + O_SFF + (((size_t)ep.layer * 8 + (sq - 4)) * 2 + (pos - (len - 2))) * 2816;
;                 stf8(so + ch, g0);
;             }
;             if (i < 2 && defer01) continue;
;             F8 g1, g2;
;             const float* hist = sq >= 4 ? ep.c1 + ((size_t)ep.layer * 8 + (sq - 4)) * 2 * 2816 + ch : nullptr;
;             if (pos >= 1) g1 = ldf8(Cs + (i - 1) * LDC + c8);
;             else if (hist) g1 = ldf8(hist + 2816);
;             else { for (int e = 0; e < 8; ++e) g1.v[e] = 0.f; }
;             if (pos >= 2) g2 = ldf8(Cs + (i - 2) * LDC + c8);
;             else if (hist) g2 = ldf8(hist + (size_t)pos * 2816);
;             else { for (int e = 0; e < 8; ++e) g2.v[e] = 0.f; }
;             F8 o;
; #pragma unroll
;             for (int e = 0; e < 8; ++e) o.v[e] = siluf(w0.v[e] * g2.v[e] + w1.v[e] * g1.v[e] + w2.v[e] * g0.v[e]) * up.v[e];
;             stb8(ep.b0 + (size_t)r * 2816 + ch, o);
; template <int MODE>
; DI void gemm_phase(const bf16_t* __restrict__ A, const bf16_t* __restrict__ Bt, int M, int N, int K, const Epi& ep) {
;     ...
;                         *(f32x4*)(Cs + (wr * 64 + m * 16 + fr) * LDC + wc * 32 + n * 16 + fq * 4) = acc[ai][bj][m][n];
;                 __syncthreads();
.LBB0_1284:
	s_or_b64 exec, exec, s[42:43]
	s_waitcnt vmcnt(0) lgkmcnt(1)
	v_pk_mul_f32 v[44:45], v[44:45], v[84:85]
	v_pk_mul_f32 v[46:47], v[46:47], v[86:87]
	v_pk_fma_f32 v[44:45], v[48:49], v[80:81], v[44:45]
	v_pk_fma_f32 v[46:47], v[50:51], v[82:83], v[46:47]
	v_pk_fma_f32 v[44:45], v[52:53], v[72:73], v[44:45]
	v_pk_fma_f32 v[46:47], v[54:55], v[74:75], v[46:47]
	v_mul_f32_e32 v48, 0xbfb8aa3b, v44
	v_mul_f32_e32 v49, 0xbfb8aa3b, v45
	v_exp_f32_e32 v48, v48
	v_exp_f32_e32 v49, v49
	s_waitcnt lgkmcnt(0)
	v_pk_mul_f32 v[32:33], v[32:33], v[76:77]
	v_pk_add_f32 v[48:49], v[48:49], 1.0 op_sel_hi:[1,0]
	s_nop 0
	v_pk_fma_f32 v[32:33], v[36:37], v[68:69], v[32:33]
	v_rcp_f32_e32 v52, v49
	s_nop 0
	v_mul_f32_e32 v45, v45, v52
	v_pk_fma_f32 v[32:33], v[40:41], v[60:61], v[32:33]
	v_rcp_f32_e32 v49, v48
	s_nop 0
	v_mul_f32_e32 v44, v44, v49
	v_mul_f32_e32 v48, 0xbfb8aa3b, v46
	v_mul_f32_e32 v49, 0xbfb8aa3b, v47
	v_exp_f32_e32 v48, v48
	v_exp_f32_e32 v49, v49
	v_mul_f32_e32 v36, 0xbfb8aa3b, v32
	v_mul_f32_e32 v37, 0xbfb8aa3b, v33
	v_exp_f32_e32 v36, v36
	v_pk_add_f32 v[48:49], v[48:49], 1.0 op_sel_hi:[1,0]
	v_exp_f32_e32 v37, v37
	s_nop 0
	v_pk_add_f32 v[36:37], v[36:37], 1.0 op_sel_hi:[1,0]
	v_pk_mul_f32 v[44:45], v[64:65], v[44:45]
	v_rcp_f32_e32 v50, v49
	s_nop 0
	v_mul_f32_e32 v47, v47, v50
	v_rcp_f32_e32 v49, v48
	s_nop 0
	v_mul_f32_e32 v46, v46, v49
	v_rcp_f32_e32 v40, v37
	s_nop 0
	v_mul_f32_e32 v33, v33, v40
	v_pk_mul_f32 v[46:47], v[66:67], v[46:47]
	v_rcp_f32_e32 v37, v36
	s_nop 0
	v_mul_f32_e32 v32, v32, v37
	v_pk_mul_f32 v[36:37], v[56:57], v[32:33]
	v_pk_mul_f32 v[32:33], v[34:35], v[78:79]
	s_nop 0
	v_pk_fma_f32 v[32:33], v[38:39], v[70:71], v[32:33]
	s_nop 0
	v_pk_fma_f32 v[32:33], v[42:43], v[62:63], v[32:33]
	s_nop 0
	v_mul_f32_e32 v34, 0xbfb8aa3b, v32
	v_mul_f32_e32 v35, 0xbfb8aa3b, v33
	v_exp_f32_e32 v34, v34
	v_exp_f32_e32 v35, v35
	s_nop 0
	v_pk_add_f32 v[34:35], v[34:35], 1.0 op_sel_hi:[1,0]
	s_nop 0
	v_rcp_f32_e32 v38, v35
	s_nop 0
	v_mul_f32_e32 v33, v33, v38
	v_rcp_f32_e32 v35, v34
	s_nop 0
	v_mul_f32_e32 v32, v32, v35
	v_pk_mul_f32 v[38:39], v[58:59], v[32:33]
	v_mov_b64_e32 v[32:33], s[84:85]
	v_mad_i64_i32 v[32:33], s[42:43], v92, s89, v[32:33]
	v_lshl_add_u64 v[40:41], v[88:89], 1, v[32:33]
	v_cvt_pk_bf16_f32 v32, v44, v45
	v_cvt_pk_bf16_f32 v33, v46, v47
	v_cvt_pk_bf16_f32 v34, v36, v37
	v_cvt_pk_bf16_f32 v35, v38, v39
	global_store_dwordx4 v[40:41], v[32:35], off sc1
.LBB0_1285:
	s_or_b64 exec, exec, s[0:1]
	s_waitcnt lgkmcnt(0)
	s_barrier
	ds_write_b128 v194, v[0:3]
	ds_write_b128 v194, v[4:7] offset:64
	ds_write_b128 v194, v[8:11] offset:8448
	ds_write_b128 v194, v[12:15] offset:8512
	ds_write_b128 v194, v[16:19] offset:16896
	ds_write_b128 v194, v[20:23] offset:16960
	ds_write_b128 v194, v[24:27] offset:25344
	ds_write_b128 v194, v[28:31] offset:25408
	v_mov_b32_e32 v24, v250
	s_waitcnt lgkmcnt(0)
	s_barrier
	s_nop 0
	v_lshlrev_b32_e32 v0, 3, v24
	v_and_b32_e32 v212, 56, v0
	v_or_b32_e32 v0, s49, v212
	v_ashrrev_i32_e32 v1, 31, v0
	v_lshl_add_u64 v[56:57], v[212:213], 0, s[26:27]
	v_lshlrev_b64 v[0:1], 2, v[0:1]
	v_lshl_add_u64 v[4:5], v[56:57], 2, s[6:7]
	v_lshl_add_u64 v[8:9], s[14:15], 0, v[0:1]
	v_lshl_add_u64 v[20:21], s[18:19], 0, v[0:1]
	global_load_dwordx4 v[0:3], v[4:5], off offset:272
	global_load_dwordx4 v[12:15], v[4:5], off offset:256
	s_nop 0
	global_load_dwordx4 v[4:7], v[8:9], off offset:16
	global_load_dwordx4 v[16:19], v[8:9], off
	s_nop 0
	global_load_dwordx4 v[8:11], v[20:21], off offset:16
	s_nop 0
	global_load_dwordx4 v[20:23], v[20:21], off
	v_ashrrev_i32_e32 v62, 3, v24
	v_mul_lo_u32 v24, v62, s35
	v_add_u32_e32 v64, 16, v24
	v_lshl_add_u32 v24, v212, 2, v64
	s_waitcnt vmcnt(7)
	ds_read_b128 v[40:43], v24
	ds_read_b128 v[28:31], v24 offset:16
	ds_read_b128 v[32:35], v24 offset:256
	ds_read_b128 v[24:27], v24 offset:272
	v_cmp_lt_i32_e32 vcc, s71, v62
	s_and_saveexec_b64 s[0:1], vcc
	s_cbranch_execz .LBB0_1287
	v_add_u32_e32 v36, 0xffffff82, v62
	v_mov_b32_e32 v37, v213
	v_lshl_add_u64 v[36:37], s[30:31], 0, v[36:37]
	v_mov_b64_e32 v[38:39], s[72:73]
	v_mad_u64_u32 v[38:39], s[26:27], v36, s3, v[38:39]
	v_mad_i32_i24 v39, v37, s3, v39
	v_lshl_add_u64 v[36:37], v[56:57], 2, v[38:39]
	s_waitcnt lgkmcnt(3)
	global_store_dwordx4 v[36:37], v[40:43], off offset:256 sc1
	s_waitcnt lgkmcnt(2)
	global_store_dwordx4 v[36:37], v[28:31], off offset:272 sc1
.LBB0_1287:
	s_or_b64 exec, exec, s[0:1]
	v_cmp_gt_i32_e32 vcc, 2, v62
	v_lshlrev_b64 v[58:59], 2, v[56:57]
	s_and_saveexec_b64 s[0:1], vcc
	s_cbranch_execz .LBB0_1289
	v_add_u32_e32 v38, s30, v62
	v_mov_b64_e32 v[36:37], s[80:81]
	v_mad_i64_i32 v[36:37], s[26:27], v38, s3, v[36:37]
	v_lshl_add_u64 v[36:37], v[36:37], 0, v[58:59]
	s_waitcnt lgkmcnt(3)
	global_store_dwordx4 v[36:37], v[40:43], off offset:256 sc1
	s_waitcnt lgkmcnt(2)
	global_store_dwordx4 v[36:37], v[28:31], off offset:272 sc1
	v_mov_b64_e32 v[36:37], s[82:83]
	v_mad_i64_i32 v[36:37], s[26:27], v38, s3, v[36:37]
	v_lshl_add_u64 v[36:37], v[36:37], 0, v[58:59]
	s_waitcnt lgkmcnt(1)
	global_store_dwordx4 v[36:37], v[32:35], off offset:256 sc1
	s_waitcnt lgkmcnt(0)
	global_store_dwordx4 v[36:37], v[24:27], off offset:272 sc1
.LBB0_1289:
	s_or_b64 exec, exec, s[0:1]
	v_add_u32_e32 v63, s54, v62
	v_add_u32_e32 v36, 0xffff8000, v63
	v_lshrrev_b32_e32 v36, 6, v36
	v_add_u32_e32 v36, 4, v36
	v_ashrrev_i32_e32 v37, 13, v63
	v_cmp_gt_i32_e64 s[0:1], s53, v63
	v_mov_b32_e32 v38, 0x1fff
	s_nop 0
	v_cndmask_b32_e64 v38, 63, v38, s[0:1]
	v_cndmask_b32_e64 v36, v36, v37, s[0:1]
	v_mov_b32_e32 v37, 0x1ffe
	v_and_b32_e32 v65, v38, v63
	v_cndmask_b32_e64 v37, 62, v37, s[0:1]
	v_cmp_ge_u32_e64 s[0:1], v65, v37
	s_and_saveexec_b64 s[26:27], s[0:1]
	s_cbranch_execz .LBB0_1291
	v_add_u32_e32 v38, -4, v36
	v_ashrrev_i32_e32 v39, 31, v36
	v_cmp_gt_i32_e64 s[0:1], 4, v36
	v_mov_b32_e32 v44, 0xd868000
	v_mov_b32_e32 v45, 0xce50000
	v_cndmask_b32_e64 v39, 0, v39, s[0:1]
	v_cndmask_b32_e64 v38, v38, v36, s[0:1]
	v_cndmask_b32_e64 v44, v44, v45, s[0:1]
	v_cndmask_b32_e64 v46, 4, 3, s[0:1]
	v_readlane_b32 s0, v255, 13
	v_readlane_b32 s1, v255, 14
	v_sub_u32_e32 v48, v65, v37
	v_mov_b32_e32 v49, v213
	v_lshlrev_b64 v[46:47], v46, s[0:1]
	v_mov_b32_e32 v45, v213
	v_lshl_add_u64 v[46:47], v[46:47], 0, v[48:49]
	v_lshl_add_u64 v[44:45], s[60:61], 0, v[44:45]
	v_lshl_add_u64 v[38:39], v[38:39], 1, v[46:47]
	v_mad_u64_u32 v[44:45], s[0:1], v38, s3, v[44:45]
	v_mad_i32_i24 v45, v39, s3, v45
	v_lshl_add_u64 v[38:39], v[56:57], 2, v[44:45]
	s_waitcnt lgkmcnt(3)
	global_store_dwordx4 v[38:39], v[40:43], off offset:256 sc1
	s_waitcnt lgkmcnt(2)
	global_store_dwordx4 v[38:39], v[28:31], off offset:272 sc1

; DI void stf8(float* p, const F8& f) { *(float4*)p = make_float4(f.v[0], f.v[1], f.v[2], f.v[3]); *(float4*)(p + 4) = make_float4(f.v[4], f.v[5], f.v[6], f.v[7]); }
; DI void stb8(bf16_t* p, const F8& f) { *(uint4*)p = pack8(f); }
; DI float siluf(float x) { return x / (1.f + __expf(-x)); }
; DI void rowinfo(int r, int& sq, int& pos, int& len) { if (r < MP) { sq = r >> 13; pos = r & 8191; len = 8192; } else { sq = 4 + ((r - MP) >> 6); pos = r & 63; len = 64; } }
; template <int MODE>
; DI void gemm_epilogue(const float* Cs, int m0, int n0, const Epi& ep) {
;     ...
;         for (int it = 0; it < 2; ++it) {
;             const int i = (tid >> 3) + 64 * it, r = m0 + i;
;             int sq, pos, len; rowinfo(r, sq, pos, len);
;             const F8 g0 = ldf8(Cs + i * LDC + c8), up = ldf8(Cs + i * LDC + 64 + c8);
;             if (i >= 126) stf8(ep.f0 + ((size_t)mt * 2 + (i - 126)) * 2816 + ch, g0);
;             if (i < 2) { stf8(ep.f1 + ((size_t)mt * 2 + i) * 2816 + ch, g0); stf8(ep.f2 + ((size_t)mt * 2 + i) * 2816 + ch, up); }
;             if (pos >= len - 2) {
;                 float* so = sq < 4 ? ep.out + O_PFF + (((size_t)ep.layer * 4 + sq) * 2 + (pos - (len - 2))) * 2816
;                                    : ep.out + O_SFF + (((size_t)ep.layer * 8 + (sq - 4)) * 2 + (pos - (len - 2))) * 2816;
;                 stf8(so + ch, g0);
;             }
;             if (i < 2 && defer01) continue;
;             F8 g1, g2;
;             const float* hist = sq >= 4 ? ep.c1 + ((size_t)ep.layer * 8 + (sq - 4)) * 2 * 2816 + ch : nullptr;
;             if (pos >= 1) g1 = ldf8(Cs + (i - 1) * LDC + c8);
;             else if (hist) g1 = ldf8(hist + 2816);
;             else { for (int e = 0; e < 8; ++e) g1.v[e] = 0.f; }
;             if (pos >= 2) g2 = ldf8(Cs + (i - 2) * LDC + c8);
;             else if (hist) g2 = ldf8(hist + (size_t)pos * 2816);
;             else { for (int e = 0; e < 8; ++e) g2.v[e] = 0.f; }
;             F8 o;
; #pragma unroll
;             for (int e = 0; e < 8; ++e) o.v[e] = siluf(w0.v[e] * g2.v[e] + w1.v[e] * g1.v[e] + w2.v[e] * g0.v[e]) * up.v[e];
;             stb8(ep.b0 + (size_t)r * 2816 + ch, o);
.LBB0_1306:
	s_or_b64 exec, exec, s[26:27]
	s_waitcnt vmcnt(0) lgkmcnt(1)
	v_pk_mul_f32 v[52:53], v[12:13], v[52:53]
	s_nop 0
	v_pk_fma_f32 v[48:49], v[16:17], v[48:49], v[52:53]
	s_nop 0
	v_pk_fma_f32 v[40:41], v[20:21], v[40:41], v[48:49]
	s_nop 0
	v_mul_f32_e32 v48, 0xbfb8aa3b, v40
	v_mul_f32_e32 v49, 0xbfb8aa3b, v41
	v_exp_f32_e32 v48, v48
	v_exp_f32_e32 v49, v49
	s_nop 0
	v_pk_add_f32 v[48:49], v[48:49], 1.0 op_sel_hi:[1,0]
	s_nop 0
	v_rcp_f32_e32 v52, v49
	s_nop 0
	v_mul_f32_e32 v41, v41, v52
	v_rcp_f32_e32 v49, v48
	s_nop 0
	v_mul_f32_e32 v40, v40, v49
	v_pk_mul_f32 v[32:33], v[32:33], v[40:41]
	v_pk_mul_f32 v[40:41], v[14:15], v[54:55]
	s_nop 0
	v_pk_fma_f32 v[40:41], v[18:19], v[50:51], v[40:41]
	s_nop 0
	v_pk_fma_f32 v[40:41], v[22:23], v[42:43], v[40:41]
	s_nop 0
	v_mul_f32_e32 v42, 0xbfb8aa3b, v40
	v_mul_f32_e32 v43, 0xbfb8aa3b, v41
	v_exp_f32_e32 v42, v42
	v_exp_f32_e32 v43, v43
	s_nop 0
	v_pk_add_f32 v[42:43], v[42:43], 1.0 op_sel_hi:[1,0]
	s_nop 0
	v_rcp_f32_e32 v48, v43
	s_nop 0
	v_mul_f32_e32 v41, v41, v48
	v_rcp_f32_e32 v43, v42
	s_nop 0
	v_mul_f32_e32 v40, v40, v43
	v_pk_mul_f32 v[34:35], v[34:35], v[40:41]
	s_waitcnt lgkmcnt(0)
	v_pk_mul_f32 v[40:41], v[0:1], v[44:45]
	s_nop 0
	v_pk_fma_f32 v[36:37], v[4:5], v[36:37], v[40:41]
	s_nop 0
	v_pk_fma_f32 v[28:29], v[8:9], v[28:29], v[36:37]
	s_nop 0
	v_mul_f32_e32 v36, 0xbfb8aa3b, v28
	v_mul_f32_e32 v37, 0xbfb8aa3b, v29
	v_exp_f32_e32 v36, v36
	v_exp_f32_e32 v37, v37
	s_nop 0
	v_pk_add_f32 v[36:37], v[36:37], 1.0 op_sel_hi:[1,0]
	s_nop 0
	v_rcp_f32_e32 v40, v37
	s_nop 0
	v_mul_f32_e32 v29, v29, v40
	v_rcp_f32_e32 v37, v36
	s_nop 0
	v_mul_f32_e32 v28, v28, v37
	v_pk_mul_f32 v[28:29], v[24:25], v[28:29]
	v_pk_mul_f32 v[24:25], v[2:3], v[46:47]
	s_nop 0
	v_pk_fma_f32 v[24:25], v[6:7], v[38:39], v[24:25]
	s_nop 0
	v_pk_fma_f32 v[24:25], v[10:11], v[30:31], v[24:25]
	s_nop 0
	v_mul_f32_e32 v30, 0xbfb8aa3b, v24
	v_mul_f32_e32 v31, 0xbfb8aa3b, v25
	v_exp_f32_e32 v30, v30
	v_exp_f32_e32 v31, v31
	s_nop 0
	v_pk_add_f32 v[30:31], v[30:31], 1.0 op_sel_hi:[1,0]
	s_nop 0
	v_rcp_f32_e32 v36, v31
	s_nop 0
	v_mul_f32_e32 v25, v25, v36
	v_rcp_f32_e32 v31, v30
	s_nop 0
	v_mul_f32_e32 v24, v24, v31
	v_pk_mul_f32 v[30:31], v[26:27], v[24:25]
	v_mov_b64_e32 v[24:25], s[84:85]
	v_mad_i64_i32 v[24:25], s[26:27], v63, s89, v[24:25]
	v_lshl_add_u64 v[36:37], v[56:57], 1, v[24:25]
	v_cvt_pk_bf16_f32 v24, v32, v33
	v_cvt_pk_bf16_f32 v25, v34, v35
	v_cvt_pk_bf16_f32 v26, v28, v29
	v_cvt_pk_bf16_f32 v27, v30, v31
	global_store_dwordx4 v[36:37], v[24:27], off offset:128 sc1
.LBB0_1307:
	s_or_b64 exec, exec, s[0:1]
	v_add_u32_e32 v36, 64, v62
	s_waitcnt lgkmcnt(0)
	v_mul_lo_u32 v24, v36, s35
	v_add_u32_e32 v61, 16, v24
	v_lshl_add_u32 v24, v212, 2, v61
	ds_read_b128 v[40:43], v24
	ds_read_b128 v[28:31], v24 offset:16
	ds_read_b128 v[32:35], v24 offset:256
	ds_read_b128 v[24:27], v24 offset:272
	v_cmp_lt_i32_e32 vcc, 61, v62
	s_and_saveexec_b64 s[0:1], vcc
	s_cbranch_execz .LBB0_1309
	v_subrev_u32_e32 v38, 62, v62
	v_mov_b32_e32 v39, v213
	v_lshl_add_u64 v[38:39], s[30:31], 0, v[38:39]
	v_mov_b64_e32 v[44:45], s[72:73]
	v_mad_u64_u32 v[44:45], s[26:27], v38, s3, v[44:45]
	v_mad_i32_i24 v45, v39, s3, v45
	v_lshl_add_u64 v[38:39], v[56:57], 2, v[44:45]
	s_waitcnt lgkmcnt(3)
	global_store_dwordx4 v[38:39], v[40:43], off offset:256 sc1
	s_waitcnt lgkmcnt(2)
	global_store_dwordx4 v[38:39], v[28:31], off offset:272 sc1
.LBB0_1309:
	s_or_b64 exec, exec, s[0:1]
	v_cmp_gt_i32_e32 vcc, s90, v62
	s_and_saveexec_b64 s[0:1], vcc
	s_cbranch_execz .LBB0_1311
	v_add_u32_e32 v37, s30, v36
	v_mov_b64_e32 v[38:39], s[80:81]
	v_mad_i64_i32 v[38:39], s[26:27], v37, s3, v[38:39]
	v_lshl_add_u64 v[38:39], v[38:39], 0, v[58:59]
	s_waitcnt lgkmcnt(3)
	global_store_dwordx4 v[38:39], v[40:43], off offset:256 sc1
	s_waitcnt lgkmcnt(2)
	global_store_dwordx4 v[38:39], v[28:31], off offset:272 sc1
	v_mov_b64_e32 v[38:39], s[82:83]
	v_mad_i64_i32 v[38:39], s[26:27], v37, s3, v[38:39]
	v_lshl_add_u64 v[38:39], v[38:39], 0, v[58:59]
	s_waitcnt lgkmcnt(1)
	global_store_dwordx4 v[38:39], v[32:35], off offset:256 sc1
	s_waitcnt lgkmcnt(0)
	global_store_dwordx4 v[38:39], v[24:27], off offset:272 sc1
.LBB0_1311:
	s_or_b64 exec, exec, s[0:1]
	v_add_u32_e32 v60, s54, v36
	v_add_u32_e32 v36, 0xffff8000, v60
	v_lshrrev_b32_e32 v36, 6, v36
	v_add_u32_e32 v36, 4, v36
	v_ashrrev_i32_e32 v37, 13, v60
	v_cmp_gt_i32_e64 s[0:1], s53, v60
	v_mov_b32_e32 v38, 0x1fff
	s_nop 0
	v_cndmask_b32_e64 v38, 63, v38, s[0:1]
	v_cndmask_b32_e64 v36, v36, v37, s[0:1]
	v_mov_b32_e32 v37, 0x1ffe
	v_and_b32_e32 v62, v38, v60
	v_cndmask_b32_e64 v37, 62, v37, s[0:1]
	v_cmp_ge_u32_e64 s[0:1], v62, v37
	s_and_saveexec_b64 s[26:27], s[0:1]
	s_cbranch_execz .LBB0_1313
	v_ashrrev_i32_e32 v38, 31, v36
	v_add_u32_e32 v44, -4, v36
	v_cmp_gt_i32_e64 s[0:1], 4, v36
	v_mov_b32_e32 v45, 0xce50000
	v_sub_u32_e32 v48, v62, v37
	v_cndmask_b32_e64 v39, 0, v38, s[0:1]
	v_cndmask_b32_e64 v38, v44, v36, s[0:1]
	v_mov_b32_e32 v44, 0xd868000
	v_cndmask_b32_e64 v44, v44, v45, s[0:1]
	v_cndmask_b32_e64 v46, 4, 3, s[0:1]
	v_readlane_b32 s0, v255, 13
	v_readlane_b32 s1, v255, 14
	v_mov_b32_e32 v49, v213
	v_mov_b32_e32 v45, v213
	v_lshlrev_b64 v[46:47], v46, s[0:1]
	v_lshl_add_u64 v[46:47], v[46:47], 0, v[48:49]
	v_lshl_add_u64 v[44:45], s[60:61], 0, v[44:45]
	v_lshl_add_u64 v[38:39], v[38:39], 1, v[46:47]
	v_mad_u64_u32 v[44:45], s[0:1], v38, s3, v[44:45]
	v_mad_i32_i24 v45, v39, s3, v45
	v_lshl_add_u64 v[38:39], v[56:57], 2, v[44:45]
	s_waitcnt lgkmcnt(3)
	global_store_dwordx4 v[38:39], v[40:43], off offset:256 sc1
	s_waitcnt lgkmcnt(2)
	global_store_dwordx4 v[38:39], v[28:31], off offset:272 sc1

; DI void stb8(bf16_t* p, const F8& f) { *(uint4*)p = pack8(f); }
; DI float siluf(float x) { return x / (1.f + __expf(-x)); }
; DI void ffn_fixup(const Params& p, int layer) {
;     ...
;     for (size_t i = gt; i < (size_t)256 * 2 * 352; i += gn) {
;         const int c = (int)(i % 352) * 8, ri = (int)((i / 352) & 1), mt = (int)(i / 704);
;         if ((mt & 63) == 0) continue;
;         const F8 w0 = ldf8(cw + c), w1 = ldf8(cw + 2816 + c), w2 = ldf8(cw + 5632 + c);
;         F8 g0, g1, g2;
;         if (ri == 0) { g0 = ldf8(HG + ((size_t)mt * 2) * 2816 + c); g1 = ldf8(HALO + ((size_t)(mt - 1) * 2 + 1) * 2816 + c); g2 = ldf8(HALO + ((size_t)(mt - 1) * 2) * 2816 + c); }
;         else { g0 = ldf8(HG + ((size_t)mt * 2 + 1) * 2816 + c); g1 = ldf8(HG + ((size_t)mt * 2) * 2816 + c); g2 = ldf8(HALO + ((size_t)(mt - 1) * 2 + 1) * 2816 + c); }
;         const F8 up = ldf8(HU + ((size_t)mt * 2 + ri) * 2816 + c);
;         F8 o;
; #pragma unroll
;         for (int e = 0; e < 8; ++e) o.v[e] = siluf(w0.v[e] * g2.v[e] + w1.v[e] * g1.v[e] + w2.v[e] * g0.v[e]) * up.v[e];
;         stb8(ACT + ((size_t)mt * 128 + ri) * 2816 + c, o);
;     }
.LBB0_1383:
	s_or_b64 exec, exec, s[0:1]
	v_lshl_add_u64 v[38:39], v[34:35], 0, v[26:27]
	global_load_dwordx4 v[32:35], v[38:39], off
	v_lshl_add_u64 v[30:31], v[30:31], 0, v[26:27]
	global_load_dwordx4 v[38:41], v[38:39], off offset:16
	s_nop 0
	global_load_dwordx4 v[42:45], v[30:31], off
	v_lshl_add_u64 v[50:51], v[28:29], 0, v[26:27]
	global_load_dwordx4 v[28:31], v[30:31], off offset:16
	s_nop 0
	global_load_dwordx4 v[46:49], v[50:51], off
	s_nop 0
	global_load_dwordx4 v[50:53], v[50:51], off offset:16
	v_readlane_b32 s0, v254, 46
	v_bfe_u32 v37, v37, 8, 1
	v_readlane_b32 s1, v254, 47
	v_lshl_or_b32 v56, v36, 1, v37
	v_lshlrev_b32_e32 v212, 1, v212
	v_mov_b64_e32 v[54:55], s[0:1]
	v_mad_u64_u32 v[54:55], s[0:1], v56, s3, v[54:55]
	v_lshl_add_u64 v[26:27], v[54:55], 0, v[26:27]
	global_load_dwordx4 v[54:57], v[26:27], off
	s_waitcnt vmcnt(6)
	v_pk_mul_f32 v[20:21], v[20:21], v[32:33]
	v_pk_mul_f32 v[22:23], v[22:23], v[34:35]
	s_waitcnt vmcnt(5)
	v_pk_mul_f32 v[4:5], v[4:5], v[38:39]
	s_waitcnt vmcnt(4)
	v_pk_fma_f32 v[12:13], v[12:13], v[42:43], v[20:21]
	v_pk_fma_f32 v[14:15], v[14:15], v[44:45], v[22:23]
	s_waitcnt vmcnt(3)
	v_pk_fma_f32 v[0:1], v[0:1], v[28:29], v[4:5]
	s_waitcnt vmcnt(2)
	v_pk_fma_f32 v[4:5], v[16:17], v[46:47], v[12:13]
	v_pk_fma_f32 v[16:17], v[18:19], v[48:49], v[14:15]
	s_waitcnt vmcnt(1)
	v_pk_fma_f32 v[0:1], v[8:9], v[50:51], v[0:1]
	v_mul_f32_e32 v12, 0xbfb8aa3b, v16
	v_mul_f32_e32 v13, 0xbfb8aa3b, v17
	v_mul_f32_e32 v14, 0xbfb8aa3b, v0
	v_mul_f32_e32 v15, 0xbfb8aa3b, v1
	v_exp_f32_e32 v18, v12
	v_exp_f32_e32 v19, v13
	v_exp_f32_e32 v20, v14
	v_exp_f32_e32 v21, v15
	global_load_dwordx4 v[12:15], v[26:27], off offset:16
	v_mul_f32_e32 v8, 0xbfb8aa3b, v4
	v_mul_f32_e32 v9, 0xbfb8aa3b, v5
	v_exp_f32_e32 v8, v8
	v_exp_f32_e32 v9, v9
	v_pk_add_f32 v[18:19], v[18:19], 1.0 op_sel_hi:[1,0]
	v_pk_add_f32 v[20:21], v[20:21], 1.0 op_sel_hi:[1,0]
	v_div_scale_f32 v28, s[36:37], v19, v19, v17
	v_pk_add_f32 v[8:9], v[8:9], 1.0 op_sel_hi:[1,0]
	v_div_scale_f32 v32, s[38:39], v18, v18, v16
	v_div_scale_f32 v26, s[0:1], v8, v8, v4
	v_rcp_f32_e32 v39, v26
	v_rcp_f32_e32 v42, v28
	v_rcp_f32_e32 v43, v32
	v_fma_f32 v46, -v26, v39, 1.0
	v_div_scale_f32 v27, s[0:1], v4, v8, v4
	v_div_scale_f32 v34, s[40:41], v21, v21, v1
	v_fma_f32 v47, -v28, v42, 1.0
	v_fmac_f32_e32 v39, v46, v39
	v_div_scale_f32 v29, s[36:37], v17, v19, v17
	v_rcp_f32_e32 v44, v34
	v_fma_f32 v48, -v32, v43, 1.0
	v_fmac_f32_e32 v42, v47, v42
	v_mul_f32_e32 v46, v27, v39
	v_div_scale_f32 v33, s[38:39], v16, v18, v16
	v_fmac_f32_e32 v43, v48, v43
	v_mul_f32_e32 v47, v29, v42
	v_fma_f32 v51, -v26, v46, v27
	v_mul_f32_e32 v48, v33, v43
	v_fma_f32 v58, -v28, v47, v29
	v_fmac_f32_e32 v46, v51, v39
	v_fma_f32 v59, -v32, v48, v33
	v_fmac_f32_e32 v47, v58, v42
	v_fma_f32 v23, -v26, v46, v27
	s_mov_b64 vcc, s[0:1]
	v_fma_f32 v49, -v34, v44, 1.0
	v_fmac_f32_e32 v48, v59, v43
	v_fma_f32 v26, -v28, v47, v29
	v_rcp_f32_e32 v22, v9
	s_nop 0
	v_mul_f32_e32 v5, v5, v22
	v_div_fmas_f32 v9, v23, v39, v46
	s_mov_b64 vcc, s[36:37]
	v_div_scale_f32 v35, s[40:41], v1, v21, v1
	v_fmac_f32_e32 v44, v49, v44
	v_fma_f32 v27, -v32, v48, v33
	v_div_fixup_f32 v4, v9, v8, v4
	v_div_fmas_f32 v8, v26, v42, v47
	s_mov_b64 vcc, s[38:39]
	v_mul_f32_e32 v49, v35, v44
	v_div_fixup_f32 v9, v8, v19, v17
	v_div_fmas_f32 v8, v27, v43, v48
	v_div_scale_f32 v17, s[0:1], v20, v20, v0
	v_div_fixup_f32 v8, v8, v18, v16
	v_fma_f32 v16, -v34, v49, v35
	v_rcp_f32_e32 v18, v17
	v_pk_mul_f32 v[6:7], v[6:7], v[40:41]
	v_fmac_f32_e32 v49, v16, v44
	v_pk_fma_f32 v[2:3], v[2:3], v[30:31], v[6:7]
	v_fma_f32 v16, -v34, v49, v35
	s_mov_b64 vcc, s[40:41]
	v_pk_fma_f32 v[2:3], v[10:11], v[52:53], v[2:3]
	v_div_fmas_f32 v16, v16, v44, v49
	v_mul_f32_e32 v6, 0xbfb8aa3b, v2
	v_mul_f32_e32 v7, 0xbfb8aa3b, v3
	v_div_fixup_f32 v1, v16, v21, v1
	v_fma_f32 v16, -v17, v18, 1.0
	v_exp_f32_e32 v6, v6
	v_exp_f32_e32 v7, v7
	v_fmac_f32_e32 v18, v16, v18
	v_div_scale_f32 v16, vcc, v0, v20, v0
	v_mul_f32_e32 v19, v16, v18
	v_fma_f32 v10, -v17, v19, v16
	v_fmac_f32_e32 v19, v10, v18
	v_pk_add_f32 v[6:7], v[6:7], 1.0 op_sel_hi:[1,0]
	v_fma_f32 v10, -v17, v19, v16
	v_div_scale_f32 v16, s[0:1], v7, v7, v3
	v_rcp_f32_e32 v17, v16
	v_div_fmas_f32 v10, v10, v18, v19
	v_div_fixup_f32 v0, v10, v20, v0
	s_waitcnt vmcnt(0)
	v_pk_mul_f32 v[10:11], v[0:1], v[12:13]
	v_fma_f32 v0, -v16, v17, 1.0
	v_fmac_f32_e32 v17, v0, v17
	v_div_scale_f32 v0, vcc, v3, v7, v3
	v_mul_f32_e32 v1, v0, v17
	v_fma_f32 v12, -v16, v1, v0
	v_fmac_f32_e32 v1, v12, v17
	s_nop 0
	v_fma_f32 v0, -v16, v1, v0
	v_div_fmas_f32 v0, v0, v17, v1
	v_div_fixup_f32 v1, v0, v7, v3
	v_rcp_f32_e32 v0, v6
	s_nop 0
	v_mul_f32_e32 v0, v2, v0
	v_pk_mul_f32 v[6:7], v[0:1], v[14:15]
	v_lshl_or_b32 v2, v36, 7, v37
	v_mov_b64_e32 v[0:1], s[84:85]
	s_movk_i32 s0, 0x1600
	v_pk_mul_f32 v[4:5], v[4:5], v[54:55]
	v_pk_mul_f32 v[8:9], v[8:9], v[56:57]
	v_mad_u64_u32 v[0:1], s[0:1], v2, s0, v[0:1]
	v_lshl_add_u64 v[12:13], v[0:1], 0, v[212:213]
	v_cvt_pk_bf16_f32 v0, v4, v5
	v_cvt_pk_bf16_f32 v1, v8, v9
	v_cvt_pk_bf16_f32 v2, v10, v11
	v_cvt_pk_bf16_f32 v3, v6, v7
	global_store_dwordx4 v[12:13], v[0:3], off sc1

; DI void stb8(bf16_t* p, const F8& f) { *(uint4*)p = pack8(f); }
; template <int MODE>
; DI void gemm_epilogue(const float* Cs, int m0, int n0, const Epi& ep) {
;     ...
;     if (MODE == 0) {
; #pragma unroll
;         for (int it = 0; it < 4; ++it) {
;             const int row = (tid >> 4) + 32 * it, cc = (tid & 15) * 8;
;             stb8(ep.b0 + (size_t)(m0 + row) * ep.ld + n0 + cc, ldf8(Cs + row * LDC + cc));
;         }
; template <int MODE>
; DI void gemm_phase(const bf16_t* __restrict__ A, const bf16_t* __restrict__ Bt, int M, int N, int K, const Epi& ep) {
;     ...
;                         *(f32x4*)(Cs + (wr * 64 + m * 16 + fr) * LDC + wc * 32 + n * 16 + fq * 4) = acc[ai][bj][m][n];
;                 __syncthreads();
;                 gemm_epilogue<MODE>(Cs, brow + ai * 128, bcol + bj * 128, ep);
;                 __syncthreads();
.LBB0_1444:
	s_or_b64 exec, exec, s[6:7]
	v_mov_b32_e32 v64, v250
	s_waitcnt vmcnt(0)
	s_barrier
	ds_write_b128 v146, v[96:99]
	ds_write_b128 v146, v[100:103] offset:64
	ds_write_b128 v146, v[104:107] offset:8448
	ds_write_b128 v146, v[108:111] offset:8512
	ds_write_b128 v146, v[112:115] offset:16896
	ds_write_b128 v146, v[116:119] offset:16960
	ds_write_b128 v146, v[120:123] offset:25344
	ds_write_b128 v146, v[124:127] offset:25408
	s_waitcnt lgkmcnt(0)
	s_barrier
	s_lshl_b64 s[0:1], s[0:1], 1
	v_ashrrev_i32_e32 v66, 4, v64
	v_add_u32_e32 v100, s22, v66
	v_lshlrev_b32_e32 v64, 3, v64
	v_ashrrev_i32_e32 v101, 31, v100
	v_and_b32_e32 v104, 0x78, v64
	v_lshlrev_b64 v[64:65], 11, v[100:101]
	v_lshlrev_b32_e32 v67, 2, v104
	v_lshl_add_u64 v[96:97], s[76:77], 0, v[64:65]
	v_mul_lo_u32 v64, v66, s35
	v_add3_u32 v105, 16, v67, v64
	ds_read_b128 v[64:67], v105
	v_lshl_add_u64 v[102:103], v[96:97], 0, s[0:1]
	ds_read_b128 v[96:99], v105 offset:16
	v_lshlrev_b32_e32 v212, 1, v104
	v_lshl_add_u64 v[102:103], v[102:103], 0, v[212:213]
	s_waitcnt lgkmcnt(1)
	v_cvt_pk_bf16_f32 v64, v64, v65
	v_cvt_pk_bf16_f32 v65, v66, v67
	s_waitcnt lgkmcnt(0)
	v_cvt_pk_bf16_f32 v66, v96, v97
	v_cvt_pk_bf16_f32 v67, v98, v99
	global_store_dwordx4 v[102:103], v[64:67], off sc1
	s_add_i32 s18, s18, 1
	s_nop 0
	v_add_u32_e32 v64, 32, v100
	v_ashrrev_i32_e32 v65, 31, v64
	v_lshlrev_b64 v[96:97], 11, v[64:65]
	ds_read_b128 v[64:67], v105 offset:16896
	v_lshl_add_u64 v[102:103], s[76:77], 0, v[96:97]
	ds_read_b128 v[96:99], v105 offset:16912
	v_lshl_add_u64 v[102:103], v[102:103], 0, s[0:1]
	v_lshl_add_u64 v[102:103], v[102:103], 0, v[212:213]
	s_waitcnt lgkmcnt(1)
	v_cvt_pk_bf16_f32 v64, v64, v65
	v_cvt_pk_bf16_f32 v65, v66, v67
	s_waitcnt lgkmcnt(0)
	v_cvt_pk_bf16_f32 v66, v96, v97
	v_cvt_pk_bf16_f32 v67, v98, v99
	global_store_dwordx4 v[102:103], v[64:67], off sc1
	s_nop 1
	v_add_u32_e32 v64, 64, v100
	v_ashrrev_i32_e32 v65, 31, v64
	v_lshlrev_b64 v[96:97], 11, v[64:65]
	ds_read_b128 v[64:67], v105 offset:33792
	v_lshl_add_u64 v[102:103], s[76:77], 0, v[96:97]
	ds_read_b128 v[96:99], v105 offset:33808
	v_lshl_add_u64 v[102:103], v[102:103], 0, s[0:1]
	v_lshl_add_u64 v[102:103], v[102:103], 0, v[212:213]
	s_waitcnt lgkmcnt(1)
	v_cvt_pk_bf16_f32 v64, v64, v65
	v_cvt_pk_bf16_f32 v65, v66, v67
	s_waitcnt lgkmcnt(0)
	v_cvt_pk_bf16_f32 v66, v96, v97
	v_cvt_pk_bf16_f32 v67, v98, v99
	global_store_dwordx4 v[102:103], v[64:67], off sc1
	s_nop 1
	v_add_u32_e32 v64, 0x60, v100
	v_ashrrev_i32_e32 v65, 31, v64
	v_lshlrev_b64 v[96:97], 11, v[64:65]
	ds_read_b128 v[64:67], v105 offset:50688
	v_lshl_add_u64 v[100:101], s[76:77], 0, v[96:97]
	ds_read_b128 v[96:99], v105 offset:50704
	v_lshl_add_u64 v[100:101], v[100:101], 0, s[0:1]
	v_lshl_add_u64 v[100:101], v[100:101], 0, v[212:213]
	s_waitcnt lgkmcnt(1)
	v_cvt_pk_bf16_f32 v64, v64, v65
	v_cvt_pk_bf16_f32 v65, v66, v67
	s_waitcnt lgkmcnt(0)
	v_cvt_pk_bf16_f32 v66, v96, v97
	v_cvt_pk_bf16_f32 v67, v98, v99
	global_store_dwordx4 v[100:101], v[64:67], off sc1
	s_barrier
	s_nop 0
	v_mov_b32_e32 v64, v250
	ds_write_b128 v146, v[222:225]
	ds_write_b128 v146, v[68:71] offset:64
	ds_write_b128 v146, v[72:75] offset:8448
	ds_write_b128 v146, v[76:79] offset:8512
	ds_write_b128 v146, v[80:83] offset:16896
	ds_write_b128 v146, v[84:87] offset:16960
	ds_write_b128 v146, v[88:91] offset:25344
	ds_write_b128 v146, v[92:95] offset:25408
	s_waitcnt lgkmcnt(0)
	s_barrier
	s_nop 0
	v_ashrrev_i32_e32 v66, 4, v64
	v_add_u32_e32 v72, s22, v66
	v_lshlrev_b32_e32 v64, 3, v64
	v_ashrrev_i32_e32 v73, 31, v72
	v_and_b32_e32 v76, 0x78, v64
	v_lshlrev_b64 v[64:65], 11, v[72:73]
	v_lshlrev_b32_e32 v67, 2, v76
	v_lshl_add_u64 v[68:69], s[76:77], 0, v[64:65]
	v_mul_lo_u32 v64, v66, s35
	v_add3_u32 v77, 16, v67, v64
	ds_read_b128 v[64:67], v77
	v_lshl_add_u64 v[74:75], v[68:69], 0, s[0:1]
	ds_read_b128 v[68:71], v77 offset:16
	v_lshlrev_b32_e32 v212, 1, v76
	v_lshl_add_u64 v[74:75], v[74:75], 0, v[212:213]
	s_waitcnt lgkmcnt(1)
	v_cvt_pk_bf16_f32 v64, v64, v65
	v_cvt_pk_bf16_f32 v65, v66, v67
	s_waitcnt lgkmcnt(0)
	v_cvt_pk_bf16_f32 v66, v68, v69
	v_cvt_pk_bf16_f32 v67, v70, v71
	global_store_dwordx4 v[74:75], v[64:67], off offset:256 sc1
	s_nop 1
	v_add_u32_e32 v64, 32, v72
	v_ashrrev_i32_e32 v65, 31, v64
	v_lshlrev_b64 v[68:69], 11, v[64:65]
	ds_read_b128 v[64:67], v77 offset:16896
	v_lshl_add_u64 v[74:75], s[76:77], 0, v[68:69]
	ds_read_b128 v[68:71], v77 offset:16912
	v_lshl_add_u64 v[74:75], v[74:75], 0, s[0:1]
	v_lshl_add_u64 v[74:75], v[74:75], 0, v[212:213]
	s_waitcnt lgkmcnt(1)
	v_cvt_pk_bf16_f32 v64, v64, v65
	v_cvt_pk_bf16_f32 v65, v66, v67
	s_waitcnt lgkmcnt(0)
	v_cvt_pk_bf16_f32 v66, v68, v69
	v_cvt_pk_bf16_f32 v67, v70, v71
	global_store_dwordx4 v[74:75], v[64:67], off offset:256 sc1
	s_nop 1
	v_add_u32_e32 v64, 64, v72
	v_ashrrev_i32_e32 v65, 31, v64
	v_lshlrev_b64 v[68:69], 11, v[64:65]
	ds_read_b128 v[64:67], v77 offset:33792
	v_lshl_add_u64 v[74:75], s[76:77], 0, v[68:69]
	ds_read_b128 v[68:71], v77 offset:33808
	v_lshl_add_u64 v[74:75], v[74:75], 0, s[0:1]
	v_lshl_add_u64 v[74:75], v[74:75], 0, v[212:213]
	s_waitcnt lgkmcnt(1)
	v_cvt_pk_bf16_f32 v64, v64, v65
	v_cvt_pk_bf16_f32 v65, v66, v67
	s_waitcnt lgkmcnt(0)
	v_cvt_pk_bf16_f32 v66, v68, v69
	v_cvt_pk_bf16_f32 v67, v70, v71
	global_store_dwordx4 v[74:75], v[64:67], off offset:256 sc1
	s_nop 1
	v_add_u32_e32 v64, 0x60, v72
	v_ashrrev_i32_e32 v65, 31, v64
	v_lshlrev_b64 v[68:69], 11, v[64:65]
	ds_read_b128 v[64:67], v77 offset:50688
	v_lshl_add_u64 v[72:73], s[76:77], 0, v[68:69]
	ds_read_b128 v[68:71], v77 offset:50704
	v_lshl_add_u64 v[72:73], v[72:73], 0, s[0:1]
	v_lshl_add_u64 v[72:73], v[72:73], 0, v[212:213]
	s_waitcnt lgkmcnt(1)
	v_cvt_pk_bf16_f32 v64, v64, v65
	v_cvt_pk_bf16_f32 v65, v66, v67
	s_waitcnt lgkmcnt(0)
	v_cvt_pk_bf16_f32 v66, v68, v69
	v_cvt_pk_bf16_f32 v67, v70, v71
	global_store_dwordx4 v[72:73], v[64:67], off offset:256 sc1
	s_barrier
; DI void stb8(bf16_t* p, const F8& f) { *(uint4*)p = pack8(f); }
; template <int MODE>
; DI void gemm_epilogue(const float* Cs, int m0, int n0, const Epi& ep) {
;     ...
;     if (MODE == 0) {
; #pragma unroll
;         for (int it = 0; it < 4; ++it) {
;             const int row = (tid >> 4) + 32 * it, cc = (tid & 15) * 8;
;             stb8(ep.b0 + (size_t)(m0 + row) * ep.ld + n0 + cc, ldf8(Cs + row * LDC + cc));
;         }
; template <int MODE>
; DI void gemm_phase(const bf16_t* __restrict__ A, const bf16_t* __restrict__ Bt, int M, int N, int K, const Epi& ep) {
;     ...
;                         *(f32x4*)(Cs + (wr * 64 + m * 16 + fr) * LDC + wc * 32 + n * 16 + fq * 4) = acc[ai][bj][m][n];
;                 __syncthreads();
;                 gemm_epilogue<MODE>(Cs, brow + ai * 128, bcol + bj * 128, ep);
;                 __syncthreads();
	ds_write_b128 v146, v[32:35]
	ds_write_b128 v146, v[36:39] offset:64
	ds_write_b128 v146, v[40:43] offset:8448
	ds_write_b128 v146, v[44:47] offset:8512
	ds_write_b128 v146, v[48:51] offset:16896
	ds_write_b128 v146, v[52:55] offset:16960
	ds_write_b128 v146, v[56:59] offset:25344
	ds_write_b128 v146, v[60:63] offset:25408
	v_mov_b32_e32 v32, v250
	s_waitcnt lgkmcnt(0)
	s_barrier
	s_nop 0
	v_ashrrev_i32_e32 v34, 4, v32
	v_add_u32_e32 v40, s19, v34
	v_lshlrev_b32_e32 v32, 3, v32
	v_ashrrev_i32_e32 v41, 31, v40
	v_and_b32_e32 v44, 0x78, v32
	v_lshlrev_b64 v[32:33], 11, v[40:41]
	v_lshlrev_b32_e32 v35, 2, v44
	v_lshl_add_u64 v[36:37], s[76:77], 0, v[32:33]
	v_mul_lo_u32 v32, v34, s35
	v_add3_u32 v45, 16, v35, v32
	ds_read_b128 v[32:35], v45
	v_lshl_add_u64 v[42:43], v[36:37], 0, s[0:1]
	ds_read_b128 v[36:39], v45 offset:16
	v_lshlrev_b32_e32 v212, 1, v44
	v_lshl_add_u64 v[42:43], v[42:43], 0, v[212:213]
	s_waitcnt lgkmcnt(1)
	v_cvt_pk_bf16_f32 v32, v32, v33
	v_cvt_pk_bf16_f32 v33, v34, v35
	s_waitcnt lgkmcnt(0)
	v_cvt_pk_bf16_f32 v34, v36, v37
	v_cvt_pk_bf16_f32 v35, v38, v39
	global_store_dwordx4 v[42:43], v[32:35], off sc1
	s_nop 1
	v_add_u32_e32 v32, 32, v40
	v_ashrrev_i32_e32 v33, 31, v32
	v_lshlrev_b64 v[36:37], 11, v[32:33]
	ds_read_b128 v[32:35], v45 offset:16896
	v_lshl_add_u64 v[42:43], s[76:77], 0, v[36:37]
	ds_read_b128 v[36:39], v45 offset:16912
	v_lshl_add_u64 v[42:43], v[42:43], 0, s[0:1]
	v_lshl_add_u64 v[42:43], v[42:43], 0, v[212:213]
	s_waitcnt lgkmcnt(1)
	v_cvt_pk_bf16_f32 v32, v32, v33
	v_cvt_pk_bf16_f32 v33, v34, v35
	s_waitcnt lgkmcnt(0)
	v_cvt_pk_bf16_f32 v34, v36, v37
	v_cvt_pk_bf16_f32 v35, v38, v39
	global_store_dwordx4 v[42:43], v[32:35], off sc1
	s_nop 1
	v_add_u32_e32 v32, 64, v40
	v_ashrrev_i32_e32 v33, 31, v32
	v_lshlrev_b64 v[36:37], 11, v[32:33]
	ds_read_b128 v[32:35], v45 offset:33792
	v_lshl_add_u64 v[42:43], s[76:77], 0, v[36:37]
	ds_read_b128 v[36:39], v45 offset:33808
	v_lshl_add_u64 v[42:43], v[42:43], 0, s[0:1]
	v_lshl_add_u64 v[42:43], v[42:43], 0, v[212:213]
	s_waitcnt lgkmcnt(1)
	v_cvt_pk_bf16_f32 v32, v32, v33
	v_cvt_pk_bf16_f32 v33, v34, v35
	s_waitcnt lgkmcnt(0)
	v_cvt_pk_bf16_f32 v34, v36, v37
	v_cvt_pk_bf16_f32 v35, v38, v39
	global_store_dwordx4 v[42:43], v[32:35], off sc1
	s_nop 1
	v_add_u32_e32 v32, 0x60, v40
	v_ashrrev_i32_e32 v33, 31, v32
	v_lshlrev_b64 v[36:37], 11, v[32:33]
	ds_read_b128 v[32:35], v45 offset:50688
	v_lshl_add_u64 v[40:41], s[76:77], 0, v[36:37]
	ds_read_b128 v[36:39], v45 offset:50704
	v_lshl_add_u64 v[40:41], v[40:41], 0, s[0:1]
	v_lshl_add_u64 v[40:41], v[40:41], 0, v[212:213]
	s_waitcnt lgkmcnt(1)
	v_cvt_pk_bf16_f32 v32, v32, v33
	v_cvt_pk_bf16_f32 v33, v34, v35
	s_waitcnt lgkmcnt(0)
	v_cvt_pk_bf16_f32 v34, v36, v37
	v_cvt_pk_bf16_f32 v35, v38, v39
	global_store_dwordx4 v[40:41], v[32:35], off sc1
	s_barrier
	ds_write_b128 v146, v[0:3]
	ds_write_b128 v146, v[4:7] offset:64
	ds_write_b128 v146, v[8:11] offset:8448
	ds_write_b128 v146, v[12:15] offset:8512
	ds_write_b128 v146, v[16:19] offset:16896
	ds_write_b128 v146, v[20:23] offset:16960
	ds_write_b128 v146, v[24:27] offset:25344
	ds_write_b128 v146, v[28:31] offset:25408
	v_mov_b32_e32 v0, v250
	s_waitcnt lgkmcnt(0)
	s_barrier
	s_nop 0
	v_ashrrev_i32_e32 v2, 4, v0
	v_add_u32_e32 v8, s19, v2
	v_lshlrev_b32_e32 v0, 3, v0
	v_ashrrev_i32_e32 v9, 31, v8
	v_and_b32_e32 v12, 0x78, v0
	v_lshlrev_b64 v[0:1], 11, v[8:9]
	v_lshlrev_b32_e32 v3, 2, v12
	v_lshl_add_u64 v[4:5], s[76:77], 0, v[0:1]
	v_mul_lo_u32 v0, v2, s35
	v_add3_u32 v13, 16, v3, v0
	ds_read_b128 v[0:3], v13
	v_lshl_add_u64 v[10:11], v[4:5], 0, s[0:1]
	ds_read_b128 v[4:7], v13 offset:16
	v_lshlrev_b32_e32 v212, 1, v12
	v_lshl_add_u64 v[10:11], v[10:11], 0, v[212:213]
	s_waitcnt lgkmcnt(1)
	v_cvt_pk_bf16_f32 v0, v0, v1
	v_cvt_pk_bf16_f32 v1, v2, v3
	s_waitcnt lgkmcnt(0)
	v_cvt_pk_bf16_f32 v2, v4, v5
	v_cvt_pk_bf16_f32 v3, v6, v7
	global_store_dwordx4 v[10:11], v[0:3], off offset:256 sc1
	s_nop 1
	v_add_u32_e32 v0, 32, v8
	v_ashrrev_i32_e32 v1, 31, v0
	v_lshlrev_b64 v[4:5], 11, v[0:1]
	ds_read_b128 v[0:3], v13 offset:16896
	v_lshl_add_u64 v[10:11], s[76:77], 0, v[4:5]
	ds_read_b128 v[4:7], v13 offset:16912
	v_lshl_add_u64 v[10:11], v[10:11], 0, s[0:1]
	v_lshl_add_u64 v[10:11], v[10:11], 0, v[212:213]
	s_waitcnt lgkmcnt(1)
	v_cvt_pk_bf16_f32 v0, v0, v1
	v_cvt_pk_bf16_f32 v1, v2, v3
	s_waitcnt lgkmcnt(0)
	v_cvt_pk_bf16_f32 v2, v4, v5
	v_cvt_pk_bf16_f32 v3, v6, v7
	global_store_dwordx4 v[10:11], v[0:3], off offset:256 sc1
	s_nop 1
	v_add_u32_e32 v0, 64, v8
	v_ashrrev_i32_e32 v1, 31, v0
	v_lshlrev_b64 v[4:5], 11, v[0:1]
	ds_read_b128 v[0:3], v13 offset:33792
	v_lshl_add_u64 v[10:11], s[76:77], 0, v[4:5]
	ds_read_b128 v[4:7], v13 offset:33808
	v_lshl_add_u64 v[10:11], v[10:11], 0, s[0:1]
	v_lshl_add_u64 v[10:11], v[10:11], 0, v[212:213]
	s_waitcnt lgkmcnt(1)
	v_cvt_pk_bf16_f32 v0, v0, v1
	v_cvt_pk_bf16_f32 v1, v2, v3
	s_waitcnt lgkmcnt(0)
	v_cvt_pk_bf16_f32 v2, v4, v5
	v_cvt_pk_bf16_f32 v3, v6, v7
	global_store_dwordx4 v[10:11], v[0:3], off offset:256 sc1
	s_nop 1
	v_add_u32_e32 v0, 0x60, v8
	v_ashrrev_i32_e32 v1, 31, v0
	v_lshlrev_b64 v[4:5], 11, v[0:1]
	ds_read_b128 v[0:3], v13 offset:50688
	v_lshl_add_u64 v[8:9], s[76:77], 0, v[4:5]
	ds_read_b128 v[4:7], v13 offset:50704
	v_lshl_add_u64 v[8:9], v[8:9], 0, s[0:1]
	s_mul_i32 s0, s18, s14
	s_add_i32 s0, s0, s15
	v_lshl_add_u64 v[8:9], v[8:9], 0, v[212:213]
	s_waitcnt lgkmcnt(1)
	v_cvt_pk_bf16_f32 v0, v0, v1
	v_cvt_pk_bf16_f32 v1, v2, v3
	s_waitcnt lgkmcnt(0)
	v_cvt_pk_bf16_f32 v2, v4, v5
	v_cvt_pk_bf16_f32 v3, v6, v7
	s_cmpk_lt_i32 s0, 0x200
	global_store_dwordx4 v[8:9], v[0:3], off offset:256 sc1
	s_barrier
	s_cbranch_scc0 .LBB0_1455

; DI F8 unpack8(uint4 u) { F8 r; r.v[0] = lo16(u.x); r.v[1] = hi16(u.x); r.v[2] = lo16(u.y); r.v[3] = hi16(u.y); r.v[4] = lo16(u.z); r.v[5] = hi16(u.z); r.v[6] = lo16(u.w); r.v[7] = hi16(u.w); return r; }
; DI float wsum(float v) { v += __shfl_xor(v, 32); v += __shfl_xor(v, 16); v += __shfl_xor(v, 8); v += __shfl_xor(v, 4); v += __shfl_xor(v, 2); v += __shfl_xor(v, 1); return v; }
; DI void ln_phase(const Params& p, const bf16_t* __restrict__ Y, const float* __restrict__ g, const float* __restrict__ b, bool final_out) {
;     ...
;     for (int r0 = gw; r0 < MT; r0 += 2 * nw) {
;         const int r1 = r0 + nw; const bool two = r1 < MT; const int rr[2] = {r0, two ? r1 : r0};
;         uint4 xr[2][2], yr[2][2];
; #pragma unroll
;         for (int q = 0; q < 2; ++q)
; #pragma unroll
;             for (int it = 0; it < 2; ++it) { const size_t off = (size_t)rr[q] * 1024 + it * 512 + lane * 8; xr[q][it] = *(const uint4*)(XB + off); yr[q][it] = *(const uint4*)(Y + off); }
;         float v[2][16];
; #pragma unroll
;         for (int q = 0; q < 2; ++q)
; #pragma unroll
;             for (int it = 0; it < 2; ++it) { const F8 x = unpack8(xr[q][it]), y = unpack8(yr[q][it]);
; #pragma unroll
;                 for (int e = 0; e < 8; ++e) v[q][it * 8 + e] = ALPHA * x.v[e] + y.v[e]; }
;         float s0 = 0.f, s1 = 0.f;
; #pragma unroll
;         for (int e = 0; e < 16; ++e) { s0 += v[0][e]; s1 += v[1][e]; }
;         const float mu0 = wsum(s0) * (1.f / 1024.f), mu1 = wsum(s1) * (1.f / 1024.f);
.LBB0_1515:
	v_add_co_u32_e32 v50, vcc, 0xee400000, v46
	v_add_u32_e32 v41, s42, v40
	s_nop 0
	v_addc_co_u32_e32 v51, vcc, -1, v47, vcc
	global_load_dwordx4 v[54:57], v[50:51], off
	v_add_co_u32_e32 v50, vcc, 0xee401000, v46
	s_mov_b32 s15, 0x8200
	s_nop 0
	v_addc_co_u32_e32 v51, vcc, -1, v47, vcc
	v_cmp_gt_i32_e64 s[36:37], s15, v41
	global_load_dwordx4 v[58:61], v[50:51], off offset:-3072
	global_load_dwordx4 v[32:35], v[46:47], off
	global_load_dwordx4 v[36:39], v[46:47], off offset:1024
	v_cndmask_b32_e64 v50, v40, v41, s[36:37]
	v_ashrrev_i32_e32 v51, 31, v50
	v_lshlrev_b64 v[52:53], 11, v[50:51]
	v_lshl_or_b32 v70, v42, 1, v52
	v_mov_b32_e32 v71, v53
	v_mov_b32_e32 v75, v53
	v_or_b32_e32 v74, 0x400, v70
	v_lshl_add_u64 v[62:63], s[82:83], 0, v[70:71]
	v_lshl_add_u64 v[66:67], s[76:77], 0, v[70:71]
	v_lshl_add_u64 v[70:71], s[82:83], 0, v[74:75]
	v_lshl_add_u64 v[74:75], s[76:77], 0, v[74:75]
	global_load_dwordx4 v[62:65], v[62:63], off
	s_mov_b32 s30, 0x3a800000
	global_load_dwordx4 v[66:69], v[66:67], off
	s_waitcnt vmcnt(5)
	v_lshlrev_b32_e32 v90, 16, v54
	global_load_dwordx4 v[70:73], v[70:71], off
	v_and_b32_e32 v91, 0xffff0000, v54
	global_load_dwordx4 v[74:77], v[74:75], off
	v_lshlrev_b32_e32 v54, 16, v55
	v_and_b32_e32 v55, 0xffff0000, v55
	v_lshlrev_b32_e32 v92, 16, v56
	s_waitcnt vmcnt(6)
	v_lshlrev_b32_e32 v94, 16, v58
	s_waitcnt vmcnt(5)
	v_lshlrev_b32_e32 v78, 16, v32
	v_and_b32_e32 v79, 0xffff0000, v32
	s_waitcnt vmcnt(4)
	v_lshlrev_b32_e32 v88, 16, v36
	v_and_b32_e32 v89, 0xffff0000, v36
	v_lshlrev_b32_e32 v36, 16, v37
	v_and_b32_e32 v37, 0xffff0000, v37
	v_and_b32_e32 v95, 0xffff0000, v58
	v_lshlrev_b32_e32 v58, 16, v59
	v_and_b32_e32 v59, 0xffff0000, v59
	v_pk_fma_f32 v[78:79], v[90:91], s[52:53], v[78:79] op_sel_hi:[1,0,1]
	v_lshlrev_b32_e32 v32, 16, v33
	v_and_b32_e32 v33, 0xffff0000, v33
	v_pk_fma_f32 v[36:37], v[58:59], s[52:53], v[36:37] op_sel_hi:[1,0,1]
	s_waitcnt vmcnt(3)
	v_lshlrev_b32_e32 v98, 16, v62
	v_and_b32_e32 v99, 0xffff0000, v62
	s_waitcnt vmcnt(2)
	v_lshlrev_b32_e32 v102, 16, v66
	v_and_b32_e32 v103, 0xffff0000, v66
	v_lshlrev_b32_e32 v62, 16, v63
	v_and_b32_e32 v63, 0xffff0000, v63
	v_lshlrev_b32_e32 v66, 16, v67
	v_and_b32_e32 v67, 0xffff0000, v67
	v_pk_fma_f32 v[62:63], v[62:63], s[52:53], v[66:67] op_sel_hi:[1,0,1]
	v_lshlrev_b32_e32 v100, 16, v64
	v_and_b32_e32 v101, 0xffff0000, v64
	v_lshlrev_b32_e32 v104, 16, v68
	v_and_b32_e32 v105, 0xffff0000, v68
	v_pk_fma_f32 v[66:67], v[100:101], s[52:53], v[104:105] op_sel_hi:[1,0,1]
	v_lshlrev_b32_e32 v64, 16, v65
	v_and_b32_e32 v65, 0xffff0000, v65
	v_lshlrev_b32_e32 v68, 16, v69
	v_and_b32_e32 v69, 0xffff0000, v69
	v_add_f32_e32 v59, 0, v78
	v_add_f32_e32 v59, v79, v59
	v_pk_fma_f32 v[32:33], v[54:55], s[52:53], v[32:33] op_sel_hi:[1,0,1]
	v_lshlrev_b32_e32 v80, 16, v34
	v_and_b32_e32 v81, 0xffff0000, v34
	v_and_b32_e32 v93, 0xffff0000, v56
	v_add_f32_e32 v54, v32, v59
	v_add_f32_e32 v54, v33, v54
	v_pk_fma_f32 v[80:81], v[92:93], s[52:53], v[80:81] op_sel_hi:[1,0,1]
	v_lshlrev_b32_e32 v34, 16, v35
	v_and_b32_e32 v35, 0xffff0000, v35
	v_lshlrev_b32_e32 v56, 16, v57
	v_and_b32_e32 v57, 0xffff0000, v57
	v_add_f32_e32 v54, v80, v54
	v_add_f32_e32 v54, v81, v54
	v_pk_fma_f32 v[34:35], v[56:57], s[52:53], v[34:35] op_sel_hi:[1,0,1]
	v_pk_fma_f32 v[88:89], v[94:95], s[52:53], v[88:89] op_sel_hi:[1,0,1]
	v_add_f32_e32 v54, v34, v54
	v_add_f32_e32 v54, v35, v54
	v_add_f32_e32 v54, v54, v88
	v_add_f32_e32 v54, v89, v54
	v_lshlrev_b32_e32 v96, 16, v60
	v_and_b32_e32 v97, 0xffff0000, v60
	v_add_f32_e32 v54, v36, v54
	v_add_f32_e32 v54, v37, v54
	v_lshlrev_b32_e32 v60, 16, v61
	v_and_b32_e32 v61, 0xffff0000, v61
	s_waitcnt vmcnt(1)
	v_lshlrev_b32_e32 v108, 16, v72
	v_and_b32_e32 v109, 0xffff0000, v72
	v_lshlrev_b32_e32 v72, 16, v73
	v_and_b32_e32 v73, 0xffff0000, v73
	s_waitcnt vmcnt(0)
	v_lshlrev_b32_e32 v112, 16, v76
	v_and_b32_e32 v113, 0xffff0000, v76
	v_lshlrev_b32_e32 v76, 16, v77
	v_and_b32_e32 v77, 0xffff0000, v77
	v_pk_fma_f32 v[72:73], v[72:73], s[52:53], v[76:77] op_sel_hi:[1,0,1]
	v_pk_fma_f32 v[76:77], v[98:99], s[52:53], v[102:103] op_sel_hi:[1,0,1]
	v_pk_fma_f32 v[98:99], v[64:65], s[52:53], v[68:69] op_sel_hi:[1,0,1]
	v_add_f32_e32 v41, 0, v76
	v_add_f32_e32 v41, v77, v41
	v_add_f32_e32 v41, v62, v41
	v_add_f32_e32 v41, v63, v41
	v_add_f32_e32 v41, v66, v41
	v_add_f32_e32 v41, v67, v41
	v_lshlrev_b32_e32 v106, 16, v70
	v_and_b32_e32 v107, 0xffff0000, v70
	v_lshlrev_b32_e32 v110, 16, v74
	v_and_b32_e32 v111, 0xffff0000, v74
	v_add_f32_e32 v41, v98, v41
	v_pk_fma_f32 v[106:107], v[106:107], s[52:53], v[110:111] op_sel_hi:[1,0,1]
	v_add_f32_e32 v41, v99, v41
	v_lshlrev_b32_e32 v70, 16, v71
	v_and_b32_e32 v71, 0xffff0000, v71
	v_lshlrev_b32_e32 v74, 16, v75
	v_and_b32_e32 v75, 0xffff0000, v75
	v_add_f32_e32 v41, v41, v106
	v_pk_fma_f32 v[70:71], v[70:71], s[52:53], v[74:75] op_sel_hi:[1,0,1]
	v_add_f32_e32 v41, v107, v41
	v_add_f32_e32 v41, v70, v41
	v_pk_fma_f32 v[74:75], v[108:109], s[52:53], v[112:113] op_sel_hi:[1,0,1]
	v_add_f32_e32 v41, v71, v41
	v_add_f32_e32 v41, v74, v41
	v_add_f32_e32 v41, v75, v41
	v_add_f32_e32 v41, v72, v41
	v_add_f32_e32 v41, v73, v41
	v_mov_b32_e32 v68, v41
	v_lshlrev_b32_e32 v64, 16, v38
	v_and_b32_e32 v65, 0xffff0000, v38
	v_pk_fma_f32 v[94:95], v[96:97], s[52:53], v[64:65] op_sel_hi:[1,0,1]
	v_lshlrev_b32_e32 v38, 16, v39
	s_waitcnt lgkmcnt(0)
	s_nop 1
	v_permlane32_swap_b32_e32 v41, v68
	v_add_f32_e32 v41, v41, v68
	v_mov_b32_e32 v68, v41
	v_and_b32_e32 v39, 0xffff0000, v39
	v_add_f32_e32 v54, v94, v54
	v_pk_fma_f32 v[38:39], v[60:61], s[52:53], v[38:39] op_sel_hi:[1,0,1]
	v_add_f32_e32 v54, v95, v54
	s_waitcnt lgkmcnt(0)
; DI void stf8(float* p, const F8& f) { *(float4*)p = make_float4(f.v[0], f.v[1], f.v[2], f.v[3]); *(float4*)(p + 4) = make_float4(f.v[4], f.v[5], f.v[6], f.v[7]); }
; DI void stb8(bf16_t* p, const F8& f) { *(uint4*)p = pack8(f); }
; DI float wsum(float v) { v += __shfl_xor(v, 32); v += __shfl_xor(v, 16); v += __shfl_xor(v, 8); v += __shfl_xor(v, 4); v += __shfl_xor(v, 2); v += __shfl_xor(v, 1); return v; }
; DI void ln_phase(const Params& p, const bf16_t* __restrict__ Y, const float* __restrict__ g, const float* __restrict__ b, bool final_out) {
;     ...
;         const float mu0 = wsum(s0) * (1.f / 1024.f), mu1 = wsum(s1) * (1.f / 1024.f);
;         float q0 = 0.f, q1 = 0.f;
; #pragma unroll
;         for (int e = 0; e < 16; ++e) { const float d0 = v[0][e] - mu0, d1 = v[1][e] - mu1; q0 += d0 * d0; q1 += d1 * d1; }
;         const float rs0 = rsqrtf(wsum(q0) * (1.f / 1024.f) + EPS), rs1 = rsqrtf(wsum(q1) * (1.f / 1024.f) + EPS);
; #pragma unroll
;         for (int q = 0; q < 2; ++q) {
;             if (q == 1 && !two) break;
;             const float mu = q ? mu1 : mu0, rs = q ? rs1 : rs0;
; #pragma unroll
;             for (int it = 0; it < 2; ++it) {
;                 const int c = it * 512 + lane * 8;
;                 F8 o;
; #pragma unroll
;                 for (int e = 0; e < 8; ++e) o.v[e] = (v[q][it * 8 + e] - mu) * rs * gg[it].v[e] + bb[it].v[e];
;                 if (final_out) stf8(p.out + (size_t)rr[q] * 1024 + c, o);
;                 else stb8(XB + (size_t)rr[q] * 1024 + c, o);
	s_nop 1
	v_permlane16_swap_b32_e32 v41, v68
	v_add_f32_e32 v41, v41, v68
	v_add_f32_e32 v54, v38, v54
	v_add_f32_e32 v54, v39, v54
	v_mov_b32_e32 v55, v54
	s_waitcnt lgkmcnt(1)
	s_nop 1
	v_add_f32_dpp v41, v41, v41 row_ror:8 row_mask:0xf bank_mask:0xf
	s_waitcnt lgkmcnt(1)
	s_nop 1
	v_permlane32_swap_b32_e32 v54, v55
	v_add_f32_e32 v54, v54, v55
	v_mov_b32_e32 v55, v54
	s_waitcnt lgkmcnt(1)
	s_nop 1
	v_add_f32_dpp v41, v41, v41 row_ror:4 row_mask:0xf bank_mask:0xf
	s_waitcnt lgkmcnt(1)
	s_nop 1
	v_permlane16_swap_b32_e32 v54, v55
	v_add_f32_e32 v54, v54, v55
	s_waitcnt lgkmcnt(1)
	s_nop 1
	v_add_f32_dpp v41, v41, v41 row_ror:2 row_mask:0xf bank_mask:0xf
	s_waitcnt lgkmcnt(1)
	s_nop 1
	v_add_f32_dpp v54, v54, v54 row_ror:8 row_mask:0xf bank_mask:0xf
	s_waitcnt lgkmcnt(1)
	s_nop 1
	v_add_f32_dpp v41, v41, v41 row_ror:1 row_mask:0xf bank_mask:0xf
	v_mul_f32_e32 v60, 0x3a800000, v41
	s_waitcnt lgkmcnt(0)
	s_nop 1
	v_add_f32_dpp v41, v54, v54 row_ror:4 row_mask:0xf bank_mask:0xf
	v_pk_add_f32 v[54:55], v[70:71], v[60:61] op_sel_hi:[1,0] neg_lo:[0,1] neg_hi:[0,1]
	v_pk_add_f32 v[68:69], v[76:77], v[60:61] op_sel_hi:[1,0] neg_lo:[0,1] neg_hi:[0,1]
	v_pk_add_f32 v[64:65], v[62:63], v[60:61] op_sel_hi:[1,0] neg_lo:[0,1] neg_hi:[0,1]
	v_pk_add_f32 v[66:67], v[66:67], v[60:61] op_sel_hi:[1,0] neg_lo:[0,1] neg_hi:[0,1]
	s_waitcnt lgkmcnt(0)
	s_nop 1
	v_add_f32_dpp v41, v41, v41 row_ror:2 row_mask:0xf bank_mask:0xf
	v_pk_add_f32 v[62:63], v[98:99], v[60:61] op_sel_hi:[1,0] neg_lo:[0,1] neg_hi:[0,1]
	v_pk_add_f32 v[56:57], v[106:107], v[60:61] op_sel_hi:[1,0] neg_lo:[0,1] neg_hi:[0,1]
	v_pk_add_f32 v[58:59], v[74:75], v[60:61] op_sel_hi:[1,0] neg_lo:[0,1] neg_hi:[0,1]
	v_pk_add_f32 v[60:61], v[72:73], v[60:61] op_sel_hi:[1,0] neg_lo:[0,1] neg_hi:[0,1]
	s_waitcnt lgkmcnt(0)
	s_nop 1
	v_add_f32_dpp v41, v41, v41 row_ror:1 row_mask:0xf bank_mask:0xf
	v_mul_f32_e32 v92, 0x3a800000, v41
	v_pk_add_f32 v[96:97], v[78:79], v[92:93] op_sel_hi:[1,0] neg_lo:[0,1] neg_hi:[0,1]
	v_mov_b32_e32 v73, v69
	v_mov_b32_e32 v72, v97
	v_mov_b32_e32 v70, v96
	v_mov_b32_e32 v71, v68
	v_pk_mul_f32 v[72:73], v[72:73], v[72:73]
	v_pk_add_f32 v[32:33], v[32:33], v[92:93] op_sel_hi:[1,0] neg_lo:[0,1] neg_hi:[0,1]
	v_pk_fma_f32 v[78:79], v[70:71], v[70:71], v[72:73]
	v_mov_b32_e32 v98, v32
	v_mov_b32_e32 v99, v64
	v_pk_add_f32 v[100:101], v[80:81], v[92:93] op_sel_hi:[1,0] neg_lo:[0,1] neg_hi:[0,1]
	v_pk_fma_f32 v[78:79], v[98:99], v[98:99], v[78:79]
	v_mov_b32_e32 v80, v33
	v_mov_b32_e32 v81, v65
	v_pk_fma_f32 v[78:79], v[80:81], v[80:81], v[78:79]
	v_mov_b32_e32 v80, v100
	v_mov_b32_e32 v81, v66
	v_pk_add_f32 v[34:35], v[34:35], v[92:93] op_sel_hi:[1,0] neg_lo:[0,1] neg_hi:[0,1]
	v_pk_fma_f32 v[78:79], v[80:81], v[80:81], v[78:79]
	v_mov_b32_e32 v80, v101
	v_mov_b32_e32 v81, v67
	v_pk_fma_f32 v[78:79], v[80:81], v[80:81], v[78:79]
	v_mov_b32_e32 v80, v34
	v_mov_b32_e32 v81, v62
	v_pk_add_f32 v[74:75], v[88:89], v[92:93] op_sel_hi:[1,0] neg_lo:[0,1] neg_hi:[0,1]
	v_pk_fma_f32 v[78:79], v[80:81], v[80:81], v[78:79]
	v_mov_b32_e32 v80, v35
	v_mov_b32_e32 v81, v63
	v_pk_fma_f32 v[78:79], v[80:81], v[80:81], v[78:79]
	v_mov_b32_e32 v80, v74
	v_mov_b32_e32 v81, v56
	v_pk_add_f32 v[72:73], v[36:37], v[92:93] op_sel_hi:[1,0] neg_lo:[0,1] neg_hi:[0,1]
	v_pk_fma_f32 v[78:79], v[80:81], v[80:81], v[78:79]
	v_mov_b32_e32 v80, v75
	v_mov_b32_e32 v81, v57
	v_pk_add_f32 v[70:71], v[94:95], v[92:93] op_sel_hi:[1,0] neg_lo:[0,1] neg_hi:[0,1]
	v_pk_fma_f32 v[78:79], v[80:81], v[80:81], v[78:79]
	v_mov_b32_e32 v80, v72
	v_mov_b32_e32 v81, v54
	v_pk_mul_f32 v[76:77], v[58:59], v[58:59]
	v_pk_mul_f32 v[36:37], v[70:71], v[70:71]
	v_pk_fma_f32 v[78:79], v[80:81], v[80:81], v[78:79]
	v_mov_b32_e32 v80, v73
	v_mov_b32_e32 v81, v55
	v_pk_fma_f32 v[78:79], v[80:81], v[80:81], v[78:79]
	v_mov_b32_e32 v80, v36
	v_mov_b32_e32 v81, v76
	v_pk_add_f32 v[80:81], v[80:81], v[78:79]
	v_pk_add_f32 v[78:79], v[38:39], v[92:93] op_sel_hi:[1,0] neg_lo:[0,1] neg_hi:[0,1]
	v_pk_mul_f32 v[90:91], v[60:61], v[60:61]
	v_pk_mul_f32 v[38:39], v[78:79], v[78:79]
	v_mov_b32_e32 v76, v37
	v_pk_add_f32 v[36:37], v[76:77], v[80:81]
	v_mov_b32_e32 v76, v38
	v_mov_b32_e32 v77, v90
	v_pk_add_f32 v[36:37], v[76:77], v[36:37]
	v_mov_b32_e32 v90, v39
	v_pk_add_f32 v[36:37], v[90:91], v[36:37]
	ds_bpermute_b32 v39, v43, v37
	ds_bpermute_b32 v38, v43, v36
	s_waitcnt lgkmcnt(0)
	v_pk_add_f32 v[36:37], v[36:37], v[38:39]
	ds_bpermute_b32 v39, v82, v37
	ds_bpermute_b32 v38, v82, v36
	s_waitcnt lgkmcnt(0)
	v_pk_add_f32 v[36:37], v[36:37], v[38:39]
	s_waitcnt lgkmcnt(0)
	s_nop 1
	v_add_f32_dpp v36, v36, v36 row_ror:8 row_mask:0xf bank_mask:0xf
	v_add_f32_dpp v37, v37, v37 row_ror:8 row_mask:0xf bank_mask:0xf
	s_waitcnt lgkmcnt(0)
	s_nop 1
	v_add_f32_dpp v36, v36, v36 row_ror:4 row_mask:0xf bank_mask:0xf
	v_add_f32_dpp v37, v37, v37 row_ror:4 row_mask:0xf bank_mask:0xf
	s_waitcnt lgkmcnt(0)
	s_nop 1
	v_add_f32_dpp v36, v36, v36 row_ror:2 row_mask:0xf bank_mask:0xf
	v_add_f32_dpp v37, v37, v37 row_ror:2 row_mask:0xf bank_mask:0xf
	ds_bpermute_b32 v39, v86, v37
	ds_bpermute_b32 v38, v86, v36
	s_waitcnt lgkmcnt(0)
	v_pk_add_f32 v[36:37], v[36:37], v[38:39]
	v_mov_b32_e32 v38, 0x358637bd
	v_pk_fma_f32 v[76:77], v[36:37], s[30:31], v[38:39] op_sel_hi:[1,0,0]
	s_mov_b64 s[30:31], -1
	v_mul_f32_e32 v36, 0x4b800000, v76
	v_cmp_gt_f32_e32 vcc, s2, v76
	v_cmp_gt_f32_e64 s[38:39], s2, v77
	s_nop 0
	v_cndmask_b32_e32 v36, v76, v36, vcc
	v_rsq_f32_e32 v36, v36
	s_nop 0
	v_mul_f32_e32 v37, 0x45800000, v36
	v_cndmask_b32_e32 v80, v36, v37, vcc
	v_pk_mul_f32 v[32:33], v[32:33], v[80:81] op_sel_hi:[1,0]
	v_pk_mul_f32 v[36:37], v[96:97], v[80:81] op_sel_hi:[1,0]
	v_pk_fma_f32 v[38:39], v[6:7], v[32:33], v[14:15]
	v_pk_mul_f32 v[32:33], v[100:101], v[80:81] op_sel_hi:[1,0]
	v_pk_mul_f32 v[34:35], v[34:35], v[80:81] op_sel_hi:[1,0]
	v_pk_fma_f32 v[36:37], v[4:5], v[36:37], v[12:13]
	v_pk_fma_f32 v[32:33], v[0:1], v[32:33], v[8:9]
	v_pk_fma_f32 v[34:35], v[2:3], v[34:35], v[10:11]
	s_and_b64 vcc, exec, s[0:1]
	s_cbranch_vccz .LBB0_1517
	s_mov_b32 s30, 0xee400000
	s_mov_b32 s31, -1
	v_lshl_add_u64 v[92:93], v[46:47], 0, s[30:31]
	v_cvt_pk_bf16_f32 v88, v36, v37
	v_cvt_pk_bf16_f32 v89, v38, v39
	v_cvt_pk_bf16_f32 v90, v32, v33
	v_cvt_pk_bf16_f32 v91, v34, v35
	global_store_dwordx4 v[92:93], v[88:91], off sc1
	s_mov_b64 s[30:31], 0
.LBB0_1517:
	s_andn2_b64 vcc, exec, s[30:31]
	s_cbranch_vccnz .LBB0_1519
	global_store_dwordx4 v[48:49], v[36:39], off offset:-2048 sc1
	global_store_dwordx4 v[48:49], v[32:35], off offset:-2032 sc1

; DI void stf8(float* p, const F8& f) { *(float4*)p = make_float4(f.v[0], f.v[1], f.v[2], f.v[3]); *(float4*)(p + 4) = make_float4(f.v[4], f.v[5], f.v[6], f.v[7]); }
; DI void stb8(bf16_t* p, const F8& f) { *(uint4*)p = pack8(f); }
; DI void ln_phase(const Params& p, const bf16_t* __restrict__ Y, const float* __restrict__ g, const float* __restrict__ b, bool final_out) {
;     ...
;         for (int q = 0; q < 2; ++q) {
;             if (q == 1 && !two) break;
;             const float mu = q ? mu1 : mu0, rs = q ? rs1 : rs0;
; #pragma unroll
;             for (int it = 0; it < 2; ++it) {
;                 const int c = it * 512 + lane * 8;
;                 F8 o;
; #pragma unroll
;                 for (int e = 0; e < 8; ++e) o.v[e] = (v[q][it * 8 + e] - mu) * rs * gg[it].v[e] + bb[it].v[e];
;                 if (final_out) stf8(p.out + (size_t)rr[q] * 1024 + c, o);
;                 else stb8(XB + (size_t)rr[q] * 1024 + c, o);
;             }
;         }
.LBB0_1522:
	s_mov_b32 s30, 0xee400400
	s_mov_b32 s31, -1
	v_lshl_add_u64 v[74:75], v[46:47], 0, s[30:31]
	v_cvt_pk_bf16_f32 v70, v36, v37
	v_cvt_pk_bf16_f32 v71, v38, v39
	v_cvt_pk_bf16_f32 v72, v32, v33
	v_cvt_pk_bf16_f32 v73, v34, v35
	global_store_dwordx4 v[74:75], v[70:73], off sc1
	s_cbranch_execnz .LBB0_1521
.LBB0_1523:
	global_store_dwordx4 v[48:49], v[36:39], off sc1
	global_store_dwordx4 v[48:49], v[32:35], off offset:16 sc1
	s_and_saveexec_b64 s[30:31], s[36:37]
	s_cbranch_execz .LBB0_1514
.LBB0_1524:
	v_mul_f32_e32 v32, 0x4b800000, v77
	v_cndmask_b32_e64 v32, v77, v32, s[38:39]
	v_rsq_f32_e32 v32, v32
	v_lshl_add_u64 v[52:53], s[82:83], 0, v[52:53]
	s_mov_b64 s[36:37], -1
	s_and_b64 vcc, exec, s[40:41]
	v_mul_f32_e32 v33, 0x45800000, v32
	v_cndmask_b32_e64 v70, v32, v33, s[38:39]
	v_pk_mul_f32 v[32:33], v[68:69], v[70:71] op_sel_hi:[1,0]
	v_pk_mul_f32 v[34:35], v[64:65], v[70:71] op_sel_hi:[1,0]
	v_pk_fma_f32 v[36:37], v[4:5], v[32:33], v[12:13]
	v_pk_fma_f32 v[38:39], v[6:7], v[34:35], v[14:15]
	v_pk_mul_f32 v[32:33], v[66:67], v[70:71] op_sel_hi:[1,0]
	v_pk_mul_f32 v[34:35], v[62:63], v[70:71] op_sel_hi:[1,0]
	v_pk_fma_f32 v[32:33], v[0:1], v[32:33], v[8:9]
	v_pk_fma_f32 v[34:35], v[2:3], v[34:35], v[10:11]
	v_lshlrev_b32_e32 v212, 1, v42
	s_cbranch_vccnz .LBB0_1526
	v_lshl_add_u64 v[66:67], v[52:53], 0, v[212:213]
	v_cvt_pk_bf16_f32 v62, v36, v37
	v_cvt_pk_bf16_f32 v63, v38, v39
	v_cvt_pk_bf16_f32 v64, v32, v33
	v_cvt_pk_bf16_f32 v65, v34, v35
	s_mov_b64 s[36:37], 0
	global_store_dwordx4 v[66:67], v[62:65], off sc1
.LBB0_1526:
	v_lshlrev_b64 v[50:51], 12, v[50:51]
	s_andn2_b64 vcc, exec, s[36:37]
	v_lshl_add_u64 v[50:51], v[44:45], 0, v[50:51]
	s_cbranch_vccnz .LBB0_1528
	global_store_dwordx4 v[50:51], v[36:39], off sc1
	global_store_dwordx4 v[50:51], v[32:35], off offset:16 sc1
.LBB0_1528:
	v_mov_b32_e32 v71, v70
	s_nop 0
	v_pk_mul_f32 v[32:33], v[56:57], v[70:71]
	v_pk_mul_f32 v[34:35], v[60:61], v[70:71]
	v_pk_fma_f32 v[36:37], v[20:21], v[32:33], v[28:29]
	v_pk_mul_f32 v[32:33], v[54:55], v[70:71]
	v_pk_fma_f32 v[34:35], v[18:19], v[34:35], v[26:27]
	v_pk_fma_f32 v[38:39], v[22:23], v[32:33], v[30:31]
	v_pk_mul_f32 v[32:33], v[58:59], v[70:71]
	s_and_b64 vcc, exec, s[40:41]
	v_pk_fma_f32 v[32:33], v[16:17], v[32:33], v[24:25]
	s_mov_b64 s[36:37], -1
	s_cbranch_vccnz .LBB0_1530
	v_lshl_add_u64 v[56:57], v[52:53], 0, v[212:213]
	v_cvt_pk_bf16_f32 v52, v36, v37
	v_cvt_pk_bf16_f32 v53, v38, v39
	v_cvt_pk_bf16_f32 v54, v32, v33
	v_cvt_pk_bf16_f32 v55, v34, v35
	s_mov_b64 s[36:37], 0
	global_store_dwordx4 v[56:57], v[52:55], off offset:1024 sc1
.LBB0_1530:
	s_andn2_b64 vcc, exec, s[36:37]
	s_cbranch_vccnz .LBB0_1514
	global_store_dwordx4 v[50:51], v[36:39], off offset:2048 sc1
	global_store_dwordx4 v[50:51], v[32:35], off offset:2064 sc1
	s_branch .LBB0_1514

; DI void stb8(bf16_t* p, const F8& f) { *(uint4*)p = pack8(f); }
; DI void wconv(const float* __restrict__ src, bf16_t* __restrict__ dst, int K, int N, int Npad, int perm, unsigned char* smem) {
;     ...
;             const int k = (tid >> 4) + 32 * j, nl4 = (tid & 15) * 4, n = n0 + nl4;
;             float4 v = make_float4(0.f, 0.f, 0.f, 0.f);
;             if (n < N) v = *(const float4*)(src + (size_t)(k0 + k) * N + n);
;             float* tp = tile + k * 65 + nl4; tp[0] = v.x; tp[1] = v.y; tp[2] = v.z; tp[3] = v.w;
;         }
;         __syncthreads();
;         const int nl = tid >> 3, kc = (tid & 7) * 8, n = n0 + nl;
;         if (n < Npad) {
;             int nd = n;
;             if (perm) nd = n < 2816 ? (n >> 6) * 128 + (n & 63) : ((n - 2816) >> 6) * 128 + 64 + ((n - 2816) & 63);
;             F8 a;
; #pragma unroll
;             for (int e = 0; e < 8; ++e) a.v[e] = tile[(kc + e) * 65 + nl];
;             stb8(dst + (size_t)nd * K + k0 + kc, a);
;         }
;         __syncthreads();
.LBB0_1539:
	s_or_b64 exec, exec, s[14:15]
	s_waitcnt vmcnt(1)
	ds_write2_b32 v13, v0, v1 offset1:1
	ds_write2_b32 v13, v2, v3 offset0:2 offset1:3
	v_add_u32_e32 v0, 0x2080, v13
	s_waitcnt vmcnt(0)
	ds_write2_b32 v0, v4, v5 offset1:1
	v_add_u32_e32 v0, 0x2088, v13
	ds_write2_b32 v0, v6, v7 offset1:1
	v_add_u32_e32 v0, s7, v12
	s_movk_i32 s7, 0x900
	v_cmp_gt_i32_e32 vcc, s7, v0
	s_waitcnt lgkmcnt(0)
	s_barrier
	s_and_saveexec_b64 s[14:15], vcc
	s_cbranch_execz .LBB0_1536
	v_add_u32_e32 v1, 0x400, v14
	ds_read2_b32 v[2:3], v14 offset1:65
	ds_read2_b32 v[4:5], v14 offset0:130 offset1:195
	ds_read2_b32 v[6:7], v1 offset0:4 offset1:69
	ds_read2_b32 v[8:9], v1 offset0:134 offset1:199
	v_ashrrev_i32_e32 v1, 31, v0
	v_lshlrev_b64 v[0:1], 11, v[0:1]
	v_lshl_add_u64 v[0:1], s[62:63], 0, v[0:1]
	s_ashr_i32 s7, s6, 31
	v_lshl_add_u64 v[0:1], s[6:7], 1, v[0:1]
	v_lshl_add_u64 v[16:17], v[0:1], 0, v[212:213]
	s_waitcnt lgkmcnt(3)
	v_cvt_pk_bf16_f32 v0, v2, v3
	s_waitcnt lgkmcnt(2)
	v_cvt_pk_bf16_f32 v1, v4, v5
	s_waitcnt lgkmcnt(1)
	v_cvt_pk_bf16_f32 v2, v6, v7
	s_waitcnt lgkmcnt(0)
	v_cvt_pk_bf16_f32 v3, v8, v9
	global_store_dwordx4 v[16:17], v[0:3], off sc1
	s_branch .LBB0_1536

; DI void stb8(bf16_t* p, const F8& f) { *(uint4*)p = pack8(f); }
; DI void wconv(const float* __restrict__ src, bf16_t* __restrict__ dst, int K, int N, int Npad, int perm, unsigned char* smem) {
;     ...
;             const int k = (tid >> 4) + 32 * j, nl4 = (tid & 15) * 4, n = n0 + nl4;
;             float4 v = make_float4(0.f, 0.f, 0.f, 0.f);
;             if (n < N) v = *(const float4*)(src + (size_t)(k0 + k) * N + n);
;             float* tp = tile + k * 65 + nl4; tp[0] = v.x; tp[1] = v.y; tp[2] = v.z; tp[3] = v.w;
;         }
;         __syncthreads();
;         const int nl = tid >> 3, kc = (tid & 7) * 8, n = n0 + nl;
;         if (n < Npad) {
;             int nd = n;
;             if (perm) nd = n < 2816 ? (n >> 6) * 128 + (n & 63) : ((n - 2816) >> 6) * 128 + 64 + ((n - 2816) & 63);
;             F8 a;
; #pragma unroll
;             for (int e = 0; e < 8; ++e) a.v[e] = tile[(kc + e) * 65 + nl];
;             stb8(dst + (size_t)nd * K + k0 + kc, a);
;         }
;         __syncthreads();
.LBB0_1546:
	s_or_b64 exec, exec, s[14:15]
	s_waitcnt vmcnt(1)
	ds_write2_b32 v13, v0, v1 offset1:1
	ds_write2_b32 v13, v2, v3 offset0:2 offset1:3
	v_add_u32_e32 v0, 0x2080, v13
	s_waitcnt vmcnt(0)
	ds_write2_b32 v0, v4, v5 offset1:1
	v_add_u32_e32 v0, 0x2088, v13
	ds_write2_b32 v0, v6, v7 offset1:1
	v_add_u32_e32 v0, s7, v12
	v_cmp_gt_i32_e32 vcc, s23, v0
	s_waitcnt lgkmcnt(0)
	s_barrier
	s_and_saveexec_b64 s[14:15], vcc
	s_cbranch_execz .LBB0_1543
	v_add_u32_e32 v1, 0x400, v14
	ds_read2_b32 v[2:3], v14 offset1:65
	ds_read2_b32 v[4:5], v14 offset0:130 offset1:195
	ds_read2_b32 v[6:7], v1 offset0:4 offset1:69
	ds_read2_b32 v[8:9], v1 offset0:134 offset1:199
	v_readlane_b32 s26, v252, 43
	v_readlane_b32 s27, v252, 44
	s_ashr_i32 s7, s6, 31
	s_nop 0
	v_mov_b64_e32 v[16:17], s[26:27]
	v_mad_i64_i32 v[0:1], s[26:27], v0, s23, v[16:17]
	v_lshl_add_u64 v[0:1], s[6:7], 1, v[0:1]
	v_lshl_add_u64 v[16:17], v[0:1], 0, v[212:213]
	s_waitcnt lgkmcnt(3)
	v_cvt_pk_bf16_f32 v0, v2, v3
	s_waitcnt lgkmcnt(2)
	v_cvt_pk_bf16_f32 v1, v4, v5
	s_waitcnt lgkmcnt(1)
	v_cvt_pk_bf16_f32 v2, v6, v7
	s_waitcnt lgkmcnt(0)
	v_cvt_pk_bf16_f32 v3, v8, v9
	global_store_dwordx4 v[16:17], v[0:3], off sc1
	s_branch .LBB0_1543

; DI void stb8(bf16_t* p, const F8& f) { *(uint4*)p = pack8(f); }
; DI void wconv(const float* __restrict__ src, bf16_t* __restrict__ dst, int K, int N, int Npad, int perm, unsigned char* smem) {
;     ...
;             const int k = (tid >> 4) + 32 * j, nl4 = (tid & 15) * 4, n = n0 + nl4;
;             float4 v = make_float4(0.f, 0.f, 0.f, 0.f);
;             if (n < N) v = *(const float4*)(src + (size_t)(k0 + k) * N + n);
;             float* tp = tile + k * 65 + nl4; tp[0] = v.x; tp[1] = v.y; tp[2] = v.z; tp[3] = v.w;
;         }
;         __syncthreads();
;         const int nl = tid >> 3, kc = (tid & 7) * 8, n = n0 + nl;
;         if (n < Npad) {
;             int nd = n;
;             if (perm) nd = n < 2816 ? (n >> 6) * 128 + (n & 63) : ((n - 2816) >> 6) * 128 + 64 + ((n - 2816) & 63);
;             F8 a;
; #pragma unroll
;             for (int e = 0; e < 8; ++e) a.v[e] = tile[(kc + e) * 65 + nl];
;             stb8(dst + (size_t)nd * K + k0 + kc, a);
;         }
;         __syncthreads();
.LBB0_1554:
	s_or_b64 exec, exec, s[14:15]
	s_waitcnt vmcnt(1)
	ds_write2_b32 v13, v0, v1 offset1:1
	ds_write2_b32 v13, v2, v3 offset0:2 offset1:3
	v_add_u32_e32 v0, 0x2080, v13
	s_waitcnt vmcnt(0)
	ds_write2_b32 v0, v4, v5 offset1:1
	v_add_u32_e32 v0, 0x2088, v13
	ds_write2_b32 v0, v6, v7 offset1:1
	v_add_u32_e32 v0, s7, v12
	v_cmp_gt_i32_e32 vcc, s19, v0
	s_waitcnt lgkmcnt(0)
	s_barrier
	s_and_saveexec_b64 s[14:15], vcc
	s_cbranch_execz .LBB0_1551
	v_add_u32_e32 v1, 0x400, v14
	ds_read2_b32 v[2:3], v14 offset1:65
	ds_read2_b32 v[4:5], v14 offset0:130 offset1:195
	ds_read2_b32 v[6:7], v1 offset0:4 offset1:69
	ds_read2_b32 v[8:9], v1 offset0:134 offset1:199
	v_ashrrev_i32_e32 v1, 31, v0
	v_readlane_b32 s26, v252, 45
	v_lshlrev_b64 v[0:1], 9, v[0:1]
	v_readlane_b32 s27, v252, 46
	s_ashr_i32 s7, s6, 31
	s_nop 0
	v_lshl_add_u64 v[0:1], s[26:27], 0, v[0:1]
	v_lshl_add_u64 v[0:1], s[6:7], 1, v[0:1]
	v_lshl_add_u64 v[16:17], v[0:1], 0, v[212:213]
	s_waitcnt lgkmcnt(3)
	v_cvt_pk_bf16_f32 v0, v2, v3
	s_waitcnt lgkmcnt(2)
	v_cvt_pk_bf16_f32 v1, v4, v5
	s_waitcnt lgkmcnt(1)
	v_cvt_pk_bf16_f32 v2, v6, v7
	s_waitcnt lgkmcnt(0)
	v_cvt_pk_bf16_f32 v3, v8, v9
	global_store_dwordx4 v[16:17], v[0:3], off sc1
	s_branch .LBB0_1551

; DI void stb8(bf16_t* p, const F8& f) { *(uint4*)p = pack8(f); }
; DI void wconv(const float* __restrict__ src, bf16_t* __restrict__ dst, int K, int N, int Npad, int perm, unsigned char* smem) {
;     ...
;             const int k = (tid >> 4) + 32 * j, nl4 = (tid & 15) * 4, n = n0 + nl4;
;             float4 v = make_float4(0.f, 0.f, 0.f, 0.f);
;             if (n < N) v = *(const float4*)(src + (size_t)(k0 + k) * N + n);
;             float* tp = tile + k * 65 + nl4; tp[0] = v.x; tp[1] = v.y; tp[2] = v.z; tp[3] = v.w;
;         }
;         __syncthreads();
;         const int nl = tid >> 3, kc = (tid & 7) * 8, n = n0 + nl;
;         if (n < Npad) {
;             int nd = n;
;             if (perm) nd = n < 2816 ? (n >> 6) * 128 + (n & 63) : ((n - 2816) >> 6) * 128 + 64 + ((n - 2816) & 63);
;             F8 a;
; #pragma unroll
;             for (int e = 0; e < 8; ++e) a.v[e] = tile[(kc + e) * 65 + nl];
;             stb8(dst + (size_t)nd * K + k0 + kc, a);
;         }
;         __syncthreads();
.LBB0_1562:
	s_or_b64 exec, exec, s[14:15]
	s_waitcnt vmcnt(1)
	ds_write2_b32 v13, v0, v1 offset1:1
	ds_write2_b32 v13, v2, v3 offset0:2 offset1:3
	v_add_u32_e32 v0, 0x2080, v13
	s_waitcnt vmcnt(0)
	ds_write2_b32 v0, v4, v5 offset1:1
	v_add_u32_e32 v0, 0x2088, v13
	ds_write2_b32 v0, v6, v7 offset1:1
	v_add_u32_e32 v0, s7, v12
	s_movk_i32 s7, 0x400
	v_cmp_gt_i32_e32 vcc, s7, v0
	s_waitcnt lgkmcnt(0)
	s_barrier
	s_and_saveexec_b64 s[14:15], vcc
	s_cbranch_execz .LBB0_1559
	v_add_u32_e32 v1, 0x400, v14
	ds_read2_b32 v[2:3], v14 offset1:65
	ds_read2_b32 v[4:5], v14 offset0:130 offset1:195
	ds_read2_b32 v[6:7], v1 offset0:4 offset1:69
	ds_read2_b32 v[8:9], v1 offset0:134 offset1:199
	v_ashrrev_i32_e32 v1, 31, v0
	v_readlane_b32 s26, v252, 47
	v_lshlrev_b64 v[0:1], 11, v[0:1]
	v_readlane_b32 s27, v252, 48
	s_ashr_i32 s7, s6, 31
	s_nop 0
	v_lshl_add_u64 v[0:1], s[26:27], 0, v[0:1]
	v_lshl_add_u64 v[0:1], s[6:7], 1, v[0:1]
	v_lshl_add_u64 v[16:17], v[0:1], 0, v[212:213]
	s_waitcnt lgkmcnt(3)
	v_cvt_pk_bf16_f32 v0, v2, v3
	s_waitcnt lgkmcnt(2)
	v_cvt_pk_bf16_f32 v1, v4, v5
	s_waitcnt lgkmcnt(1)
	v_cvt_pk_bf16_f32 v2, v6, v7
	s_waitcnt lgkmcnt(0)
	v_cvt_pk_bf16_f32 v3, v8, v9
	global_store_dwordx4 v[16:17], v[0:3], off sc1
	s_branch .LBB0_1559

; DI void stb8(bf16_t* p, const F8& f) { *(uint4*)p = pack8(f); }
; DI void wconv(const float* __restrict__ src, bf16_t* __restrict__ dst, int K, int N, int Npad, int perm, unsigned char* smem) {
;     ...
;             const int k = (tid >> 4) + 32 * j, nl4 = (tid & 15) * 4, n = n0 + nl4;
;             float4 v = make_float4(0.f, 0.f, 0.f, 0.f);
;             if (n < N) v = *(const float4*)(src + (size_t)(k0 + k) * N + n);
;             float* tp = tile + k * 65 + nl4; tp[0] = v.x; tp[1] = v.y; tp[2] = v.z; tp[3] = v.w;
;         }
;         __syncthreads();
;         const int nl = tid >> 3, kc = (tid & 7) * 8, n = n0 + nl;
;         if (n < Npad) {
;             int nd = n;
;             if (perm) nd = n < 2816 ? (n >> 6) * 128 + (n & 63) : ((n - 2816) >> 6) * 128 + 64 + ((n - 2816) & 63);
;             F8 a;
; #pragma unroll
;             for (int e = 0; e < 8; ++e) a.v[e] = tile[(kc + e) * 65 + nl];
;             stb8(dst + (size_t)nd * K + k0 + kc, a);
;         }
;         __syncthreads();
.LBB0_1571:
	s_or_b64 exec, exec, s[14:15]
	s_waitcnt vmcnt(1)
	ds_write2_b32 v13, v0, v1 offset1:1
	ds_write2_b32 v13, v2, v3 offset0:2 offset1:3
	v_add_u32_e32 v0, 0x2080, v13
	s_waitcnt vmcnt(0)
	ds_write2_b32 v0, v4, v5 offset1:1
	v_add_u32_e32 v0, 0x2088, v13
	ds_write2_b32 v0, v6, v7 offset1:1
	v_add_u32_e32 v0, s7, v12
	s_movk_i32 s7, 0x1100
	v_cmp_gt_i32_e32 vcc, s7, v0
	s_waitcnt lgkmcnt(0)
	s_barrier
	s_and_saveexec_b64 s[14:15], vcc
	s_cbranch_execz .LBB0_1568
	v_add_u32_e32 v1, 0x400, v14
	ds_read2_b32 v[2:3], v14 offset1:65
	ds_read2_b32 v[4:5], v14 offset0:130 offset1:195
	ds_read2_b32 v[6:7], v1 offset0:4 offset1:69
	ds_read2_b32 v[8:9], v1 offset0:134 offset1:199
	v_ashrrev_i32_e32 v1, 31, v0
	v_lshlrev_b64 v[0:1], 11, v[0:1]
	v_lshl_add_u64 v[0:1], s[62:63], 0, v[0:1]
	s_ashr_i32 s7, s6, 31
	v_lshl_add_u64 v[0:1], s[6:7], 1, v[0:1]
	v_lshl_add_u64 v[16:17], v[0:1], 0, v[212:213]
	s_waitcnt lgkmcnt(3)
	v_cvt_pk_bf16_f32 v0, v2, v3
	s_waitcnt lgkmcnt(2)
	v_cvt_pk_bf16_f32 v1, v4, v5
	s_waitcnt lgkmcnt(1)
	v_cvt_pk_bf16_f32 v2, v6, v7
	s_waitcnt lgkmcnt(0)
	v_cvt_pk_bf16_f32 v3, v8, v9
	global_store_dwordx4 v[16:17], v[0:3], off sc1
	s_branch .LBB0_1568

; DI void stb8(bf16_t* p, const F8& f) { *(uint4*)p = pack8(f); }
; DI void wconv(const float* __restrict__ src, bf16_t* __restrict__ dst, int K, int N, int Npad, int perm, unsigned char* smem) {
;     ...
;         const int nl = tid >> 3, kc = (tid & 7) * 8, n = n0 + nl;
;         if (n < Npad) {
;             int nd = n;
;             if (perm) nd = n < 2816 ? (n >> 6) * 128 + (n & 63) : ((n - 2816) >> 6) * 128 + 64 + ((n - 2816) & 63);
;             F8 a;
; #pragma unroll
;             for (int e = 0; e < 8; ++e) a.v[e] = tile[(kc + e) * 65 + nl];
;             stb8(dst + (size_t)nd * K + k0 + kc, a);
;         }
.LBB0_1582:
	s_or_b64 exec, exec, s[18:19]
	v_add_u32_e32 v1, 0x400, v16
	ds_read2_b32 v[2:3], v16 offset1:65
	ds_read2_b32 v[4:5], v16 offset0:130 offset1:195
	ds_read2_b32 v[6:7], v1 offset0:4 offset1:69
	ds_read2_b32 v[8:9], v1 offset0:134 offset1:199
	v_ashrrev_i32_e32 v1, 31, v0
	v_readlane_b32 s18, v252, 49
	v_lshlrev_b64 v[0:1], 11, v[0:1]
	v_readlane_b32 s19, v252, 50
	s_ashr_i32 s7, s6, 31
	s_nop 0
	v_lshl_add_u64 v[0:1], s[18:19], 0, v[0:1]
	v_lshl_add_u64 v[0:1], s[6:7], 1, v[0:1]
	v_lshl_add_u64 v[18:19], v[0:1], 0, v[212:213]
	s_waitcnt lgkmcnt(3)
	v_cvt_pk_bf16_f32 v0, v2, v3
	s_waitcnt lgkmcnt(2)
	v_cvt_pk_bf16_f32 v1, v4, v5
	s_waitcnt lgkmcnt(1)
	v_cvt_pk_bf16_f32 v2, v6, v7
	s_waitcnt lgkmcnt(0)
	v_cvt_pk_bf16_f32 v3, v8, v9
	global_store_dwordx4 v[18:19], v[0:3], off sc1

; DI void stb8(bf16_t* p, const F8& f) { *(uint4*)p = pack8(f); }
; DI void wconv(const float* __restrict__ src, bf16_t* __restrict__ dst, int K, int N, int Npad, int perm, unsigned char* smem) {
;     ...
;             const int k = (tid >> 4) + 32 * j, nl4 = (tid & 15) * 4, n = n0 + nl4;
;             float4 v = make_float4(0.f, 0.f, 0.f, 0.f);
;             if (n < N) v = *(const float4*)(src + (size_t)(k0 + k) * N + n);
;             float* tp = tile + k * 65 + nl4; tp[0] = v.x; tp[1] = v.y; tp[2] = v.z; tp[3] = v.w;
;         }
;         __syncthreads();
;         const int nl = tid >> 3, kc = (tid & 7) * 8, n = n0 + nl;
;         if (n < Npad) {
;             int nd = n;
;             if (perm) nd = n < 2816 ? (n >> 6) * 128 + (n & 63) : ((n - 2816) >> 6) * 128 + 64 + ((n - 2816) & 63);
;             F8 a;
; #pragma unroll
;             for (int e = 0; e < 8; ++e) a.v[e] = tile[(kc + e) * 65 + nl];
;             stb8(dst + (size_t)nd * K + k0 + kc, a);
;         }
;         __syncthreads();
.LBB0_1597:
	s_or_b64 exec, exec, s[14:15]
	s_waitcnt vmcnt(1)
	ds_write2_b32 v13, v0, v1 offset1:1
	ds_write2_b32 v13, v2, v3 offset0:2 offset1:3
	v_add_u32_e32 v0, 0x2080, v13
	s_waitcnt vmcnt(0)
	ds_write2_b32 v0, v4, v5 offset1:1
	v_add_u32_e32 v0, 0x2088, v13
	ds_write2_b32 v0, v6, v7 offset1:1
	v_add_u32_e32 v0, s7, v12
	v_cmp_gt_i32_e32 vcc, s19, v0
	s_waitcnt lgkmcnt(0)
	s_barrier
	s_and_saveexec_b64 s[14:15], vcc
	s_cbranch_execz .LBB0_1594
	v_add_u32_e32 v1, 0x400, v14
	ds_read2_b32 v[2:3], v14 offset1:65
	ds_read2_b32 v[4:5], v14 offset0:130 offset1:195
	ds_read2_b32 v[6:7], v1 offset0:4 offset1:69
	ds_read2_b32 v[8:9], v1 offset0:134 offset1:199
	v_readlane_b32 s22, v252, 51
	v_readlane_b32 s23, v252, 52
	s_ashr_i32 s7, s6, 31
	s_nop 0
	v_mov_b64_e32 v[16:17], s[22:23]
	v_mad_i64_i32 v[0:1], s[22:23], v0, s26, v[16:17]
	v_lshl_add_u64 v[0:1], s[6:7], 1, v[0:1]
	v_lshl_add_u64 v[16:17], v[0:1], 0, v[212:213]
	s_waitcnt lgkmcnt(3)
	v_cvt_pk_bf16_f32 v0, v2, v3
	s_waitcnt lgkmcnt(2)
	v_cvt_pk_bf16_f32 v1, v4, v5
	s_waitcnt lgkmcnt(1)
	v_cvt_pk_bf16_f32 v2, v6, v7
	s_waitcnt lgkmcnt(0)
	v_cvt_pk_bf16_f32 v3, v8, v9
	global_store_dwordx4 v[16:17], v[0:3], off sc1
	s_branch .LBB0_1594
